# combined (inverted prio + attention D!=C + fold) + snake-order MFMA clusters
# baseline (speedup 1.0000x reference)
; #define PG8_STAGE(bufoff, gbase, voff) do { _Pragma("unroll") for (int _i = 0; _i < 2; ++_i) \
;         __builtin_amdgcn_global_load_lds((const unsigned*)((const char*)(gbase) + (voff)[_i]), (LAS unsigned*)(lds + (bufoff) + ldsw + _i * 8192), 16, 0, 0); } while (0)
; #define PG8_LDA(dst, b, h) do { _Pragma("unroll") for (int m = 0; m < 4; ++m) _Pragma("unroll") for (int k = 0; k < 2; ++k) dst[m][k] = *(const LAS bf16x8*)(lds + PG8_SA(b, h) + aoff + m * 2048 + k * 1024); } while (0)
; #define PG8_LDB(dst, b, h) do { _Pragma("unroll") for (int n = 0; n < 2; ++n) _Pragma("unroll") for (int k = 0; k < 2; ++k) dst[n][k] = *(const LAS bf16x8*)(lds + PG8_SB(b, h) + boff + n * 2048 + k * 1024); } while (0)
; #define PG8_MMA(ai, bj, At, Bt) do { __builtin_amdgcn_s_setprio(1); _Pragma("unroll") for (int m = 0; m < 4; ++m) _Pragma("unroll") for (int n = 0; n < 2; ++n) _Pragma("unroll") for (int k = 0; k < 2; ++k) \
;         acc[ai][bj][m][n] = __builtin_amdgcn_mfma_f32_16x16x32_bf16(Bt[n][k], At[m][k], acc[ai][bj][m][n], 0, 0, 0); __builtin_amdgcn_s_setprio(0); } while (0)
; #define PG8_WAIT_V(n) asm volatile("s_waitcnt vmcnt(" #n ")" ::: "memory")
; #define PG8_WAIT_L(n) asm volatile("s_waitcnt lgkmcnt(" #n ")" ::: "memory")
; #define PG8_BAR __builtin_amdgcn_s_barrier()
; #define PG8_SCHED __builtin_amdgcn_sched_barrier(0)
; template <class Epi>
; __device__ __forceinline__ void gemm_phase(LAS unsigned char* lds, const Gemm g, int G, int c, const Epi& E) {
;     ...
;             const bool last = (t == nt - 2);
;             const char* a1 = cA + (size_t)(t + 1) * kstep;
;             const char* a2 = last ? nA : cA + (size_t)(t + 2) * kstep; const char* b2 = last ? nB : cB + (size_t)(t + 2) * kstep;
;             const char* a3 = a2 + kstep; const char* b3 = b2 + kstep;
;             PG8_LDB(B0, 0, 0); PG8_LDB(B1, 0, 1); PG8_SCHED; PG8_LDA(At, 0, 0); PG8_STAGE(PG8_SA(1, 1), a1 + hstepA, voffA);
;             PG8_WAIT_V(8); PG8_WAIT_L(0); PG8_BAR; PG8_MMA(0, 0, At, B0); PG8_MMA(0, 1, At, B1); PG8_BAR; PG8_SCHED;
;             PG8_LDA(At, 0, 1); PG8_STAGE(PG8_SB(0, 0), b2, voffB); PG8_STAGE(PG8_SB(0, 1), b2 + hstepB, voffB); PG8_STAGE(PG8_SA(0, 0), a2, voffA);
;             PG8_WAIT_V(8); PG8_WAIT_L(0); PG8_BAR; PG8_MMA(1, 0, At, B0); PG8_MMA(1, 1, At, B1); PG8_BAR; PG8_SCHED;
.LBB0_236:
	ds_read_b128 v[146:149], v152
	ds_read_b128 v[158:161], v152 offset:1024
	ds_read_b128 v[162:165], v152 offset:2048
	ds_read_b128 v[166:169], v152 offset:3072
	ds_read_b128 v[170:173], v153
	ds_read_b128 v[174:177], v153 offset:1024
	ds_read_b128 v[178:181], v153 offset:2048
	ds_read_b128 v[182:185], v153 offset:3072
	s_add_u32 s33, s4, 0xfffc0080
	s_addc_u32 s54, s5, -1
	s_cmp_eq_u32 s85, 12
	s_cselect_b32 s57, s47, s54
	s_cselect_b32 s56, s46, s33
	s_cselect_b32 s55, s7, s84
	s_cselect_b32 s54, s43, s45
	v_lshl_add_u64 v[218:219], s[4:5], 0, v[138:139]
	s_add_i32 m0, s11, 0xc000
	ds_read_b128 v[186:189], v154
	ds_read_b128 v[190:193], v154 offset:1024
	ds_read_b128 v[194:197], v154 offset:2048
	ds_read_b128 v[198:201], v154 offset:3072
	ds_read_b128 v[202:205], v154 offset:4096
	ds_read_b128 v[206:209], v154 offset:5120
	ds_read_b128 v[210:213], v154 offset:6144
	ds_read_b128 v[214:217], v154 offset:7168
	global_load_lds_dwordx4 v[218:219], off
	v_lshl_add_u64 v[218:219], s[4:5], 0, v[140:141]
	s_add_i32 m0, s11, 0xe000
	s_nop 0
	global_load_lds_dwordx4 v[218:219], off
	s_waitcnt vmcnt(8)
	s_waitcnt lgkmcnt(0)
	s_barrier
	s_setprio 0
	s_waitcnt lgkmcnt(0)
	v_mfma_f32_16x16x32_bf16 v[126:129], v[146:149], v[186:189], v[126:129]
	v_mfma_f32_16x16x32_bf16 v[122:125], v[162:165], v[186:189], v[122:125]
	v_mfma_f32_16x16x32_bf16 v[106:109], v[162:165], v[194:197], v[106:109]
	v_mfma_f32_16x16x32_bf16 v[110:113], v[146:149], v[194:197], v[110:113]
	v_mfma_f32_16x16x32_bf16 v[94:97], v[146:149], v[202:205], v[94:97]
	v_mfma_f32_16x16x32_bf16 v[90:93], v[162:165], v[202:205], v[90:93]
	v_mfma_f32_16x16x32_bf16 v[74:77], v[162:165], v[210:213], v[74:77]
	v_mfma_f32_16x16x32_bf16 v[78:81], v[146:149], v[210:213], v[78:81]
	v_mfma_f32_16x16x32_bf16 v[126:129], v[158:161], v[190:193], v[126:129]
	v_mfma_f32_16x16x32_bf16 v[122:125], v[166:169], v[190:193], v[122:125]
	v_mfma_f32_16x16x32_bf16 v[106:109], v[166:169], v[198:201], v[106:109]
	v_mfma_f32_16x16x32_bf16 v[110:113], v[158:161], v[198:201], v[110:113]
	v_mfma_f32_16x16x32_bf16 v[94:97], v[158:161], v[206:209], v[94:97]
	v_mfma_f32_16x16x32_bf16 v[90:93], v[166:169], v[206:209], v[90:93]
	v_mfma_f32_16x16x32_bf16 v[74:77], v[166:169], v[214:217], v[74:77]
	v_mfma_f32_16x16x32_bf16 v[78:81], v[158:161], v[214:217], v[78:81]
	s_setprio 2
	s_setprio 0
	v_mfma_f32_16x16x32_bf16 v[118:121], v[170:173], v[186:189], v[118:121]
	v_mfma_f32_16x16x32_bf16 v[114:117], v[178:181], v[186:189], v[114:117]
	v_mfma_f32_16x16x32_bf16 v[98:101], v[178:181], v[194:197], v[98:101]
	v_mfma_f32_16x16x32_bf16 v[102:105], v[170:173], v[194:197], v[102:105]
	v_mfma_f32_16x16x32_bf16 v[86:89], v[170:173], v[202:205], v[86:89]
	v_mfma_f32_16x16x32_bf16 v[82:85], v[178:181], v[202:205], v[82:85]
	v_mfma_f32_16x16x32_bf16 v[66:69], v[178:181], v[210:213], v[66:69]
	v_mfma_f32_16x16x32_bf16 v[70:73], v[170:173], v[210:213], v[70:73]
	v_mfma_f32_16x16x32_bf16 v[118:121], v[174:177], v[190:193], v[118:121]
	v_mfma_f32_16x16x32_bf16 v[114:117], v[182:185], v[190:193], v[114:117]
	v_mfma_f32_16x16x32_bf16 v[98:101], v[182:185], v[198:201], v[98:101]
	v_mfma_f32_16x16x32_bf16 v[102:105], v[174:177], v[198:201], v[102:105]
	v_mfma_f32_16x16x32_bf16 v[86:89], v[174:177], v[206:209], v[86:89]
	v_mfma_f32_16x16x32_bf16 v[82:85], v[182:185], v[206:209], v[82:85]
	v_mfma_f32_16x16x32_bf16 v[66:69], v[182:185], v[214:217], v[66:69]
	v_mfma_f32_16x16x32_bf16 v[70:73], v[174:177], v[214:217], v[70:73]
	s_setprio 2
	s_barrier
	s_add_i32 s33, s79, s60
	v_lshl_add_u64 v[218:219], s[54:55], 0, v[132:133]
	s_mov_b32 m0, s33
	ds_read_b128 v[186:189], v154 offset:16384
	ds_read_b128 v[190:193], v154 offset:17408
	ds_read_b128 v[194:197], v154 offset:18432
	ds_read_b128 v[198:201], v154 offset:19456
	ds_read_b128 v[202:205], v154 offset:20480
	ds_read_b128 v[206:209], v154 offset:21504
	ds_read_b128 v[210:213], v154 offset:22528
	ds_read_b128 v[214:217], v154 offset:23552
	global_load_lds_dwordx4 v[218:219], off
	s_add_i32 m0, s33, 0x2000
	s_add_u32 s62, s54, 0x40000
	v_lshl_add_u64 v[220:221], s[54:55], 0, v[136:137]
	s_addc_u32 s63, s55, 0
	s_add_i32 s33, s80, s60
	global_load_lds_dwordx4 v[220:221], off
	v_lshl_add_u64 v[222:223], s[62:63], 0, v[132:133]
	s_mov_b32 m0, s33
	v_lshl_add_u64 v[224:225], s[56:57], 0, v[134:135]
	global_load_lds_dwordx4 v[222:223], off
	v_lshl_add_u64 v[222:223], s[62:63], 0, v[136:137]
	s_add_i32 m0, s33, 0x2000
	s_nop 0
	global_load_lds_dwordx4 v[222:223], off
	v_lshl_add_u64 v[222:223], s[56:57], 0, v[130:131]
	s_mov_b32 m0, s11
	s_nop 0
	global_load_lds_dwordx4 v[222:223], off
	s_mov_b32 m0, s61
	s_nop 0
	global_load_lds_dwordx4 v[224:225], off
	s_waitcnt vmcnt(8)
	s_waitcnt lgkmcnt(0)
	s_barrier
; #define PG8_STAGE(bufoff, gbase, voff) do { _Pragma("unroll") for (int _i = 0; _i < 2; ++_i) \
;         __builtin_amdgcn_global_load_lds((const unsigned*)((const char*)(gbase) + (voff)[_i]), (LAS unsigned*)(lds + (bufoff) + ldsw + _i * 8192), 16, 0, 0); } while (0)
; #define PG8_LDA(dst, b, h) do { _Pragma("unroll") for (int m = 0; m < 4; ++m) _Pragma("unroll") for (int k = 0; k < 2; ++k) dst[m][k] = *(const LAS bf16x8*)(lds + PG8_SA(b, h) + aoff + m * 2048 + k * 1024); } while (0)
; #define PG8_LDB(dst, b, h) do { _Pragma("unroll") for (int n = 0; n < 2; ++n) _Pragma("unroll") for (int k = 0; k < 2; ++k) dst[n][k] = *(const LAS bf16x8*)(lds + PG8_SB(b, h) + boff + n * 2048 + k * 1024); } while (0)
; #define PG8_MMA(ai, bj, At, Bt) do { __builtin_amdgcn_s_setprio(1); _Pragma("unroll") for (int m = 0; m < 4; ++m) _Pragma("unroll") for (int n = 0; n < 2; ++n) _Pragma("unroll") for (int k = 0; k < 2; ++k) \
;         acc[ai][bj][m][n] = __builtin_amdgcn_mfma_f32_16x16x32_bf16(Bt[n][k], At[m][k], acc[ai][bj][m][n], 0, 0, 0); __builtin_amdgcn_s_setprio(0); } while (0)
; #define PG8_WAIT_V(n) asm volatile("s_waitcnt vmcnt(" #n ")" ::: "memory")
; #define PG8_WAIT_L(n) asm volatile("s_waitcnt lgkmcnt(" #n ")" ::: "memory")
; #define PG8_BAR __builtin_amdgcn_s_barrier()
; #define PG8_SCHED __builtin_amdgcn_sched_barrier(0)
; template <class Epi>
; __device__ __forceinline__ void gemm_phase(LAS unsigned char* lds, const Gemm g, int G, int c, const Epi& E) {
;     ...
;             PG8_WAIT_V(8); PG8_WAIT_L(0); PG8_BAR; PG8_MMA(1, 0, At, B0); PG8_MMA(1, 1, At, B1); PG8_BAR; PG8_SCHED;
;             PG8_LDB(B0, 1, 0); PG8_LDB(B1, 1, 1); PG8_SCHED; PG8_LDA(At, 1, 0); PG8_STAGE(PG8_SA(0, 1), a2 + hstepA, voffA);
;             PG8_WAIT_V(8); PG8_WAIT_L(0); PG8_BAR; PG8_MMA(0, 0, At, B0); PG8_MMA(0, 1, At, B1); PG8_BAR; PG8_SCHED;
	s_setprio 0
	s_waitcnt lgkmcnt(0)
	v_mfma_f32_16x16x32_bf16 v[62:65], v[146:149], v[186:189], v[62:65]
	v_mfma_f32_16x16x32_bf16 v[58:61], v[162:165], v[186:189], v[58:61]
	v_mfma_f32_16x16x32_bf16 v[42:45], v[162:165], v[194:197], v[42:45]
	v_mfma_f32_16x16x32_bf16 v[46:49], v[146:149], v[194:197], v[46:49]
	v_mfma_f32_16x16x32_bf16 v[30:33], v[146:149], v[202:205], v[30:33]
	v_mfma_f32_16x16x32_bf16 v[26:29], v[162:165], v[202:205], v[26:29]
	v_mfma_f32_16x16x32_bf16 v[10:13], v[162:165], v[210:213], v[10:13]
	v_mfma_f32_16x16x32_bf16 v[14:17], v[146:149], v[210:213], v[14:17]
	v_mfma_f32_16x16x32_bf16 v[62:65], v[158:161], v[190:193], v[62:65]
	v_mfma_f32_16x16x32_bf16 v[58:61], v[166:169], v[190:193], v[58:61]
	v_mfma_f32_16x16x32_bf16 v[42:45], v[166:169], v[198:201], v[42:45]
	v_mfma_f32_16x16x32_bf16 v[46:49], v[158:161], v[198:201], v[46:49]
	v_mfma_f32_16x16x32_bf16 v[30:33], v[158:161], v[206:209], v[30:33]
	v_mfma_f32_16x16x32_bf16 v[26:29], v[166:169], v[206:209], v[26:29]
	v_mfma_f32_16x16x32_bf16 v[10:13], v[166:169], v[214:217], v[10:13]
	v_mfma_f32_16x16x32_bf16 v[14:17], v[158:161], v[214:217], v[14:17]
	s_setprio 2
	s_setprio 0
	v_mfma_f32_16x16x32_bf16 v[54:57], v[170:173], v[186:189], v[54:57]
	v_mfma_f32_16x16x32_bf16 v[50:53], v[178:181], v[186:189], v[50:53]
	v_mfma_f32_16x16x32_bf16 v[34:37], v[178:181], v[194:197], v[34:37]
	v_mfma_f32_16x16x32_bf16 v[38:41], v[170:173], v[194:197], v[38:41]
	v_mfma_f32_16x16x32_bf16 v[22:25], v[170:173], v[202:205], v[22:25]
	v_mfma_f32_16x16x32_bf16 v[18:21], v[178:181], v[202:205], v[18:21]
	v_mfma_f32_16x16x32_bf16 v[2:5], v[178:181], v[210:213], v[2:5]
	v_mfma_f32_16x16x32_bf16 v[6:9], v[170:173], v[210:213], v[6:9]
	v_mfma_f32_16x16x32_bf16 v[54:57], v[174:177], v[190:193], v[54:57]
	v_mfma_f32_16x16x32_bf16 v[50:53], v[182:185], v[190:193], v[50:53]
	v_mfma_f32_16x16x32_bf16 v[34:37], v[182:185], v[198:201], v[34:37]
	v_mfma_f32_16x16x32_bf16 v[38:41], v[174:177], v[198:201], v[38:41]
	v_mfma_f32_16x16x32_bf16 v[22:25], v[174:177], v[206:209], v[22:25]
	v_mfma_f32_16x16x32_bf16 v[18:21], v[182:185], v[206:209], v[18:21]
	v_mfma_f32_16x16x32_bf16 v[2:5], v[182:185], v[214:217], v[2:5]
	v_mfma_f32_16x16x32_bf16 v[6:9], v[174:177], v[214:217], v[6:9]
	s_setprio 2
	s_barrier
	s_add_i32 s33, 0, 0x18000
	v_add_u32_e32 v157, s33, v151
	s_add_i32 s62, 0, 0x1c000
	ds_read_b128 v[146:149], v157
	ds_read_b128 v[158:161], v157 offset:1024
	ds_read_b128 v[162:165], v157 offset:2048
	ds_read_b128 v[166:169], v157 offset:3072
	v_add_u32_e32 v157, s62, v151
	ds_read_b128 v[170:173], v157
	ds_read_b128 v[174:177], v157 offset:1024
	ds_read_b128 v[178:181], v157 offset:2048
	ds_read_b128 v[182:185], v157 offset:3072
	s_add_u32 s56, s56, 0x40000
	s_addc_u32 s57, s57, 0
	s_mov_b32 m0, s66
	v_lshl_add_u64 v[226:227], s[56:57], 0, v[130:131]
	ds_read_b128 v[186:189], v154 offset:32768
	ds_read_b128 v[190:193], v154 offset:33792
	ds_read_b128 v[194:197], v154 offset:34816
	ds_read_b128 v[198:201], v154 offset:35840
	ds_read_b128 v[202:205], v154 offset:36864
	ds_read_b128 v[206:209], v154 offset:37888
	ds_read_b128 v[210:213], v154 offset:38912
	ds_read_b128 v[214:217], v154 offset:39936
	global_load_lds_dwordx4 v[226:227], off
	v_lshl_add_u64 v[226:227], s[56:57], 0, v[134:135]
	s_mov_b32 m0, s67
	s_nop 0
	global_load_lds_dwordx4 v[226:227], off
	s_waitcnt vmcnt(8)
	s_waitcnt lgkmcnt(0)
	s_barrier
	s_setprio 0
	s_waitcnt lgkmcnt(0)
	v_mfma_f32_16x16x32_bf16 v[126:129], v[146:149], v[186:189], v[126:129]
	v_mfma_f32_16x16x32_bf16 v[122:125], v[162:165], v[186:189], v[122:125]
	v_mfma_f32_16x16x32_bf16 v[106:109], v[162:165], v[194:197], v[106:109]
	v_mfma_f32_16x16x32_bf16 v[110:113], v[146:149], v[194:197], v[110:113]
	v_mfma_f32_16x16x32_bf16 v[94:97], v[146:149], v[202:205], v[94:97]
	v_mfma_f32_16x16x32_bf16 v[90:93], v[162:165], v[202:205], v[90:93]
	v_mfma_f32_16x16x32_bf16 v[74:77], v[162:165], v[210:213], v[74:77]
	v_mfma_f32_16x16x32_bf16 v[78:81], v[146:149], v[210:213], v[78:81]
	v_mfma_f32_16x16x32_bf16 v[126:129], v[158:161], v[190:193], v[126:129]
	v_mfma_f32_16x16x32_bf16 v[122:125], v[166:169], v[190:193], v[122:125]
	v_mfma_f32_16x16x32_bf16 v[106:109], v[166:169], v[198:201], v[106:109]
	v_mfma_f32_16x16x32_bf16 v[110:113], v[158:161], v[198:201], v[110:113]
	v_mfma_f32_16x16x32_bf16 v[94:97], v[158:161], v[206:209], v[94:97]
	v_mfma_f32_16x16x32_bf16 v[90:93], v[166:169], v[206:209], v[90:93]
	v_mfma_f32_16x16x32_bf16 v[74:77], v[166:169], v[214:217], v[74:77]
	v_mfma_f32_16x16x32_bf16 v[78:81], v[158:161], v[214:217], v[78:81]
	s_setprio 2
	s_setprio 0
	v_mfma_f32_16x16x32_bf16 v[118:121], v[170:173], v[186:189], v[118:121]
	v_mfma_f32_16x16x32_bf16 v[114:117], v[178:181], v[186:189], v[114:117]
	v_mfma_f32_16x16x32_bf16 v[98:101], v[178:181], v[194:197], v[98:101]
	v_mfma_f32_16x16x32_bf16 v[102:105], v[170:173], v[194:197], v[102:105]
	v_mfma_f32_16x16x32_bf16 v[86:89], v[170:173], v[202:205], v[86:89]
	v_mfma_f32_16x16x32_bf16 v[82:85], v[178:181], v[202:205], v[82:85]
	v_mfma_f32_16x16x32_bf16 v[66:69], v[178:181], v[210:213], v[66:69]
	v_mfma_f32_16x16x32_bf16 v[70:73], v[170:173], v[210:213], v[70:73]
	v_mfma_f32_16x16x32_bf16 v[118:121], v[174:177], v[190:193], v[118:121]
	v_mfma_f32_16x16x32_bf16 v[114:117], v[182:185], v[190:193], v[114:117]
	v_mfma_f32_16x16x32_bf16 v[98:101], v[182:185], v[198:201], v[98:101]
	v_mfma_f32_16x16x32_bf16 v[102:105], v[174:177], v[198:201], v[102:105]
	v_mfma_f32_16x16x32_bf16 v[86:89], v[174:177], v[206:209], v[86:89]
	v_mfma_f32_16x16x32_bf16 v[82:85], v[182:185], v[206:209], v[82:85]
	v_mfma_f32_16x16x32_bf16 v[66:69], v[182:185], v[214:217], v[66:69]
	v_mfma_f32_16x16x32_bf16 v[70:73], v[174:177], v[214:217], v[70:73]
	s_setprio 2
	s_barrier
; #define PG8_STAGE(bufoff, gbase, voff) do { _Pragma("unroll") for (int _i = 0; _i < 2; ++_i) \
;         __builtin_amdgcn_global_load_lds((const unsigned*)((const char*)(gbase) + (voff)[_i]), (LAS unsigned*)(lds + (bufoff) + ldsw + _i * 8192), 16, 0, 0); } while (0)
; #define PG8_LDA(dst, b, h) do { _Pragma("unroll") for (int m = 0; m < 4; ++m) _Pragma("unroll") for (int k = 0; k < 2; ++k) dst[m][k] = *(const LAS bf16x8*)(lds + PG8_SA(b, h) + aoff + m * 2048 + k * 1024); } while (0)
; #define PG8_MMA(ai, bj, At, Bt) do { __builtin_amdgcn_s_setprio(1); _Pragma("unroll") for (int m = 0; m < 4; ++m) _Pragma("unroll") for (int n = 0; n < 2; ++n) _Pragma("unroll") for (int k = 0; k < 2; ++k) \
;         acc[ai][bj][m][n] = __builtin_amdgcn_mfma_f32_16x16x32_bf16(Bt[n][k], At[m][k], acc[ai][bj][m][n], 0, 0, 0); __builtin_amdgcn_s_setprio(0); } while (0)
; #define PG8_WAIT_V(n) asm volatile("s_waitcnt vmcnt(" #n ")" ::: "memory")
; #define PG8_WAIT_L(n) asm volatile("s_waitcnt lgkmcnt(" #n ")" ::: "memory")
; #define PG8_BAR __builtin_amdgcn_s_barrier()
; #define PG8_SCHED __builtin_amdgcn_sched_barrier(0)
; template <class Epi>
; __device__ __forceinline__ void gemm_phase(LAS unsigned char* lds, const Gemm g, int G, int c, const Epi& E) {
;     ...
;             PG8_LDA(At, 1, 1); PG8_STAGE(PG8_SB(1, 0), b3, voffB); PG8_STAGE(PG8_SB(1, 1), b3 + hstepB, voffB); PG8_STAGE(PG8_SA(1, 0), a3, voffA);
;             PG8_WAIT_V(8); PG8_WAIT_L(0); PG8_BAR; PG8_MMA(1, 0, At, B0); PG8_MMA(1, 1, At, B1); PG8_BAR; PG8_SCHED;
;         }
	s_add_i32 s33, s33, s60
	v_lshl_add_u64 v[218:219], v[218:219], 0, s[20:21]
	s_mov_b32 m0, s33
	ds_read_b128 v[186:189], v154 offset:49152
	ds_read_b128 v[190:193], v154 offset:50176
	ds_read_b128 v[194:197], v154 offset:51200
	ds_read_b128 v[198:201], v154 offset:52224
	ds_read_b128 v[202:205], v154 offset:53248
	ds_read_b128 v[206:209], v154 offset:54272
	ds_read_b128 v[210:213], v154 offset:55296
	ds_read_b128 v[214:217], v154 offset:56320
	global_load_lds_dwordx4 v[218:219], off
	s_add_i32 m0, s33, 0x2000
	s_add_u32 s54, s54, 0x40080
	v_lshl_add_u64 v[218:219], v[220:221], 0, s[20:21]
	s_addc_u32 s55, s55, 0
	s_add_i32 s33, s62, s60
	global_load_lds_dwordx4 v[218:219], off
	v_lshl_add_u64 v[218:219], s[54:55], 0, v[132:133]
	s_mov_b32 m0, s33
	s_nop 0
	global_load_lds_dwordx4 v[218:219], off
	v_lshl_add_u64 v[218:219], s[54:55], 0, v[136:137]
	s_add_i32 m0, s33, 0x2000
	s_nop 0
	global_load_lds_dwordx4 v[218:219], off
	v_lshl_add_u64 v[218:219], v[222:223], 0, s[20:21]
	s_mov_b32 m0, s71
	s_nop 0
	global_load_lds_dwordx4 v[218:219], off
	v_lshl_add_u64 v[218:219], v[224:225], 0, s[20:21]
	s_mov_b32 m0, s72
	s_nop 0
	global_load_lds_dwordx4 v[218:219], off
	s_waitcnt vmcnt(8)
	s_waitcnt lgkmcnt(0)
	s_barrier
	s_setprio 0
	s_waitcnt lgkmcnt(0)
	v_mfma_f32_16x16x32_bf16 v[62:65], v[146:149], v[186:189], v[62:65]
	v_mfma_f32_16x16x32_bf16 v[58:61], v[162:165], v[186:189], v[58:61]
	v_mfma_f32_16x16x32_bf16 v[42:45], v[162:165], v[194:197], v[42:45]
	v_mfma_f32_16x16x32_bf16 v[46:49], v[146:149], v[194:197], v[46:49]
	v_mfma_f32_16x16x32_bf16 v[30:33], v[146:149], v[202:205], v[30:33]
	v_mfma_f32_16x16x32_bf16 v[26:29], v[162:165], v[202:205], v[26:29]
	v_mfma_f32_16x16x32_bf16 v[10:13], v[162:165], v[210:213], v[10:13]
	v_mfma_f32_16x16x32_bf16 v[14:17], v[146:149], v[210:213], v[14:17]
	v_mfma_f32_16x16x32_bf16 v[62:65], v[158:161], v[190:193], v[62:65]
	v_mfma_f32_16x16x32_bf16 v[58:61], v[166:169], v[190:193], v[58:61]
	v_mfma_f32_16x16x32_bf16 v[42:45], v[166:169], v[198:201], v[42:45]
	v_mfma_f32_16x16x32_bf16 v[46:49], v[158:161], v[198:201], v[46:49]
	v_mfma_f32_16x16x32_bf16 v[30:33], v[158:161], v[206:209], v[30:33]
	v_mfma_f32_16x16x32_bf16 v[26:29], v[166:169], v[206:209], v[26:29]
	v_mfma_f32_16x16x32_bf16 v[10:13], v[166:169], v[214:217], v[10:13]
	v_mfma_f32_16x16x32_bf16 v[14:17], v[158:161], v[214:217], v[14:17]
	s_setprio 2
	s_setprio 0
	v_mfma_f32_16x16x32_bf16 v[54:57], v[170:173], v[186:189], v[54:57]
	v_mfma_f32_16x16x32_bf16 v[50:53], v[178:181], v[186:189], v[50:53]
	v_mfma_f32_16x16x32_bf16 v[34:37], v[178:181], v[194:197], v[34:37]
	v_mfma_f32_16x16x32_bf16 v[38:41], v[170:173], v[194:197], v[38:41]
	v_mfma_f32_16x16x32_bf16 v[22:25], v[170:173], v[202:205], v[22:25]
	v_mfma_f32_16x16x32_bf16 v[18:21], v[178:181], v[202:205], v[18:21]
	v_mfma_f32_16x16x32_bf16 v[2:5], v[178:181], v[210:213], v[2:5]
	v_mfma_f32_16x16x32_bf16 v[6:9], v[170:173], v[210:213], v[6:9]
	v_mfma_f32_16x16x32_bf16 v[54:57], v[174:177], v[190:193], v[54:57]
	v_mfma_f32_16x16x32_bf16 v[50:53], v[182:185], v[190:193], v[50:53]
	v_mfma_f32_16x16x32_bf16 v[34:37], v[182:185], v[198:201], v[34:37]
	v_mfma_f32_16x16x32_bf16 v[38:41], v[174:177], v[198:201], v[38:41]
	v_mfma_f32_16x16x32_bf16 v[22:25], v[174:177], v[206:209], v[22:25]
	v_mfma_f32_16x16x32_bf16 v[18:21], v[182:185], v[206:209], v[18:21]
	v_mfma_f32_16x16x32_bf16 v[2:5], v[182:185], v[214:217], v[2:5]
	v_mfma_f32_16x16x32_bf16 v[6:9], v[174:177], v[214:217], v[6:9]
	s_setprio 2
	s_barrier
	s_add_i32 s85, s85, 2
	s_add_u32 s4, s4, 0x100
	s_addc_u32 s5, s5, 0
	s_add_u32 s45, s45, 0x100
	s_addc_u32 s84, s84, 0
	s_cmp_gt_u32 s85, 13
	s_cbranch_scc0 .LBB0_236
	s_and_b64 vcc, exec, s[22:23]
	s_cbranch_vccz .LBB0_239
	s_barrier

; #define PG8_STAGE(bufoff, gbase, voff) do { _Pragma("unroll") for (int _i = 0; _i < 2; ++_i) \
;         __builtin_amdgcn_global_load_lds((const unsigned*)((const char*)(gbase) + (voff)[_i]), (LAS unsigned*)(lds + (bufoff) + ldsw + _i * 8192), 16, 0, 0); } while (0)
; #define PG8_LDA(dst, b, h) do { _Pragma("unroll") for (int m = 0; m < 4; ++m) _Pragma("unroll") for (int k = 0; k < 2; ++k) dst[m][k] = *(const LAS bf16x8*)(lds + PG8_SA(b, h) + aoff + m * 2048 + k * 1024); } while (0)
; #define PG8_LDB(dst, b, h) do { _Pragma("unroll") for (int n = 0; n < 2; ++n) _Pragma("unroll") for (int k = 0; k < 2; ++k) dst[n][k] = *(const LAS bf16x8*)(lds + PG8_SB(b, h) + boff + n * 2048 + k * 1024); } while (0)
; #define PG8_MMA(ai, bj, At, Bt) do { __builtin_amdgcn_s_setprio(1); _Pragma("unroll") for (int m = 0; m < 4; ++m) _Pragma("unroll") for (int n = 0; n < 2; ++n) _Pragma("unroll") for (int k = 0; k < 2; ++k) \
;         acc[ai][bj][m][n] = __builtin_amdgcn_mfma_f32_16x16x32_bf16(Bt[n][k], At[m][k], acc[ai][bj][m][n], 0, 0, 0); __builtin_amdgcn_s_setprio(0); } while (0)
; #define PG8_WAIT_V(n) asm volatile("s_waitcnt vmcnt(" #n ")" ::: "memory")
; #define PG8_WAIT_L(n) asm volatile("s_waitcnt lgkmcnt(" #n ")" ::: "memory")
; #define PG8_BAR __builtin_amdgcn_s_barrier()
; #define PG8_SCHED __builtin_amdgcn_sched_barrier(0)
; template <class Epi>
; __device__ __forceinline__ void gemm_phase(LAS unsigned char* lds, const Gemm g, int G, int c, const Epi& E) {
;     ...
;             const bool last = (t == nt - 2);
;             const char* a1 = cA + (size_t)(t + 1) * kstep;
;             const char* a2 = last ? nA : cA + (size_t)(t + 2) * kstep; const char* b2 = last ? nB : cB + (size_t)(t + 2) * kstep;
;             const char* a3 = a2 + kstep; const char* b3 = b2 + kstep;
;             PG8_LDB(B0, 0, 0); PG8_LDB(B1, 0, 1); PG8_SCHED; PG8_LDA(At, 0, 0); PG8_STAGE(PG8_SA(1, 1), a1 + hstepA, voffA);
;             PG8_WAIT_V(8); PG8_WAIT_L(0); PG8_BAR; PG8_MMA(0, 0, At, B0); PG8_MMA(0, 1, At, B1); PG8_BAR; PG8_SCHED;
;             PG8_LDA(At, 0, 1); PG8_STAGE(PG8_SB(0, 0), b2, voffB); PG8_STAGE(PG8_SB(0, 1), b2 + hstepB, voffB); PG8_STAGE(PG8_SA(0, 0), a2, voffA);
;             PG8_WAIT_V(8); PG8_WAIT_L(0); PG8_BAR; PG8_MMA(1, 0, At, B0); PG8_MMA(1, 1, At, B1); PG8_BAR; PG8_SCHED;
.LBB0_368:
	s_add_u32 s33, s20, s13
	s_addc_u32 s42, s21, 0
	s_add_u32 s43, s33, 0x100
	s_addc_u32 s44, s42, 0
	s_and_b64 s[38:39], s[24:25], exec
	s_cselect_b32 s45, s5, s44
	s_cselect_b32 s44, s4, s43
	s_add_u32 s13, s18, s13
	s_addc_u32 s38, s19, 0
	s_add_u32 s13, s13, 0x100
	s_addc_u32 s38, s38, 0
	s_and_b64 s[24:25], s[24:25], exec
	s_cselect_b32 s47, s17, s38
	s_cselect_b32 s46, s16, s13
	s_add_u32 s54, s33, 0xb0080
	s_addc_u32 s55, s42, 0
	s_add_i32 s65, s81, s56
	ds_read_b128 v[142:145], v148
	ds_read_b128 v[152:155], v148 offset:1024
	ds_read_b128 v[156:159], v148 offset:2048
	ds_read_b128 v[160:163], v148 offset:3072
	ds_read_b128 v[164:167], v149
	ds_read_b128 v[168:171], v149 offset:1024
	ds_read_b128 v[172:175], v149 offset:2048
	ds_read_b128 v[176:179], v149 offset:3072
	s_add_i32 m0, s57, 0xc000
	s_add_i32 s74, s57, 0xe000
	s_add_i32 s62, s65, 0x2000
	s_add_u32 s52, s46, 0xb0000
	s_addc_u32 s53, s47, 0
	s_add_i32 s64, s82, s56
	s_add_i32 s63, s64, 0x2000
	s_add_i32 s73, 0, 0x18000
	s_add_i32 s33, 0, 0x1c000
	s_add_u32 s42, s44, 0xb0000
	s_addc_u32 s43, s45, 0
	s_add_i32 s88, s73, s56
	s_add_i32 s38, s88, 0x2000
	s_add_u32 s24, s46, 0xb0080
	s_addc_u32 s25, s47, 0
	s_add_i32 s39, s33, s56
	s_add_i32 s13, s39, 0x2000
	v_lshl_add_u64 v[212:213], s[54:55], 0, v[136:137]
	ds_read_b128 v[180:183], v150
	ds_read_b128 v[184:187], v150 offset:1024
	ds_read_b128 v[188:191], v150 offset:2048
	ds_read_b128 v[192:195], v150 offset:3072
	ds_read_b128 v[196:199], v150 offset:4096
	ds_read_b128 v[200:203], v150 offset:5120
	ds_read_b128 v[204:207], v150 offset:6144
	ds_read_b128 v[208:211], v150 offset:7168
	global_load_lds_dwordx4 v[212:213], off
	v_lshl_add_u64 v[212:213], s[54:55], 0, v[132:133]
	s_mov_b32 m0, s74
	s_nop 0
	global_load_lds_dwordx4 v[212:213], off
	s_waitcnt vmcnt(8)
	s_waitcnt lgkmcnt(0)
	s_barrier
	s_setprio 0
	s_waitcnt lgkmcnt(0)
	v_mfma_f32_16x16x32_bf16 v[126:129], v[142:145], v[180:183], v[126:129]
	v_mfma_f32_16x16x32_bf16 v[122:125], v[156:159], v[180:183], v[122:125]
	v_mfma_f32_16x16x32_bf16 v[110:113], v[156:159], v[188:191], v[110:113]
	v_mfma_f32_16x16x32_bf16 v[118:121], v[142:145], v[188:191], v[118:121]
	v_mfma_f32_16x16x32_bf16 v[102:105], v[142:145], v[196:199], v[102:105]
	v_mfma_f32_16x16x32_bf16 v[94:97], v[156:159], v[196:199], v[94:97]
	v_mfma_f32_16x16x32_bf16 v[78:81], v[156:159], v[204:207], v[78:81]
	v_mfma_f32_16x16x32_bf16 v[86:89], v[142:145], v[204:207], v[86:89]
	v_mfma_f32_16x16x32_bf16 v[126:129], v[152:155], v[184:187], v[126:129]
	v_mfma_f32_16x16x32_bf16 v[122:125], v[160:163], v[184:187], v[122:125]
	v_mfma_f32_16x16x32_bf16 v[110:113], v[160:163], v[192:195], v[110:113]
	v_mfma_f32_16x16x32_bf16 v[118:121], v[152:155], v[192:195], v[118:121]
	v_mfma_f32_16x16x32_bf16 v[102:105], v[152:155], v[200:203], v[102:105]
	v_mfma_f32_16x16x32_bf16 v[94:97], v[160:163], v[200:203], v[94:97]
	v_mfma_f32_16x16x32_bf16 v[78:81], v[160:163], v[208:211], v[78:81]
	v_mfma_f32_16x16x32_bf16 v[86:89], v[152:155], v[208:211], v[86:89]
	s_setprio 2
	s_setprio 0
	v_mfma_f32_16x16x32_bf16 v[114:117], v[164:167], v[180:183], v[114:117]
	v_mfma_f32_16x16x32_bf16 v[106:109], v[172:175], v[180:183], v[106:109]
	v_mfma_f32_16x16x32_bf16 v[90:93], v[172:175], v[188:191], v[90:93]
	v_mfma_f32_16x16x32_bf16 v[98:101], v[164:167], v[188:191], v[98:101]
	v_mfma_f32_16x16x32_bf16 v[82:85], v[164:167], v[196:199], v[82:85]
	v_mfma_f32_16x16x32_bf16 v[74:77], v[172:175], v[196:199], v[74:77]
	v_mfma_f32_16x16x32_bf16 v[66:69], v[172:175], v[204:207], v[66:69]
	v_mfma_f32_16x16x32_bf16 v[70:73], v[164:167], v[204:207], v[70:73]
	v_mfma_f32_16x16x32_bf16 v[114:117], v[168:171], v[184:187], v[114:117]
	v_mfma_f32_16x16x32_bf16 v[106:109], v[176:179], v[184:187], v[106:109]
	v_mfma_f32_16x16x32_bf16 v[90:93], v[176:179], v[192:195], v[90:93]
	v_mfma_f32_16x16x32_bf16 v[98:101], v[168:171], v[192:195], v[98:101]
	v_mfma_f32_16x16x32_bf16 v[82:85], v[168:171], v[200:203], v[82:85]
	v_mfma_f32_16x16x32_bf16 v[74:77], v[176:179], v[200:203], v[74:77]
	v_mfma_f32_16x16x32_bf16 v[66:69], v[176:179], v[208:211], v[66:69]
	v_mfma_f32_16x16x32_bf16 v[70:73], v[168:171], v[208:211], v[70:73]
	s_setprio 2
	s_barrier
	s_mov_b32 m0, s65
	v_lshl_add_u64 v[212:213], s[46:47], 0, v[134:135]
	ds_read_b128 v[180:183], v150 offset:16384
	ds_read_b128 v[184:187], v150 offset:17408
	ds_read_b128 v[188:191], v150 offset:18432
	ds_read_b128 v[192:195], v150 offset:19456
	ds_read_b128 v[196:199], v150 offset:20480
	ds_read_b128 v[200:203], v150 offset:21504
	ds_read_b128 v[204:207], v150 offset:22528
	ds_read_b128 v[208:211], v150 offset:23552
	global_load_lds_dwordx4 v[212:213], off
	v_lshl_add_u64 v[214:215], s[46:47], 0, v[130:131]
	s_mov_b32 m0, s62
	v_lshl_add_u64 v[216:217], s[52:53], 0, v[134:135]
	global_load_lds_dwordx4 v[214:215], off
	s_mov_b32 m0, s64
	v_lshl_add_u64 v[218:219], s[44:45], 0, v[132:133]
	global_load_lds_dwordx4 v[216:217], off
	v_lshl_add_u64 v[216:217], s[52:53], 0, v[130:131]
	s_mov_b32 m0, s63
	s_nop 0
	global_load_lds_dwordx4 v[216:217], off
	v_lshl_add_u64 v[216:217], s[44:45], 0, v[136:137]
	s_mov_b32 m0, s57
	s_nop 0
	global_load_lds_dwordx4 v[216:217], off
	s_mov_b32 m0, s58
	s_nop 0
	global_load_lds_dwordx4 v[218:219], off
	s_waitcnt vmcnt(8)
	s_waitcnt lgkmcnt(0)
	s_barrier
; #define PG8_STAGE(bufoff, gbase, voff) do { _Pragma("unroll") for (int _i = 0; _i < 2; ++_i) \
;         __builtin_amdgcn_global_load_lds((const unsigned*)((const char*)(gbase) + (voff)[_i]), (LAS unsigned*)(lds + (bufoff) + ldsw + _i * 8192), 16, 0, 0); } while (0)
; #define PG8_LDA(dst, b, h) do { _Pragma("unroll") for (int m = 0; m < 4; ++m) _Pragma("unroll") for (int k = 0; k < 2; ++k) dst[m][k] = *(const LAS bf16x8*)(lds + PG8_SA(b, h) + aoff + m * 2048 + k * 1024); } while (0)
; #define PG8_LDB(dst, b, h) do { _Pragma("unroll") for (int n = 0; n < 2; ++n) _Pragma("unroll") for (int k = 0; k < 2; ++k) dst[n][k] = *(const LAS bf16x8*)(lds + PG8_SB(b, h) + boff + n * 2048 + k * 1024); } while (0)
; #define PG8_MMA(ai, bj, At, Bt) do { __builtin_amdgcn_s_setprio(1); _Pragma("unroll") for (int m = 0; m < 4; ++m) _Pragma("unroll") for (int n = 0; n < 2; ++n) _Pragma("unroll") for (int k = 0; k < 2; ++k) \
;         acc[ai][bj][m][n] = __builtin_amdgcn_mfma_f32_16x16x32_bf16(Bt[n][k], At[m][k], acc[ai][bj][m][n], 0, 0, 0); __builtin_amdgcn_s_setprio(0); } while (0)
; #define PG8_WAIT_V(n) asm volatile("s_waitcnt vmcnt(" #n ")" ::: "memory")
; #define PG8_WAIT_L(n) asm volatile("s_waitcnt lgkmcnt(" #n ")" ::: "memory")
; #define PG8_BAR __builtin_amdgcn_s_barrier()
; #define PG8_SCHED __builtin_amdgcn_sched_barrier(0)
; template <class Epi>
; __device__ __forceinline__ void gemm_phase(LAS unsigned char* lds, const Gemm g, int G, int c, const Epi& E) {
;     ...
;             PG8_WAIT_V(8); PG8_WAIT_L(0); PG8_BAR; PG8_MMA(1, 0, At, B0); PG8_MMA(1, 1, At, B1); PG8_BAR; PG8_SCHED;
;             PG8_LDB(B0, 1, 0); PG8_LDB(B1, 1, 1); PG8_SCHED; PG8_LDA(At, 1, 0); PG8_STAGE(PG8_SA(0, 1), a2 + hstepA, voffA);
;             PG8_WAIT_V(8); PG8_WAIT_L(0); PG8_BAR; PG8_MMA(0, 0, At, B0); PG8_MMA(0, 1, At, B1); PG8_BAR; PG8_SCHED;
	s_setprio 0
	s_waitcnt lgkmcnt(0)
	v_mfma_f32_16x16x32_bf16 v[62:65], v[142:145], v[180:183], v[62:65]
	v_mfma_f32_16x16x32_bf16 v[58:61], v[156:159], v[180:183], v[58:61]
	v_mfma_f32_16x16x32_bf16 v[46:49], v[156:159], v[188:191], v[46:49]
	v_mfma_f32_16x16x32_bf16 v[54:57], v[142:145], v[188:191], v[54:57]
	v_mfma_f32_16x16x32_bf16 v[38:41], v[142:145], v[196:199], v[38:41]
	v_mfma_f32_16x16x32_bf16 v[30:33], v[156:159], v[196:199], v[30:33]
	v_mfma_f32_16x16x32_bf16 v[14:17], v[156:159], v[204:207], v[14:17]
	v_mfma_f32_16x16x32_bf16 v[22:25], v[142:145], v[204:207], v[22:25]
	v_mfma_f32_16x16x32_bf16 v[62:65], v[152:155], v[184:187], v[62:65]
	v_mfma_f32_16x16x32_bf16 v[58:61], v[160:163], v[184:187], v[58:61]
	v_mfma_f32_16x16x32_bf16 v[46:49], v[160:163], v[192:195], v[46:49]
	v_mfma_f32_16x16x32_bf16 v[54:57], v[152:155], v[192:195], v[54:57]
	v_mfma_f32_16x16x32_bf16 v[38:41], v[152:155], v[200:203], v[38:41]
	v_mfma_f32_16x16x32_bf16 v[30:33], v[160:163], v[200:203], v[30:33]
	v_mfma_f32_16x16x32_bf16 v[14:17], v[160:163], v[208:211], v[14:17]
	v_mfma_f32_16x16x32_bf16 v[22:25], v[152:155], v[208:211], v[22:25]
	s_setprio 2
	s_setprio 0
	v_mfma_f32_16x16x32_bf16 v[50:53], v[164:167], v[180:183], v[50:53]
	v_mfma_f32_16x16x32_bf16 v[42:45], v[172:175], v[180:183], v[42:45]
	v_mfma_f32_16x16x32_bf16 v[26:29], v[172:175], v[188:191], v[26:29]
	v_mfma_f32_16x16x32_bf16 v[34:37], v[164:167], v[188:191], v[34:37]
	v_mfma_f32_16x16x32_bf16 v[18:21], v[164:167], v[196:199], v[18:21]
	v_mfma_f32_16x16x32_bf16 v[10:13], v[172:175], v[196:199], v[10:13]
	v_mfma_f32_16x16x32_bf16 v[2:5], v[172:175], v[204:207], v[2:5]
	v_mfma_f32_16x16x32_bf16 v[6:9], v[164:167], v[204:207], v[6:9]
	v_mfma_f32_16x16x32_bf16 v[50:53], v[168:171], v[184:187], v[50:53]
	v_mfma_f32_16x16x32_bf16 v[42:45], v[176:179], v[184:187], v[42:45]
	v_mfma_f32_16x16x32_bf16 v[26:29], v[176:179], v[192:195], v[26:29]
	v_mfma_f32_16x16x32_bf16 v[34:37], v[168:171], v[192:195], v[34:37]
	v_mfma_f32_16x16x32_bf16 v[18:21], v[168:171], v[200:203], v[18:21]
	v_mfma_f32_16x16x32_bf16 v[10:13], v[176:179], v[200:203], v[10:13]
	v_mfma_f32_16x16x32_bf16 v[2:5], v[176:179], v[208:211], v[2:5]
	v_mfma_f32_16x16x32_bf16 v[6:9], v[168:171], v[208:211], v[6:9]
	s_setprio 2
	s_barrier
	v_add_u32_e32 v151, s73, v147
	ds_read_b128 v[142:145], v151
	ds_read_b128 v[152:155], v151 offset:1024
	ds_read_b128 v[156:159], v151 offset:2048
	ds_read_b128 v[160:163], v151 offset:3072
	v_add_u32_e32 v151, s33, v147
	ds_read_b128 v[164:167], v151
	ds_read_b128 v[168:171], v151 offset:1024
	ds_read_b128 v[172:175], v151 offset:2048
	ds_read_b128 v[176:179], v151 offset:3072
	s_mov_b32 m0, s59
	v_lshl_add_u64 v[220:221], s[42:43], 0, v[136:137]
	ds_read_b128 v[180:183], v150 offset:32768
	ds_read_b128 v[184:187], v150 offset:33792
	ds_read_b128 v[188:191], v150 offset:34816
	ds_read_b128 v[192:195], v150 offset:35840
	ds_read_b128 v[196:199], v150 offset:36864
	ds_read_b128 v[200:203], v150 offset:37888
	ds_read_b128 v[204:207], v150 offset:38912
	ds_read_b128 v[208:211], v150 offset:39936
	global_load_lds_dwordx4 v[220:221], off
	v_lshl_add_u64 v[220:221], s[42:43], 0, v[132:133]
	s_mov_b32 m0, s60
	s_nop 0
	global_load_lds_dwordx4 v[220:221], off
	s_waitcnt vmcnt(8)
	s_waitcnt lgkmcnt(0)
	s_barrier
	s_setprio 0
	s_waitcnt lgkmcnt(0)
	v_mfma_f32_16x16x32_bf16 v[126:129], v[142:145], v[180:183], v[126:129]
	v_mfma_f32_16x16x32_bf16 v[122:125], v[156:159], v[180:183], v[122:125]
	v_mfma_f32_16x16x32_bf16 v[110:113], v[156:159], v[188:191], v[110:113]
	v_mfma_f32_16x16x32_bf16 v[118:121], v[142:145], v[188:191], v[118:121]
	v_mfma_f32_16x16x32_bf16 v[102:105], v[142:145], v[196:199], v[102:105]
	v_mfma_f32_16x16x32_bf16 v[94:97], v[156:159], v[196:199], v[94:97]
	v_mfma_f32_16x16x32_bf16 v[78:81], v[156:159], v[204:207], v[78:81]
	v_mfma_f32_16x16x32_bf16 v[86:89], v[142:145], v[204:207], v[86:89]
	v_mfma_f32_16x16x32_bf16 v[126:129], v[152:155], v[184:187], v[126:129]
	v_mfma_f32_16x16x32_bf16 v[122:125], v[160:163], v[184:187], v[122:125]
	v_mfma_f32_16x16x32_bf16 v[110:113], v[160:163], v[192:195], v[110:113]
	v_mfma_f32_16x16x32_bf16 v[118:121], v[152:155], v[192:195], v[118:121]
	v_mfma_f32_16x16x32_bf16 v[102:105], v[152:155], v[200:203], v[102:105]
	v_mfma_f32_16x16x32_bf16 v[94:97], v[160:163], v[200:203], v[94:97]
	v_mfma_f32_16x16x32_bf16 v[78:81], v[160:163], v[208:211], v[78:81]
	v_mfma_f32_16x16x32_bf16 v[86:89], v[152:155], v[208:211], v[86:89]
	s_setprio 2
	s_setprio 0
	v_mfma_f32_16x16x32_bf16 v[114:117], v[164:167], v[180:183], v[114:117]
	v_mfma_f32_16x16x32_bf16 v[106:109], v[172:175], v[180:183], v[106:109]
	v_mfma_f32_16x16x32_bf16 v[90:93], v[172:175], v[188:191], v[90:93]
	v_mfma_f32_16x16x32_bf16 v[98:101], v[164:167], v[188:191], v[98:101]
	v_mfma_f32_16x16x32_bf16 v[82:85], v[164:167], v[196:199], v[82:85]
	v_mfma_f32_16x16x32_bf16 v[74:77], v[172:175], v[196:199], v[74:77]
	v_mfma_f32_16x16x32_bf16 v[66:69], v[172:175], v[204:207], v[66:69]
	v_mfma_f32_16x16x32_bf16 v[70:73], v[164:167], v[204:207], v[70:73]
	v_mfma_f32_16x16x32_bf16 v[114:117], v[168:171], v[184:187], v[114:117]
	v_mfma_f32_16x16x32_bf16 v[106:109], v[176:179], v[184:187], v[106:109]
	v_mfma_f32_16x16x32_bf16 v[90:93], v[176:179], v[192:195], v[90:93]
	v_mfma_f32_16x16x32_bf16 v[98:101], v[168:171], v[192:195], v[98:101]
	v_mfma_f32_16x16x32_bf16 v[82:85], v[168:171], v[200:203], v[82:85]
	v_mfma_f32_16x16x32_bf16 v[74:77], v[176:179], v[200:203], v[74:77]
	v_mfma_f32_16x16x32_bf16 v[66:69], v[176:179], v[208:211], v[66:69]
	v_mfma_f32_16x16x32_bf16 v[70:73], v[168:171], v[208:211], v[70:73]
	s_setprio 2
	s_barrier
; #define PG8_STAGE(bufoff, gbase, voff) do { _Pragma("unroll") for (int _i = 0; _i < 2; ++_i) \
;         __builtin_amdgcn_global_load_lds((const unsigned*)((const char*)(gbase) + (voff)[_i]), (LAS unsigned*)(lds + (bufoff) + ldsw + _i * 8192), 16, 0, 0); } while (0)
; #define PG8_LDA(dst, b, h) do { _Pragma("unroll") for (int m = 0; m < 4; ++m) _Pragma("unroll") for (int k = 0; k < 2; ++k) dst[m][k] = *(const LAS bf16x8*)(lds + PG8_SA(b, h) + aoff + m * 2048 + k * 1024); } while (0)
; #define PG8_MMA(ai, bj, At, Bt) do { __builtin_amdgcn_s_setprio(1); _Pragma("unroll") for (int m = 0; m < 4; ++m) _Pragma("unroll") for (int n = 0; n < 2; ++n) _Pragma("unroll") for (int k = 0; k < 2; ++k) \
;         acc[ai][bj][m][n] = __builtin_amdgcn_mfma_f32_16x16x32_bf16(Bt[n][k], At[m][k], acc[ai][bj][m][n], 0, 0, 0); __builtin_amdgcn_s_setprio(0); } while (0)
; #define PG8_WAIT_V(n) asm volatile("s_waitcnt vmcnt(" #n ")" ::: "memory")
; #define PG8_WAIT_L(n) asm volatile("s_waitcnt lgkmcnt(" #n ")" ::: "memory")
; #define PG8_BAR __builtin_amdgcn_s_barrier()
; #define PG8_SCHED __builtin_amdgcn_sched_barrier(0)
; template <class Epi>
; __device__ __forceinline__ void gemm_phase(LAS unsigned char* lds, const Gemm g, int G, int c, const Epi& E) {
;     ...
;             PG8_LDA(At, 1, 1); PG8_STAGE(PG8_SB(1, 0), b3, voffB); PG8_STAGE(PG8_SB(1, 1), b3 + hstepB, voffB); PG8_STAGE(PG8_SA(1, 0), a3, voffA);
;             PG8_WAIT_V(8); PG8_WAIT_L(0); PG8_BAR; PG8_MMA(1, 0, At, B0); PG8_MMA(1, 1, At, B1); PG8_BAR; PG8_SCHED;
;         }
	s_mov_b32 m0, s88
	v_lshl_add_u64 v[212:213], v[212:213], 0, s[8:9]
	ds_read_b128 v[180:183], v150 offset:49152
	ds_read_b128 v[184:187], v150 offset:50176
	ds_read_b128 v[188:191], v150 offset:51200
	ds_read_b128 v[192:195], v150 offset:52224
	ds_read_b128 v[196:199], v150 offset:53248
	ds_read_b128 v[200:203], v150 offset:54272
	ds_read_b128 v[204:207], v150 offset:55296
	ds_read_b128 v[208:211], v150 offset:56320
	global_load_lds_dwordx4 v[212:213], off
	v_lshl_add_u64 v[212:213], v[214:215], 0, s[8:9]
	s_mov_b32 m0, s38
	s_nop 0
	global_load_lds_dwordx4 v[212:213], off
	v_lshl_add_u64 v[212:213], s[24:25], 0, v[134:135]
	s_mov_b32 m0, s39
	s_nop 0
	global_load_lds_dwordx4 v[212:213], off
	v_lshl_add_u64 v[212:213], s[24:25], 0, v[130:131]
	s_mov_b32 m0, s13
	s_nop 0
	global_load_lds_dwordx4 v[212:213], off
	v_lshl_add_u64 v[212:213], v[216:217], 0, s[8:9]
	s_mov_b32 m0, s79
	s_nop 0
	global_load_lds_dwordx4 v[212:213], off
	v_lshl_add_u64 v[212:213], v[218:219], 0, s[8:9]
	s_mov_b32 m0, s80
	s_nop 0
	global_load_lds_dwordx4 v[212:213], off
	s_waitcnt vmcnt(8)
	s_waitcnt lgkmcnt(0)
	s_barrier
	s_setprio 0
	s_waitcnt lgkmcnt(0)
	v_mfma_f32_16x16x32_bf16 v[62:65], v[142:145], v[180:183], v[62:65]
	v_mfma_f32_16x16x32_bf16 v[58:61], v[156:159], v[180:183], v[58:61]
	v_mfma_f32_16x16x32_bf16 v[46:49], v[156:159], v[188:191], v[46:49]
	v_mfma_f32_16x16x32_bf16 v[54:57], v[142:145], v[188:191], v[54:57]
	v_mfma_f32_16x16x32_bf16 v[38:41], v[142:145], v[196:199], v[38:41]
	v_mfma_f32_16x16x32_bf16 v[30:33], v[156:159], v[196:199], v[30:33]
	v_mfma_f32_16x16x32_bf16 v[14:17], v[156:159], v[204:207], v[14:17]
	v_mfma_f32_16x16x32_bf16 v[22:25], v[142:145], v[204:207], v[22:25]
	v_mfma_f32_16x16x32_bf16 v[62:65], v[152:155], v[184:187], v[62:65]
	v_mfma_f32_16x16x32_bf16 v[58:61], v[160:163], v[184:187], v[58:61]
	v_mfma_f32_16x16x32_bf16 v[46:49], v[160:163], v[192:195], v[46:49]
	v_mfma_f32_16x16x32_bf16 v[54:57], v[152:155], v[192:195], v[54:57]
	v_mfma_f32_16x16x32_bf16 v[38:41], v[152:155], v[200:203], v[38:41]
	v_mfma_f32_16x16x32_bf16 v[30:33], v[160:163], v[200:203], v[30:33]
	v_mfma_f32_16x16x32_bf16 v[14:17], v[160:163], v[208:211], v[14:17]
	v_mfma_f32_16x16x32_bf16 v[22:25], v[152:155], v[208:211], v[22:25]
	s_setprio 2
	s_setprio 0
	v_mfma_f32_16x16x32_bf16 v[50:53], v[164:167], v[180:183], v[50:53]
	v_mfma_f32_16x16x32_bf16 v[42:45], v[172:175], v[180:183], v[42:45]
	v_mfma_f32_16x16x32_bf16 v[26:29], v[172:175], v[188:191], v[26:29]
	v_mfma_f32_16x16x32_bf16 v[34:37], v[164:167], v[188:191], v[34:37]
	v_mfma_f32_16x16x32_bf16 v[18:21], v[164:167], v[196:199], v[18:21]
	v_mfma_f32_16x16x32_bf16 v[10:13], v[172:175], v[196:199], v[10:13]
	v_mfma_f32_16x16x32_bf16 v[2:5], v[172:175], v[204:207], v[2:5]
	v_mfma_f32_16x16x32_bf16 v[6:9], v[164:167], v[204:207], v[6:9]
	v_mfma_f32_16x16x32_bf16 v[50:53], v[168:171], v[184:187], v[50:53]
	v_mfma_f32_16x16x32_bf16 v[42:45], v[176:179], v[184:187], v[42:45]
	v_mfma_f32_16x16x32_bf16 v[26:29], v[176:179], v[192:195], v[26:29]
	v_mfma_f32_16x16x32_bf16 v[34:37], v[168:171], v[192:195], v[34:37]
	v_mfma_f32_16x16x32_bf16 v[18:21], v[168:171], v[200:203], v[18:21]
	v_mfma_f32_16x16x32_bf16 v[10:13], v[176:179], v[200:203], v[10:13]
	v_mfma_f32_16x16x32_bf16 v[2:5], v[176:179], v[208:211], v[2:5]
	v_mfma_f32_16x16x32_bf16 v[6:9], v[168:171], v[208:211], v[6:9]
	s_setprio 2
	s_barrier
	s_movk_i32 s13, 0x100
	s_andn2_b64 vcc, exec, s[22:23]
	s_mov_b64 s[24:25], -1
	s_mov_b64 s[22:23], 0
	s_cbranch_vccz .LBB0_368
	s_and_b64 vcc, exec, s[10:11]
	s_cbranch_vccz .LBB0_371
	s_barrier

; #define PG8_STAGE(bufoff, gbase, voff) do { _Pragma("unroll") for (int _i = 0; _i < 2; ++_i) \
;         __builtin_amdgcn_global_load_lds((const unsigned*)((const char*)(gbase) + (voff)[_i]), (LAS unsigned*)(lds + (bufoff) + ldsw + _i * 8192), 16, 0, 0); } while (0)
; #define PG8_LDA(dst, b, h) do { _Pragma("unroll") for (int m = 0; m < 4; ++m) _Pragma("unroll") for (int k = 0; k < 2; ++k) dst[m][k] = *(const LAS bf16x8*)(lds + PG8_SA(b, h) + aoff + m * 2048 + k * 1024); } while (0)
; #define PG8_LDB(dst, b, h) do { _Pragma("unroll") for (int n = 0; n < 2; ++n) _Pragma("unroll") for (int k = 0; k < 2; ++k) dst[n][k] = *(const LAS bf16x8*)(lds + PG8_SB(b, h) + boff + n * 2048 + k * 1024); } while (0)
; #define PG8_MMA(ai, bj, At, Bt) do { __builtin_amdgcn_s_setprio(1); _Pragma("unroll") for (int m = 0; m < 4; ++m) _Pragma("unroll") for (int n = 0; n < 2; ++n) _Pragma("unroll") for (int k = 0; k < 2; ++k) \
;         acc[ai][bj][m][n] = __builtin_amdgcn_mfma_f32_16x16x32_bf16(Bt[n][k], At[m][k], acc[ai][bj][m][n], 0, 0, 0); __builtin_amdgcn_s_setprio(0); } while (0)
; #define PG8_WAIT_V(n) asm volatile("s_waitcnt vmcnt(" #n ")" ::: "memory")
; #define PG8_WAIT_L(n) asm volatile("s_waitcnt lgkmcnt(" #n ")" ::: "memory")
; #define PG8_BAR __builtin_amdgcn_s_barrier()
; #define PG8_SCHED __builtin_amdgcn_sched_barrier(0)
; template <class Epi>
; __device__ __forceinline__ void gemm_phase(LAS unsigned char* lds, const Gemm g, int G, int c, const Epi& E) {
;     ...
;             const bool last = (t == nt - 2);
;             const char* a1 = cA + (size_t)(t + 1) * kstep;
;             const char* a2 = last ? nA : cA + (size_t)(t + 2) * kstep; const char* b2 = last ? nB : cB + (size_t)(t + 2) * kstep;
;             const char* a3 = a2 + kstep; const char* b3 = b2 + kstep;
;             PG8_LDB(B0, 0, 0); PG8_LDB(B1, 0, 1); PG8_SCHED; PG8_LDA(At, 0, 0); PG8_STAGE(PG8_SA(1, 1), a1 + hstepA, voffA);
;             PG8_WAIT_V(8); PG8_WAIT_L(0); PG8_BAR; PG8_MMA(0, 0, At, B0); PG8_MMA(0, 1, At, B1); PG8_BAR; PG8_SCHED;
;             PG8_LDA(At, 0, 1); PG8_STAGE(PG8_SB(0, 0), b2, voffB); PG8_STAGE(PG8_SB(0, 1), b2 + hstepB, voffB); PG8_STAGE(PG8_SA(0, 0), a2, voffA);
;             PG8_WAIT_V(8); PG8_WAIT_L(0); PG8_BAR; PG8_MMA(1, 0, At, B0); PG8_MMA(1, 1, At, B1); PG8_BAR; PG8_SCHED;
.LBB0_390:
	s_add_u32 s33, s8, s38
	s_addc_u32 s39, s9, 0
	s_add_u32 s56, s33, 0x100
	s_addc_u32 s57, s39, 0
	s_and_b64 s[54:55], s[10:11], exec
	s_cselect_b32 s57, s47, s57
	s_cselect_b32 s56, s46, s56
	s_add_u32 s38, s6, s38
	s_addc_u32 s54, s7, 0
	s_add_u32 s38, s38, 0x100
	s_addc_u32 s54, s54, 0
	s_and_b64 s[10:11], s[10:11], exec
	s_cselect_b32 s59, s53, s54
	s_cselect_b32 s58, s52, s38
	s_add_u32 s66, s33, 0xb0080
	s_addc_u32 s67, s39, 0
	s_add_i32 s65, s87, s14
	ds_read_b128 v[142:145], v160
	ds_read_b128 v[146:149], v160 offset:1024
	ds_read_b128 v[150:153], v160 offset:2048
	ds_read_b128 v[154:157], v160 offset:3072
	ds_read_b128 v[166:169], v161
	ds_read_b128 v[170:173], v161 offset:1024
	ds_read_b128 v[174:177], v161 offset:2048
	ds_read_b128 v[178:181], v161 offset:3072
	s_add_i32 m0, s78, 0xc000
	s_add_i32 s74, s78, 0xe000
	s_add_i32 s62, s65, 0x2000
	s_add_u32 s60, s58, 0xb0000
	s_addc_u32 s61, s59, 0
	s_add_i32 s64, s88, s14
	s_add_i32 s63, s64, 0x2000
	s_add_i32 s73, 0, 0x18000
	s_add_i32 s33, 0, 0x1c000
	s_add_u32 s54, s56, 0xb0000
	s_addc_u32 s55, s57, 0
	s_add_i32 vcc_hi, s73, s14
	s_add_i32 s39, vcc_hi, 0x2000
	s_add_u32 s10, s58, 0xb0080
	s_addc_u32 s11, s59, 0
	s_add_i32 vcc_lo, s33, s14
	s_add_i32 s38, vcc_lo, 0x2000
	v_lshl_add_u64 v[214:215], s[66:67], 0, v[130:131]
	ds_read_b128 v[182:185], v162
	ds_read_b128 v[186:189], v162 offset:1024
	ds_read_b128 v[190:193], v162 offset:2048
	ds_read_b128 v[194:197], v162 offset:3072
	ds_read_b128 v[198:201], v162 offset:4096
	ds_read_b128 v[202:205], v162 offset:5120
	ds_read_b128 v[206:209], v162 offset:6144
	ds_read_b128 v[210:213], v162 offset:7168
	global_load_lds_dwordx4 v[214:215], off
	v_lshl_add_u64 v[214:215], s[66:67], 0, v[134:135]
	s_mov_b32 m0, s74
	s_nop 0
	global_load_lds_dwordx4 v[214:215], off
	s_waitcnt vmcnt(8)
	s_waitcnt lgkmcnt(0)
	s_barrier
	s_setprio 0
	s_waitcnt lgkmcnt(0)
	v_mfma_f32_16x16x32_bf16 v[126:129], v[142:145], v[182:185], v[126:129]
	v_mfma_f32_16x16x32_bf16 v[122:125], v[150:153], v[182:185], v[122:125]
	v_mfma_f32_16x16x32_bf16 v[106:109], v[150:153], v[190:193], v[106:109]
	v_mfma_f32_16x16x32_bf16 v[110:113], v[142:145], v[190:193], v[110:113]
	v_mfma_f32_16x16x32_bf16 v[94:97], v[142:145], v[198:201], v[94:97]
	v_mfma_f32_16x16x32_bf16 v[90:93], v[150:153], v[198:201], v[90:93]
	v_mfma_f32_16x16x32_bf16 v[74:77], v[150:153], v[206:209], v[74:77]
	v_mfma_f32_16x16x32_bf16 v[78:81], v[142:145], v[206:209], v[78:81]
	v_mfma_f32_16x16x32_bf16 v[126:129], v[146:149], v[186:189], v[126:129]
	v_mfma_f32_16x16x32_bf16 v[122:125], v[154:157], v[186:189], v[122:125]
	v_mfma_f32_16x16x32_bf16 v[106:109], v[154:157], v[194:197], v[106:109]
	v_mfma_f32_16x16x32_bf16 v[110:113], v[146:149], v[194:197], v[110:113]
	v_mfma_f32_16x16x32_bf16 v[94:97], v[146:149], v[202:205], v[94:97]
	v_mfma_f32_16x16x32_bf16 v[90:93], v[154:157], v[202:205], v[90:93]
	v_mfma_f32_16x16x32_bf16 v[74:77], v[154:157], v[210:213], v[74:77]
	v_mfma_f32_16x16x32_bf16 v[78:81], v[146:149], v[210:213], v[78:81]
	s_setprio 2
	s_setprio 0
	v_mfma_f32_16x16x32_bf16 v[118:121], v[166:169], v[182:185], v[118:121]
	v_mfma_f32_16x16x32_bf16 v[114:117], v[174:177], v[182:185], v[114:117]
	v_mfma_f32_16x16x32_bf16 v[98:101], v[174:177], v[190:193], v[98:101]
	v_mfma_f32_16x16x32_bf16 v[102:105], v[166:169], v[190:193], v[102:105]
	v_mfma_f32_16x16x32_bf16 v[86:89], v[166:169], v[198:201], v[86:89]
	v_mfma_f32_16x16x32_bf16 v[82:85], v[174:177], v[198:201], v[82:85]
	v_mfma_f32_16x16x32_bf16 v[66:69], v[174:177], v[206:209], v[66:69]
	v_mfma_f32_16x16x32_bf16 v[70:73], v[166:169], v[206:209], v[70:73]
	v_mfma_f32_16x16x32_bf16 v[118:121], v[170:173], v[186:189], v[118:121]
	v_mfma_f32_16x16x32_bf16 v[114:117], v[178:181], v[186:189], v[114:117]
	v_mfma_f32_16x16x32_bf16 v[98:101], v[178:181], v[194:197], v[98:101]
	v_mfma_f32_16x16x32_bf16 v[102:105], v[170:173], v[194:197], v[102:105]
	v_mfma_f32_16x16x32_bf16 v[86:89], v[170:173], v[202:205], v[86:89]
	v_mfma_f32_16x16x32_bf16 v[82:85], v[178:181], v[202:205], v[82:85]
	v_mfma_f32_16x16x32_bf16 v[66:69], v[178:181], v[210:213], v[66:69]
	v_mfma_f32_16x16x32_bf16 v[70:73], v[170:173], v[210:213], v[70:73]
	s_setprio 2
	s_barrier
	s_mov_b32 m0, s65
	v_lshl_add_u64 v[214:215], s[58:59], 0, v[132:133]
	ds_read_b128 v[182:185], v162 offset:16384
	ds_read_b128 v[186:189], v162 offset:17408
	ds_read_b128 v[190:193], v162 offset:18432
	ds_read_b128 v[194:197], v162 offset:19456
	ds_read_b128 v[198:201], v162 offset:20480
	ds_read_b128 v[202:205], v162 offset:21504
	ds_read_b128 v[206:209], v162 offset:22528
	ds_read_b128 v[210:213], v162 offset:23552
	global_load_lds_dwordx4 v[214:215], off
	v_lshl_add_u64 v[216:217], s[58:59], 0, v[136:137]
	s_mov_b32 m0, s62
	v_lshl_add_u64 v[218:219], s[60:61], 0, v[132:133]
	global_load_lds_dwordx4 v[216:217], off
	s_mov_b32 m0, s64
	v_lshl_add_u64 v[220:221], s[56:57], 0, v[134:135]
	global_load_lds_dwordx4 v[218:219], off
	v_lshl_add_u64 v[218:219], s[60:61], 0, v[136:137]
	s_mov_b32 m0, s63
	s_nop 0
	global_load_lds_dwordx4 v[218:219], off
	v_lshl_add_u64 v[218:219], s[56:57], 0, v[130:131]
	s_mov_b32 m0, s78
	s_nop 0
	global_load_lds_dwordx4 v[218:219], off
	s_mov_b32 m0, s79
	s_nop 0
	global_load_lds_dwordx4 v[220:221], off
	s_waitcnt vmcnt(8)
	s_waitcnt lgkmcnt(0)
	s_barrier
; #define PG8_STAGE(bufoff, gbase, voff) do { _Pragma("unroll") for (int _i = 0; _i < 2; ++_i) \
;         __builtin_amdgcn_global_load_lds((const unsigned*)((const char*)(gbase) + (voff)[_i]), (LAS unsigned*)(lds + (bufoff) + ldsw + _i * 8192), 16, 0, 0); } while (0)
; #define PG8_LDA(dst, b, h) do { _Pragma("unroll") for (int m = 0; m < 4; ++m) _Pragma("unroll") for (int k = 0; k < 2; ++k) dst[m][k] = *(const LAS bf16x8*)(lds + PG8_SA(b, h) + aoff + m * 2048 + k * 1024); } while (0)
; #define PG8_LDB(dst, b, h) do { _Pragma("unroll") for (int n = 0; n < 2; ++n) _Pragma("unroll") for (int k = 0; k < 2; ++k) dst[n][k] = *(const LAS bf16x8*)(lds + PG8_SB(b, h) + boff + n * 2048 + k * 1024); } while (0)
; #define PG8_MMA(ai, bj, At, Bt) do { __builtin_amdgcn_s_setprio(1); _Pragma("unroll") for (int m = 0; m < 4; ++m) _Pragma("unroll") for (int n = 0; n < 2; ++n) _Pragma("unroll") for (int k = 0; k < 2; ++k) \
;         acc[ai][bj][m][n] = __builtin_amdgcn_mfma_f32_16x16x32_bf16(Bt[n][k], At[m][k], acc[ai][bj][m][n], 0, 0, 0); __builtin_amdgcn_s_setprio(0); } while (0)
; #define PG8_WAIT_V(n) asm volatile("s_waitcnt vmcnt(" #n ")" ::: "memory")
; #define PG8_WAIT_L(n) asm volatile("s_waitcnt lgkmcnt(" #n ")" ::: "memory")
; #define PG8_BAR __builtin_amdgcn_s_barrier()
; #define PG8_SCHED __builtin_amdgcn_sched_barrier(0)
; template <class Epi>
; __device__ __forceinline__ void gemm_phase(LAS unsigned char* lds, const Gemm g, int G, int c, const Epi& E) {
;     ...
;             PG8_WAIT_V(8); PG8_WAIT_L(0); PG8_BAR; PG8_MMA(1, 0, At, B0); PG8_MMA(1, 1, At, B1); PG8_BAR; PG8_SCHED;
;             PG8_LDB(B0, 1, 0); PG8_LDB(B1, 1, 1); PG8_SCHED; PG8_LDA(At, 1, 0); PG8_STAGE(PG8_SA(0, 1), a2 + hstepA, voffA);
;             PG8_WAIT_V(8); PG8_WAIT_L(0); PG8_BAR; PG8_MMA(0, 0, At, B0); PG8_MMA(0, 1, At, B1); PG8_BAR; PG8_SCHED;
	s_setprio 0
	s_waitcnt lgkmcnt(0)
	v_mfma_f32_16x16x32_bf16 v[62:65], v[142:145], v[182:185], v[62:65]
	v_mfma_f32_16x16x32_bf16 v[58:61], v[150:153], v[182:185], v[58:61]
	v_mfma_f32_16x16x32_bf16 v[42:45], v[150:153], v[190:193], v[42:45]
	v_mfma_f32_16x16x32_bf16 v[46:49], v[142:145], v[190:193], v[46:49]
	v_mfma_f32_16x16x32_bf16 v[30:33], v[142:145], v[198:201], v[30:33]
	v_mfma_f32_16x16x32_bf16 v[26:29], v[150:153], v[198:201], v[26:29]
	v_mfma_f32_16x16x32_bf16 v[10:13], v[150:153], v[206:209], v[10:13]
	v_mfma_f32_16x16x32_bf16 v[14:17], v[142:145], v[206:209], v[14:17]
	v_mfma_f32_16x16x32_bf16 v[62:65], v[146:149], v[186:189], v[62:65]
	v_mfma_f32_16x16x32_bf16 v[58:61], v[154:157], v[186:189], v[58:61]
	v_mfma_f32_16x16x32_bf16 v[42:45], v[154:157], v[194:197], v[42:45]
	v_mfma_f32_16x16x32_bf16 v[46:49], v[146:149], v[194:197], v[46:49]
	v_mfma_f32_16x16x32_bf16 v[30:33], v[146:149], v[202:205], v[30:33]
	v_mfma_f32_16x16x32_bf16 v[26:29], v[154:157], v[202:205], v[26:29]
	v_mfma_f32_16x16x32_bf16 v[10:13], v[154:157], v[210:213], v[10:13]
	v_mfma_f32_16x16x32_bf16 v[14:17], v[146:149], v[210:213], v[14:17]
	s_setprio 2
	s_setprio 0
	v_mfma_f32_16x16x32_bf16 v[54:57], v[166:169], v[182:185], v[54:57]
	v_mfma_f32_16x16x32_bf16 v[50:53], v[174:177], v[182:185], v[50:53]
	v_mfma_f32_16x16x32_bf16 v[34:37], v[174:177], v[190:193], v[34:37]
	v_mfma_f32_16x16x32_bf16 v[38:41], v[166:169], v[190:193], v[38:41]
	v_mfma_f32_16x16x32_bf16 v[22:25], v[166:169], v[198:201], v[22:25]
	v_mfma_f32_16x16x32_bf16 v[18:21], v[174:177], v[198:201], v[18:21]
	v_mfma_f32_16x16x32_bf16 v[2:5], v[174:177], v[206:209], v[2:5]
	v_mfma_f32_16x16x32_bf16 v[6:9], v[166:169], v[206:209], v[6:9]
	v_mfma_f32_16x16x32_bf16 v[54:57], v[170:173], v[186:189], v[54:57]
	v_mfma_f32_16x16x32_bf16 v[50:53], v[178:181], v[186:189], v[50:53]
	v_mfma_f32_16x16x32_bf16 v[34:37], v[178:181], v[194:197], v[34:37]
	v_mfma_f32_16x16x32_bf16 v[38:41], v[170:173], v[194:197], v[38:41]
	v_mfma_f32_16x16x32_bf16 v[22:25], v[170:173], v[202:205], v[22:25]
	v_mfma_f32_16x16x32_bf16 v[18:21], v[178:181], v[202:205], v[18:21]
	v_mfma_f32_16x16x32_bf16 v[2:5], v[178:181], v[210:213], v[2:5]
	v_mfma_f32_16x16x32_bf16 v[6:9], v[170:173], v[210:213], v[6:9]
	s_setprio 2
	s_barrier
	v_add_u32_e32 v154, s73, v159
	v_add_u32_e32 v178, s33, v159
	ds_read_b128 v[142:145], v154
	ds_read_b128 v[146:149], v154 offset:1024
	ds_read_b128 v[150:153], v154 offset:2048
	ds_read_b128 v[154:157], v154 offset:3072
	ds_read_b128 v[166:169], v178
	ds_read_b128 v[170:173], v178 offset:1024
	ds_read_b128 v[174:177], v178 offset:2048
	ds_read_b128 v[178:181], v178 offset:3072
	s_mov_b32 m0, s80
	v_lshl_add_u64 v[222:223], s[54:55], 0, v[130:131]
	ds_read_b128 v[182:185], v162 offset:32768
	ds_read_b128 v[186:189], v162 offset:33792
	ds_read_b128 v[190:193], v162 offset:34816
	ds_read_b128 v[194:197], v162 offset:35840
	ds_read_b128 v[198:201], v162 offset:36864
	ds_read_b128 v[202:205], v162 offset:37888
	ds_read_b128 v[206:209], v162 offset:38912
	ds_read_b128 v[210:213], v162 offset:39936
	global_load_lds_dwordx4 v[222:223], off
	v_lshl_add_u64 v[222:223], s[54:55], 0, v[134:135]
	s_mov_b32 m0, s81
	s_nop 0
	global_load_lds_dwordx4 v[222:223], off
	s_waitcnt vmcnt(8)
	s_waitcnt lgkmcnt(0)
	s_barrier
	s_setprio 0
	s_waitcnt lgkmcnt(0)
	v_mfma_f32_16x16x32_bf16 v[126:129], v[142:145], v[182:185], v[126:129]
	v_mfma_f32_16x16x32_bf16 v[122:125], v[150:153], v[182:185], v[122:125]
	v_mfma_f32_16x16x32_bf16 v[106:109], v[150:153], v[190:193], v[106:109]
	v_mfma_f32_16x16x32_bf16 v[110:113], v[142:145], v[190:193], v[110:113]
	v_mfma_f32_16x16x32_bf16 v[94:97], v[142:145], v[198:201], v[94:97]
	v_mfma_f32_16x16x32_bf16 v[90:93], v[150:153], v[198:201], v[90:93]
	v_mfma_f32_16x16x32_bf16 v[74:77], v[150:153], v[206:209], v[74:77]
	v_mfma_f32_16x16x32_bf16 v[78:81], v[142:145], v[206:209], v[78:81]
	v_mfma_f32_16x16x32_bf16 v[126:129], v[146:149], v[186:189], v[126:129]
	v_mfma_f32_16x16x32_bf16 v[122:125], v[154:157], v[186:189], v[122:125]
	v_mfma_f32_16x16x32_bf16 v[106:109], v[154:157], v[194:197], v[106:109]
	v_mfma_f32_16x16x32_bf16 v[110:113], v[146:149], v[194:197], v[110:113]
	v_mfma_f32_16x16x32_bf16 v[94:97], v[146:149], v[202:205], v[94:97]
	v_mfma_f32_16x16x32_bf16 v[90:93], v[154:157], v[202:205], v[90:93]
	v_mfma_f32_16x16x32_bf16 v[74:77], v[154:157], v[210:213], v[74:77]
	v_mfma_f32_16x16x32_bf16 v[78:81], v[146:149], v[210:213], v[78:81]
	s_setprio 2
	s_setprio 0
	v_mfma_f32_16x16x32_bf16 v[118:121], v[166:169], v[182:185], v[118:121]
	v_mfma_f32_16x16x32_bf16 v[114:117], v[174:177], v[182:185], v[114:117]
	v_mfma_f32_16x16x32_bf16 v[98:101], v[174:177], v[190:193], v[98:101]
	v_mfma_f32_16x16x32_bf16 v[102:105], v[166:169], v[190:193], v[102:105]
	v_mfma_f32_16x16x32_bf16 v[86:89], v[166:169], v[198:201], v[86:89]
	v_mfma_f32_16x16x32_bf16 v[82:85], v[174:177], v[198:201], v[82:85]
	v_mfma_f32_16x16x32_bf16 v[66:69], v[174:177], v[206:209], v[66:69]
	v_mfma_f32_16x16x32_bf16 v[70:73], v[166:169], v[206:209], v[70:73]
	v_mfma_f32_16x16x32_bf16 v[118:121], v[170:173], v[186:189], v[118:121]
	v_mfma_f32_16x16x32_bf16 v[114:117], v[178:181], v[186:189], v[114:117]
	v_mfma_f32_16x16x32_bf16 v[98:101], v[178:181], v[194:197], v[98:101]
	v_mfma_f32_16x16x32_bf16 v[102:105], v[170:173], v[194:197], v[102:105]
	v_mfma_f32_16x16x32_bf16 v[86:89], v[170:173], v[202:205], v[86:89]
	v_mfma_f32_16x16x32_bf16 v[82:85], v[178:181], v[202:205], v[82:85]
	v_mfma_f32_16x16x32_bf16 v[66:69], v[178:181], v[210:213], v[66:69]
	v_mfma_f32_16x16x32_bf16 v[70:73], v[170:173], v[210:213], v[70:73]
	s_setprio 2
	s_barrier
; #define PG8_STAGE(bufoff, gbase, voff) do { _Pragma("unroll") for (int _i = 0; _i < 2; ++_i) \
;         __builtin_amdgcn_global_load_lds((const unsigned*)((const char*)(gbase) + (voff)[_i]), (LAS unsigned*)(lds + (bufoff) + ldsw + _i * 8192), 16, 0, 0); } while (0)
; #define PG8_LDA(dst, b, h) do { _Pragma("unroll") for (int m = 0; m < 4; ++m) _Pragma("unroll") for (int k = 0; k < 2; ++k) dst[m][k] = *(const LAS bf16x8*)(lds + PG8_SA(b, h) + aoff + m * 2048 + k * 1024); } while (0)
; #define PG8_MMA(ai, bj, At, Bt) do { __builtin_amdgcn_s_setprio(1); _Pragma("unroll") for (int m = 0; m < 4; ++m) _Pragma("unroll") for (int n = 0; n < 2; ++n) _Pragma("unroll") for (int k = 0; k < 2; ++k) \
;         acc[ai][bj][m][n] = __builtin_amdgcn_mfma_f32_16x16x32_bf16(Bt[n][k], At[m][k], acc[ai][bj][m][n], 0, 0, 0); __builtin_amdgcn_s_setprio(0); } while (0)
; #define PG8_WAIT_V(n) asm volatile("s_waitcnt vmcnt(" #n ")" ::: "memory")
; #define PG8_WAIT_L(n) asm volatile("s_waitcnt lgkmcnt(" #n ")" ::: "memory")
; #define PG8_BAR __builtin_amdgcn_s_barrier()
; #define PG8_SCHED __builtin_amdgcn_sched_barrier(0)
; template <class Epi>
; __device__ __forceinline__ void gemm_phase(LAS unsigned char* lds, const Gemm g, int G, int c, const Epi& E) {
;     ...
;             PG8_LDA(At, 1, 1); PG8_STAGE(PG8_SB(1, 0), b3, voffB); PG8_STAGE(PG8_SB(1, 1), b3 + hstepB, voffB); PG8_STAGE(PG8_SA(1, 0), a3, voffA);
;             PG8_WAIT_V(8); PG8_WAIT_L(0); PG8_BAR; PG8_MMA(1, 0, At, B0); PG8_MMA(1, 1, At, B1); PG8_BAR; PG8_SCHED;
;         }
	s_mov_b32 m0, vcc_hi
	v_lshl_add_u64 v[214:215], v[214:215], 0, s[24:25]
	ds_read_b128 v[182:185], v162 offset:49152
	ds_read_b128 v[186:189], v162 offset:50176
	ds_read_b128 v[190:193], v162 offset:51200
	ds_read_b128 v[194:197], v162 offset:52224
	ds_read_b128 v[198:201], v162 offset:53248
	ds_read_b128 v[202:205], v162 offset:54272
	ds_read_b128 v[206:209], v162 offset:55296
	ds_read_b128 v[210:213], v162 offset:56320
	global_load_lds_dwordx4 v[214:215], off
	v_lshl_add_u64 v[214:215], v[216:217], 0, s[24:25]
	s_mov_b32 m0, s39
	s_nop 0
	global_load_lds_dwordx4 v[214:215], off
	v_lshl_add_u64 v[214:215], s[10:11], 0, v[132:133]
	s_mov_b32 m0, vcc_lo
	s_nop 0
	global_load_lds_dwordx4 v[214:215], off
	v_lshl_add_u64 v[214:215], s[10:11], 0, v[136:137]
	s_mov_b32 m0, s38
	s_nop 0
	global_load_lds_dwordx4 v[214:215], off
	v_lshl_add_u64 v[214:215], v[218:219], 0, s[24:25]
	s_mov_b32 m0, s85
	s_nop 0
	global_load_lds_dwordx4 v[214:215], off
	v_lshl_add_u64 v[214:215], v[220:221], 0, s[24:25]
	s_mov_b32 m0, s86
	s_nop 0
	global_load_lds_dwordx4 v[214:215], off
	s_waitcnt vmcnt(8)
	s_waitcnt lgkmcnt(0)
	s_barrier
	s_setprio 0
	s_waitcnt lgkmcnt(0)
	v_mfma_f32_16x16x32_bf16 v[62:65], v[142:145], v[182:185], v[62:65]
	v_mfma_f32_16x16x32_bf16 v[58:61], v[150:153], v[182:185], v[58:61]
	v_mfma_f32_16x16x32_bf16 v[42:45], v[150:153], v[190:193], v[42:45]
	v_mfma_f32_16x16x32_bf16 v[46:49], v[142:145], v[190:193], v[46:49]
	v_mfma_f32_16x16x32_bf16 v[30:33], v[142:145], v[198:201], v[30:33]
	v_mfma_f32_16x16x32_bf16 v[26:29], v[150:153], v[198:201], v[26:29]
	v_mfma_f32_16x16x32_bf16 v[10:13], v[150:153], v[206:209], v[10:13]
	v_mfma_f32_16x16x32_bf16 v[14:17], v[142:145], v[206:209], v[14:17]
	v_mfma_f32_16x16x32_bf16 v[62:65], v[146:149], v[186:189], v[62:65]
	v_mfma_f32_16x16x32_bf16 v[58:61], v[154:157], v[186:189], v[58:61]
	v_mfma_f32_16x16x32_bf16 v[42:45], v[154:157], v[194:197], v[42:45]
	v_mfma_f32_16x16x32_bf16 v[46:49], v[146:149], v[194:197], v[46:49]
	v_mfma_f32_16x16x32_bf16 v[30:33], v[146:149], v[202:205], v[30:33]
	v_mfma_f32_16x16x32_bf16 v[26:29], v[154:157], v[202:205], v[26:29]
	v_mfma_f32_16x16x32_bf16 v[10:13], v[154:157], v[210:213], v[10:13]
	v_mfma_f32_16x16x32_bf16 v[14:17], v[146:149], v[210:213], v[14:17]
	s_setprio 2
	s_setprio 0
	v_mfma_f32_16x16x32_bf16 v[54:57], v[166:169], v[182:185], v[54:57]
	v_mfma_f32_16x16x32_bf16 v[50:53], v[174:177], v[182:185], v[50:53]
	v_mfma_f32_16x16x32_bf16 v[34:37], v[174:177], v[190:193], v[34:37]
	v_mfma_f32_16x16x32_bf16 v[38:41], v[166:169], v[190:193], v[38:41]
	v_mfma_f32_16x16x32_bf16 v[22:25], v[166:169], v[198:201], v[22:25]
	v_mfma_f32_16x16x32_bf16 v[18:21], v[174:177], v[198:201], v[18:21]
	v_mfma_f32_16x16x32_bf16 v[2:5], v[174:177], v[206:209], v[2:5]
	v_mfma_f32_16x16x32_bf16 v[6:9], v[166:169], v[206:209], v[6:9]
	v_mfma_f32_16x16x32_bf16 v[54:57], v[170:173], v[186:189], v[54:57]
	v_mfma_f32_16x16x32_bf16 v[50:53], v[178:181], v[186:189], v[50:53]
	v_mfma_f32_16x16x32_bf16 v[34:37], v[178:181], v[194:197], v[34:37]
	v_mfma_f32_16x16x32_bf16 v[38:41], v[170:173], v[194:197], v[38:41]
	v_mfma_f32_16x16x32_bf16 v[22:25], v[170:173], v[202:205], v[22:25]
	v_mfma_f32_16x16x32_bf16 v[18:21], v[178:181], v[202:205], v[18:21]
	v_mfma_f32_16x16x32_bf16 v[2:5], v[178:181], v[210:213], v[2:5]
	v_mfma_f32_16x16x32_bf16 v[6:9], v[170:173], v[210:213], v[6:9]
	s_setprio 2
	s_barrier
	s_movk_i32 s38, 0x100
	s_andn2_b64 vcc, exec, s[4:5]
	s_mov_b64 s[10:11], -1
	s_mov_b64 s[4:5], 0
	s_cbranch_vccz .LBB0_390
	s_and_b64 vcc, exec, s[44:45]
	s_cbranch_vccz .LBB0_393
	s_barrier

; #define PG8_STAGE(bufoff, gbase, voff) do { _Pragma("unroll") for (int _i = 0; _i < 2; ++_i) \
;         __builtin_amdgcn_global_load_lds((const unsigned*)((const char*)(gbase) + (voff)[_i]), (LAS unsigned*)(lds + (bufoff) + ldsw + _i * 8192), 16, 0, 0); } while (0)
; #define PG8_LDA(dst, b, h) do { _Pragma("unroll") for (int m = 0; m < 4; ++m) _Pragma("unroll") for (int k = 0; k < 2; ++k) dst[m][k] = *(const LAS bf16x8*)(lds + PG8_SA(b, h) + aoff + m * 2048 + k * 1024); } while (0)
; #define PG8_LDB(dst, b, h) do { _Pragma("unroll") for (int n = 0; n < 2; ++n) _Pragma("unroll") for (int k = 0; k < 2; ++k) dst[n][k] = *(const LAS bf16x8*)(lds + PG8_SB(b, h) + boff + n * 2048 + k * 1024); } while (0)
; #define PG8_MMA(ai, bj, At, Bt) do { __builtin_amdgcn_s_setprio(1); _Pragma("unroll") for (int m = 0; m < 4; ++m) _Pragma("unroll") for (int n = 0; n < 2; ++n) _Pragma("unroll") for (int k = 0; k < 2; ++k) \
;         acc[ai][bj][m][n] = __builtin_amdgcn_mfma_f32_16x16x32_bf16(Bt[n][k], At[m][k], acc[ai][bj][m][n], 0, 0, 0); __builtin_amdgcn_s_setprio(0); } while (0)
; #define PG8_WAIT_V(n) asm volatile("s_waitcnt vmcnt(" #n ")" ::: "memory")
; #define PG8_WAIT_L(n) asm volatile("s_waitcnt lgkmcnt(" #n ")" ::: "memory")
; #define PG8_BAR __builtin_amdgcn_s_barrier()
; #define PG8_SCHED __builtin_amdgcn_sched_barrier(0)
; template <class Epi>
; __device__ __forceinline__ void gemm_phase(LAS unsigned char* lds, const Gemm g, int G, int c, const Epi& E) {
;     ...
;             const bool last = (t == nt - 2);
;             const char* a1 = cA + (size_t)(t + 1) * kstep;
;             const char* a2 = last ? nA : cA + (size_t)(t + 2) * kstep; const char* b2 = last ? nB : cB + (size_t)(t + 2) * kstep;
;             const char* a3 = a2 + kstep; const char* b3 = b2 + kstep;
;             PG8_LDB(B0, 0, 0); PG8_LDB(B1, 0, 1); PG8_SCHED; PG8_LDA(At, 0, 0); PG8_STAGE(PG8_SA(1, 1), a1 + hstepA, voffA);
;             PG8_WAIT_V(8); PG8_WAIT_L(0); PG8_BAR; PG8_MMA(0, 0, At, B0); PG8_MMA(0, 1, At, B1); PG8_BAR; PG8_SCHED;
;             PG8_LDA(At, 0, 1); PG8_STAGE(PG8_SB(0, 0), b2, voffB); PG8_STAGE(PG8_SB(0, 1), b2 + hstepB, voffB); PG8_STAGE(PG8_SA(0, 0), a2, voffA);
;             PG8_WAIT_V(8); PG8_WAIT_L(0); PG8_BAR; PG8_MMA(1, 0, At, B0); PG8_MMA(1, 1, At, B1); PG8_BAR; PG8_SCHED;
.LBB0_476:
	s_add_u32 s33, s8, s38
	s_addc_u32 s39, s9, 0
	s_add_u32 s56, s33, 0x100
	s_addc_u32 s57, s39, 0
	s_and_b64 s[54:55], s[10:11], exec
	s_cselect_b32 s57, s47, s57
	s_cselect_b32 s56, s46, s56
	s_add_u32 s38, s6, s38
	s_addc_u32 s54, s7, 0
	s_add_u32 s38, s38, 0x100
	s_addc_u32 s54, s54, 0
	s_and_b64 s[10:11], s[10:11], exec
	s_cselect_b32 s59, s53, s54
	s_cselect_b32 s58, s52, s38
	s_add_u32 s66, s33, 0xb0080
	ds_read_b128 v[130:133], v166
	ds_read_b128 v[134:137], v166 offset:1024
	ds_read_b128 v[150:153], v166 offset:2048
	ds_read_b128 v[154:157], v166 offset:3072
	ds_read_b128 v[158:161], v167
	ds_read_b128 v[172:175], v167 offset:1024
	ds_read_b128 v[176:179], v167 offset:2048
	ds_read_b128 v[180:183], v167 offset:3072
	s_addc_u32 s67, s39, 0
	s_add_i32 s63, s95, s83
	s_add_i32 m0, s86, 0xc000
	s_add_i32 s64, s86, 0xe000
	s_add_i32 s74, s63, 0x2000
	s_add_u32 s60, s58, 0xb0000
	s_addc_u32 s61, s59, 0
	s_add_i32 s75, s96, s83
	s_add_i32 s62, s75, 0x2000
	s_add_i32 vcc_hi, 0, 0x18000
	s_add_i32 vcc_lo, 0, 0x1c000
	s_add_u32 s54, s56, 0xb0000
	s_addc_u32 s55, s57, 0
	s_add_i32 s39, vcc_hi, s83
	s_add_i32 s73, s39, 0x2000
	s_add_u32 s10, s58, 0xb0080
	s_addc_u32 s11, s59, 0
	s_add_i32 s38, vcc_lo, s83
	s_add_i32 s33, s38, 0x2000
	v_lshl_add_u64 v[162:163], s[66:67], 0, v[138:139]
	ds_read_b128 v[184:187], v168
	ds_read_b128 v[188:191], v168 offset:1024
	ds_read_b128 v[192:195], v168 offset:2048
	ds_read_b128 v[196:199], v168 offset:3072
	ds_read_b128 v[200:203], v168 offset:4096
	ds_read_b128 v[204:207], v168 offset:5120
	ds_read_b128 v[208:211], v168 offset:6144
	ds_read_b128 v[212:215], v168 offset:7168
	global_load_lds_dwordx4 v[162:163], off
	v_lshl_add_u64 v[162:163], s[66:67], 0, v[142:143]
	s_mov_b32 m0, s64
	s_nop 0
	global_load_lds_dwordx4 v[162:163], off
	s_waitcnt vmcnt(8)
	s_waitcnt lgkmcnt(0)
	s_barrier
	s_setprio 0
	s_waitcnt lgkmcnt(0)
	v_mfma_f32_16x16x32_bf16 v[126:129], v[130:133], v[184:187], v[126:129]
	v_mfma_f32_16x16x32_bf16 v[122:125], v[150:153], v[184:187], v[122:125]
	v_mfma_f32_16x16x32_bf16 v[106:109], v[150:153], v[192:195], v[106:109]
	v_mfma_f32_16x16x32_bf16 v[110:113], v[130:133], v[192:195], v[110:113]
	v_mfma_f32_16x16x32_bf16 v[94:97], v[130:133], v[200:203], v[94:97]
	v_mfma_f32_16x16x32_bf16 v[90:93], v[150:153], v[200:203], v[90:93]
	v_mfma_f32_16x16x32_bf16 v[74:77], v[150:153], v[208:211], v[74:77]
	v_mfma_f32_16x16x32_bf16 v[78:81], v[130:133], v[208:211], v[78:81]
	v_mfma_f32_16x16x32_bf16 v[126:129], v[134:137], v[188:191], v[126:129]
	v_mfma_f32_16x16x32_bf16 v[122:125], v[154:157], v[188:191], v[122:125]
	v_mfma_f32_16x16x32_bf16 v[106:109], v[154:157], v[196:199], v[106:109]
	v_mfma_f32_16x16x32_bf16 v[110:113], v[134:137], v[196:199], v[110:113]
	v_mfma_f32_16x16x32_bf16 v[94:97], v[134:137], v[204:207], v[94:97]
	v_mfma_f32_16x16x32_bf16 v[90:93], v[154:157], v[204:207], v[90:93]
	v_mfma_f32_16x16x32_bf16 v[74:77], v[154:157], v[212:215], v[74:77]
	v_mfma_f32_16x16x32_bf16 v[78:81], v[134:137], v[212:215], v[78:81]
	s_setprio 2
	s_setprio 0
	v_mfma_f32_16x16x32_bf16 v[118:121], v[158:161], v[184:187], v[118:121]
	v_mfma_f32_16x16x32_bf16 v[114:117], v[176:179], v[184:187], v[114:117]
	v_mfma_f32_16x16x32_bf16 v[98:101], v[176:179], v[192:195], v[98:101]
	v_mfma_f32_16x16x32_bf16 v[102:105], v[158:161], v[192:195], v[102:105]
	v_mfma_f32_16x16x32_bf16 v[86:89], v[158:161], v[200:203], v[86:89]
	v_mfma_f32_16x16x32_bf16 v[82:85], v[176:179], v[200:203], v[82:85]
	v_mfma_f32_16x16x32_bf16 v[66:69], v[176:179], v[208:211], v[66:69]
	v_mfma_f32_16x16x32_bf16 v[70:73], v[158:161], v[208:211], v[70:73]
	v_mfma_f32_16x16x32_bf16 v[118:121], v[172:175], v[188:191], v[118:121]
	v_mfma_f32_16x16x32_bf16 v[114:117], v[180:183], v[188:191], v[114:117]
	v_mfma_f32_16x16x32_bf16 v[98:101], v[180:183], v[196:199], v[98:101]
	v_mfma_f32_16x16x32_bf16 v[102:105], v[172:175], v[196:199], v[102:105]
	v_mfma_f32_16x16x32_bf16 v[86:89], v[172:175], v[204:207], v[86:89]
	v_mfma_f32_16x16x32_bf16 v[82:85], v[180:183], v[204:207], v[82:85]
	v_mfma_f32_16x16x32_bf16 v[66:69], v[180:183], v[212:215], v[66:69]
	v_mfma_f32_16x16x32_bf16 v[70:73], v[172:175], v[212:215], v[70:73]
	s_setprio 2
	s_barrier
	s_mov_b32 m0, s63
	v_lshl_add_u64 v[162:163], s[58:59], 0, v[140:141]
	ds_read_b128 v[184:187], v168 offset:16384
	ds_read_b128 v[188:191], v168 offset:17408
	ds_read_b128 v[192:195], v168 offset:18432
	ds_read_b128 v[196:199], v168 offset:19456
	ds_read_b128 v[200:203], v168 offset:20480
	ds_read_b128 v[204:207], v168 offset:21504
	ds_read_b128 v[208:211], v168 offset:22528
	ds_read_b128 v[212:215], v168 offset:23552
	global_load_lds_dwordx4 v[162:163], off
	v_lshl_add_u64 v[216:217], s[58:59], 0, v[144:145]
	s_mov_b32 m0, s74
	v_lshl_add_u64 v[218:219], s[60:61], 0, v[140:141]
	global_load_lds_dwordx4 v[216:217], off
	s_mov_b32 m0, s75
	v_lshl_add_u64 v[220:221], s[56:57], 0, v[142:143]
	global_load_lds_dwordx4 v[218:219], off
	v_lshl_add_u64 v[218:219], s[60:61], 0, v[144:145]
	s_mov_b32 m0, s62
	s_nop 0
	global_load_lds_dwordx4 v[218:219], off
	v_lshl_add_u64 v[218:219], s[56:57], 0, v[138:139]
	s_mov_b32 m0, s86
	s_nop 0
	global_load_lds_dwordx4 v[218:219], off
	s_mov_b32 m0, s87
	s_nop 0
	global_load_lds_dwordx4 v[220:221], off
	s_waitcnt vmcnt(8)
	s_waitcnt lgkmcnt(0)
	s_barrier
; #define PG8_STAGE(bufoff, gbase, voff) do { _Pragma("unroll") for (int _i = 0; _i < 2; ++_i) \
;         __builtin_amdgcn_global_load_lds((const unsigned*)((const char*)(gbase) + (voff)[_i]), (LAS unsigned*)(lds + (bufoff) + ldsw + _i * 8192), 16, 0, 0); } while (0)
; #define PG8_LDA(dst, b, h) do { _Pragma("unroll") for (int m = 0; m < 4; ++m) _Pragma("unroll") for (int k = 0; k < 2; ++k) dst[m][k] = *(const LAS bf16x8*)(lds + PG8_SA(b, h) + aoff + m * 2048 + k * 1024); } while (0)
; #define PG8_LDB(dst, b, h) do { _Pragma("unroll") for (int n = 0; n < 2; ++n) _Pragma("unroll") for (int k = 0; k < 2; ++k) dst[n][k] = *(const LAS bf16x8*)(lds + PG8_SB(b, h) + boff + n * 2048 + k * 1024); } while (0)
; #define PG8_MMA(ai, bj, At, Bt) do { __builtin_amdgcn_s_setprio(1); _Pragma("unroll") for (int m = 0; m < 4; ++m) _Pragma("unroll") for (int n = 0; n < 2; ++n) _Pragma("unroll") for (int k = 0; k < 2; ++k) \
;         acc[ai][bj][m][n] = __builtin_amdgcn_mfma_f32_16x16x32_bf16(Bt[n][k], At[m][k], acc[ai][bj][m][n], 0, 0, 0); __builtin_amdgcn_s_setprio(0); } while (0)
; #define PG8_WAIT_V(n) asm volatile("s_waitcnt vmcnt(" #n ")" ::: "memory")
; #define PG8_WAIT_L(n) asm volatile("s_waitcnt lgkmcnt(" #n ")" ::: "memory")
; #define PG8_BAR __builtin_amdgcn_s_barrier()
; #define PG8_SCHED __builtin_amdgcn_sched_barrier(0)
; template <class Epi>
; __device__ __forceinline__ void gemm_phase(LAS unsigned char* lds, const Gemm g, int G, int c, const Epi& E) {
;     ...
;             PG8_WAIT_V(8); PG8_WAIT_L(0); PG8_BAR; PG8_MMA(1, 0, At, B0); PG8_MMA(1, 1, At, B1); PG8_BAR; PG8_SCHED;
;             PG8_LDB(B0, 1, 0); PG8_LDB(B1, 1, 1); PG8_SCHED; PG8_LDA(At, 1, 0); PG8_STAGE(PG8_SA(0, 1), a2 + hstepA, voffA);
;             PG8_WAIT_V(8); PG8_WAIT_L(0); PG8_BAR; PG8_MMA(0, 0, At, B0); PG8_MMA(0, 1, At, B1); PG8_BAR; PG8_SCHED;
	s_setprio 0
	s_waitcnt lgkmcnt(0)
	v_mfma_f32_16x16x32_bf16 v[62:65], v[130:133], v[184:187], v[62:65]
	v_mfma_f32_16x16x32_bf16 v[58:61], v[150:153], v[184:187], v[58:61]
	v_mfma_f32_16x16x32_bf16 v[42:45], v[150:153], v[192:195], v[42:45]
	v_mfma_f32_16x16x32_bf16 v[46:49], v[130:133], v[192:195], v[46:49]
	v_mfma_f32_16x16x32_bf16 v[30:33], v[130:133], v[200:203], v[30:33]
	v_mfma_f32_16x16x32_bf16 v[26:29], v[150:153], v[200:203], v[26:29]
	v_mfma_f32_16x16x32_bf16 v[10:13], v[150:153], v[208:211], v[10:13]
	v_mfma_f32_16x16x32_bf16 v[14:17], v[130:133], v[208:211], v[14:17]
	v_mfma_f32_16x16x32_bf16 v[62:65], v[134:137], v[188:191], v[62:65]
	v_mfma_f32_16x16x32_bf16 v[58:61], v[154:157], v[188:191], v[58:61]
	v_mfma_f32_16x16x32_bf16 v[42:45], v[154:157], v[196:199], v[42:45]
	v_mfma_f32_16x16x32_bf16 v[46:49], v[134:137], v[196:199], v[46:49]
	v_mfma_f32_16x16x32_bf16 v[30:33], v[134:137], v[204:207], v[30:33]
	v_mfma_f32_16x16x32_bf16 v[26:29], v[154:157], v[204:207], v[26:29]
	v_mfma_f32_16x16x32_bf16 v[10:13], v[154:157], v[212:215], v[10:13]
	v_mfma_f32_16x16x32_bf16 v[14:17], v[134:137], v[212:215], v[14:17]
	s_setprio 2
	s_setprio 0
	v_mfma_f32_16x16x32_bf16 v[54:57], v[158:161], v[184:187], v[54:57]
	v_mfma_f32_16x16x32_bf16 v[50:53], v[176:179], v[184:187], v[50:53]
	v_mfma_f32_16x16x32_bf16 v[34:37], v[176:179], v[192:195], v[34:37]
	v_mfma_f32_16x16x32_bf16 v[38:41], v[158:161], v[192:195], v[38:41]
	v_mfma_f32_16x16x32_bf16 v[22:25], v[158:161], v[200:203], v[22:25]
	v_mfma_f32_16x16x32_bf16 v[18:21], v[176:179], v[200:203], v[18:21]
	v_mfma_f32_16x16x32_bf16 v[2:5], v[176:179], v[208:211], v[2:5]
	v_mfma_f32_16x16x32_bf16 v[6:9], v[158:161], v[208:211], v[6:9]
	v_mfma_f32_16x16x32_bf16 v[54:57], v[172:175], v[188:191], v[54:57]
	v_mfma_f32_16x16x32_bf16 v[50:53], v[180:183], v[188:191], v[50:53]
	v_mfma_f32_16x16x32_bf16 v[34:37], v[180:183], v[196:199], v[34:37]
	v_mfma_f32_16x16x32_bf16 v[38:41], v[172:175], v[196:199], v[38:41]
	v_mfma_f32_16x16x32_bf16 v[22:25], v[172:175], v[204:207], v[22:25]
	v_mfma_f32_16x16x32_bf16 v[18:21], v[180:183], v[204:207], v[18:21]
	v_mfma_f32_16x16x32_bf16 v[2:5], v[180:183], v[212:215], v[2:5]
	v_mfma_f32_16x16x32_bf16 v[6:9], v[172:175], v[212:215], v[6:9]
	s_setprio 2
	s_barrier
	v_add_u32_e32 v154, vcc_hi, v165
	v_add_u32_e32 v180, vcc_lo, v165
	ds_read_b128 v[130:133], v154
	ds_read_b128 v[134:137], v154 offset:1024
	ds_read_b128 v[150:153], v154 offset:2048
	ds_read_b128 v[154:157], v154 offset:3072
	ds_read_b128 v[158:161], v180
	ds_read_b128 v[172:175], v180 offset:1024
	ds_read_b128 v[176:179], v180 offset:2048
	ds_read_b128 v[180:183], v180 offset:3072
	s_mov_b32 m0, s88
	v_lshl_add_u64 v[222:223], s[54:55], 0, v[138:139]
	ds_read_b128 v[184:187], v168 offset:32768
	ds_read_b128 v[188:191], v168 offset:33792
	ds_read_b128 v[192:195], v168 offset:34816
	ds_read_b128 v[196:199], v168 offset:35840
	ds_read_b128 v[200:203], v168 offset:36864
	ds_read_b128 v[204:207], v168 offset:37888
	ds_read_b128 v[208:211], v168 offset:38912
	ds_read_b128 v[212:215], v168 offset:39936
	global_load_lds_dwordx4 v[222:223], off
	v_lshl_add_u64 v[222:223], s[54:55], 0, v[142:143]
	s_mov_b32 m0, s89
	s_nop 0
	global_load_lds_dwordx4 v[222:223], off
	s_waitcnt vmcnt(8)
	s_waitcnt lgkmcnt(0)
	s_barrier
	s_setprio 0
	s_waitcnt lgkmcnt(0)
	v_mfma_f32_16x16x32_bf16 v[126:129], v[130:133], v[184:187], v[126:129]
	v_mfma_f32_16x16x32_bf16 v[122:125], v[150:153], v[184:187], v[122:125]
	v_mfma_f32_16x16x32_bf16 v[106:109], v[150:153], v[192:195], v[106:109]
	v_mfma_f32_16x16x32_bf16 v[110:113], v[130:133], v[192:195], v[110:113]
	v_mfma_f32_16x16x32_bf16 v[94:97], v[130:133], v[200:203], v[94:97]
	v_mfma_f32_16x16x32_bf16 v[90:93], v[150:153], v[200:203], v[90:93]
	v_mfma_f32_16x16x32_bf16 v[74:77], v[150:153], v[208:211], v[74:77]
	v_mfma_f32_16x16x32_bf16 v[78:81], v[130:133], v[208:211], v[78:81]
	v_mfma_f32_16x16x32_bf16 v[126:129], v[134:137], v[188:191], v[126:129]
	v_mfma_f32_16x16x32_bf16 v[122:125], v[154:157], v[188:191], v[122:125]
	v_mfma_f32_16x16x32_bf16 v[106:109], v[154:157], v[196:199], v[106:109]
	v_mfma_f32_16x16x32_bf16 v[110:113], v[134:137], v[196:199], v[110:113]
	v_mfma_f32_16x16x32_bf16 v[94:97], v[134:137], v[204:207], v[94:97]
	v_mfma_f32_16x16x32_bf16 v[90:93], v[154:157], v[204:207], v[90:93]
	v_mfma_f32_16x16x32_bf16 v[74:77], v[154:157], v[212:215], v[74:77]
	v_mfma_f32_16x16x32_bf16 v[78:81], v[134:137], v[212:215], v[78:81]
	s_setprio 2
	s_setprio 0
	v_mfma_f32_16x16x32_bf16 v[118:121], v[158:161], v[184:187], v[118:121]
	v_mfma_f32_16x16x32_bf16 v[114:117], v[176:179], v[184:187], v[114:117]
	v_mfma_f32_16x16x32_bf16 v[98:101], v[176:179], v[192:195], v[98:101]
	v_mfma_f32_16x16x32_bf16 v[102:105], v[158:161], v[192:195], v[102:105]
	v_mfma_f32_16x16x32_bf16 v[86:89], v[158:161], v[200:203], v[86:89]
	v_mfma_f32_16x16x32_bf16 v[82:85], v[176:179], v[200:203], v[82:85]
	v_mfma_f32_16x16x32_bf16 v[66:69], v[176:179], v[208:211], v[66:69]
	v_mfma_f32_16x16x32_bf16 v[70:73], v[158:161], v[208:211], v[70:73]
	v_mfma_f32_16x16x32_bf16 v[118:121], v[172:175], v[188:191], v[118:121]
	v_mfma_f32_16x16x32_bf16 v[114:117], v[180:183], v[188:191], v[114:117]
	v_mfma_f32_16x16x32_bf16 v[98:101], v[180:183], v[196:199], v[98:101]
	v_mfma_f32_16x16x32_bf16 v[102:105], v[172:175], v[196:199], v[102:105]
	v_mfma_f32_16x16x32_bf16 v[86:89], v[172:175], v[204:207], v[86:89]
	v_mfma_f32_16x16x32_bf16 v[82:85], v[180:183], v[204:207], v[82:85]
	v_mfma_f32_16x16x32_bf16 v[66:69], v[180:183], v[212:215], v[66:69]
	v_mfma_f32_16x16x32_bf16 v[70:73], v[172:175], v[212:215], v[70:73]
	s_setprio 2
	s_barrier
; #define PG8_STAGE(bufoff, gbase, voff) do { _Pragma("unroll") for (int _i = 0; _i < 2; ++_i) \
;         __builtin_amdgcn_global_load_lds((const unsigned*)((const char*)(gbase) + (voff)[_i]), (LAS unsigned*)(lds + (bufoff) + ldsw + _i * 8192), 16, 0, 0); } while (0)
; #define PG8_LDA(dst, b, h) do { _Pragma("unroll") for (int m = 0; m < 4; ++m) _Pragma("unroll") for (int k = 0; k < 2; ++k) dst[m][k] = *(const LAS bf16x8*)(lds + PG8_SA(b, h) + aoff + m * 2048 + k * 1024); } while (0)
; #define PG8_MMA(ai, bj, At, Bt) do { __builtin_amdgcn_s_setprio(1); _Pragma("unroll") for (int m = 0; m < 4; ++m) _Pragma("unroll") for (int n = 0; n < 2; ++n) _Pragma("unroll") for (int k = 0; k < 2; ++k) \
;         acc[ai][bj][m][n] = __builtin_amdgcn_mfma_f32_16x16x32_bf16(Bt[n][k], At[m][k], acc[ai][bj][m][n], 0, 0, 0); __builtin_amdgcn_s_setprio(0); } while (0)
; #define PG8_WAIT_V(n) asm volatile("s_waitcnt vmcnt(" #n ")" ::: "memory")
; #define PG8_WAIT_L(n) asm volatile("s_waitcnt lgkmcnt(" #n ")" ::: "memory")
; #define PG8_BAR __builtin_amdgcn_s_barrier()
; #define PG8_SCHED __builtin_amdgcn_sched_barrier(0)
; template <class Epi>
; __device__ __forceinline__ void gemm_phase(LAS unsigned char* lds, const Gemm g, int G, int c, const Epi& E) {
;     ...
;             PG8_LDA(At, 1, 1); PG8_STAGE(PG8_SB(1, 0), b3, voffB); PG8_STAGE(PG8_SB(1, 1), b3 + hstepB, voffB); PG8_STAGE(PG8_SA(1, 0), a3, voffA);
;             PG8_WAIT_V(8); PG8_WAIT_L(0); PG8_BAR; PG8_MMA(1, 0, At, B0); PG8_MMA(1, 1, At, B1); PG8_BAR; PG8_SCHED;
;         }
	s_mov_b32 m0, s39
	v_lshl_add_u64 v[162:163], v[162:163], 0, s[24:25]
	ds_read_b128 v[184:187], v168 offset:49152
	ds_read_b128 v[188:191], v168 offset:50176
	ds_read_b128 v[192:195], v168 offset:51200
	ds_read_b128 v[196:199], v168 offset:52224
	ds_read_b128 v[200:203], v168 offset:53248
	ds_read_b128 v[204:207], v168 offset:54272
	ds_read_b128 v[208:211], v168 offset:55296
	ds_read_b128 v[212:215], v168 offset:56320
	global_load_lds_dwordx4 v[162:163], off
	v_lshl_add_u64 v[162:163], v[216:217], 0, s[24:25]
	s_mov_b32 m0, s73
	s_nop 0
	global_load_lds_dwordx4 v[162:163], off
	v_lshl_add_u64 v[162:163], s[10:11], 0, v[140:141]
	s_mov_b32 m0, s38
	s_nop 0
	global_load_lds_dwordx4 v[162:163], off
	v_lshl_add_u64 v[162:163], s[10:11], 0, v[144:145]
	s_mov_b32 m0, s33
	s_nop 0
	global_load_lds_dwordx4 v[162:163], off
	v_lshl_add_u64 v[162:163], v[218:219], 0, s[24:25]
	s_mov_b32 m0, s93
	s_nop 0
	global_load_lds_dwordx4 v[162:163], off
	v_lshl_add_u64 v[162:163], v[220:221], 0, s[24:25]
	s_mov_b32 m0, s94
	s_nop 0
	global_load_lds_dwordx4 v[162:163], off
	s_waitcnt vmcnt(8)
	s_waitcnt lgkmcnt(0)
	s_barrier
	s_setprio 0
	s_waitcnt lgkmcnt(0)
	v_mfma_f32_16x16x32_bf16 v[62:65], v[130:133], v[184:187], v[62:65]
	v_mfma_f32_16x16x32_bf16 v[58:61], v[150:153], v[184:187], v[58:61]
	v_mfma_f32_16x16x32_bf16 v[42:45], v[150:153], v[192:195], v[42:45]
	v_mfma_f32_16x16x32_bf16 v[46:49], v[130:133], v[192:195], v[46:49]
	v_mfma_f32_16x16x32_bf16 v[30:33], v[130:133], v[200:203], v[30:33]
	v_mfma_f32_16x16x32_bf16 v[26:29], v[150:153], v[200:203], v[26:29]
	v_mfma_f32_16x16x32_bf16 v[10:13], v[150:153], v[208:211], v[10:13]
	v_mfma_f32_16x16x32_bf16 v[14:17], v[130:133], v[208:211], v[14:17]
	v_mfma_f32_16x16x32_bf16 v[62:65], v[134:137], v[188:191], v[62:65]
	v_mfma_f32_16x16x32_bf16 v[58:61], v[154:157], v[188:191], v[58:61]
	v_mfma_f32_16x16x32_bf16 v[42:45], v[154:157], v[196:199], v[42:45]
	v_mfma_f32_16x16x32_bf16 v[46:49], v[134:137], v[196:199], v[46:49]
	v_mfma_f32_16x16x32_bf16 v[30:33], v[134:137], v[204:207], v[30:33]
	v_mfma_f32_16x16x32_bf16 v[26:29], v[154:157], v[204:207], v[26:29]
	v_mfma_f32_16x16x32_bf16 v[10:13], v[154:157], v[212:215], v[10:13]
	v_mfma_f32_16x16x32_bf16 v[14:17], v[134:137], v[212:215], v[14:17]
	s_setprio 2
	s_setprio 0
	v_mfma_f32_16x16x32_bf16 v[54:57], v[158:161], v[184:187], v[54:57]
	v_mfma_f32_16x16x32_bf16 v[50:53], v[176:179], v[184:187], v[50:53]
	v_mfma_f32_16x16x32_bf16 v[34:37], v[176:179], v[192:195], v[34:37]
	v_mfma_f32_16x16x32_bf16 v[38:41], v[158:161], v[192:195], v[38:41]
	v_mfma_f32_16x16x32_bf16 v[22:25], v[158:161], v[200:203], v[22:25]
	v_mfma_f32_16x16x32_bf16 v[18:21], v[176:179], v[200:203], v[18:21]
	v_mfma_f32_16x16x32_bf16 v[2:5], v[176:179], v[208:211], v[2:5]
	v_mfma_f32_16x16x32_bf16 v[6:9], v[158:161], v[208:211], v[6:9]
	v_mfma_f32_16x16x32_bf16 v[54:57], v[172:175], v[188:191], v[54:57]
	v_mfma_f32_16x16x32_bf16 v[50:53], v[180:183], v[188:191], v[50:53]
	v_mfma_f32_16x16x32_bf16 v[34:37], v[180:183], v[196:199], v[34:37]
	v_mfma_f32_16x16x32_bf16 v[38:41], v[172:175], v[196:199], v[38:41]
	v_mfma_f32_16x16x32_bf16 v[22:25], v[172:175], v[204:207], v[22:25]
	v_mfma_f32_16x16x32_bf16 v[18:21], v[180:183], v[204:207], v[18:21]
	v_mfma_f32_16x16x32_bf16 v[2:5], v[180:183], v[212:215], v[2:5]
	v_mfma_f32_16x16x32_bf16 v[6:9], v[172:175], v[212:215], v[6:9]
	s_setprio 2
	s_barrier
	s_movk_i32 s38, 0x100
	s_andn2_b64 vcc, exec, s[4:5]
	s_mov_b64 s[10:11], -1
	s_mov_b64 s[4:5], 0
	s_cbranch_vccz .LBB0_476
	s_and_b64 vcc, exec, s[44:45]
	s_cbranch_vccz .LBB0_479
	s_barrier

; #define PG8_STAGE(bufoff, gbase, voff) do { _Pragma("unroll") for (int _i = 0; _i < 2; ++_i) \
;         __builtin_amdgcn_global_load_lds((const unsigned*)((const char*)(gbase) + (voff)[_i]), (LAS unsigned*)(lds + (bufoff) + ldsw + _i * 8192), 16, 0, 0); } while (0)
; #define PG8_LDA(dst, b, h) do { _Pragma("unroll") for (int m = 0; m < 4; ++m) _Pragma("unroll") for (int k = 0; k < 2; ++k) dst[m][k] = *(const LAS bf16x8*)(lds + PG8_SA(b, h) + aoff + m * 2048 + k * 1024); } while (0)
; #define PG8_LDB(dst, b, h) do { _Pragma("unroll") for (int n = 0; n < 2; ++n) _Pragma("unroll") for (int k = 0; k < 2; ++k) dst[n][k] = *(const LAS bf16x8*)(lds + PG8_SB(b, h) + boff + n * 2048 + k * 1024); } while (0)
; #define PG8_MMA(ai, bj, At, Bt) do { __builtin_amdgcn_s_setprio(1); _Pragma("unroll") for (int m = 0; m < 4; ++m) _Pragma("unroll") for (int n = 0; n < 2; ++n) _Pragma("unroll") for (int k = 0; k < 2; ++k) \
;         acc[ai][bj][m][n] = __builtin_amdgcn_mfma_f32_16x16x32_bf16(Bt[n][k], At[m][k], acc[ai][bj][m][n], 0, 0, 0); __builtin_amdgcn_s_setprio(0); } while (0)
; #define PG8_WAIT_V(n) asm volatile("s_waitcnt vmcnt(" #n ")" ::: "memory")
; #define PG8_WAIT_L(n) asm volatile("s_waitcnt lgkmcnt(" #n ")" ::: "memory")
; #define PG8_BAR __builtin_amdgcn_s_barrier()
; #define PG8_SCHED __builtin_amdgcn_sched_barrier(0)
; template <class Epi>
; __device__ __forceinline__ void gemm_phase(LAS unsigned char* lds, const Gemm g, int G, int c, const Epi& E) {
;     ...
;             const bool last = (t == nt - 2);
;             const char* a1 = cA + (size_t)(t + 1) * kstep;
;             const char* a2 = last ? nA : cA + (size_t)(t + 2) * kstep; const char* b2 = last ? nB : cB + (size_t)(t + 2) * kstep;
;             const char* a3 = a2 + kstep; const char* b3 = b2 + kstep;
;             PG8_LDB(B0, 0, 0); PG8_LDB(B1, 0, 1); PG8_SCHED; PG8_LDA(At, 0, 0); PG8_STAGE(PG8_SA(1, 1), a1 + hstepA, voffA);
;             PG8_WAIT_V(8); PG8_WAIT_L(0); PG8_BAR; PG8_MMA(0, 0, At, B0); PG8_MMA(0, 1, At, B1); PG8_BAR; PG8_SCHED;
;             PG8_LDA(At, 0, 1); PG8_STAGE(PG8_SB(0, 0), b2, voffB); PG8_STAGE(PG8_SB(0, 1), b2 + hstepB, voffB); PG8_STAGE(PG8_SA(0, 0), a2, voffA);
;             PG8_WAIT_V(8); PG8_WAIT_L(0); PG8_BAR; PG8_MMA(1, 0, At, B0); PG8_MMA(1, 1, At, B1); PG8_BAR; PG8_SCHED;
.LBB0_594:
	s_add_u32 s33, s8, s38
	s_addc_u32 s62, s9, 0
	s_add_u32 s39, s33, 0x100
	s_addc_u32 s58, s62, 0
	s_and_b64 s[56:57], s[54:55], exec
	s_cselect_b32 s59, s45, s58
	s_cselect_b32 s58, s44, s39
	s_add_u32 s38, s6, s38
	s_addc_u32 s39, s7, 0
	s_add_u32 s56, s38, 0x100
	s_addc_u32 s57, s39, 0
	s_and_b64 s[38:39], s[54:55], exec
	s_cselect_b32 s61, s47, s57
	s_cselect_b32 s60, s46, s56
	s_add_u32 s68, s33, 0xb0080
	s_addc_u32 s69, s62, 0
	s_add_i32 s63, s86, s23
	ds_read_b128 v[142:145], v166
	ds_read_b128 v[146:149], v166 offset:1024
	ds_read_b128 v[150:153], v166 offset:2048
	ds_read_b128 v[154:157], v166 offset:3072
	ds_read_b128 v[158:161], v167
	ds_read_b128 v[170:173], v167 offset:1024
	ds_read_b128 v[174:177], v167 offset:2048
	ds_read_b128 v[178:181], v167 offset:3072
	s_add_i32 m0, s72, 0xc000
	s_add_i32 s64, s72, 0xe000
	s_add_i32 s74, s63, 0x2000
	s_add_u32 s66, s60, 0xb0000
	s_addc_u32 s67, s61, 0
	s_add_i32 s62, s87, s23
	s_add_i32 s75, s62, 0x2000
	s_add_i32 s97, 0, 0x18000
	s_add_i32 s33, 0, 0x1c000
	s_add_u32 s56, s58, 0xb0000
	s_addc_u32 s57, s59, 0
	s_add_i32 s96, s97, s23
	s_add_i32 s39, s96, 0x2000
	s_add_u32 s54, s60, 0xb0080
	s_addc_u32 s55, s61, 0
	s_add_i32 s95, s33, s23
	s_add_i32 s38, s95, 0x2000
	v_lshl_add_u64 v[162:163], s[68:69], 0, v[136:137]
	ds_read_b128 v[182:185], v168
	ds_read_b128 v[186:189], v168 offset:1024
	ds_read_b128 v[190:193], v168 offset:2048
	ds_read_b128 v[194:197], v168 offset:3072
	ds_read_b128 v[198:201], v168 offset:4096
	ds_read_b128 v[202:205], v168 offset:5120
	ds_read_b128 v[206:209], v168 offset:6144
	ds_read_b128 v[210:213], v168 offset:7168
	global_load_lds_dwordx4 v[162:163], off
	v_lshl_add_u64 v[162:163], s[68:69], 0, v[132:133]
	s_mov_b32 m0, s64
	s_nop 0
	global_load_lds_dwordx4 v[162:163], off
	s_waitcnt vmcnt(8)
	s_waitcnt lgkmcnt(0)
	s_barrier
	s_setprio 0
	s_waitcnt lgkmcnt(0)
	v_mfma_f32_16x16x32_bf16 v[126:129], v[142:145], v[182:185], v[126:129]
	v_mfma_f32_16x16x32_bf16 v[122:125], v[150:153], v[182:185], v[122:125]
	v_mfma_f32_16x16x32_bf16 v[106:109], v[150:153], v[190:193], v[106:109]
	v_mfma_f32_16x16x32_bf16 v[110:113], v[142:145], v[190:193], v[110:113]
	v_mfma_f32_16x16x32_bf16 v[94:97], v[142:145], v[198:201], v[94:97]
	v_mfma_f32_16x16x32_bf16 v[90:93], v[150:153], v[198:201], v[90:93]
	v_mfma_f32_16x16x32_bf16 v[74:77], v[150:153], v[206:209], v[74:77]
	v_mfma_f32_16x16x32_bf16 v[78:81], v[142:145], v[206:209], v[78:81]
	v_mfma_f32_16x16x32_bf16 v[126:129], v[146:149], v[186:189], v[126:129]
	v_mfma_f32_16x16x32_bf16 v[122:125], v[154:157], v[186:189], v[122:125]
	v_mfma_f32_16x16x32_bf16 v[106:109], v[154:157], v[194:197], v[106:109]
	v_mfma_f32_16x16x32_bf16 v[110:113], v[146:149], v[194:197], v[110:113]
	v_mfma_f32_16x16x32_bf16 v[94:97], v[146:149], v[202:205], v[94:97]
	v_mfma_f32_16x16x32_bf16 v[90:93], v[154:157], v[202:205], v[90:93]
	v_mfma_f32_16x16x32_bf16 v[74:77], v[154:157], v[210:213], v[74:77]
	v_mfma_f32_16x16x32_bf16 v[78:81], v[146:149], v[210:213], v[78:81]
	s_setprio 2
	s_setprio 0
	v_mfma_f32_16x16x32_bf16 v[118:121], v[158:161], v[182:185], v[118:121]
	v_mfma_f32_16x16x32_bf16 v[114:117], v[174:177], v[182:185], v[114:117]
	v_mfma_f32_16x16x32_bf16 v[98:101], v[174:177], v[190:193], v[98:101]
	v_mfma_f32_16x16x32_bf16 v[102:105], v[158:161], v[190:193], v[102:105]
	v_mfma_f32_16x16x32_bf16 v[86:89], v[158:161], v[198:201], v[86:89]
	v_mfma_f32_16x16x32_bf16 v[82:85], v[174:177], v[198:201], v[82:85]
	v_mfma_f32_16x16x32_bf16 v[66:69], v[174:177], v[206:209], v[66:69]
	v_mfma_f32_16x16x32_bf16 v[70:73], v[158:161], v[206:209], v[70:73]
	v_mfma_f32_16x16x32_bf16 v[118:121], v[170:173], v[186:189], v[118:121]
	v_mfma_f32_16x16x32_bf16 v[114:117], v[178:181], v[186:189], v[114:117]
	v_mfma_f32_16x16x32_bf16 v[98:101], v[178:181], v[194:197], v[98:101]
	v_mfma_f32_16x16x32_bf16 v[102:105], v[170:173], v[194:197], v[102:105]
	v_mfma_f32_16x16x32_bf16 v[86:89], v[170:173], v[202:205], v[86:89]
	v_mfma_f32_16x16x32_bf16 v[82:85], v[178:181], v[202:205], v[82:85]
	v_mfma_f32_16x16x32_bf16 v[66:69], v[178:181], v[210:213], v[66:69]
	v_mfma_f32_16x16x32_bf16 v[70:73], v[170:173], v[210:213], v[70:73]
	s_setprio 2
	s_barrier
	s_mov_b32 m0, s63
	v_lshl_add_u64 v[162:163], s[60:61], 0, v[134:135]
	ds_read_b128 v[182:185], v168 offset:16384
	ds_read_b128 v[186:189], v168 offset:17408
	ds_read_b128 v[190:193], v168 offset:18432
	ds_read_b128 v[194:197], v168 offset:19456
	ds_read_b128 v[198:201], v168 offset:20480
	ds_read_b128 v[202:205], v168 offset:21504
	ds_read_b128 v[206:209], v168 offset:22528
	ds_read_b128 v[210:213], v168 offset:23552
	global_load_lds_dwordx4 v[162:163], off
	v_lshl_add_u64 v[214:215], s[60:61], 0, v[130:131]
	s_mov_b32 m0, s74
	v_lshl_add_u64 v[216:217], s[66:67], 0, v[134:135]
	global_load_lds_dwordx4 v[214:215], off
	s_mov_b32 m0, s62
	v_lshl_add_u64 v[218:219], s[58:59], 0, v[132:133]
	global_load_lds_dwordx4 v[216:217], off
	v_lshl_add_u64 v[216:217], s[66:67], 0, v[130:131]
	s_mov_b32 m0, s75
	s_nop 0
	global_load_lds_dwordx4 v[216:217], off
	v_lshl_add_u64 v[216:217], s[58:59], 0, v[136:137]
	s_mov_b32 m0, s72
	s_nop 0
	global_load_lds_dwordx4 v[216:217], off
	s_mov_b32 m0, s73
	s_nop 0
	global_load_lds_dwordx4 v[218:219], off
	s_waitcnt vmcnt(8)
	s_waitcnt lgkmcnt(0)
	s_barrier
; #define PG8_STAGE(bufoff, gbase, voff) do { _Pragma("unroll") for (int _i = 0; _i < 2; ++_i) \
;         __builtin_amdgcn_global_load_lds((const unsigned*)((const char*)(gbase) + (voff)[_i]), (LAS unsigned*)(lds + (bufoff) + ldsw + _i * 8192), 16, 0, 0); } while (0)
; #define PG8_LDA(dst, b, h) do { _Pragma("unroll") for (int m = 0; m < 4; ++m) _Pragma("unroll") for (int k = 0; k < 2; ++k) dst[m][k] = *(const LAS bf16x8*)(lds + PG8_SA(b, h) + aoff + m * 2048 + k * 1024); } while (0)
; #define PG8_LDB(dst, b, h) do { _Pragma("unroll") for (int n = 0; n < 2; ++n) _Pragma("unroll") for (int k = 0; k < 2; ++k) dst[n][k] = *(const LAS bf16x8*)(lds + PG8_SB(b, h) + boff + n * 2048 + k * 1024); } while (0)
; #define PG8_MMA(ai, bj, At, Bt) do { __builtin_amdgcn_s_setprio(1); _Pragma("unroll") for (int m = 0; m < 4; ++m) _Pragma("unroll") for (int n = 0; n < 2; ++n) _Pragma("unroll") for (int k = 0; k < 2; ++k) \
;         acc[ai][bj][m][n] = __builtin_amdgcn_mfma_f32_16x16x32_bf16(Bt[n][k], At[m][k], acc[ai][bj][m][n], 0, 0, 0); __builtin_amdgcn_s_setprio(0); } while (0)
; #define PG8_WAIT_V(n) asm volatile("s_waitcnt vmcnt(" #n ")" ::: "memory")
; #define PG8_WAIT_L(n) asm volatile("s_waitcnt lgkmcnt(" #n ")" ::: "memory")
; #define PG8_BAR __builtin_amdgcn_s_barrier()
; #define PG8_SCHED __builtin_amdgcn_sched_barrier(0)
; template <class Epi>
; __device__ __forceinline__ void gemm_phase(LAS unsigned char* lds, const Gemm g, int G, int c, const Epi& E) {
;     ...
;             PG8_WAIT_V(8); PG8_WAIT_L(0); PG8_BAR; PG8_MMA(1, 0, At, B0); PG8_MMA(1, 1, At, B1); PG8_BAR; PG8_SCHED;
;             PG8_LDB(B0, 1, 0); PG8_LDB(B1, 1, 1); PG8_SCHED; PG8_LDA(At, 1, 0); PG8_STAGE(PG8_SA(0, 1), a2 + hstepA, voffA);
;             PG8_WAIT_V(8); PG8_WAIT_L(0); PG8_BAR; PG8_MMA(0, 0, At, B0); PG8_MMA(0, 1, At, B1); PG8_BAR; PG8_SCHED;
	s_setprio 0
	s_waitcnt lgkmcnt(0)
	v_mfma_f32_16x16x32_bf16 v[62:65], v[142:145], v[182:185], v[62:65]
	v_mfma_f32_16x16x32_bf16 v[58:61], v[150:153], v[182:185], v[58:61]
	v_mfma_f32_16x16x32_bf16 v[42:45], v[150:153], v[190:193], v[42:45]
	v_mfma_f32_16x16x32_bf16 v[46:49], v[142:145], v[190:193], v[46:49]
	v_mfma_f32_16x16x32_bf16 v[30:33], v[142:145], v[198:201], v[30:33]
	v_mfma_f32_16x16x32_bf16 v[26:29], v[150:153], v[198:201], v[26:29]
	v_mfma_f32_16x16x32_bf16 v[10:13], v[150:153], v[206:209], v[10:13]
	v_mfma_f32_16x16x32_bf16 v[14:17], v[142:145], v[206:209], v[14:17]
	v_mfma_f32_16x16x32_bf16 v[62:65], v[146:149], v[186:189], v[62:65]
	v_mfma_f32_16x16x32_bf16 v[58:61], v[154:157], v[186:189], v[58:61]
	v_mfma_f32_16x16x32_bf16 v[42:45], v[154:157], v[194:197], v[42:45]
	v_mfma_f32_16x16x32_bf16 v[46:49], v[146:149], v[194:197], v[46:49]
	v_mfma_f32_16x16x32_bf16 v[30:33], v[146:149], v[202:205], v[30:33]
	v_mfma_f32_16x16x32_bf16 v[26:29], v[154:157], v[202:205], v[26:29]
	v_mfma_f32_16x16x32_bf16 v[10:13], v[154:157], v[210:213], v[10:13]
	v_mfma_f32_16x16x32_bf16 v[14:17], v[146:149], v[210:213], v[14:17]
	s_setprio 2
	s_setprio 0
	v_mfma_f32_16x16x32_bf16 v[54:57], v[158:161], v[182:185], v[54:57]
	v_mfma_f32_16x16x32_bf16 v[50:53], v[174:177], v[182:185], v[50:53]
	v_mfma_f32_16x16x32_bf16 v[34:37], v[174:177], v[190:193], v[34:37]
	v_mfma_f32_16x16x32_bf16 v[38:41], v[158:161], v[190:193], v[38:41]
	v_mfma_f32_16x16x32_bf16 v[22:25], v[158:161], v[198:201], v[22:25]
	v_mfma_f32_16x16x32_bf16 v[18:21], v[174:177], v[198:201], v[18:21]
	v_mfma_f32_16x16x32_bf16 v[2:5], v[174:177], v[206:209], v[2:5]
	v_mfma_f32_16x16x32_bf16 v[6:9], v[158:161], v[206:209], v[6:9]
	v_mfma_f32_16x16x32_bf16 v[54:57], v[170:173], v[186:189], v[54:57]
	v_mfma_f32_16x16x32_bf16 v[50:53], v[178:181], v[186:189], v[50:53]
	v_mfma_f32_16x16x32_bf16 v[34:37], v[178:181], v[194:197], v[34:37]
	v_mfma_f32_16x16x32_bf16 v[38:41], v[170:173], v[194:197], v[38:41]
	v_mfma_f32_16x16x32_bf16 v[22:25], v[170:173], v[202:205], v[22:25]
	v_mfma_f32_16x16x32_bf16 v[18:21], v[178:181], v[202:205], v[18:21]
	v_mfma_f32_16x16x32_bf16 v[2:5], v[178:181], v[210:213], v[2:5]
	v_mfma_f32_16x16x32_bf16 v[6:9], v[170:173], v[210:213], v[6:9]
	s_setprio 2
	s_barrier
	v_add_u32_e32 v154, s97, v165
	v_add_u32_e32 v178, s33, v165
	ds_read_b128 v[142:145], v154
	ds_read_b128 v[146:149], v154 offset:1024
	ds_read_b128 v[150:153], v154 offset:2048
	ds_read_b128 v[154:157], v154 offset:3072
	ds_read_b128 v[158:161], v178
	ds_read_b128 v[170:173], v178 offset:1024
	ds_read_b128 v[174:177], v178 offset:2048
	ds_read_b128 v[178:181], v178 offset:3072
	s_mov_b32 m0, s78
	v_lshl_add_u64 v[220:221], s[56:57], 0, v[136:137]
	ds_read_b128 v[182:185], v168 offset:32768
	ds_read_b128 v[186:189], v168 offset:33792
	ds_read_b128 v[190:193], v168 offset:34816
	ds_read_b128 v[194:197], v168 offset:35840
	ds_read_b128 v[198:201], v168 offset:36864
	ds_read_b128 v[202:205], v168 offset:37888
	ds_read_b128 v[206:209], v168 offset:38912
	ds_read_b128 v[210:213], v168 offset:39936
	global_load_lds_dwordx4 v[220:221], off
	v_lshl_add_u64 v[220:221], s[56:57], 0, v[132:133]
	s_mov_b32 m0, s81
	s_nop 0
	global_load_lds_dwordx4 v[220:221], off
	s_waitcnt vmcnt(8)
	s_waitcnt lgkmcnt(0)
	s_barrier
	s_setprio 0
	s_waitcnt lgkmcnt(0)
	v_mfma_f32_16x16x32_bf16 v[126:129], v[142:145], v[182:185], v[126:129]
	v_mfma_f32_16x16x32_bf16 v[122:125], v[150:153], v[182:185], v[122:125]
	v_mfma_f32_16x16x32_bf16 v[106:109], v[150:153], v[190:193], v[106:109]
	v_mfma_f32_16x16x32_bf16 v[110:113], v[142:145], v[190:193], v[110:113]
	v_mfma_f32_16x16x32_bf16 v[94:97], v[142:145], v[198:201], v[94:97]
	v_mfma_f32_16x16x32_bf16 v[90:93], v[150:153], v[198:201], v[90:93]
	v_mfma_f32_16x16x32_bf16 v[74:77], v[150:153], v[206:209], v[74:77]
	v_mfma_f32_16x16x32_bf16 v[78:81], v[142:145], v[206:209], v[78:81]
	v_mfma_f32_16x16x32_bf16 v[126:129], v[146:149], v[186:189], v[126:129]
	v_mfma_f32_16x16x32_bf16 v[122:125], v[154:157], v[186:189], v[122:125]
	v_mfma_f32_16x16x32_bf16 v[106:109], v[154:157], v[194:197], v[106:109]
	v_mfma_f32_16x16x32_bf16 v[110:113], v[146:149], v[194:197], v[110:113]
	v_mfma_f32_16x16x32_bf16 v[94:97], v[146:149], v[202:205], v[94:97]
	v_mfma_f32_16x16x32_bf16 v[90:93], v[154:157], v[202:205], v[90:93]
	v_mfma_f32_16x16x32_bf16 v[74:77], v[154:157], v[210:213], v[74:77]
	v_mfma_f32_16x16x32_bf16 v[78:81], v[146:149], v[210:213], v[78:81]
	s_setprio 2
	s_setprio 0
	v_mfma_f32_16x16x32_bf16 v[118:121], v[158:161], v[182:185], v[118:121]
	v_mfma_f32_16x16x32_bf16 v[114:117], v[174:177], v[182:185], v[114:117]
	v_mfma_f32_16x16x32_bf16 v[98:101], v[174:177], v[190:193], v[98:101]
	v_mfma_f32_16x16x32_bf16 v[102:105], v[158:161], v[190:193], v[102:105]
	v_mfma_f32_16x16x32_bf16 v[86:89], v[158:161], v[198:201], v[86:89]
	v_mfma_f32_16x16x32_bf16 v[82:85], v[174:177], v[198:201], v[82:85]
	v_mfma_f32_16x16x32_bf16 v[66:69], v[174:177], v[206:209], v[66:69]
	v_mfma_f32_16x16x32_bf16 v[70:73], v[158:161], v[206:209], v[70:73]
	v_mfma_f32_16x16x32_bf16 v[118:121], v[170:173], v[186:189], v[118:121]
	v_mfma_f32_16x16x32_bf16 v[114:117], v[178:181], v[186:189], v[114:117]
	v_mfma_f32_16x16x32_bf16 v[98:101], v[178:181], v[194:197], v[98:101]
	v_mfma_f32_16x16x32_bf16 v[102:105], v[170:173], v[194:197], v[102:105]
	v_mfma_f32_16x16x32_bf16 v[86:89], v[170:173], v[202:205], v[86:89]
	v_mfma_f32_16x16x32_bf16 v[82:85], v[178:181], v[202:205], v[82:85]
	v_mfma_f32_16x16x32_bf16 v[66:69], v[178:181], v[210:213], v[66:69]
	v_mfma_f32_16x16x32_bf16 v[70:73], v[170:173], v[210:213], v[70:73]
	s_setprio 2
	s_barrier
; #define PG8_STAGE(bufoff, gbase, voff) do { _Pragma("unroll") for (int _i = 0; _i < 2; ++_i) \
;         __builtin_amdgcn_global_load_lds((const unsigned*)((const char*)(gbase) + (voff)[_i]), (LAS unsigned*)(lds + (bufoff) + ldsw + _i * 8192), 16, 0, 0); } while (0)
; #define PG8_LDA(dst, b, h) do { _Pragma("unroll") for (int m = 0; m < 4; ++m) _Pragma("unroll") for (int k = 0; k < 2; ++k) dst[m][k] = *(const LAS bf16x8*)(lds + PG8_SA(b, h) + aoff + m * 2048 + k * 1024); } while (0)
; #define PG8_MMA(ai, bj, At, Bt) do { __builtin_amdgcn_s_setprio(1); _Pragma("unroll") for (int m = 0; m < 4; ++m) _Pragma("unroll") for (int n = 0; n < 2; ++n) _Pragma("unroll") for (int k = 0; k < 2; ++k) \
;         acc[ai][bj][m][n] = __builtin_amdgcn_mfma_f32_16x16x32_bf16(Bt[n][k], At[m][k], acc[ai][bj][m][n], 0, 0, 0); __builtin_amdgcn_s_setprio(0); } while (0)
; #define PG8_WAIT_V(n) asm volatile("s_waitcnt vmcnt(" #n ")" ::: "memory")
; #define PG8_WAIT_L(n) asm volatile("s_waitcnt lgkmcnt(" #n ")" ::: "memory")
; #define PG8_BAR __builtin_amdgcn_s_barrier()
; #define PG8_SCHED __builtin_amdgcn_sched_barrier(0)
; template <class Epi>
; __device__ __forceinline__ void gemm_phase(LAS unsigned char* lds, const Gemm g, int G, int c, const Epi& E) {
;     ...
;             PG8_LDA(At, 1, 1); PG8_STAGE(PG8_SB(1, 0), b3, voffB); PG8_STAGE(PG8_SB(1, 1), b3 + hstepB, voffB); PG8_STAGE(PG8_SA(1, 0), a3, voffA);
;             PG8_WAIT_V(8); PG8_WAIT_L(0); PG8_BAR; PG8_MMA(1, 0, At, B0); PG8_MMA(1, 1, At, B1); PG8_BAR; PG8_SCHED;
;         }
	s_mov_b32 m0, s96
	v_lshl_add_u64 v[162:163], v[162:163], 0, s[18:19]
	ds_read_b128 v[182:185], v168 offset:49152
	ds_read_b128 v[186:189], v168 offset:50176
	ds_read_b128 v[190:193], v168 offset:51200
	ds_read_b128 v[194:197], v168 offset:52224
	ds_read_b128 v[198:201], v168 offset:53248
	ds_read_b128 v[202:205], v168 offset:54272
	ds_read_b128 v[206:209], v168 offset:55296
	ds_read_b128 v[210:213], v168 offset:56320
	global_load_lds_dwordx4 v[162:163], off
	v_lshl_add_u64 v[162:163], v[214:215], 0, s[18:19]
	s_mov_b32 m0, s39
	s_nop 0
	global_load_lds_dwordx4 v[162:163], off
	v_lshl_add_u64 v[162:163], s[54:55], 0, v[134:135]
	s_mov_b32 m0, s95
	s_nop 0
	global_load_lds_dwordx4 v[162:163], off
	v_lshl_add_u64 v[162:163], s[54:55], 0, v[130:131]
	s_mov_b32 m0, s38
	s_nop 0
	global_load_lds_dwordx4 v[162:163], off
	v_lshl_add_u64 v[162:163], v[216:217], 0, s[18:19]
	s_mov_b32 m0, s84
	s_nop 0
	global_load_lds_dwordx4 v[162:163], off
	v_lshl_add_u64 v[162:163], v[218:219], 0, s[18:19]
	s_mov_b32 m0, s85
	s_nop 0
	global_load_lds_dwordx4 v[162:163], off
	s_waitcnt vmcnt(8)
	s_waitcnt lgkmcnt(0)
	s_barrier
	s_setprio 0
	s_waitcnt lgkmcnt(0)
	v_mfma_f32_16x16x32_bf16 v[62:65], v[142:145], v[182:185], v[62:65]
	v_mfma_f32_16x16x32_bf16 v[58:61], v[150:153], v[182:185], v[58:61]
	v_mfma_f32_16x16x32_bf16 v[42:45], v[150:153], v[190:193], v[42:45]
	v_mfma_f32_16x16x32_bf16 v[46:49], v[142:145], v[190:193], v[46:49]
	v_mfma_f32_16x16x32_bf16 v[30:33], v[142:145], v[198:201], v[30:33]
	v_mfma_f32_16x16x32_bf16 v[26:29], v[150:153], v[198:201], v[26:29]
	v_mfma_f32_16x16x32_bf16 v[10:13], v[150:153], v[206:209], v[10:13]
	v_mfma_f32_16x16x32_bf16 v[14:17], v[142:145], v[206:209], v[14:17]
	v_mfma_f32_16x16x32_bf16 v[62:65], v[146:149], v[186:189], v[62:65]
	v_mfma_f32_16x16x32_bf16 v[58:61], v[154:157], v[186:189], v[58:61]
	v_mfma_f32_16x16x32_bf16 v[42:45], v[154:157], v[194:197], v[42:45]
	v_mfma_f32_16x16x32_bf16 v[46:49], v[146:149], v[194:197], v[46:49]
	v_mfma_f32_16x16x32_bf16 v[30:33], v[146:149], v[202:205], v[30:33]
	v_mfma_f32_16x16x32_bf16 v[26:29], v[154:157], v[202:205], v[26:29]
	v_mfma_f32_16x16x32_bf16 v[10:13], v[154:157], v[210:213], v[10:13]
	v_mfma_f32_16x16x32_bf16 v[14:17], v[146:149], v[210:213], v[14:17]
	s_setprio 2
	s_setprio 0
	v_mfma_f32_16x16x32_bf16 v[54:57], v[158:161], v[182:185], v[54:57]
	v_mfma_f32_16x16x32_bf16 v[50:53], v[174:177], v[182:185], v[50:53]
	v_mfma_f32_16x16x32_bf16 v[34:37], v[174:177], v[190:193], v[34:37]
	v_mfma_f32_16x16x32_bf16 v[38:41], v[158:161], v[190:193], v[38:41]
	v_mfma_f32_16x16x32_bf16 v[22:25], v[158:161], v[198:201], v[22:25]
	v_mfma_f32_16x16x32_bf16 v[18:21], v[174:177], v[198:201], v[18:21]
	v_mfma_f32_16x16x32_bf16 v[2:5], v[174:177], v[206:209], v[2:5]
	v_mfma_f32_16x16x32_bf16 v[6:9], v[158:161], v[206:209], v[6:9]
	v_mfma_f32_16x16x32_bf16 v[54:57], v[170:173], v[186:189], v[54:57]
	v_mfma_f32_16x16x32_bf16 v[50:53], v[178:181], v[186:189], v[50:53]
	v_mfma_f32_16x16x32_bf16 v[34:37], v[178:181], v[194:197], v[34:37]
	v_mfma_f32_16x16x32_bf16 v[38:41], v[170:173], v[194:197], v[38:41]
	v_mfma_f32_16x16x32_bf16 v[22:25], v[170:173], v[202:205], v[22:25]
	v_mfma_f32_16x16x32_bf16 v[18:21], v[178:181], v[202:205], v[18:21]
	v_mfma_f32_16x16x32_bf16 v[2:5], v[178:181], v[210:213], v[2:5]
	v_mfma_f32_16x16x32_bf16 v[6:9], v[170:173], v[210:213], v[6:9]
	s_setprio 2
	s_barrier
	s_movk_i32 s38, 0x100
	s_andn2_b64 vcc, exec, s[4:5]
	s_mov_b64 s[54:55], -1
	s_mov_b64 s[4:5], 0
	s_cbranch_vccz .LBB0_594
	s_and_b64 vcc, exec, s[20:21]
	s_cbranch_vccz .LBB0_597
	s_barrier

; #define PG8_STAGE(bufoff, gbase, voff) do { _Pragma("unroll") for (int _i = 0; _i < 2; ++_i) \
;         __builtin_amdgcn_global_load_lds((const unsigned*)((const char*)(gbase) + (voff)[_i]), (LAS unsigned*)(lds + (bufoff) + ldsw + _i * 8192), 16, 0, 0); } while (0)
; #define PG8_LDA(dst, b, h) do { _Pragma("unroll") for (int m = 0; m < 4; ++m) _Pragma("unroll") for (int k = 0; k < 2; ++k) dst[m][k] = *(const LAS bf16x8*)(lds + PG8_SA(b, h) + aoff + m * 2048 + k * 1024); } while (0)
; #define PG8_LDB(dst, b, h) do { _Pragma("unroll") for (int n = 0; n < 2; ++n) _Pragma("unroll") for (int k = 0; k < 2; ++k) dst[n][k] = *(const LAS bf16x8*)(lds + PG8_SB(b, h) + boff + n * 2048 + k * 1024); } while (0)
; #define PG8_MMA(ai, bj, At, Bt) do { __builtin_amdgcn_s_setprio(1); _Pragma("unroll") for (int m = 0; m < 4; ++m) _Pragma("unroll") for (int n = 0; n < 2; ++n) _Pragma("unroll") for (int k = 0; k < 2; ++k) \
;         acc[ai][bj][m][n] = __builtin_amdgcn_mfma_f32_16x16x32_bf16(Bt[n][k], At[m][k], acc[ai][bj][m][n], 0, 0, 0); __builtin_amdgcn_s_setprio(0); } while (0)
; #define PG8_WAIT_V(n) asm volatile("s_waitcnt vmcnt(" #n ")" ::: "memory")
; #define PG8_WAIT_L(n) asm volatile("s_waitcnt lgkmcnt(" #n ")" ::: "memory")
; #define PG8_BAR __builtin_amdgcn_s_barrier()
; #define PG8_SCHED __builtin_amdgcn_sched_barrier(0)
; template <class Epi>
; __device__ __forceinline__ void gemm_phase(LAS unsigned char* lds, const Gemm g, int G, int c, const Epi& E) {
;     ...
;             const bool last = (t == nt - 2);
;             const char* a1 = cA + (size_t)(t + 1) * kstep;
;             const char* a2 = last ? nA : cA + (size_t)(t + 2) * kstep; const char* b2 = last ? nB : cB + (size_t)(t + 2) * kstep;
;             const char* a3 = a2 + kstep; const char* b3 = b2 + kstep;
;             PG8_LDB(B0, 0, 0); PG8_LDB(B1, 0, 1); PG8_SCHED; PG8_LDA(At, 0, 0); PG8_STAGE(PG8_SA(1, 1), a1 + hstepA, voffA);
;             PG8_WAIT_V(8); PG8_WAIT_L(0); PG8_BAR; PG8_MMA(0, 0, At, B0); PG8_MMA(0, 1, At, B1); PG8_BAR; PG8_SCHED;
;             PG8_LDA(At, 0, 1); PG8_STAGE(PG8_SB(0, 0), b2, voffB); PG8_STAGE(PG8_SB(0, 1), b2 + hstepB, voffB); PG8_STAGE(PG8_SA(0, 0), a2, voffA);
;             PG8_WAIT_V(8); PG8_WAIT_L(0); PG8_BAR; PG8_MMA(1, 0, At, B0); PG8_MMA(1, 1, At, B1); PG8_BAR; PG8_SCHED;
.LBB0_765:
	ds_read_b128 v[146:149], v152
	ds_read_b128 v[156:159], v152 offset:1024
	ds_read_b128 v[160:163], v152 offset:2048
	ds_read_b128 v[164:167], v152 offset:3072
	ds_read_b128 v[168:171], v153
	ds_read_b128 v[172:175], v153 offset:1024
	ds_read_b128 v[176:179], v153 offset:2048
	ds_read_b128 v[180:183], v153 offset:3072
	s_add_u32 s33, s44, 0xfff00080
	s_addc_u32 s46, s45, -1
	s_cmp_eq_u32 s83, 60
	s_cselect_b32 s53, s15, s46
	s_cselect_b32 s52, s78, s33
	s_cselect_b32 s47, s11, s82
	s_cselect_b32 s46, s13, s81
	v_lshl_add_u64 v[216:217], s[44:45], 0, v[138:139]
	s_add_i32 m0, s17, 0xc000
	ds_read_b128 v[184:187], v154
	ds_read_b128 v[188:191], v154 offset:1024
	ds_read_b128 v[192:195], v154 offset:2048
	ds_read_b128 v[196:199], v154 offset:3072
	ds_read_b128 v[200:203], v154 offset:4096
	ds_read_b128 v[204:207], v154 offset:5120
	ds_read_b128 v[208:211], v154 offset:6144
	ds_read_b128 v[212:215], v154 offset:7168
	global_load_lds_dwordx4 v[216:217], off
	v_lshl_add_u64 v[216:217], s[44:45], 0, v[140:141]
	s_add_i32 m0, s17, 0xe000
	s_nop 0
	global_load_lds_dwordx4 v[216:217], off
	s_waitcnt vmcnt(8)
	s_waitcnt lgkmcnt(0)
	s_barrier
	s_setprio 0
	s_waitcnt lgkmcnt(0)
	v_mfma_f32_16x16x32_bf16 v[126:129], v[146:149], v[184:187], v[126:129]
	v_mfma_f32_16x16x32_bf16 v[122:125], v[160:163], v[184:187], v[122:125]
	v_mfma_f32_16x16x32_bf16 v[110:113], v[160:163], v[192:195], v[110:113]
	v_mfma_f32_16x16x32_bf16 v[118:121], v[146:149], v[192:195], v[118:121]
	v_mfma_f32_16x16x32_bf16 v[102:105], v[146:149], v[200:203], v[102:105]
	v_mfma_f32_16x16x32_bf16 v[94:97], v[160:163], v[200:203], v[94:97]
	v_mfma_f32_16x16x32_bf16 v[78:81], v[160:163], v[208:211], v[78:81]
	v_mfma_f32_16x16x32_bf16 v[86:89], v[146:149], v[208:211], v[86:89]
	v_mfma_f32_16x16x32_bf16 v[126:129], v[156:159], v[188:191], v[126:129]
	v_mfma_f32_16x16x32_bf16 v[122:125], v[164:167], v[188:191], v[122:125]
	v_mfma_f32_16x16x32_bf16 v[110:113], v[164:167], v[196:199], v[110:113]
	v_mfma_f32_16x16x32_bf16 v[118:121], v[156:159], v[196:199], v[118:121]
	v_mfma_f32_16x16x32_bf16 v[102:105], v[156:159], v[204:207], v[102:105]
	v_mfma_f32_16x16x32_bf16 v[94:97], v[164:167], v[204:207], v[94:97]
	v_mfma_f32_16x16x32_bf16 v[78:81], v[164:167], v[212:215], v[78:81]
	v_mfma_f32_16x16x32_bf16 v[86:89], v[156:159], v[212:215], v[86:89]
	s_setprio 2
	s_setprio 0
	v_mfma_f32_16x16x32_bf16 v[114:117], v[168:171], v[184:187], v[114:117]
	v_mfma_f32_16x16x32_bf16 v[106:109], v[176:179], v[184:187], v[106:109]
	v_mfma_f32_16x16x32_bf16 v[90:93], v[176:179], v[192:195], v[90:93]
	v_mfma_f32_16x16x32_bf16 v[98:101], v[168:171], v[192:195], v[98:101]
	v_mfma_f32_16x16x32_bf16 v[82:85], v[168:171], v[200:203], v[82:85]
	v_mfma_f32_16x16x32_bf16 v[74:77], v[176:179], v[200:203], v[74:77]
	v_mfma_f32_16x16x32_bf16 v[66:69], v[176:179], v[208:211], v[66:69]
	v_mfma_f32_16x16x32_bf16 v[70:73], v[168:171], v[208:211], v[70:73]
	v_mfma_f32_16x16x32_bf16 v[114:117], v[172:175], v[188:191], v[114:117]
	v_mfma_f32_16x16x32_bf16 v[106:109], v[180:183], v[188:191], v[106:109]
	v_mfma_f32_16x16x32_bf16 v[90:93], v[180:183], v[196:199], v[90:93]
	v_mfma_f32_16x16x32_bf16 v[98:101], v[172:175], v[196:199], v[98:101]
	v_mfma_f32_16x16x32_bf16 v[82:85], v[172:175], v[204:207], v[82:85]
	v_mfma_f32_16x16x32_bf16 v[74:77], v[180:183], v[204:207], v[74:77]
	v_mfma_f32_16x16x32_bf16 v[66:69], v[180:183], v[212:215], v[66:69]
	v_mfma_f32_16x16x32_bf16 v[70:73], v[172:175], v[212:215], v[70:73]
	s_setprio 2
	s_barrier
	s_add_i32 s33, s72, s61
	v_lshl_add_u64 v[216:217], s[46:47], 0, v[134:135]
	s_mov_b32 m0, s33
	ds_read_b128 v[184:187], v154 offset:16384
	ds_read_b128 v[188:191], v154 offset:17408
	ds_read_b128 v[192:195], v154 offset:18432
	ds_read_b128 v[196:199], v154 offset:19456
	ds_read_b128 v[200:203], v154 offset:20480
	ds_read_b128 v[204:207], v154 offset:21504
	ds_read_b128 v[208:211], v154 offset:22528
	ds_read_b128 v[212:215], v154 offset:23552
	global_load_lds_dwordx4 v[216:217], off
	s_add_i32 m0, s33, 0x2000
	s_add_u32 s62, s46, 0x100000
	v_lshl_add_u64 v[218:219], s[46:47], 0, v[130:131]
	s_addc_u32 s63, s47, 0
	s_add_i32 s33, s73, s61
	global_load_lds_dwordx4 v[218:219], off
	v_lshl_add_u64 v[220:221], s[62:63], 0, v[134:135]
	s_mov_b32 m0, s33
	v_lshl_add_u64 v[224:225], s[52:53], 0, v[132:133]
	global_load_lds_dwordx4 v[220:221], off
	v_lshl_add_u64 v[220:221], s[62:63], 0, v[130:131]
	s_add_i32 m0, s33, 0x2000
	s_nop 0
	global_load_lds_dwordx4 v[220:221], off
	v_lshl_add_u64 v[220:221], s[52:53], 0, v[136:137]
	s_mov_b32 m0, s17
	s_nop 0
	global_load_lds_dwordx4 v[220:221], off
	s_mov_b32 m0, s39
	s_nop 0
	global_load_lds_dwordx4 v[224:225], off
	s_waitcnt vmcnt(8)
	s_waitcnt lgkmcnt(0)
	s_barrier
; #define PG8_STAGE(bufoff, gbase, voff) do { _Pragma("unroll") for (int _i = 0; _i < 2; ++_i) \
;         __builtin_amdgcn_global_load_lds((const unsigned*)((const char*)(gbase) + (voff)[_i]), (LAS unsigned*)(lds + (bufoff) + ldsw + _i * 8192), 16, 0, 0); } while (0)
; #define PG8_LDA(dst, b, h) do { _Pragma("unroll") for (int m = 0; m < 4; ++m) _Pragma("unroll") for (int k = 0; k < 2; ++k) dst[m][k] = *(const LAS bf16x8*)(lds + PG8_SA(b, h) + aoff + m * 2048 + k * 1024); } while (0)
; #define PG8_LDB(dst, b, h) do { _Pragma("unroll") for (int n = 0; n < 2; ++n) _Pragma("unroll") for (int k = 0; k < 2; ++k) dst[n][k] = *(const LAS bf16x8*)(lds + PG8_SB(b, h) + boff + n * 2048 + k * 1024); } while (0)
; #define PG8_MMA(ai, bj, At, Bt) do { __builtin_amdgcn_s_setprio(1); _Pragma("unroll") for (int m = 0; m < 4; ++m) _Pragma("unroll") for (int n = 0; n < 2; ++n) _Pragma("unroll") for (int k = 0; k < 2; ++k) \
;         acc[ai][bj][m][n] = __builtin_amdgcn_mfma_f32_16x16x32_bf16(Bt[n][k], At[m][k], acc[ai][bj][m][n], 0, 0, 0); __builtin_amdgcn_s_setprio(0); } while (0)
; #define PG8_WAIT_V(n) asm volatile("s_waitcnt vmcnt(" #n ")" ::: "memory")
; #define PG8_WAIT_L(n) asm volatile("s_waitcnt lgkmcnt(" #n ")" ::: "memory")
; #define PG8_BAR __builtin_amdgcn_s_barrier()
; #define PG8_SCHED __builtin_amdgcn_sched_barrier(0)
; template <class Epi>
; __device__ __forceinline__ void gemm_phase(LAS unsigned char* lds, const Gemm g, int G, int c, const Epi& E) {
;     ...
;             PG8_WAIT_V(8); PG8_WAIT_L(0); PG8_BAR; PG8_MMA(1, 0, At, B0); PG8_MMA(1, 1, At, B1); PG8_BAR; PG8_SCHED;
;             PG8_LDB(B0, 1, 0); PG8_LDB(B1, 1, 1); PG8_SCHED; PG8_LDA(At, 1, 0); PG8_STAGE(PG8_SA(0, 1), a2 + hstepA, voffA);
;             PG8_WAIT_V(8); PG8_WAIT_L(0); PG8_BAR; PG8_MMA(0, 0, At, B0); PG8_MMA(0, 1, At, B1); PG8_BAR; PG8_SCHED;
	s_setprio 0
	s_waitcnt lgkmcnt(0)
	v_mfma_f32_16x16x32_bf16 v[62:65], v[146:149], v[184:187], v[62:65]
	v_mfma_f32_16x16x32_bf16 v[58:61], v[160:163], v[184:187], v[58:61]
	v_mfma_f32_16x16x32_bf16 v[46:49], v[160:163], v[192:195], v[46:49]
	v_mfma_f32_16x16x32_bf16 v[54:57], v[146:149], v[192:195], v[54:57]
	v_mfma_f32_16x16x32_bf16 v[38:41], v[146:149], v[200:203], v[38:41]
	v_mfma_f32_16x16x32_bf16 v[30:33], v[160:163], v[200:203], v[30:33]
	v_mfma_f32_16x16x32_bf16 v[14:17], v[160:163], v[208:211], v[14:17]
	v_mfma_f32_16x16x32_bf16 v[22:25], v[146:149], v[208:211], v[22:25]
	v_mfma_f32_16x16x32_bf16 v[62:65], v[156:159], v[188:191], v[62:65]
	v_mfma_f32_16x16x32_bf16 v[58:61], v[164:167], v[188:191], v[58:61]
	v_mfma_f32_16x16x32_bf16 v[46:49], v[164:167], v[196:199], v[46:49]
	v_mfma_f32_16x16x32_bf16 v[54:57], v[156:159], v[196:199], v[54:57]
	v_mfma_f32_16x16x32_bf16 v[38:41], v[156:159], v[204:207], v[38:41]
	v_mfma_f32_16x16x32_bf16 v[30:33], v[164:167], v[204:207], v[30:33]
	v_mfma_f32_16x16x32_bf16 v[14:17], v[164:167], v[212:215], v[14:17]
	v_mfma_f32_16x16x32_bf16 v[22:25], v[156:159], v[212:215], v[22:25]
	s_setprio 2
	s_setprio 0
	v_mfma_f32_16x16x32_bf16 v[50:53], v[168:171], v[184:187], v[50:53]
	v_mfma_f32_16x16x32_bf16 v[42:45], v[176:179], v[184:187], v[42:45]
	v_mfma_f32_16x16x32_bf16 v[26:29], v[176:179], v[192:195], v[26:29]
	v_mfma_f32_16x16x32_bf16 v[34:37], v[168:171], v[192:195], v[34:37]
	v_mfma_f32_16x16x32_bf16 v[18:21], v[168:171], v[200:203], v[18:21]
	v_mfma_f32_16x16x32_bf16 v[10:13], v[176:179], v[200:203], v[10:13]
	v_mfma_f32_16x16x32_bf16 v[2:5], v[176:179], v[208:211], v[2:5]
	v_mfma_f32_16x16x32_bf16 v[6:9], v[168:171], v[208:211], v[6:9]
	v_mfma_f32_16x16x32_bf16 v[50:53], v[172:175], v[188:191], v[50:53]
	v_mfma_f32_16x16x32_bf16 v[42:45], v[180:183], v[188:191], v[42:45]
	v_mfma_f32_16x16x32_bf16 v[26:29], v[180:183], v[196:199], v[26:29]
	v_mfma_f32_16x16x32_bf16 v[34:37], v[172:175], v[196:199], v[34:37]
	v_mfma_f32_16x16x32_bf16 v[18:21], v[172:175], v[204:207], v[18:21]
	v_mfma_f32_16x16x32_bf16 v[10:13], v[180:183], v[204:207], v[10:13]
	v_mfma_f32_16x16x32_bf16 v[2:5], v[180:183], v[212:215], v[2:5]
	v_mfma_f32_16x16x32_bf16 v[6:9], v[172:175], v[212:215], v[6:9]
	s_setprio 2
	s_barrier
	s_add_i32 s33, 0, 0x18000
	v_add_u32_e32 v155, s33, v151
	s_add_i32 s62, 0, 0x1c000
	ds_read_b128 v[146:149], v155
	ds_read_b128 v[156:159], v155 offset:1024
	ds_read_b128 v[160:163], v155 offset:2048
	ds_read_b128 v[164:167], v155 offset:3072
	v_add_u32_e32 v155, s62, v151
	ds_read_b128 v[168:171], v155
	ds_read_b128 v[172:175], v155 offset:1024
	ds_read_b128 v[176:179], v155 offset:2048
	ds_read_b128 v[180:183], v155 offset:3072
	s_add_u32 s52, s52, 0x100000
	s_addc_u32 s53, s53, 0
	s_mov_b32 m0, s43
	v_lshl_add_u64 v[226:227], s[52:53], 0, v[136:137]
	ds_read_b128 v[184:187], v154 offset:32768
	ds_read_b128 v[188:191], v154 offset:33792
	ds_read_b128 v[192:195], v154 offset:34816
	ds_read_b128 v[196:199], v154 offset:35840
	ds_read_b128 v[200:203], v154 offset:36864
	ds_read_b128 v[204:207], v154 offset:37888
	ds_read_b128 v[208:211], v154 offset:38912
	ds_read_b128 v[212:215], v154 offset:39936
	global_load_lds_dwordx4 v[226:227], off
	v_lshl_add_u64 v[226:227], s[52:53], 0, v[132:133]
	s_mov_b32 m0, s66
	s_nop 0
	global_load_lds_dwordx4 v[226:227], off
	s_waitcnt vmcnt(8)
	s_waitcnt lgkmcnt(0)
	s_barrier
	s_setprio 0
	s_waitcnt lgkmcnt(0)
	v_mfma_f32_16x16x32_bf16 v[126:129], v[146:149], v[184:187], v[126:129]
	v_mfma_f32_16x16x32_bf16 v[122:125], v[160:163], v[184:187], v[122:125]
	v_mfma_f32_16x16x32_bf16 v[110:113], v[160:163], v[192:195], v[110:113]
	v_mfma_f32_16x16x32_bf16 v[118:121], v[146:149], v[192:195], v[118:121]
	v_mfma_f32_16x16x32_bf16 v[102:105], v[146:149], v[200:203], v[102:105]
	v_mfma_f32_16x16x32_bf16 v[94:97], v[160:163], v[200:203], v[94:97]
	v_mfma_f32_16x16x32_bf16 v[78:81], v[160:163], v[208:211], v[78:81]
	v_mfma_f32_16x16x32_bf16 v[86:89], v[146:149], v[208:211], v[86:89]
	v_mfma_f32_16x16x32_bf16 v[126:129], v[156:159], v[188:191], v[126:129]
	v_mfma_f32_16x16x32_bf16 v[122:125], v[164:167], v[188:191], v[122:125]
	v_mfma_f32_16x16x32_bf16 v[110:113], v[164:167], v[196:199], v[110:113]
	v_mfma_f32_16x16x32_bf16 v[118:121], v[156:159], v[196:199], v[118:121]
	v_mfma_f32_16x16x32_bf16 v[102:105], v[156:159], v[204:207], v[102:105]
	v_mfma_f32_16x16x32_bf16 v[94:97], v[164:167], v[204:207], v[94:97]
	v_mfma_f32_16x16x32_bf16 v[78:81], v[164:167], v[212:215], v[78:81]
	v_mfma_f32_16x16x32_bf16 v[86:89], v[156:159], v[212:215], v[86:89]
	s_setprio 2
	s_setprio 0
	v_mfma_f32_16x16x32_bf16 v[114:117], v[168:171], v[184:187], v[114:117]
	v_mfma_f32_16x16x32_bf16 v[106:109], v[176:179], v[184:187], v[106:109]
	v_mfma_f32_16x16x32_bf16 v[90:93], v[176:179], v[192:195], v[90:93]
	v_mfma_f32_16x16x32_bf16 v[98:101], v[168:171], v[192:195], v[98:101]
	v_mfma_f32_16x16x32_bf16 v[82:85], v[168:171], v[200:203], v[82:85]
	v_mfma_f32_16x16x32_bf16 v[74:77], v[176:179], v[200:203], v[74:77]
	v_mfma_f32_16x16x32_bf16 v[66:69], v[176:179], v[208:211], v[66:69]
	v_mfma_f32_16x16x32_bf16 v[70:73], v[168:171], v[208:211], v[70:73]
	v_mfma_f32_16x16x32_bf16 v[114:117], v[172:175], v[188:191], v[114:117]
	v_mfma_f32_16x16x32_bf16 v[106:109], v[180:183], v[188:191], v[106:109]
	v_mfma_f32_16x16x32_bf16 v[90:93], v[180:183], v[196:199], v[90:93]
	v_mfma_f32_16x16x32_bf16 v[98:101], v[172:175], v[196:199], v[98:101]
	v_mfma_f32_16x16x32_bf16 v[82:85], v[172:175], v[204:207], v[82:85]
	v_mfma_f32_16x16x32_bf16 v[74:77], v[180:183], v[204:207], v[74:77]
	v_mfma_f32_16x16x32_bf16 v[66:69], v[180:183], v[212:215], v[66:69]
	v_mfma_f32_16x16x32_bf16 v[70:73], v[172:175], v[212:215], v[70:73]
	s_setprio 2
	s_barrier
; #define PG8_STAGE(bufoff, gbase, voff) do { _Pragma("unroll") for (int _i = 0; _i < 2; ++_i) \
;         __builtin_amdgcn_global_load_lds((const unsigned*)((const char*)(gbase) + (voff)[_i]), (LAS unsigned*)(lds + (bufoff) + ldsw + _i * 8192), 16, 0, 0); } while (0)
; #define PG8_LDA(dst, b, h) do { _Pragma("unroll") for (int m = 0; m < 4; ++m) _Pragma("unroll") for (int k = 0; k < 2; ++k) dst[m][k] = *(const LAS bf16x8*)(lds + PG8_SA(b, h) + aoff + m * 2048 + k * 1024); } while (0)
; #define PG8_MMA(ai, bj, At, Bt) do { __builtin_amdgcn_s_setprio(1); _Pragma("unroll") for (int m = 0; m < 4; ++m) _Pragma("unroll") for (int n = 0; n < 2; ++n) _Pragma("unroll") for (int k = 0; k < 2; ++k) \
;         acc[ai][bj][m][n] = __builtin_amdgcn_mfma_f32_16x16x32_bf16(Bt[n][k], At[m][k], acc[ai][bj][m][n], 0, 0, 0); __builtin_amdgcn_s_setprio(0); } while (0)
; #define PG8_WAIT_V(n) asm volatile("s_waitcnt vmcnt(" #n ")" ::: "memory")
; #define PG8_WAIT_L(n) asm volatile("s_waitcnt lgkmcnt(" #n ")" ::: "memory")
; #define PG8_BAR __builtin_amdgcn_s_barrier()
; #define PG8_SCHED __builtin_amdgcn_sched_barrier(0)
; template <class Epi>
; __device__ __forceinline__ void gemm_phase(LAS unsigned char* lds, const Gemm g, int G, int c, const Epi& E) {
;     ...
;             PG8_LDA(At, 1, 1); PG8_STAGE(PG8_SB(1, 0), b3, voffB); PG8_STAGE(PG8_SB(1, 1), b3 + hstepB, voffB); PG8_STAGE(PG8_SA(1, 0), a3, voffA);
;             PG8_WAIT_V(8); PG8_WAIT_L(0); PG8_BAR; PG8_MMA(1, 0, At, B0); PG8_MMA(1, 1, At, B1); PG8_BAR; PG8_SCHED;
;         }
;         if (wr == 0) PG8_BAR;
	s_add_i32 s33, s33, s61
	v_lshl_add_u64 v[216:217], v[216:217], 0, s[6:7]
	s_mov_b32 m0, s33
	ds_read_b128 v[184:187], v154 offset:49152
	ds_read_b128 v[188:191], v154 offset:50176
	ds_read_b128 v[192:195], v154 offset:51200
	ds_read_b128 v[196:199], v154 offset:52224
	ds_read_b128 v[200:203], v154 offset:53248
	ds_read_b128 v[204:207], v154 offset:54272
	ds_read_b128 v[208:211], v154 offset:55296
	ds_read_b128 v[212:215], v154 offset:56320
	global_load_lds_dwordx4 v[216:217], off
	s_add_i32 m0, s33, 0x2000
	s_add_u32 s46, s46, 0x100080
	v_lshl_add_u64 v[216:217], v[218:219], 0, s[6:7]
	s_addc_u32 s47, s47, 0
	s_add_i32 s33, s62, s61
	global_load_lds_dwordx4 v[216:217], off
	v_lshl_add_u64 v[216:217], s[46:47], 0, v[134:135]
	s_mov_b32 m0, s33
	s_nop 0
	global_load_lds_dwordx4 v[216:217], off
	v_lshl_add_u64 v[216:217], s[46:47], 0, v[130:131]
	s_add_i32 m0, s33, 0x2000
	s_nop 0
	global_load_lds_dwordx4 v[216:217], off
	v_lshl_add_u64 v[216:217], v[220:221], 0, s[6:7]
	s_mov_b32 m0, s70
	s_nop 0
	global_load_lds_dwordx4 v[216:217], off
	v_lshl_add_u64 v[216:217], v[224:225], 0, s[6:7]
	s_mov_b32 m0, s71
	s_nop 0
	global_load_lds_dwordx4 v[216:217], off
	s_waitcnt vmcnt(8)
	s_waitcnt lgkmcnt(0)
	s_barrier
	s_setprio 0
	s_waitcnt lgkmcnt(0)
	v_mfma_f32_16x16x32_bf16 v[62:65], v[146:149], v[184:187], v[62:65]
	v_mfma_f32_16x16x32_bf16 v[58:61], v[160:163], v[184:187], v[58:61]
	v_mfma_f32_16x16x32_bf16 v[46:49], v[160:163], v[192:195], v[46:49]
	v_mfma_f32_16x16x32_bf16 v[54:57], v[146:149], v[192:195], v[54:57]
	v_mfma_f32_16x16x32_bf16 v[38:41], v[146:149], v[200:203], v[38:41]
	v_mfma_f32_16x16x32_bf16 v[30:33], v[160:163], v[200:203], v[30:33]
	v_mfma_f32_16x16x32_bf16 v[14:17], v[160:163], v[208:211], v[14:17]
	v_mfma_f32_16x16x32_bf16 v[22:25], v[146:149], v[208:211], v[22:25]
	v_mfma_f32_16x16x32_bf16 v[62:65], v[156:159], v[188:191], v[62:65]
	v_mfma_f32_16x16x32_bf16 v[58:61], v[164:167], v[188:191], v[58:61]
	v_mfma_f32_16x16x32_bf16 v[46:49], v[164:167], v[196:199], v[46:49]
	v_mfma_f32_16x16x32_bf16 v[54:57], v[156:159], v[196:199], v[54:57]
	v_mfma_f32_16x16x32_bf16 v[38:41], v[156:159], v[204:207], v[38:41]
	v_mfma_f32_16x16x32_bf16 v[30:33], v[164:167], v[204:207], v[30:33]
	v_mfma_f32_16x16x32_bf16 v[14:17], v[164:167], v[212:215], v[14:17]
	v_mfma_f32_16x16x32_bf16 v[22:25], v[156:159], v[212:215], v[22:25]
	s_setprio 2
	s_setprio 0
	v_mfma_f32_16x16x32_bf16 v[50:53], v[168:171], v[184:187], v[50:53]
	v_mfma_f32_16x16x32_bf16 v[42:45], v[176:179], v[184:187], v[42:45]
	v_mfma_f32_16x16x32_bf16 v[26:29], v[176:179], v[192:195], v[26:29]
	v_mfma_f32_16x16x32_bf16 v[34:37], v[168:171], v[192:195], v[34:37]
	v_mfma_f32_16x16x32_bf16 v[18:21], v[168:171], v[200:203], v[18:21]
	v_mfma_f32_16x16x32_bf16 v[10:13], v[176:179], v[200:203], v[10:13]
	v_mfma_f32_16x16x32_bf16 v[2:5], v[176:179], v[208:211], v[2:5]
	v_mfma_f32_16x16x32_bf16 v[6:9], v[168:171], v[208:211], v[6:9]
	v_mfma_f32_16x16x32_bf16 v[50:53], v[172:175], v[188:191], v[50:53]
	v_mfma_f32_16x16x32_bf16 v[42:45], v[180:183], v[188:191], v[42:45]
	v_mfma_f32_16x16x32_bf16 v[26:29], v[180:183], v[196:199], v[26:29]
	v_mfma_f32_16x16x32_bf16 v[34:37], v[172:175], v[196:199], v[34:37]
	v_mfma_f32_16x16x32_bf16 v[18:21], v[172:175], v[204:207], v[18:21]
	v_mfma_f32_16x16x32_bf16 v[10:13], v[180:183], v[204:207], v[10:13]
	v_mfma_f32_16x16x32_bf16 v[2:5], v[180:183], v[212:215], v[2:5]
	v_mfma_f32_16x16x32_bf16 v[6:9], v[172:175], v[212:215], v[6:9]
	s_setprio 2
	s_barrier
	s_add_i32 s83, s83, 2
	s_add_u32 s44, s44, 0x100
	s_addc_u32 s45, s45, 0
	s_add_u32 s81, s81, 0x100
	s_addc_u32 s82, s82, 0
	s_cmp_gt_u32 s83, 61
	s_cbranch_scc0 .LBB0_765
	s_and_b64 vcc, exec, s[8:9]
	s_cbranch_vccz .LBB0_768
	s_barrier

; #define PG8_STAGE(bufoff, gbase, voff) do { _Pragma("unroll") for (int _i = 0; _i < 2; ++_i) \
;         __builtin_amdgcn_global_load_lds((const unsigned*)((const char*)(gbase) + (voff)[_i]), (LAS unsigned*)(lds + (bufoff) + ldsw + _i * 8192), 16, 0, 0); } while (0)
; #define PG8_LDA(dst, b, h) do { _Pragma("unroll") for (int m = 0; m < 4; ++m) _Pragma("unroll") for (int k = 0; k < 2; ++k) dst[m][k] = *(const LAS bf16x8*)(lds + PG8_SA(b, h) + aoff + m * 2048 + k * 1024); } while (0)
; #define PG8_LDB(dst, b, h) do { _Pragma("unroll") for (int n = 0; n < 2; ++n) _Pragma("unroll") for (int k = 0; k < 2; ++k) dst[n][k] = *(const LAS bf16x8*)(lds + PG8_SB(b, h) + boff + n * 2048 + k * 1024); } while (0)
; #define PG8_MMA(ai, bj, At, Bt) do { __builtin_amdgcn_s_setprio(1); _Pragma("unroll") for (int m = 0; m < 4; ++m) _Pragma("unroll") for (int n = 0; n < 2; ++n) _Pragma("unroll") for (int k = 0; k < 2; ++k) \
;         acc[ai][bj][m][n] = __builtin_amdgcn_mfma_f32_16x16x32_bf16(Bt[n][k], At[m][k], acc[ai][bj][m][n], 0, 0, 0); __builtin_amdgcn_s_setprio(0); } while (0)
; #define PG8_WAIT_V(n) asm volatile("s_waitcnt vmcnt(" #n ")" ::: "memory")
; #define PG8_WAIT_L(n) asm volatile("s_waitcnt lgkmcnt(" #n ")" ::: "memory")
; #define PG8_BAR __builtin_amdgcn_s_barrier()
; #define PG8_SCHED __builtin_amdgcn_sched_barrier(0)
; template <class Epi>
; __device__ __forceinline__ void gemm_phase(LAS unsigned char* lds, const Gemm g, int G, int c, const Epi& E) {
;     ...
;         for (int t = 0; t < nt; t += 2) {
;             const bool last = (t == nt - 2);
;             const char* a1 = cA + (size_t)(t + 1) * kstep;
;             const char* a2 = last ? nA : cA + (size_t)(t + 2) * kstep; const char* b2 = last ? nB : cB + (size_t)(t + 2) * kstep;
;             const char* a3 = a2 + kstep; const char* b3 = b2 + kstep;
;             PG8_LDB(B0, 0, 0); PG8_LDB(B1, 0, 1); PG8_SCHED; PG8_LDA(At, 0, 0); PG8_STAGE(PG8_SA(1, 1), a1 + hstepA, voffA);
;             PG8_WAIT_V(8); PG8_WAIT_L(0); PG8_BAR; PG8_MMA(0, 0, At, B0); PG8_MMA(0, 1, At, B1); PG8_BAR; PG8_SCHED;
;             PG8_LDA(At, 0, 1); PG8_STAGE(PG8_SB(0, 0), b2, voffB); PG8_STAGE(PG8_SB(0, 1), b2 + hstepB, voffB); PG8_STAGE(PG8_SA(0, 0), a2, voffA);
.LBB0_781:
	ds_read_b128 v[150:153], v146
	ds_read_b128 v[154:157], v146 offset:1024
	ds_read_b128 v[158:161], v146 offset:2048
	ds_read_b128 v[162:165], v146 offset:3072
	ds_read_b128 v[166:169], v147
	ds_read_b128 v[170:173], v147 offset:1024
	ds_read_b128 v[174:177], v147 offset:2048
	ds_read_b128 v[178:181], v147 offset:3072
	s_add_u32 s52, s46, 0x100
	s_addc_u32 s53, s47, 0
	s_add_u32 s33, s90, s46
	s_addc_u32 s55, s91, s47
	s_cmp_eq_u32 s92, 4
	s_cselect_b32 s56, 0, s52
	s_cselect_b32 s57, 0, s53
	s_cselect_b32 s54, s89, s33
	s_cselect_b32 s55, s25, s55
	s_add_u32 s56, s2, s56
	s_addc_u32 s57, s3, s57
	s_mov_b32 m0, s83
	v_lshl_add_u64 v[142:143], v[138:139], 0, s[46:47]
	ds_read_b128 v[182:185], v148
	ds_read_b128 v[186:189], v148 offset:1024
	ds_read_b128 v[190:193], v148 offset:2048
	ds_read_b128 v[194:197], v148 offset:3072
	ds_read_b128 v[198:201], v148 offset:4096
	ds_read_b128 v[202:205], v148 offset:5120
	ds_read_b128 v[206:209], v148 offset:6144
	ds_read_b128 v[210:213], v148 offset:7168
	global_load_lds_dwordx4 v[142:143], off
	v_lshl_add_u64 v[142:143], v[140:141], 0, s[46:47]
	s_mov_b32 m0, s84
	s_nop 0
	global_load_lds_dwordx4 v[142:143], off
	s_waitcnt vmcnt(8)
	s_waitcnt lgkmcnt(0)
	s_barrier
	s_setprio 0
	s_waitcnt lgkmcnt(0)
	v_mfma_f32_16x16x32_bf16 v[126:129], v[150:153], v[182:185], v[126:129]
	v_mfma_f32_16x16x32_bf16 v[122:125], v[158:161], v[182:185], v[122:125]
	v_mfma_f32_16x16x32_bf16 v[110:113], v[158:161], v[190:193], v[110:113]
	v_mfma_f32_16x16x32_bf16 v[118:121], v[150:153], v[190:193], v[118:121]
	v_mfma_f32_16x16x32_bf16 v[102:105], v[150:153], v[198:201], v[102:105]
	v_mfma_f32_16x16x32_bf16 v[94:97], v[158:161], v[198:201], v[94:97]
	v_mfma_f32_16x16x32_bf16 v[78:81], v[158:161], v[206:209], v[78:81]
	v_mfma_f32_16x16x32_bf16 v[86:89], v[150:153], v[206:209], v[86:89]
	v_mfma_f32_16x16x32_bf16 v[126:129], v[154:157], v[186:189], v[126:129]
	v_mfma_f32_16x16x32_bf16 v[122:125], v[162:165], v[186:189], v[122:125]
	v_mfma_f32_16x16x32_bf16 v[110:113], v[162:165], v[194:197], v[110:113]
	v_mfma_f32_16x16x32_bf16 v[118:121], v[154:157], v[194:197], v[118:121]
	v_mfma_f32_16x16x32_bf16 v[102:105], v[154:157], v[202:205], v[102:105]
	v_mfma_f32_16x16x32_bf16 v[94:97], v[162:165], v[202:205], v[94:97]
	v_mfma_f32_16x16x32_bf16 v[78:81], v[162:165], v[210:213], v[78:81]
	v_mfma_f32_16x16x32_bf16 v[86:89], v[154:157], v[210:213], v[86:89]
	s_setprio 2
	s_setprio 0
	v_mfma_f32_16x16x32_bf16 v[114:117], v[166:169], v[182:185], v[114:117]
	v_mfma_f32_16x16x32_bf16 v[106:109], v[174:177], v[182:185], v[106:109]
	v_mfma_f32_16x16x32_bf16 v[90:93], v[174:177], v[190:193], v[90:93]
	v_mfma_f32_16x16x32_bf16 v[98:101], v[166:169], v[190:193], v[98:101]
	v_mfma_f32_16x16x32_bf16 v[82:85], v[166:169], v[198:201], v[82:85]
	v_mfma_f32_16x16x32_bf16 v[74:77], v[174:177], v[198:201], v[74:77]
	v_mfma_f32_16x16x32_bf16 v[66:69], v[174:177], v[206:209], v[66:69]
	v_mfma_f32_16x16x32_bf16 v[70:73], v[166:169], v[206:209], v[70:73]
	v_mfma_f32_16x16x32_bf16 v[114:117], v[170:173], v[186:189], v[114:117]
	v_mfma_f32_16x16x32_bf16 v[106:109], v[178:181], v[186:189], v[106:109]
	v_mfma_f32_16x16x32_bf16 v[90:93], v[178:181], v[194:197], v[90:93]
	v_mfma_f32_16x16x32_bf16 v[98:101], v[170:173], v[194:197], v[98:101]
	v_mfma_f32_16x16x32_bf16 v[82:85], v[170:173], v[202:205], v[82:85]
	v_mfma_f32_16x16x32_bf16 v[74:77], v[178:181], v[202:205], v[74:77]
	v_mfma_f32_16x16x32_bf16 v[66:69], v[178:181], v[210:213], v[66:69]
	v_mfma_f32_16x16x32_bf16 v[70:73], v[170:173], v[210:213], v[70:73]
	s_setprio 2
	s_barrier
	s_mov_b32 m0, s85
	v_lshl_add_u64 v[142:143], s[54:55], 0, v[134:135]
	s_add_u32 s46, s54, 0x20000
	ds_read_b128 v[182:185], v148 offset:16384
	ds_read_b128 v[186:189], v148 offset:17408
	ds_read_b128 v[190:193], v148 offset:18432
	ds_read_b128 v[194:197], v148 offset:19456
	ds_read_b128 v[198:201], v148 offset:20480
	ds_read_b128 v[202:205], v148 offset:21504
	ds_read_b128 v[206:209], v148 offset:22528
	ds_read_b128 v[210:213], v148 offset:23552
	global_load_lds_dwordx4 v[142:143], off
	v_lshl_add_u64 v[214:215], s[54:55], 0, v[130:131]
	s_mov_b32 m0, s86
	s_addc_u32 s47, s55, 0
	global_load_lds_dwordx4 v[214:215], off
	v_lshl_add_u64 v[216:217], s[46:47], 0, v[134:135]
	s_mov_b32 m0, s87
	v_lshl_add_u64 v[218:219], s[56:57], 0, v[132:133]
	global_load_lds_dwordx4 v[216:217], off
	v_lshl_add_u64 v[216:217], s[46:47], 0, v[130:131]
	s_mov_b32 m0, s88
	s_nop 0
	global_load_lds_dwordx4 v[216:217], off
	v_lshl_add_u64 v[216:217], s[56:57], 0, v[136:137]
	s_mov_b32 m0, s45
	s_nop 0
	global_load_lds_dwordx4 v[216:217], off
	s_mov_b32 m0, s61
	s_nop 0
	global_load_lds_dwordx4 v[218:219], off
	s_waitcnt vmcnt(8)
	s_waitcnt lgkmcnt(0)
	s_barrier
; #define PG8_STAGE(bufoff, gbase, voff) do { _Pragma("unroll") for (int _i = 0; _i < 2; ++_i) \
;         __builtin_amdgcn_global_load_lds((const unsigned*)((const char*)(gbase) + (voff)[_i]), (LAS unsigned*)(lds + (bufoff) + ldsw + _i * 8192), 16, 0, 0); } while (0)
; #define PG8_LDA(dst, b, h) do { _Pragma("unroll") for (int m = 0; m < 4; ++m) _Pragma("unroll") for (int k = 0; k < 2; ++k) dst[m][k] = *(const LAS bf16x8*)(lds + PG8_SA(b, h) + aoff + m * 2048 + k * 1024); } while (0)
; #define PG8_LDB(dst, b, h) do { _Pragma("unroll") for (int n = 0; n < 2; ++n) _Pragma("unroll") for (int k = 0; k < 2; ++k) dst[n][k] = *(const LAS bf16x8*)(lds + PG8_SB(b, h) + boff + n * 2048 + k * 1024); } while (0)
; #define PG8_MMA(ai, bj, At, Bt) do { __builtin_amdgcn_s_setprio(1); _Pragma("unroll") for (int m = 0; m < 4; ++m) _Pragma("unroll") for (int n = 0; n < 2; ++n) _Pragma("unroll") for (int k = 0; k < 2; ++k) \
;         acc[ai][bj][m][n] = __builtin_amdgcn_mfma_f32_16x16x32_bf16(Bt[n][k], At[m][k], acc[ai][bj][m][n], 0, 0, 0); __builtin_amdgcn_s_setprio(0); } while (0)
; #define PG8_WAIT_V(n) asm volatile("s_waitcnt vmcnt(" #n ")" ::: "memory")
; #define PG8_WAIT_L(n) asm volatile("s_waitcnt lgkmcnt(" #n ")" ::: "memory")
; #define PG8_BAR __builtin_amdgcn_s_barrier()
; #define PG8_SCHED __builtin_amdgcn_sched_barrier(0)
; template <class Epi>
; __device__ __forceinline__ void gemm_phase(LAS unsigned char* lds, const Gemm g, int G, int c, const Epi& E) {
;     ...
;             PG8_WAIT_V(8); PG8_WAIT_L(0); PG8_BAR; PG8_MMA(1, 0, At, B0); PG8_MMA(1, 1, At, B1); PG8_BAR; PG8_SCHED;
;             PG8_LDB(B0, 1, 0); PG8_LDB(B1, 1, 1); PG8_SCHED; PG8_LDA(At, 1, 0); PG8_STAGE(PG8_SA(0, 1), a2 + hstepA, voffA);
;             PG8_WAIT_V(8); PG8_WAIT_L(0); PG8_BAR; PG8_MMA(0, 0, At, B0); PG8_MMA(0, 1, At, B1); PG8_BAR; PG8_SCHED;
	s_setprio 0
	s_waitcnt lgkmcnt(0)
	v_mfma_f32_16x16x32_bf16 v[62:65], v[150:153], v[182:185], v[62:65]
	v_mfma_f32_16x16x32_bf16 v[58:61], v[158:161], v[182:185], v[58:61]
	v_mfma_f32_16x16x32_bf16 v[46:49], v[158:161], v[190:193], v[46:49]
	v_mfma_f32_16x16x32_bf16 v[54:57], v[150:153], v[190:193], v[54:57]
	v_mfma_f32_16x16x32_bf16 v[38:41], v[150:153], v[198:201], v[38:41]
	v_mfma_f32_16x16x32_bf16 v[30:33], v[158:161], v[198:201], v[30:33]
	v_mfma_f32_16x16x32_bf16 v[14:17], v[158:161], v[206:209], v[14:17]
	v_mfma_f32_16x16x32_bf16 v[22:25], v[150:153], v[206:209], v[22:25]
	v_mfma_f32_16x16x32_bf16 v[62:65], v[154:157], v[186:189], v[62:65]
	v_mfma_f32_16x16x32_bf16 v[58:61], v[162:165], v[186:189], v[58:61]
	v_mfma_f32_16x16x32_bf16 v[46:49], v[162:165], v[194:197], v[46:49]
	v_mfma_f32_16x16x32_bf16 v[54:57], v[154:157], v[194:197], v[54:57]
	v_mfma_f32_16x16x32_bf16 v[38:41], v[154:157], v[202:205], v[38:41]
	v_mfma_f32_16x16x32_bf16 v[30:33], v[162:165], v[202:205], v[30:33]
	v_mfma_f32_16x16x32_bf16 v[14:17], v[162:165], v[210:213], v[14:17]
	v_mfma_f32_16x16x32_bf16 v[22:25], v[154:157], v[210:213], v[22:25]
	s_setprio 2
	s_setprio 0
	v_mfma_f32_16x16x32_bf16 v[50:53], v[166:169], v[182:185], v[50:53]
	v_mfma_f32_16x16x32_bf16 v[42:45], v[174:177], v[182:185], v[42:45]
	v_mfma_f32_16x16x32_bf16 v[26:29], v[174:177], v[190:193], v[26:29]
	v_mfma_f32_16x16x32_bf16 v[34:37], v[166:169], v[190:193], v[34:37]
	v_mfma_f32_16x16x32_bf16 v[18:21], v[166:169], v[198:201], v[18:21]
	v_mfma_f32_16x16x32_bf16 v[10:13], v[174:177], v[198:201], v[10:13]
	v_mfma_f32_16x16x32_bf16 v[2:5], v[174:177], v[206:209], v[2:5]
	v_mfma_f32_16x16x32_bf16 v[6:9], v[166:169], v[206:209], v[6:9]
	v_mfma_f32_16x16x32_bf16 v[50:53], v[170:173], v[186:189], v[50:53]
	v_mfma_f32_16x16x32_bf16 v[42:45], v[178:181], v[186:189], v[42:45]
	v_mfma_f32_16x16x32_bf16 v[26:29], v[178:181], v[194:197], v[26:29]
	v_mfma_f32_16x16x32_bf16 v[34:37], v[170:173], v[194:197], v[34:37]
	v_mfma_f32_16x16x32_bf16 v[18:21], v[170:173], v[202:205], v[18:21]
	v_mfma_f32_16x16x32_bf16 v[10:13], v[178:181], v[202:205], v[10:13]
	v_mfma_f32_16x16x32_bf16 v[2:5], v[178:181], v[210:213], v[2:5]
	v_mfma_f32_16x16x32_bf16 v[6:9], v[170:173], v[210:213], v[6:9]
	s_setprio 2
	s_barrier
	s_add_i32 s33, 0, 0x18000
	v_add_u32_e32 v149, s33, v145
	s_add_i32 s62, 0, 0x1c000
	ds_read_b128 v[150:153], v149
	ds_read_b128 v[154:157], v149 offset:1024
	ds_read_b128 v[158:161], v149 offset:2048
	ds_read_b128 v[162:165], v149 offset:3072
	v_add_u32_e32 v149, s62, v145
	ds_read_b128 v[166:169], v149
	ds_read_b128 v[170:173], v149 offset:1024
	ds_read_b128 v[174:177], v149 offset:2048
	ds_read_b128 v[178:181], v149 offset:3072
	s_add_u32 s46, s56, 0x20000
	s_addc_u32 s47, s57, 0
	s_mov_b32 m0, s66
	v_lshl_add_u64 v[220:221], s[46:47], 0, v[136:137]
	ds_read_b128 v[182:185], v148 offset:32768
	ds_read_b128 v[186:189], v148 offset:33792
	ds_read_b128 v[190:193], v148 offset:34816
	ds_read_b128 v[194:197], v148 offset:35840
	ds_read_b128 v[198:201], v148 offset:36864
	ds_read_b128 v[202:205], v148 offset:37888
	ds_read_b128 v[206:209], v148 offset:38912
	ds_read_b128 v[210:213], v148 offset:39936
	global_load_lds_dwordx4 v[220:221], off
	v_lshl_add_u64 v[220:221], s[46:47], 0, v[132:133]
	s_mov_b32 m0, s67
	s_nop 0
	global_load_lds_dwordx4 v[220:221], off
	s_waitcnt vmcnt(8)
	s_waitcnt lgkmcnt(0)
	s_barrier
	s_setprio 0
	s_waitcnt lgkmcnt(0)
	v_mfma_f32_16x16x32_bf16 v[126:129], v[150:153], v[182:185], v[126:129]
	v_mfma_f32_16x16x32_bf16 v[122:125], v[158:161], v[182:185], v[122:125]
	v_mfma_f32_16x16x32_bf16 v[110:113], v[158:161], v[190:193], v[110:113]
	v_mfma_f32_16x16x32_bf16 v[118:121], v[150:153], v[190:193], v[118:121]
	v_mfma_f32_16x16x32_bf16 v[102:105], v[150:153], v[198:201], v[102:105]
	v_mfma_f32_16x16x32_bf16 v[94:97], v[158:161], v[198:201], v[94:97]
	v_mfma_f32_16x16x32_bf16 v[78:81], v[158:161], v[206:209], v[78:81]
	v_mfma_f32_16x16x32_bf16 v[86:89], v[150:153], v[206:209], v[86:89]
	v_mfma_f32_16x16x32_bf16 v[126:129], v[154:157], v[186:189], v[126:129]
	v_mfma_f32_16x16x32_bf16 v[122:125], v[162:165], v[186:189], v[122:125]
	v_mfma_f32_16x16x32_bf16 v[110:113], v[162:165], v[194:197], v[110:113]
	v_mfma_f32_16x16x32_bf16 v[118:121], v[154:157], v[194:197], v[118:121]
	v_mfma_f32_16x16x32_bf16 v[102:105], v[154:157], v[202:205], v[102:105]
	v_mfma_f32_16x16x32_bf16 v[94:97], v[162:165], v[202:205], v[94:97]
	v_mfma_f32_16x16x32_bf16 v[78:81], v[162:165], v[210:213], v[78:81]
	v_mfma_f32_16x16x32_bf16 v[86:89], v[154:157], v[210:213], v[86:89]
	s_setprio 2
	s_setprio 0
	v_mfma_f32_16x16x32_bf16 v[114:117], v[166:169], v[182:185], v[114:117]
	v_mfma_f32_16x16x32_bf16 v[106:109], v[174:177], v[182:185], v[106:109]
	v_mfma_f32_16x16x32_bf16 v[90:93], v[174:177], v[190:193], v[90:93]
	v_mfma_f32_16x16x32_bf16 v[98:101], v[166:169], v[190:193], v[98:101]
	v_mfma_f32_16x16x32_bf16 v[82:85], v[166:169], v[198:201], v[82:85]
	v_mfma_f32_16x16x32_bf16 v[74:77], v[174:177], v[198:201], v[74:77]
	v_mfma_f32_16x16x32_bf16 v[66:69], v[174:177], v[206:209], v[66:69]
	v_mfma_f32_16x16x32_bf16 v[70:73], v[166:169], v[206:209], v[70:73]
	v_mfma_f32_16x16x32_bf16 v[114:117], v[170:173], v[186:189], v[114:117]
	v_mfma_f32_16x16x32_bf16 v[106:109], v[178:181], v[186:189], v[106:109]
	v_mfma_f32_16x16x32_bf16 v[90:93], v[178:181], v[194:197], v[90:93]
	v_mfma_f32_16x16x32_bf16 v[98:101], v[170:173], v[194:197], v[98:101]
	v_mfma_f32_16x16x32_bf16 v[82:85], v[170:173], v[202:205], v[82:85]
	v_mfma_f32_16x16x32_bf16 v[74:77], v[178:181], v[202:205], v[74:77]
	v_mfma_f32_16x16x32_bf16 v[66:69], v[178:181], v[210:213], v[66:69]
	v_mfma_f32_16x16x32_bf16 v[70:73], v[170:173], v[210:213], v[70:73]
	s_setprio 2
	s_barrier
; #define PG8_STAGE(bufoff, gbase, voff) do { _Pragma("unroll") for (int _i = 0; _i < 2; ++_i) \
;         __builtin_amdgcn_global_load_lds((const unsigned*)((const char*)(gbase) + (voff)[_i]), (LAS unsigned*)(lds + (bufoff) + ldsw + _i * 8192), 16, 0, 0); } while (0)
; #define PG8_LDA(dst, b, h) do { _Pragma("unroll") for (int m = 0; m < 4; ++m) _Pragma("unroll") for (int k = 0; k < 2; ++k) dst[m][k] = *(const LAS bf16x8*)(lds + PG8_SA(b, h) + aoff + m * 2048 + k * 1024); } while (0)
; #define PG8_MMA(ai, bj, At, Bt) do { __builtin_amdgcn_s_setprio(1); _Pragma("unroll") for (int m = 0; m < 4; ++m) _Pragma("unroll") for (int n = 0; n < 2; ++n) _Pragma("unroll") for (int k = 0; k < 2; ++k) \
;         acc[ai][bj][m][n] = __builtin_amdgcn_mfma_f32_16x16x32_bf16(Bt[n][k], At[m][k], acc[ai][bj][m][n], 0, 0, 0); __builtin_amdgcn_s_setprio(0); } while (0)
; #define PG8_WAIT_V(n) asm volatile("s_waitcnt vmcnt(" #n ")" ::: "memory")
; #define PG8_WAIT_L(n) asm volatile("s_waitcnt lgkmcnt(" #n ")" ::: "memory")
; #define PG8_BAR __builtin_amdgcn_s_barrier()
; #define PG8_SCHED __builtin_amdgcn_sched_barrier(0)
; template <class Epi>
; __device__ __forceinline__ void gemm_phase(LAS unsigned char* lds, const Gemm g, int G, int c, const Epi& E) {
;     ...
;             PG8_LDA(At, 1, 1); PG8_STAGE(PG8_SB(1, 0), b3, voffB); PG8_STAGE(PG8_SB(1, 1), b3 + hstepB, voffB); PG8_STAGE(PG8_SA(1, 0), a3, voffA);
;             PG8_WAIT_V(8); PG8_WAIT_L(0); PG8_BAR; PG8_MMA(1, 0, At, B0); PG8_MMA(1, 1, At, B1); PG8_BAR; PG8_SCHED;
;         }
;         if (wr == 0) PG8_BAR;
	s_add_i32 s33, s33, s58
	v_lshl_add_u64 v[142:143], v[142:143], 0, s[6:7]
	s_mov_b32 m0, s33
	ds_read_b128 v[182:185], v148 offset:49152
	ds_read_b128 v[186:189], v148 offset:50176
	ds_read_b128 v[190:193], v148 offset:51200
	ds_read_b128 v[194:197], v148 offset:52224
	ds_read_b128 v[198:201], v148 offset:53248
	ds_read_b128 v[202:205], v148 offset:54272
	ds_read_b128 v[206:209], v148 offset:55296
	ds_read_b128 v[210:213], v148 offset:56320
	global_load_lds_dwordx4 v[142:143], off
	s_add_i32 m0, s33, 0x2000
	s_add_u32 s46, s54, 0x20080
	v_lshl_add_u64 v[142:143], v[214:215], 0, s[6:7]
	s_addc_u32 s47, s55, 0
	s_add_i32 s33, s62, s58
	global_load_lds_dwordx4 v[142:143], off
	v_lshl_add_u64 v[142:143], s[46:47], 0, v[134:135]
	s_mov_b32 m0, s33
	s_nop 0
	global_load_lds_dwordx4 v[142:143], off
	v_lshl_add_u64 v[142:143], s[46:47], 0, v[130:131]
	s_add_i32 m0, s33, 0x2000
	s_nop 0
	global_load_lds_dwordx4 v[142:143], off
	v_lshl_add_u64 v[142:143], v[216:217], 0, s[6:7]
	s_mov_b32 m0, s71
	s_nop 0
	global_load_lds_dwordx4 v[142:143], off
	v_lshl_add_u64 v[142:143], v[218:219], 0, s[6:7]
	s_mov_b32 m0, s72
	s_nop 0
	global_load_lds_dwordx4 v[142:143], off
	s_waitcnt vmcnt(8)
	s_waitcnt lgkmcnt(0)
	s_barrier
	s_setprio 0
	s_waitcnt lgkmcnt(0)
	v_mfma_f32_16x16x32_bf16 v[62:65], v[150:153], v[182:185], v[62:65]
	v_mfma_f32_16x16x32_bf16 v[58:61], v[158:161], v[182:185], v[58:61]
	v_mfma_f32_16x16x32_bf16 v[46:49], v[158:161], v[190:193], v[46:49]
	v_mfma_f32_16x16x32_bf16 v[54:57], v[150:153], v[190:193], v[54:57]
	v_mfma_f32_16x16x32_bf16 v[38:41], v[150:153], v[198:201], v[38:41]
	v_mfma_f32_16x16x32_bf16 v[30:33], v[158:161], v[198:201], v[30:33]
	v_mfma_f32_16x16x32_bf16 v[14:17], v[158:161], v[206:209], v[14:17]
	v_mfma_f32_16x16x32_bf16 v[22:25], v[150:153], v[206:209], v[22:25]
	v_mfma_f32_16x16x32_bf16 v[62:65], v[154:157], v[186:189], v[62:65]
	v_mfma_f32_16x16x32_bf16 v[58:61], v[162:165], v[186:189], v[58:61]
	v_mfma_f32_16x16x32_bf16 v[46:49], v[162:165], v[194:197], v[46:49]
	v_mfma_f32_16x16x32_bf16 v[54:57], v[154:157], v[194:197], v[54:57]
	v_mfma_f32_16x16x32_bf16 v[38:41], v[154:157], v[202:205], v[38:41]
	v_mfma_f32_16x16x32_bf16 v[30:33], v[162:165], v[202:205], v[30:33]
	v_mfma_f32_16x16x32_bf16 v[14:17], v[162:165], v[210:213], v[14:17]
	v_mfma_f32_16x16x32_bf16 v[22:25], v[154:157], v[210:213], v[22:25]
	s_setprio 2
	s_setprio 0
	v_mfma_f32_16x16x32_bf16 v[50:53], v[166:169], v[182:185], v[50:53]
	v_mfma_f32_16x16x32_bf16 v[42:45], v[174:177], v[182:185], v[42:45]
	v_mfma_f32_16x16x32_bf16 v[26:29], v[174:177], v[190:193], v[26:29]
	v_mfma_f32_16x16x32_bf16 v[34:37], v[166:169], v[190:193], v[34:37]
	v_mfma_f32_16x16x32_bf16 v[18:21], v[166:169], v[198:201], v[18:21]
	v_mfma_f32_16x16x32_bf16 v[10:13], v[174:177], v[198:201], v[10:13]
	v_mfma_f32_16x16x32_bf16 v[2:5], v[174:177], v[206:209], v[2:5]
	v_mfma_f32_16x16x32_bf16 v[6:9], v[166:169], v[206:209], v[6:9]
	v_mfma_f32_16x16x32_bf16 v[50:53], v[170:173], v[186:189], v[50:53]
	v_mfma_f32_16x16x32_bf16 v[42:45], v[178:181], v[186:189], v[42:45]
	v_mfma_f32_16x16x32_bf16 v[26:29], v[178:181], v[194:197], v[26:29]
	v_mfma_f32_16x16x32_bf16 v[34:37], v[170:173], v[194:197], v[34:37]
	v_mfma_f32_16x16x32_bf16 v[18:21], v[170:173], v[202:205], v[18:21]
	v_mfma_f32_16x16x32_bf16 v[10:13], v[178:181], v[202:205], v[10:13]
	v_mfma_f32_16x16x32_bf16 v[2:5], v[178:181], v[210:213], v[2:5]
	v_mfma_f32_16x16x32_bf16 v[6:9], v[170:173], v[210:213], v[6:9]
	s_setprio 2
	s_barrier
	s_add_i32 s92, s92, 2
	s_cmp_gt_u32 s92, 5
	s_mov_b64 s[46:47], s[52:53]
	s_cbranch_scc0 .LBB0_781
	s_and_b64 vcc, exec, s[8:9]
	s_cbranch_vccz .LBB0_784
	s_barrier

; #define PG8_STAGE(bufoff, gbase, voff) do { _Pragma("unroll") for (int _i = 0; _i < 2; ++_i) \
;         __builtin_amdgcn_global_load_lds((const unsigned*)((const char*)(gbase) + (voff)[_i]), (LAS unsigned*)(lds + (bufoff) + ldsw + _i * 8192), 16, 0, 0); } while (0)
; #define PG8_LDA(dst, b, h) do { _Pragma("unroll") for (int m = 0; m < 4; ++m) _Pragma("unroll") for (int k = 0; k < 2; ++k) dst[m][k] = *(const LAS bf16x8*)(lds + PG8_SA(b, h) + aoff + m * 2048 + k * 1024); } while (0)
; #define PG8_LDB(dst, b, h) do { _Pragma("unroll") for (int n = 0; n < 2; ++n) _Pragma("unroll") for (int k = 0; k < 2; ++k) dst[n][k] = *(const LAS bf16x8*)(lds + PG8_SB(b, h) + boff + n * 2048 + k * 1024); } while (0)
; #define PG8_MMA(ai, bj, At, Bt) do { __builtin_amdgcn_s_setprio(1); _Pragma("unroll") for (int m = 0; m < 4; ++m) _Pragma("unroll") for (int n = 0; n < 2; ++n) _Pragma("unroll") for (int k = 0; k < 2; ++k) \
;         acc[ai][bj][m][n] = __builtin_amdgcn_mfma_f32_16x16x32_bf16(Bt[n][k], At[m][k], acc[ai][bj][m][n], 0, 0, 0); __builtin_amdgcn_s_setprio(0); } while (0)
; #define PG8_WAIT_V(n) asm volatile("s_waitcnt vmcnt(" #n ")" ::: "memory")
; #define PG8_WAIT_L(n) asm volatile("s_waitcnt lgkmcnt(" #n ")" ::: "memory")
; #define PG8_BAR __builtin_amdgcn_s_barrier()
; #define PG8_SCHED __builtin_amdgcn_sched_barrier(0)
; template <class Epi>
; __device__ __forceinline__ void gemm_phase(LAS unsigned char* lds, const Gemm g, int G, int c, const Epi& E) {
;     ...
;         for (int t = 0; t < nt; t += 2) {
;             const bool last = (t == nt - 2);
;             const char* a1 = cA + (size_t)(t + 1) * kstep;
;             const char* a2 = last ? nA : cA + (size_t)(t + 2) * kstep; const char* b2 = last ? nB : cB + (size_t)(t + 2) * kstep;
;             const char* a3 = a2 + kstep; const char* b3 = b2 + kstep;
;             PG8_LDB(B0, 0, 0); PG8_LDB(B1, 0, 1); PG8_SCHED; PG8_LDA(At, 0, 0); PG8_STAGE(PG8_SA(1, 1), a1 + hstepA, voffA);
;             PG8_WAIT_V(8); PG8_WAIT_L(0); PG8_BAR; PG8_MMA(0, 0, At, B0); PG8_MMA(0, 1, At, B1); PG8_BAR; PG8_SCHED;
;             PG8_LDA(At, 0, 1); PG8_STAGE(PG8_SB(0, 0), b2, voffB); PG8_STAGE(PG8_SB(0, 1), b2 + hstepB, voffB); PG8_STAGE(PG8_SA(0, 0), a2, voffA);
.LBB0_903:
	ds_read_b128 v[130:133], v170
	ds_read_b128 v[134:137], v170 offset:1024
	ds_read_b128 v[138:141], v170 offset:2048
	ds_read_b128 v[142:145], v170 offset:3072
	ds_read_b128 v[162:165], v171
	ds_read_b128 v[174:177], v171 offset:1024
	ds_read_b128 v[178:181], v171 offset:2048
	ds_read_b128 v[182:185], v171 offset:3072
	s_add_u32 s33, s4, 0xfffc0080
	s_addc_u32 s42, s5, -1
	s_cmp_eq_u32 s46, 12
	s_cselect_b32 s45, s19, s42
	s_cselect_b32 s44, s18, s33
	s_cselect_b32 s43, s15, s39
	s_cselect_b32 s42, s17, s23
	v_lshl_add_u64 v[166:167], s[4:5], 0, v[154:155]
	s_add_i32 m0, s25, 0xc000
	ds_read_b128 v[186:189], v172
	ds_read_b128 v[190:193], v172 offset:1024
	ds_read_b128 v[194:197], v172 offset:2048
	ds_read_b128 v[198:201], v172 offset:3072
	ds_read_b128 v[202:205], v172 offset:4096
	ds_read_b128 v[206:209], v172 offset:5120
	ds_read_b128 v[210:213], v172 offset:6144
	ds_read_b128 v[214:217], v172 offset:7168
	global_load_lds_dwordx4 v[166:167], off
	v_lshl_add_u64 v[166:167], s[4:5], 0, v[156:157]
	s_add_i32 m0, s25, 0xe000
	s_nop 0
	global_load_lds_dwordx4 v[166:167], off
	s_waitcnt vmcnt(8)
	s_waitcnt lgkmcnt(0)
	s_barrier
	s_setprio 0
	s_waitcnt lgkmcnt(0)
	v_mfma_f32_16x16x32_bf16 v[126:129], v[130:133], v[186:189], v[126:129]
	v_mfma_f32_16x16x32_bf16 v[122:125], v[138:141], v[186:189], v[122:125]
	v_mfma_f32_16x16x32_bf16 v[106:109], v[138:141], v[194:197], v[106:109]
	v_mfma_f32_16x16x32_bf16 v[110:113], v[130:133], v[194:197], v[110:113]
	v_mfma_f32_16x16x32_bf16 v[94:97], v[130:133], v[202:205], v[94:97]
	v_mfma_f32_16x16x32_bf16 v[90:93], v[138:141], v[202:205], v[90:93]
	v_mfma_f32_16x16x32_bf16 v[74:77], v[138:141], v[210:213], v[74:77]
	v_mfma_f32_16x16x32_bf16 v[78:81], v[130:133], v[210:213], v[78:81]
	v_mfma_f32_16x16x32_bf16 v[126:129], v[134:137], v[190:193], v[126:129]
	v_mfma_f32_16x16x32_bf16 v[122:125], v[142:145], v[190:193], v[122:125]
	v_mfma_f32_16x16x32_bf16 v[106:109], v[142:145], v[198:201], v[106:109]
	v_mfma_f32_16x16x32_bf16 v[110:113], v[134:137], v[198:201], v[110:113]
	v_mfma_f32_16x16x32_bf16 v[94:97], v[134:137], v[206:209], v[94:97]
	v_mfma_f32_16x16x32_bf16 v[90:93], v[142:145], v[206:209], v[90:93]
	v_mfma_f32_16x16x32_bf16 v[74:77], v[142:145], v[214:217], v[74:77]
	v_mfma_f32_16x16x32_bf16 v[78:81], v[134:137], v[214:217], v[78:81]
	s_setprio 2
	s_setprio 0
	v_mfma_f32_16x16x32_bf16 v[118:121], v[162:165], v[186:189], v[118:121]
	v_mfma_f32_16x16x32_bf16 v[114:117], v[178:181], v[186:189], v[114:117]
	v_mfma_f32_16x16x32_bf16 v[98:101], v[178:181], v[194:197], v[98:101]
	v_mfma_f32_16x16x32_bf16 v[102:105], v[162:165], v[194:197], v[102:105]
	v_mfma_f32_16x16x32_bf16 v[86:89], v[162:165], v[202:205], v[86:89]
	v_mfma_f32_16x16x32_bf16 v[82:85], v[178:181], v[202:205], v[82:85]
	v_mfma_f32_16x16x32_bf16 v[66:69], v[178:181], v[210:213], v[66:69]
	v_mfma_f32_16x16x32_bf16 v[70:73], v[162:165], v[210:213], v[70:73]
	v_mfma_f32_16x16x32_bf16 v[118:121], v[174:177], v[190:193], v[118:121]
	v_mfma_f32_16x16x32_bf16 v[114:117], v[182:185], v[190:193], v[114:117]
	v_mfma_f32_16x16x32_bf16 v[98:101], v[182:185], v[198:201], v[98:101]
	v_mfma_f32_16x16x32_bf16 v[102:105], v[174:177], v[198:201], v[102:105]
	v_mfma_f32_16x16x32_bf16 v[86:89], v[174:177], v[206:209], v[86:89]
	v_mfma_f32_16x16x32_bf16 v[82:85], v[182:185], v[206:209], v[82:85]
	v_mfma_f32_16x16x32_bf16 v[66:69], v[182:185], v[214:217], v[66:69]
	v_mfma_f32_16x16x32_bf16 v[70:73], v[174:177], v[214:217], v[70:73]
	s_setprio 2
	s_barrier
	s_add_i32 s33, s72, s54
	v_lshl_add_u64 v[166:167], s[42:43], 0, v[150:151]
	s_mov_b32 m0, s33
	ds_read_b128 v[186:189], v172 offset:16384
	ds_read_b128 v[190:193], v172 offset:17408
	ds_read_b128 v[194:197], v172 offset:18432
	ds_read_b128 v[198:201], v172 offset:19456
	ds_read_b128 v[202:205], v172 offset:20480
	ds_read_b128 v[206:209], v172 offset:21504
	ds_read_b128 v[210:213], v172 offset:22528
	ds_read_b128 v[214:217], v172 offset:23552
	global_load_lds_dwordx4 v[166:167], off
	s_add_i32 m0, s33, 0x2000
	s_add_u32 s62, s42, 0x40000
	v_lshl_add_u64 v[218:219], s[42:43], 0, v[146:147]
	s_addc_u32 s63, s43, 0
	s_add_i32 s33, s73, s54
	global_load_lds_dwordx4 v[218:219], off
	v_lshl_add_u64 v[220:221], s[62:63], 0, v[150:151]
	s_mov_b32 m0, s33
	v_lshl_add_u64 v[222:223], s[44:45], 0, v[148:149]
	global_load_lds_dwordx4 v[220:221], off
	v_lshl_add_u64 v[220:221], s[62:63], 0, v[146:147]
	s_add_i32 m0, s33, 0x2000
	s_nop 0
	global_load_lds_dwordx4 v[220:221], off
	v_lshl_add_u64 v[220:221], s[44:45], 0, v[152:153]
	s_mov_b32 m0, s25
	s_nop 0
	global_load_lds_dwordx4 v[220:221], off
	s_mov_b32 m0, s57
	s_nop 0
	global_load_lds_dwordx4 v[222:223], off
	s_waitcnt vmcnt(8)
	s_waitcnt lgkmcnt(0)
	s_barrier
; #define PG8_STAGE(bufoff, gbase, voff) do { _Pragma("unroll") for (int _i = 0; _i < 2; ++_i) \
;         __builtin_amdgcn_global_load_lds((const unsigned*)((const char*)(gbase) + (voff)[_i]), (LAS unsigned*)(lds + (bufoff) + ldsw + _i * 8192), 16, 0, 0); } while (0)
; #define PG8_LDA(dst, b, h) do { _Pragma("unroll") for (int m = 0; m < 4; ++m) _Pragma("unroll") for (int k = 0; k < 2; ++k) dst[m][k] = *(const LAS bf16x8*)(lds + PG8_SA(b, h) + aoff + m * 2048 + k * 1024); } while (0)
; #define PG8_LDB(dst, b, h) do { _Pragma("unroll") for (int n = 0; n < 2; ++n) _Pragma("unroll") for (int k = 0; k < 2; ++k) dst[n][k] = *(const LAS bf16x8*)(lds + PG8_SB(b, h) + boff + n * 2048 + k * 1024); } while (0)
; #define PG8_MMA(ai, bj, At, Bt) do { __builtin_amdgcn_s_setprio(1); _Pragma("unroll") for (int m = 0; m < 4; ++m) _Pragma("unroll") for (int n = 0; n < 2; ++n) _Pragma("unroll") for (int k = 0; k < 2; ++k) \
;         acc[ai][bj][m][n] = __builtin_amdgcn_mfma_f32_16x16x32_bf16(Bt[n][k], At[m][k], acc[ai][bj][m][n], 0, 0, 0); __builtin_amdgcn_s_setprio(0); } while (0)
; #define PG8_WAIT_V(n) asm volatile("s_waitcnt vmcnt(" #n ")" ::: "memory")
; #define PG8_WAIT_L(n) asm volatile("s_waitcnt lgkmcnt(" #n ")" ::: "memory")
; #define PG8_BAR __builtin_amdgcn_s_barrier()
; #define PG8_SCHED __builtin_amdgcn_sched_barrier(0)
; template <class Epi>
; __device__ __forceinline__ void gemm_phase(LAS unsigned char* lds, const Gemm g, int G, int c, const Epi& E) {
;     ...
;             PG8_WAIT_V(8); PG8_WAIT_L(0); PG8_BAR; PG8_MMA(1, 0, At, B0); PG8_MMA(1, 1, At, B1); PG8_BAR; PG8_SCHED;
;             PG8_LDB(B0, 1, 0); PG8_LDB(B1, 1, 1); PG8_SCHED; PG8_LDA(At, 1, 0); PG8_STAGE(PG8_SA(0, 1), a2 + hstepA, voffA);
;             PG8_WAIT_V(8); PG8_WAIT_L(0); PG8_BAR; PG8_MMA(0, 0, At, B0); PG8_MMA(0, 1, At, B1); PG8_BAR; PG8_SCHED;
	s_setprio 0
	s_waitcnt lgkmcnt(0)
	v_mfma_f32_16x16x32_bf16 v[62:65], v[130:133], v[186:189], v[62:65]
	v_mfma_f32_16x16x32_bf16 v[58:61], v[138:141], v[186:189], v[58:61]
	v_mfma_f32_16x16x32_bf16 v[42:45], v[138:141], v[194:197], v[42:45]
	v_mfma_f32_16x16x32_bf16 v[46:49], v[130:133], v[194:197], v[46:49]
	v_mfma_f32_16x16x32_bf16 v[30:33], v[130:133], v[202:205], v[30:33]
	v_mfma_f32_16x16x32_bf16 v[26:29], v[138:141], v[202:205], v[26:29]
	v_mfma_f32_16x16x32_bf16 v[10:13], v[138:141], v[210:213], v[10:13]
	v_mfma_f32_16x16x32_bf16 v[14:17], v[130:133], v[210:213], v[14:17]
	v_mfma_f32_16x16x32_bf16 v[62:65], v[134:137], v[190:193], v[62:65]
	v_mfma_f32_16x16x32_bf16 v[58:61], v[142:145], v[190:193], v[58:61]
	v_mfma_f32_16x16x32_bf16 v[42:45], v[142:145], v[198:201], v[42:45]
	v_mfma_f32_16x16x32_bf16 v[46:49], v[134:137], v[198:201], v[46:49]
	v_mfma_f32_16x16x32_bf16 v[30:33], v[134:137], v[206:209], v[30:33]
	v_mfma_f32_16x16x32_bf16 v[26:29], v[142:145], v[206:209], v[26:29]
	v_mfma_f32_16x16x32_bf16 v[10:13], v[142:145], v[214:217], v[10:13]
	v_mfma_f32_16x16x32_bf16 v[14:17], v[134:137], v[214:217], v[14:17]
	s_setprio 2
	s_setprio 0
	v_mfma_f32_16x16x32_bf16 v[54:57], v[162:165], v[186:189], v[54:57]
	v_mfma_f32_16x16x32_bf16 v[50:53], v[178:181], v[186:189], v[50:53]
	v_mfma_f32_16x16x32_bf16 v[34:37], v[178:181], v[194:197], v[34:37]
	v_mfma_f32_16x16x32_bf16 v[38:41], v[162:165], v[194:197], v[38:41]
	v_mfma_f32_16x16x32_bf16 v[22:25], v[162:165], v[202:205], v[22:25]
	v_mfma_f32_16x16x32_bf16 v[18:21], v[178:181], v[202:205], v[18:21]
	v_mfma_f32_16x16x32_bf16 v[2:5], v[178:181], v[210:213], v[2:5]
	v_mfma_f32_16x16x32_bf16 v[6:9], v[162:165], v[210:213], v[6:9]
	v_mfma_f32_16x16x32_bf16 v[54:57], v[174:177], v[190:193], v[54:57]
	v_mfma_f32_16x16x32_bf16 v[50:53], v[182:185], v[190:193], v[50:53]
	v_mfma_f32_16x16x32_bf16 v[34:37], v[182:185], v[198:201], v[34:37]
	v_mfma_f32_16x16x32_bf16 v[38:41], v[174:177], v[198:201], v[38:41]
	v_mfma_f32_16x16x32_bf16 v[22:25], v[174:177], v[206:209], v[22:25]
	v_mfma_f32_16x16x32_bf16 v[18:21], v[182:185], v[206:209], v[18:21]
	v_mfma_f32_16x16x32_bf16 v[2:5], v[182:185], v[214:217], v[2:5]
	v_mfma_f32_16x16x32_bf16 v[6:9], v[174:177], v[214:217], v[6:9]
	s_setprio 2
	s_barrier
	s_add_i32 s33, 0, 0x18000
	s_add_i32 s47, 0, 0x1c000
	v_add_u32_e32 v142, s33, v169
	v_add_u32_e32 v173, s47, v169
	ds_read_b128 v[130:133], v142
	ds_read_b128 v[134:137], v142 offset:1024
	ds_read_b128 v[138:141], v142 offset:2048
	ds_read_b128 v[142:145], v142 offset:3072
	ds_read_b128 v[162:165], v173
	ds_read_b128 v[174:177], v173 offset:1024
	ds_read_b128 v[178:181], v173 offset:2048
	ds_read_b128 v[182:185], v173 offset:3072
	s_add_u32 s44, s44, 0x40000
	s_addc_u32 s45, s45, 0
	s_mov_b32 m0, s58
	v_lshl_add_u64 v[224:225], s[44:45], 0, v[152:153]
	ds_read_b128 v[186:189], v172 offset:32768
	ds_read_b128 v[190:193], v172 offset:33792
	ds_read_b128 v[194:197], v172 offset:34816
	ds_read_b128 v[198:201], v172 offset:35840
	ds_read_b128 v[202:205], v172 offset:36864
	ds_read_b128 v[206:209], v172 offset:37888
	ds_read_b128 v[210:213], v172 offset:38912
	ds_read_b128 v[214:217], v172 offset:39936
	global_load_lds_dwordx4 v[224:225], off
	v_lshl_add_u64 v[224:225], s[44:45], 0, v[148:149]
	s_mov_b32 m0, s59
	s_nop 0
	global_load_lds_dwordx4 v[224:225], off
	s_waitcnt vmcnt(8)
	s_waitcnt lgkmcnt(0)
	s_barrier
	s_setprio 0
	s_waitcnt lgkmcnt(0)
	v_mfma_f32_16x16x32_bf16 v[126:129], v[130:133], v[186:189], v[126:129]
	v_mfma_f32_16x16x32_bf16 v[122:125], v[138:141], v[186:189], v[122:125]
	v_mfma_f32_16x16x32_bf16 v[106:109], v[138:141], v[194:197], v[106:109]
	v_mfma_f32_16x16x32_bf16 v[110:113], v[130:133], v[194:197], v[110:113]
	v_mfma_f32_16x16x32_bf16 v[94:97], v[130:133], v[202:205], v[94:97]
	v_mfma_f32_16x16x32_bf16 v[90:93], v[138:141], v[202:205], v[90:93]
	v_mfma_f32_16x16x32_bf16 v[74:77], v[138:141], v[210:213], v[74:77]
	v_mfma_f32_16x16x32_bf16 v[78:81], v[130:133], v[210:213], v[78:81]
	v_mfma_f32_16x16x32_bf16 v[126:129], v[134:137], v[190:193], v[126:129]
	v_mfma_f32_16x16x32_bf16 v[122:125], v[142:145], v[190:193], v[122:125]
	v_mfma_f32_16x16x32_bf16 v[106:109], v[142:145], v[198:201], v[106:109]
	v_mfma_f32_16x16x32_bf16 v[110:113], v[134:137], v[198:201], v[110:113]
	v_mfma_f32_16x16x32_bf16 v[94:97], v[134:137], v[206:209], v[94:97]
	v_mfma_f32_16x16x32_bf16 v[90:93], v[142:145], v[206:209], v[90:93]
	v_mfma_f32_16x16x32_bf16 v[74:77], v[142:145], v[214:217], v[74:77]
	v_mfma_f32_16x16x32_bf16 v[78:81], v[134:137], v[214:217], v[78:81]
	s_setprio 2
	s_setprio 0
	v_mfma_f32_16x16x32_bf16 v[118:121], v[162:165], v[186:189], v[118:121]
	v_mfma_f32_16x16x32_bf16 v[114:117], v[178:181], v[186:189], v[114:117]
	v_mfma_f32_16x16x32_bf16 v[98:101], v[178:181], v[194:197], v[98:101]
	v_mfma_f32_16x16x32_bf16 v[102:105], v[162:165], v[194:197], v[102:105]
	v_mfma_f32_16x16x32_bf16 v[86:89], v[162:165], v[202:205], v[86:89]
	v_mfma_f32_16x16x32_bf16 v[82:85], v[178:181], v[202:205], v[82:85]
	v_mfma_f32_16x16x32_bf16 v[66:69], v[178:181], v[210:213], v[66:69]
	v_mfma_f32_16x16x32_bf16 v[70:73], v[162:165], v[210:213], v[70:73]
	v_mfma_f32_16x16x32_bf16 v[118:121], v[174:177], v[190:193], v[118:121]
	v_mfma_f32_16x16x32_bf16 v[114:117], v[182:185], v[190:193], v[114:117]
	v_mfma_f32_16x16x32_bf16 v[98:101], v[182:185], v[198:201], v[98:101]
	v_mfma_f32_16x16x32_bf16 v[102:105], v[174:177], v[198:201], v[102:105]
	v_mfma_f32_16x16x32_bf16 v[86:89], v[174:177], v[206:209], v[86:89]
	v_mfma_f32_16x16x32_bf16 v[82:85], v[182:185], v[206:209], v[82:85]
	v_mfma_f32_16x16x32_bf16 v[66:69], v[182:185], v[214:217], v[66:69]
	v_mfma_f32_16x16x32_bf16 v[70:73], v[174:177], v[214:217], v[70:73]
	s_setprio 2
	s_barrier
; #define PG8_STAGE(bufoff, gbase, voff) do { _Pragma("unroll") for (int _i = 0; _i < 2; ++_i) \
;         __builtin_amdgcn_global_load_lds((const unsigned*)((const char*)(gbase) + (voff)[_i]), (LAS unsigned*)(lds + (bufoff) + ldsw + _i * 8192), 16, 0, 0); } while (0)
; #define PG8_LDA(dst, b, h) do { _Pragma("unroll") for (int m = 0; m < 4; ++m) _Pragma("unroll") for (int k = 0; k < 2; ++k) dst[m][k] = *(const LAS bf16x8*)(lds + PG8_SA(b, h) + aoff + m * 2048 + k * 1024); } while (0)
; #define PG8_MMA(ai, bj, At, Bt) do { __builtin_amdgcn_s_setprio(1); _Pragma("unroll") for (int m = 0; m < 4; ++m) _Pragma("unroll") for (int n = 0; n < 2; ++n) _Pragma("unroll") for (int k = 0; k < 2; ++k) \
;         acc[ai][bj][m][n] = __builtin_amdgcn_mfma_f32_16x16x32_bf16(Bt[n][k], At[m][k], acc[ai][bj][m][n], 0, 0, 0); __builtin_amdgcn_s_setprio(0); } while (0)
; #define PG8_WAIT_V(n) asm volatile("s_waitcnt vmcnt(" #n ")" ::: "memory")
; #define PG8_WAIT_L(n) asm volatile("s_waitcnt lgkmcnt(" #n ")" ::: "memory")
; #define PG8_BAR __builtin_amdgcn_s_barrier()
; #define PG8_SCHED __builtin_amdgcn_sched_barrier(0)
; template <class Epi>
; __device__ __forceinline__ void gemm_phase(LAS unsigned char* lds, const Gemm g, int G, int c, const Epi& E) {
;     ...
;             PG8_LDA(At, 1, 1); PG8_STAGE(PG8_SB(1, 0), b3, voffB); PG8_STAGE(PG8_SB(1, 1), b3 + hstepB, voffB); PG8_STAGE(PG8_SA(1, 0), a3, voffA);
;             PG8_WAIT_V(8); PG8_WAIT_L(0); PG8_BAR; PG8_MMA(1, 0, At, B0); PG8_MMA(1, 1, At, B1); PG8_BAR; PG8_SCHED;
;         }
;         if (wr == 0) PG8_BAR;
	s_add_i32 s33, s33, s54
	v_lshl_add_u64 v[166:167], v[166:167], 0, s[10:11]
	s_mov_b32 m0, s33
	ds_read_b128 v[186:189], v172 offset:49152
	ds_read_b128 v[190:193], v172 offset:50176
	ds_read_b128 v[194:197], v172 offset:51200
	ds_read_b128 v[198:201], v172 offset:52224
	ds_read_b128 v[202:205], v172 offset:53248
	ds_read_b128 v[206:209], v172 offset:54272
	ds_read_b128 v[210:213], v172 offset:55296
	ds_read_b128 v[214:217], v172 offset:56320
	global_load_lds_dwordx4 v[166:167], off
	s_add_i32 m0, s33, 0x2000
	s_add_u32 s42, s42, 0x40080
	v_lshl_add_u64 v[166:167], v[218:219], 0, s[10:11]
	s_addc_u32 s43, s43, 0
	s_add_i32 s33, s47, s54
	global_load_lds_dwordx4 v[166:167], off
	v_lshl_add_u64 v[166:167], s[42:43], 0, v[150:151]
	s_mov_b32 m0, s33
	s_nop 0
	global_load_lds_dwordx4 v[166:167], off
	v_lshl_add_u64 v[166:167], s[42:43], 0, v[146:147]
	s_add_i32 m0, s33, 0x2000
	s_nop 0
	global_load_lds_dwordx4 v[166:167], off
	v_lshl_add_u64 v[166:167], v[220:221], 0, s[10:11]
	s_mov_b32 m0, s69
	s_nop 0
	global_load_lds_dwordx4 v[166:167], off
	v_lshl_add_u64 v[166:167], v[222:223], 0, s[10:11]
	s_mov_b32 m0, s70
	s_nop 0
	global_load_lds_dwordx4 v[166:167], off
	s_waitcnt vmcnt(8)
	s_waitcnt lgkmcnt(0)
	s_barrier
	s_setprio 0
	s_waitcnt lgkmcnt(0)
	v_mfma_f32_16x16x32_bf16 v[62:65], v[130:133], v[186:189], v[62:65]
	v_mfma_f32_16x16x32_bf16 v[58:61], v[138:141], v[186:189], v[58:61]
	v_mfma_f32_16x16x32_bf16 v[42:45], v[138:141], v[194:197], v[42:45]
	v_mfma_f32_16x16x32_bf16 v[46:49], v[130:133], v[194:197], v[46:49]
	v_mfma_f32_16x16x32_bf16 v[30:33], v[130:133], v[202:205], v[30:33]
	v_mfma_f32_16x16x32_bf16 v[26:29], v[138:141], v[202:205], v[26:29]
	v_mfma_f32_16x16x32_bf16 v[10:13], v[138:141], v[210:213], v[10:13]
	v_mfma_f32_16x16x32_bf16 v[14:17], v[130:133], v[210:213], v[14:17]
	v_mfma_f32_16x16x32_bf16 v[62:65], v[134:137], v[190:193], v[62:65]
	v_mfma_f32_16x16x32_bf16 v[58:61], v[142:145], v[190:193], v[58:61]
	v_mfma_f32_16x16x32_bf16 v[42:45], v[142:145], v[198:201], v[42:45]
	v_mfma_f32_16x16x32_bf16 v[46:49], v[134:137], v[198:201], v[46:49]
	v_mfma_f32_16x16x32_bf16 v[30:33], v[134:137], v[206:209], v[30:33]
	v_mfma_f32_16x16x32_bf16 v[26:29], v[142:145], v[206:209], v[26:29]
	v_mfma_f32_16x16x32_bf16 v[10:13], v[142:145], v[214:217], v[10:13]
	v_mfma_f32_16x16x32_bf16 v[14:17], v[134:137], v[214:217], v[14:17]
	s_setprio 2
	s_setprio 0
	v_mfma_f32_16x16x32_bf16 v[54:57], v[162:165], v[186:189], v[54:57]
	v_mfma_f32_16x16x32_bf16 v[50:53], v[178:181], v[186:189], v[50:53]
	v_mfma_f32_16x16x32_bf16 v[34:37], v[178:181], v[194:197], v[34:37]
	v_mfma_f32_16x16x32_bf16 v[38:41], v[162:165], v[194:197], v[38:41]
	v_mfma_f32_16x16x32_bf16 v[22:25], v[162:165], v[202:205], v[22:25]
	v_mfma_f32_16x16x32_bf16 v[18:21], v[178:181], v[202:205], v[18:21]
	v_mfma_f32_16x16x32_bf16 v[2:5], v[178:181], v[210:213], v[2:5]
	v_mfma_f32_16x16x32_bf16 v[6:9], v[162:165], v[210:213], v[6:9]
	v_mfma_f32_16x16x32_bf16 v[54:57], v[174:177], v[190:193], v[54:57]
	v_mfma_f32_16x16x32_bf16 v[50:53], v[182:185], v[190:193], v[50:53]
	v_mfma_f32_16x16x32_bf16 v[34:37], v[182:185], v[198:201], v[34:37]
	v_mfma_f32_16x16x32_bf16 v[38:41], v[174:177], v[198:201], v[38:41]
	v_mfma_f32_16x16x32_bf16 v[22:25], v[174:177], v[206:209], v[22:25]
	v_mfma_f32_16x16x32_bf16 v[18:21], v[182:185], v[206:209], v[18:21]
	v_mfma_f32_16x16x32_bf16 v[2:5], v[182:185], v[214:217], v[2:5]
	v_mfma_f32_16x16x32_bf16 v[6:9], v[174:177], v[214:217], v[6:9]
	s_setprio 2
	s_barrier
	s_add_i32 s46, s46, 2
	s_add_u32 s4, s4, 0x100
	s_addc_u32 s5, s5, 0
	s_add_u32 s23, s23, 0x100
	s_addc_u32 s39, s39, 0
	s_cmp_gt_u32 s46, 13
	s_cbranch_scc0 .LBB0_903
	s_and_b64 vcc, exec, s[12:13]
	s_cbranch_vccz .LBB0_906
	s_barrier

; #define PG8_STAGE(bufoff, gbase, voff) do { _Pragma("unroll") for (int _i = 0; _i < 2; ++_i) \
;         __builtin_amdgcn_global_load_lds((const unsigned*)((const char*)(gbase) + (voff)[_i]), (LAS unsigned*)(lds + (bufoff) + ldsw + _i * 8192), 16, 0, 0); } while (0)
; #define PG8_LDA(dst, b, h) do { _Pragma("unroll") for (int m = 0; m < 4; ++m) _Pragma("unroll") for (int k = 0; k < 2; ++k) dst[m][k] = *(const LAS bf16x8*)(lds + PG8_SA(b, h) + aoff + m * 2048 + k * 1024); } while (0)
; #define PG8_LDB(dst, b, h) do { _Pragma("unroll") for (int n = 0; n < 2; ++n) _Pragma("unroll") for (int k = 0; k < 2; ++k) dst[n][k] = *(const LAS bf16x8*)(lds + PG8_SB(b, h) + boff + n * 2048 + k * 1024); } while (0)
; #define PG8_MMA(ai, bj, At, Bt) do { __builtin_amdgcn_s_setprio(1); _Pragma("unroll") for (int m = 0; m < 4; ++m) _Pragma("unroll") for (int n = 0; n < 2; ++n) _Pragma("unroll") for (int k = 0; k < 2; ++k) \
;         acc[ai][bj][m][n] = __builtin_amdgcn_mfma_f32_16x16x32_bf16(Bt[n][k], At[m][k], acc[ai][bj][m][n], 0, 0, 0); __builtin_amdgcn_s_setprio(0); } while (0)
; #define PG8_WAIT_V(n) asm volatile("s_waitcnt vmcnt(" #n ")" ::: "memory")
; #define PG8_WAIT_L(n) asm volatile("s_waitcnt lgkmcnt(" #n ")" ::: "memory")
; #define PG8_BAR __builtin_amdgcn_s_barrier()
; #define PG8_SCHED __builtin_amdgcn_sched_barrier(0)
; template <class Epi>
; __device__ __forceinline__ void gemm_phase(LAS unsigned char* lds, const Gemm g, int G, int c, const Epi& E) {
;     ...
;         for (int t = 0; t < nt; t += 2) {
;             const bool last = (t == nt - 2);
;             const char* a1 = cA + (size_t)(t + 1) * kstep;
;             const char* a2 = last ? nA : cA + (size_t)(t + 2) * kstep; const char* b2 = last ? nB : cB + (size_t)(t + 2) * kstep;
;             const char* a3 = a2 + kstep; const char* b3 = b2 + kstep;
;             PG8_LDB(B0, 0, 0); PG8_LDB(B1, 0, 1); PG8_SCHED; PG8_LDA(At, 0, 0); PG8_STAGE(PG8_SA(1, 1), a1 + hstepA, voffA);
;             PG8_WAIT_V(8); PG8_WAIT_L(0); PG8_BAR; PG8_MMA(0, 0, At, B0); PG8_MMA(0, 1, At, B1); PG8_BAR; PG8_SCHED;
;             PG8_LDA(At, 0, 1); PG8_STAGE(PG8_SB(0, 0), b2, voffB); PG8_STAGE(PG8_SB(0, 1), b2 + hstepB, voffB); PG8_STAGE(PG8_SA(0, 0), a2, voffA);
.LBB0_1058:
	ds_read_b128 v[152:155], v148
	ds_read_b128 v[156:159], v148 offset:1024
	ds_read_b128 v[160:163], v148 offset:2048
	ds_read_b128 v[164:167], v148 offset:3072
	ds_read_b128 v[168:171], v149
	ds_read_b128 v[172:175], v149 offset:1024
	ds_read_b128 v[176:179], v149 offset:2048
	ds_read_b128 v[180:183], v149 offset:3072
	s_add_u32 s33, s4, 0xfffc0080
	s_addc_u32 s38, s5, -1
	s_cmp_eq_u32 s80, 12
	s_cselect_b32 s41, s21, s38
	s_cselect_b32 s40, s20, s33
	s_cselect_b32 s39, s17, s79
	s_cselect_b32 s38, s19, s78
	v_lshl_add_u64 v[216:217], s[4:5], 0, v[138:139]
	s_add_i32 m0, s25, 0xc000
	ds_read_b128 v[184:187], v150
	ds_read_b128 v[188:191], v150 offset:1024
	ds_read_b128 v[192:195], v150 offset:2048
	ds_read_b128 v[196:199], v150 offset:3072
	ds_read_b128 v[200:203], v150 offset:4096
	ds_read_b128 v[204:207], v150 offset:5120
	ds_read_b128 v[208:211], v150 offset:6144
	ds_read_b128 v[212:215], v150 offset:7168
	global_load_lds_dwordx4 v[216:217], off
	v_lshl_add_u64 v[216:217], s[4:5], 0, v[140:141]
	s_add_i32 m0, s25, 0xe000
	s_nop 0
	global_load_lds_dwordx4 v[216:217], off
	s_waitcnt vmcnt(8)
	s_waitcnt lgkmcnt(0)
	s_barrier
	s_setprio 0
	s_waitcnt lgkmcnt(0)
	v_mfma_f32_16x16x32_bf16 v[126:129], v[152:155], v[184:187], v[126:129]
	v_mfma_f32_16x16x32_bf16 v[122:125], v[160:163], v[184:187], v[122:125]
	v_mfma_f32_16x16x32_bf16 v[106:109], v[160:163], v[192:195], v[106:109]
	v_mfma_f32_16x16x32_bf16 v[110:113], v[152:155], v[192:195], v[110:113]
	v_mfma_f32_16x16x32_bf16 v[94:97], v[152:155], v[200:203], v[94:97]
	v_mfma_f32_16x16x32_bf16 v[90:93], v[160:163], v[200:203], v[90:93]
	v_mfma_f32_16x16x32_bf16 v[74:77], v[160:163], v[208:211], v[74:77]
	v_mfma_f32_16x16x32_bf16 v[78:81], v[152:155], v[208:211], v[78:81]
	v_mfma_f32_16x16x32_bf16 v[126:129], v[156:159], v[188:191], v[126:129]
	v_mfma_f32_16x16x32_bf16 v[122:125], v[164:167], v[188:191], v[122:125]
	v_mfma_f32_16x16x32_bf16 v[106:109], v[164:167], v[196:199], v[106:109]
	v_mfma_f32_16x16x32_bf16 v[110:113], v[156:159], v[196:199], v[110:113]
	v_mfma_f32_16x16x32_bf16 v[94:97], v[156:159], v[204:207], v[94:97]
	v_mfma_f32_16x16x32_bf16 v[90:93], v[164:167], v[204:207], v[90:93]
	v_mfma_f32_16x16x32_bf16 v[74:77], v[164:167], v[212:215], v[74:77]
	v_mfma_f32_16x16x32_bf16 v[78:81], v[156:159], v[212:215], v[78:81]
	s_setprio 2
	s_setprio 0
	v_mfma_f32_16x16x32_bf16 v[118:121], v[168:171], v[184:187], v[118:121]
	v_mfma_f32_16x16x32_bf16 v[114:117], v[176:179], v[184:187], v[114:117]
	v_mfma_f32_16x16x32_bf16 v[98:101], v[176:179], v[192:195], v[98:101]
	v_mfma_f32_16x16x32_bf16 v[102:105], v[168:171], v[192:195], v[102:105]
	v_mfma_f32_16x16x32_bf16 v[86:89], v[168:171], v[200:203], v[86:89]
	v_mfma_f32_16x16x32_bf16 v[82:85], v[176:179], v[200:203], v[82:85]
	v_mfma_f32_16x16x32_bf16 v[66:69], v[176:179], v[208:211], v[66:69]
	v_mfma_f32_16x16x32_bf16 v[70:73], v[168:171], v[208:211], v[70:73]
	v_mfma_f32_16x16x32_bf16 v[118:121], v[172:175], v[188:191], v[118:121]
	v_mfma_f32_16x16x32_bf16 v[114:117], v[180:183], v[188:191], v[114:117]
	v_mfma_f32_16x16x32_bf16 v[98:101], v[180:183], v[196:199], v[98:101]
	v_mfma_f32_16x16x32_bf16 v[102:105], v[172:175], v[196:199], v[102:105]
	v_mfma_f32_16x16x32_bf16 v[86:89], v[172:175], v[204:207], v[86:89]
	v_mfma_f32_16x16x32_bf16 v[82:85], v[180:183], v[204:207], v[82:85]
	v_mfma_f32_16x16x32_bf16 v[66:69], v[180:183], v[212:215], v[66:69]
	v_mfma_f32_16x16x32_bf16 v[70:73], v[172:175], v[212:215], v[70:73]
	s_setprio 2
	s_barrier
	s_add_i32 s33, s60, s46
	v_lshl_add_u64 v[216:217], s[38:39], 0, v[134:135]
	s_mov_b32 m0, s33
	ds_read_b128 v[184:187], v150 offset:16384
	ds_read_b128 v[188:191], v150 offset:17408
	ds_read_b128 v[192:195], v150 offset:18432
	ds_read_b128 v[196:199], v150 offset:19456
	ds_read_b128 v[200:203], v150 offset:20480
	ds_read_b128 v[204:207], v150 offset:21504
	ds_read_b128 v[208:211], v150 offset:22528
	ds_read_b128 v[212:215], v150 offset:23552
	global_load_lds_dwordx4 v[216:217], off
	s_add_i32 m0, s33, 0x2000
	s_add_u32 s62, s38, 0x40000
	v_lshl_add_u64 v[218:219], s[38:39], 0, v[130:131]
	s_addc_u32 s63, s39, 0
	s_add_i32 s33, s61, s46
	global_load_lds_dwordx4 v[218:219], off
	v_lshl_add_u64 v[220:221], s[62:63], 0, v[134:135]
	s_mov_b32 m0, s33
	v_lshl_add_u64 v[222:223], s[40:41], 0, v[132:133]
	global_load_lds_dwordx4 v[220:221], off
	v_lshl_add_u64 v[220:221], s[62:63], 0, v[130:131]
	s_add_i32 m0, s33, 0x2000
	s_nop 0
	global_load_lds_dwordx4 v[220:221], off
	v_lshl_add_u64 v[220:221], s[40:41], 0, v[136:137]
	s_mov_b32 m0, s25
	s_nop 0
	global_load_lds_dwordx4 v[220:221], off
	s_mov_b32 m0, s37
	s_nop 0
	global_load_lds_dwordx4 v[222:223], off
	s_waitcnt vmcnt(8)
	s_waitcnt lgkmcnt(0)
	s_barrier
; #define PG8_STAGE(bufoff, gbase, voff) do { _Pragma("unroll") for (int _i = 0; _i < 2; ++_i) \
;         __builtin_amdgcn_global_load_lds((const unsigned*)((const char*)(gbase) + (voff)[_i]), (LAS unsigned*)(lds + (bufoff) + ldsw + _i * 8192), 16, 0, 0); } while (0)
; #define PG8_LDA(dst, b, h) do { _Pragma("unroll") for (int m = 0; m < 4; ++m) _Pragma("unroll") for (int k = 0; k < 2; ++k) dst[m][k] = *(const LAS bf16x8*)(lds + PG8_SA(b, h) + aoff + m * 2048 + k * 1024); } while (0)
; #define PG8_LDB(dst, b, h) do { _Pragma("unroll") for (int n = 0; n < 2; ++n) _Pragma("unroll") for (int k = 0; k < 2; ++k) dst[n][k] = *(const LAS bf16x8*)(lds + PG8_SB(b, h) + boff + n * 2048 + k * 1024); } while (0)
; #define PG8_MMA(ai, bj, At, Bt) do { __builtin_amdgcn_s_setprio(1); _Pragma("unroll") for (int m = 0; m < 4; ++m) _Pragma("unroll") for (int n = 0; n < 2; ++n) _Pragma("unroll") for (int k = 0; k < 2; ++k) \
;         acc[ai][bj][m][n] = __builtin_amdgcn_mfma_f32_16x16x32_bf16(Bt[n][k], At[m][k], acc[ai][bj][m][n], 0, 0, 0); __builtin_amdgcn_s_setprio(0); } while (0)
; #define PG8_WAIT_V(n) asm volatile("s_waitcnt vmcnt(" #n ")" ::: "memory")
; #define PG8_WAIT_L(n) asm volatile("s_waitcnt lgkmcnt(" #n ")" ::: "memory")
; #define PG8_BAR __builtin_amdgcn_s_barrier()
; #define PG8_SCHED __builtin_amdgcn_sched_barrier(0)
; template <class Epi>
; __device__ __forceinline__ void gemm_phase(LAS unsigned char* lds, const Gemm g, int G, int c, const Epi& E) {
;     ...
;             PG8_WAIT_V(8); PG8_WAIT_L(0); PG8_BAR; PG8_MMA(1, 0, At, B0); PG8_MMA(1, 1, At, B1); PG8_BAR; PG8_SCHED;
;             PG8_LDB(B0, 1, 0); PG8_LDB(B1, 1, 1); PG8_SCHED; PG8_LDA(At, 1, 0); PG8_STAGE(PG8_SA(0, 1), a2 + hstepA, voffA);
;             PG8_WAIT_V(8); PG8_WAIT_L(0); PG8_BAR; PG8_MMA(0, 0, At, B0); PG8_MMA(0, 1, At, B1); PG8_BAR; PG8_SCHED;
	s_setprio 0
	s_waitcnt lgkmcnt(0)
	v_mfma_f32_16x16x32_bf16 v[62:65], v[152:155], v[184:187], v[62:65]
	v_mfma_f32_16x16x32_bf16 v[58:61], v[160:163], v[184:187], v[58:61]
	v_mfma_f32_16x16x32_bf16 v[42:45], v[160:163], v[192:195], v[42:45]
	v_mfma_f32_16x16x32_bf16 v[46:49], v[152:155], v[192:195], v[46:49]
	v_mfma_f32_16x16x32_bf16 v[30:33], v[152:155], v[200:203], v[30:33]
	v_mfma_f32_16x16x32_bf16 v[26:29], v[160:163], v[200:203], v[26:29]
	v_mfma_f32_16x16x32_bf16 v[10:13], v[160:163], v[208:211], v[10:13]
	v_mfma_f32_16x16x32_bf16 v[14:17], v[152:155], v[208:211], v[14:17]
	v_mfma_f32_16x16x32_bf16 v[62:65], v[156:159], v[188:191], v[62:65]
	v_mfma_f32_16x16x32_bf16 v[58:61], v[164:167], v[188:191], v[58:61]
	v_mfma_f32_16x16x32_bf16 v[42:45], v[164:167], v[196:199], v[42:45]
	v_mfma_f32_16x16x32_bf16 v[46:49], v[156:159], v[196:199], v[46:49]
	v_mfma_f32_16x16x32_bf16 v[30:33], v[156:159], v[204:207], v[30:33]
	v_mfma_f32_16x16x32_bf16 v[26:29], v[164:167], v[204:207], v[26:29]
	v_mfma_f32_16x16x32_bf16 v[10:13], v[164:167], v[212:215], v[10:13]
	v_mfma_f32_16x16x32_bf16 v[14:17], v[156:159], v[212:215], v[14:17]
	s_setprio 2
	s_setprio 0
	v_mfma_f32_16x16x32_bf16 v[54:57], v[168:171], v[184:187], v[54:57]
	v_mfma_f32_16x16x32_bf16 v[50:53], v[176:179], v[184:187], v[50:53]
	v_mfma_f32_16x16x32_bf16 v[34:37], v[176:179], v[192:195], v[34:37]
	v_mfma_f32_16x16x32_bf16 v[38:41], v[168:171], v[192:195], v[38:41]
	v_mfma_f32_16x16x32_bf16 v[22:25], v[168:171], v[200:203], v[22:25]
	v_mfma_f32_16x16x32_bf16 v[18:21], v[176:179], v[200:203], v[18:21]
	v_mfma_f32_16x16x32_bf16 v[2:5], v[176:179], v[208:211], v[2:5]
	v_mfma_f32_16x16x32_bf16 v[6:9], v[168:171], v[208:211], v[6:9]
	v_mfma_f32_16x16x32_bf16 v[54:57], v[172:175], v[188:191], v[54:57]
	v_mfma_f32_16x16x32_bf16 v[50:53], v[180:183], v[188:191], v[50:53]
	v_mfma_f32_16x16x32_bf16 v[34:37], v[180:183], v[196:199], v[34:37]
	v_mfma_f32_16x16x32_bf16 v[38:41], v[172:175], v[196:199], v[38:41]
	v_mfma_f32_16x16x32_bf16 v[22:25], v[172:175], v[204:207], v[22:25]
	v_mfma_f32_16x16x32_bf16 v[18:21], v[180:183], v[204:207], v[18:21]
	v_mfma_f32_16x16x32_bf16 v[2:5], v[180:183], v[212:215], v[2:5]
	v_mfma_f32_16x16x32_bf16 v[6:9], v[172:175], v[212:215], v[6:9]
	s_setprio 2
	s_barrier
	s_add_i32 s33, 0, 0x18000
	s_add_i32 s62, 0, 0x1c000
	v_add_u32_e32 v164, s33, v147
	v_add_u32_e32 v180, s62, v147
	ds_read_b128 v[152:155], v164
	ds_read_b128 v[156:159], v164 offset:1024
	ds_read_b128 v[160:163], v164 offset:2048
	ds_read_b128 v[164:167], v164 offset:3072
	ds_read_b128 v[168:171], v180
	ds_read_b128 v[172:175], v180 offset:1024
	ds_read_b128 v[176:179], v180 offset:2048
	ds_read_b128 v[180:183], v180 offset:3072
	s_add_u32 s40, s40, 0x40000
	s_addc_u32 s41, s41, 0
	s_mov_b32 m0, s47
	v_lshl_add_u64 v[224:225], s[40:41], 0, v[136:137]
	ds_read_b128 v[184:187], v150 offset:32768
	ds_read_b128 v[188:191], v150 offset:33792
	ds_read_b128 v[192:195], v150 offset:34816
	ds_read_b128 v[196:199], v150 offset:35840
	ds_read_b128 v[200:203], v150 offset:36864
	ds_read_b128 v[204:207], v150 offset:37888
	ds_read_b128 v[208:211], v150 offset:38912
	ds_read_b128 v[212:215], v150 offset:39936
	global_load_lds_dwordx4 v[224:225], off
	v_lshl_add_u64 v[224:225], s[40:41], 0, v[132:133]
	s_mov_b32 m0, s52
	s_nop 0
	global_load_lds_dwordx4 v[224:225], off
	s_waitcnt vmcnt(8)
	s_waitcnt lgkmcnt(0)
	s_barrier
	s_setprio 0
	s_waitcnt lgkmcnt(0)
	v_mfma_f32_16x16x32_bf16 v[126:129], v[152:155], v[184:187], v[126:129]
	v_mfma_f32_16x16x32_bf16 v[122:125], v[160:163], v[184:187], v[122:125]
	v_mfma_f32_16x16x32_bf16 v[106:109], v[160:163], v[192:195], v[106:109]
	v_mfma_f32_16x16x32_bf16 v[110:113], v[152:155], v[192:195], v[110:113]
	v_mfma_f32_16x16x32_bf16 v[94:97], v[152:155], v[200:203], v[94:97]
	v_mfma_f32_16x16x32_bf16 v[90:93], v[160:163], v[200:203], v[90:93]
	v_mfma_f32_16x16x32_bf16 v[74:77], v[160:163], v[208:211], v[74:77]
	v_mfma_f32_16x16x32_bf16 v[78:81], v[152:155], v[208:211], v[78:81]
	v_mfma_f32_16x16x32_bf16 v[126:129], v[156:159], v[188:191], v[126:129]
	v_mfma_f32_16x16x32_bf16 v[122:125], v[164:167], v[188:191], v[122:125]
	v_mfma_f32_16x16x32_bf16 v[106:109], v[164:167], v[196:199], v[106:109]
	v_mfma_f32_16x16x32_bf16 v[110:113], v[156:159], v[196:199], v[110:113]
	v_mfma_f32_16x16x32_bf16 v[94:97], v[156:159], v[204:207], v[94:97]
	v_mfma_f32_16x16x32_bf16 v[90:93], v[164:167], v[204:207], v[90:93]
	v_mfma_f32_16x16x32_bf16 v[74:77], v[164:167], v[212:215], v[74:77]
	v_mfma_f32_16x16x32_bf16 v[78:81], v[156:159], v[212:215], v[78:81]
	s_setprio 2
	s_setprio 0
	v_mfma_f32_16x16x32_bf16 v[118:121], v[168:171], v[184:187], v[118:121]
	v_mfma_f32_16x16x32_bf16 v[114:117], v[176:179], v[184:187], v[114:117]
	v_mfma_f32_16x16x32_bf16 v[98:101], v[176:179], v[192:195], v[98:101]
	v_mfma_f32_16x16x32_bf16 v[102:105], v[168:171], v[192:195], v[102:105]
	v_mfma_f32_16x16x32_bf16 v[86:89], v[168:171], v[200:203], v[86:89]
	v_mfma_f32_16x16x32_bf16 v[82:85], v[176:179], v[200:203], v[82:85]
	v_mfma_f32_16x16x32_bf16 v[66:69], v[176:179], v[208:211], v[66:69]
	v_mfma_f32_16x16x32_bf16 v[70:73], v[168:171], v[208:211], v[70:73]
	v_mfma_f32_16x16x32_bf16 v[118:121], v[172:175], v[188:191], v[118:121]
	v_mfma_f32_16x16x32_bf16 v[114:117], v[180:183], v[188:191], v[114:117]
	v_mfma_f32_16x16x32_bf16 v[98:101], v[180:183], v[196:199], v[98:101]
	v_mfma_f32_16x16x32_bf16 v[102:105], v[172:175], v[196:199], v[102:105]
	v_mfma_f32_16x16x32_bf16 v[86:89], v[172:175], v[204:207], v[86:89]
	v_mfma_f32_16x16x32_bf16 v[82:85], v[180:183], v[204:207], v[82:85]
	v_mfma_f32_16x16x32_bf16 v[66:69], v[180:183], v[212:215], v[66:69]
	v_mfma_f32_16x16x32_bf16 v[70:73], v[172:175], v[212:215], v[70:73]
	s_setprio 2
	s_barrier
; #define PG8_STAGE(bufoff, gbase, voff) do { _Pragma("unroll") for (int _i = 0; _i < 2; ++_i) \
;         __builtin_amdgcn_global_load_lds((const unsigned*)((const char*)(gbase) + (voff)[_i]), (LAS unsigned*)(lds + (bufoff) + ldsw + _i * 8192), 16, 0, 0); } while (0)
; #define PG8_LDA(dst, b, h) do { _Pragma("unroll") for (int m = 0; m < 4; ++m) _Pragma("unroll") for (int k = 0; k < 2; ++k) dst[m][k] = *(const LAS bf16x8*)(lds + PG8_SA(b, h) + aoff + m * 2048 + k * 1024); } while (0)
; #define PG8_MMA(ai, bj, At, Bt) do { __builtin_amdgcn_s_setprio(1); _Pragma("unroll") for (int m = 0; m < 4; ++m) _Pragma("unroll") for (int n = 0; n < 2; ++n) _Pragma("unroll") for (int k = 0; k < 2; ++k) \
;         acc[ai][bj][m][n] = __builtin_amdgcn_mfma_f32_16x16x32_bf16(Bt[n][k], At[m][k], acc[ai][bj][m][n], 0, 0, 0); __builtin_amdgcn_s_setprio(0); } while (0)
; #define PG8_WAIT_V(n) asm volatile("s_waitcnt vmcnt(" #n ")" ::: "memory")
; #define PG8_WAIT_L(n) asm volatile("s_waitcnt lgkmcnt(" #n ")" ::: "memory")
; #define PG8_BAR __builtin_amdgcn_s_barrier()
; #define PG8_SCHED __builtin_amdgcn_sched_barrier(0)
; template <class Epi>
; __device__ __forceinline__ void gemm_phase(LAS unsigned char* lds, const Gemm g, int G, int c, const Epi& E) {
;     ...
;             PG8_LDA(At, 1, 1); PG8_STAGE(PG8_SB(1, 0), b3, voffB); PG8_STAGE(PG8_SB(1, 1), b3 + hstepB, voffB); PG8_STAGE(PG8_SA(1, 0), a3, voffA);
;             PG8_WAIT_V(8); PG8_WAIT_L(0); PG8_BAR; PG8_MMA(1, 0, At, B0); PG8_MMA(1, 1, At, B1); PG8_BAR; PG8_SCHED;
;         }
;         if (wr == 0) PG8_BAR;
	s_add_i32 s33, s33, s46
	v_lshl_add_u64 v[216:217], v[216:217], 0, s[12:13]
	s_mov_b32 m0, s33
	ds_read_b128 v[184:187], v150 offset:49152
	ds_read_b128 v[188:191], v150 offset:50176
	ds_read_b128 v[192:195], v150 offset:51200
	ds_read_b128 v[196:199], v150 offset:52224
	ds_read_b128 v[200:203], v150 offset:53248
	ds_read_b128 v[204:207], v150 offset:54272
	ds_read_b128 v[208:211], v150 offset:55296
	ds_read_b128 v[212:215], v150 offset:56320
	global_load_lds_dwordx4 v[216:217], off
	s_add_i32 m0, s33, 0x2000
	s_add_u32 s38, s38, 0x40080
	v_lshl_add_u64 v[216:217], v[218:219], 0, s[12:13]
	s_addc_u32 s39, s39, 0
	s_add_i32 s33, s62, s46
	global_load_lds_dwordx4 v[216:217], off
	v_lshl_add_u64 v[216:217], s[38:39], 0, v[134:135]
	s_mov_b32 m0, s33
	s_nop 0
	global_load_lds_dwordx4 v[216:217], off
	v_lshl_add_u64 v[216:217], s[38:39], 0, v[130:131]
	s_add_i32 m0, s33, 0x2000
	s_nop 0
	global_load_lds_dwordx4 v[216:217], off
	v_lshl_add_u64 v[216:217], v[220:221], 0, s[12:13]
	s_mov_b32 m0, s57
	s_nop 0
	global_load_lds_dwordx4 v[216:217], off
	v_lshl_add_u64 v[216:217], v[222:223], 0, s[12:13]
	s_mov_b32 m0, s58
	s_nop 0
	global_load_lds_dwordx4 v[216:217], off
	s_waitcnt vmcnt(8)
	s_waitcnt lgkmcnt(0)
	s_barrier
	s_setprio 0
	s_waitcnt lgkmcnt(0)
	v_mfma_f32_16x16x32_bf16 v[62:65], v[152:155], v[184:187], v[62:65]
	v_mfma_f32_16x16x32_bf16 v[58:61], v[160:163], v[184:187], v[58:61]
	v_mfma_f32_16x16x32_bf16 v[42:45], v[160:163], v[192:195], v[42:45]
	v_mfma_f32_16x16x32_bf16 v[46:49], v[152:155], v[192:195], v[46:49]
	v_mfma_f32_16x16x32_bf16 v[30:33], v[152:155], v[200:203], v[30:33]
	v_mfma_f32_16x16x32_bf16 v[26:29], v[160:163], v[200:203], v[26:29]
	v_mfma_f32_16x16x32_bf16 v[10:13], v[160:163], v[208:211], v[10:13]
	v_mfma_f32_16x16x32_bf16 v[14:17], v[152:155], v[208:211], v[14:17]
	v_mfma_f32_16x16x32_bf16 v[62:65], v[156:159], v[188:191], v[62:65]
	v_mfma_f32_16x16x32_bf16 v[58:61], v[164:167], v[188:191], v[58:61]
	v_mfma_f32_16x16x32_bf16 v[42:45], v[164:167], v[196:199], v[42:45]
	v_mfma_f32_16x16x32_bf16 v[46:49], v[156:159], v[196:199], v[46:49]
	v_mfma_f32_16x16x32_bf16 v[30:33], v[156:159], v[204:207], v[30:33]
	v_mfma_f32_16x16x32_bf16 v[26:29], v[164:167], v[204:207], v[26:29]
	v_mfma_f32_16x16x32_bf16 v[10:13], v[164:167], v[212:215], v[10:13]
	v_mfma_f32_16x16x32_bf16 v[14:17], v[156:159], v[212:215], v[14:17]
	s_setprio 2
	s_setprio 0
	v_mfma_f32_16x16x32_bf16 v[54:57], v[168:171], v[184:187], v[54:57]
	v_mfma_f32_16x16x32_bf16 v[50:53], v[176:179], v[184:187], v[50:53]
	v_mfma_f32_16x16x32_bf16 v[34:37], v[176:179], v[192:195], v[34:37]
	v_mfma_f32_16x16x32_bf16 v[38:41], v[168:171], v[192:195], v[38:41]
	v_mfma_f32_16x16x32_bf16 v[22:25], v[168:171], v[200:203], v[22:25]
	v_mfma_f32_16x16x32_bf16 v[18:21], v[176:179], v[200:203], v[18:21]
	v_mfma_f32_16x16x32_bf16 v[2:5], v[176:179], v[208:211], v[2:5]
	v_mfma_f32_16x16x32_bf16 v[6:9], v[168:171], v[208:211], v[6:9]
	v_mfma_f32_16x16x32_bf16 v[54:57], v[172:175], v[188:191], v[54:57]
	v_mfma_f32_16x16x32_bf16 v[50:53], v[180:183], v[188:191], v[50:53]
	v_mfma_f32_16x16x32_bf16 v[34:37], v[180:183], v[196:199], v[34:37]
	v_mfma_f32_16x16x32_bf16 v[38:41], v[172:175], v[196:199], v[38:41]
	v_mfma_f32_16x16x32_bf16 v[22:25], v[172:175], v[204:207], v[22:25]
	v_mfma_f32_16x16x32_bf16 v[18:21], v[180:183], v[204:207], v[18:21]
	v_mfma_f32_16x16x32_bf16 v[2:5], v[180:183], v[212:215], v[2:5]
	v_mfma_f32_16x16x32_bf16 v[6:9], v[172:175], v[212:215], v[6:9]
	s_setprio 2
	s_barrier
	s_add_i32 s80, s80, 2
	s_add_u32 s4, s4, 0x100
	s_addc_u32 s5, s5, 0
	s_add_u32 s78, s78, 0x100
	s_addc_u32 s79, s79, 0
	s_cmp_gt_u32 s80, 13
	s_cbranch_scc0 .LBB0_1058
	s_and_b64 vcc, exec, s[14:15]
	s_cbranch_vccz .LBB0_1061
	s_barrier

; #define PG8_STAGE(bufoff, gbase, voff) do { _Pragma("unroll") for (int _i = 0; _i < 2; ++_i) \
;         __builtin_amdgcn_global_load_lds((const unsigned*)((const char*)(gbase) + (voff)[_i]), (LAS unsigned*)(lds + (bufoff) + ldsw + _i * 8192), 16, 0, 0); } while (0)
; #define PG8_LDA(dst, b, h) do { _Pragma("unroll") for (int m = 0; m < 4; ++m) _Pragma("unroll") for (int k = 0; k < 2; ++k) dst[m][k] = *(const LAS bf16x8*)(lds + PG8_SA(b, h) + aoff + m * 2048 + k * 1024); } while (0)
; #define PG8_LDB(dst, b, h) do { _Pragma("unroll") for (int n = 0; n < 2; ++n) _Pragma("unroll") for (int k = 0; k < 2; ++k) dst[n][k] = *(const LAS bf16x8*)(lds + PG8_SB(b, h) + boff + n * 2048 + k * 1024); } while (0)
; #define PG8_MMA(ai, bj, At, Bt) do { __builtin_amdgcn_s_setprio(1); _Pragma("unroll") for (int m = 0; m < 4; ++m) _Pragma("unroll") for (int n = 0; n < 2; ++n) _Pragma("unroll") for (int k = 0; k < 2; ++k) \
;         acc[ai][bj][m][n] = __builtin_amdgcn_mfma_f32_16x16x32_bf16(Bt[n][k], At[m][k], acc[ai][bj][m][n], 0, 0, 0); __builtin_amdgcn_s_setprio(0); } while (0)
; #define PG8_WAIT_V(n) asm volatile("s_waitcnt vmcnt(" #n ")" ::: "memory")
; #define PG8_WAIT_L(n) asm volatile("s_waitcnt lgkmcnt(" #n ")" ::: "memory")
; #define PG8_BAR __builtin_amdgcn_s_barrier()
; #define PG8_SCHED __builtin_amdgcn_sched_barrier(0)
; template <class Epi>
; __device__ __forceinline__ void gemm_phase(LAS unsigned char* lds, const Gemm g, int G, int c, const Epi& E) {
;     ...
;         for (int t = 0; t < nt; t += 2) {
;             const bool last = (t == nt - 2);
;             const char* a1 = cA + (size_t)(t + 1) * kstep;
;             const char* a2 = last ? nA : cA + (size_t)(t + 2) * kstep; const char* b2 = last ? nB : cB + (size_t)(t + 2) * kstep;
;             const char* a3 = a2 + kstep; const char* b3 = b2 + kstep;
;             PG8_LDB(B0, 0, 0); PG8_LDB(B1, 0, 1); PG8_SCHED; PG8_LDA(At, 0, 0); PG8_STAGE(PG8_SA(1, 1), a1 + hstepA, voffA);
;             PG8_WAIT_V(8); PG8_WAIT_L(0); PG8_BAR; PG8_MMA(0, 0, At, B0); PG8_MMA(0, 1, At, B1); PG8_BAR; PG8_SCHED;
;             PG8_LDA(At, 0, 1); PG8_STAGE(PG8_SB(0, 0), b2, voffB); PG8_STAGE(PG8_SB(0, 1), b2 + hstepB, voffB); PG8_STAGE(PG8_SA(0, 0), a2, voffA);
.LBB0_1143:
	ds_read_b128 v[122:125], v168
	ds_read_b128 v[126:129], v168 offset:1024
	ds_read_b128 v[130:133], v168 offset:2048
	ds_read_b128 v[134:137], v168 offset:3072
	ds_read_b128 v[162:165], v169
	ds_read_b128 v[172:175], v169 offset:1024
	ds_read_b128 v[176:179], v169 offset:2048
	ds_read_b128 v[180:183], v169 offset:3072
	s_add_u32 s18, s16, 0x100
	s_addc_u32 s19, s17, 0
	s_cmp_eq_u32 s68, 40
	s_cselect_b32 s23, s5, s19
	s_cselect_b32 s22, s4, s18
	s_cselect_b32 s21, s15, s67
	s_cselect_b32 s20, s14, s66
	v_lshl_add_u64 v[216:217], s[16:17], 0, v[154:155]
	s_add_i32 m0, s38, 0xc000
	ds_read_b128 v[184:187], v170
	ds_read_b128 v[188:191], v170 offset:1024
	ds_read_b128 v[192:195], v170 offset:2048
	ds_read_b128 v[196:199], v170 offset:3072
	ds_read_b128 v[200:203], v170 offset:4096
	ds_read_b128 v[204:207], v170 offset:5120
	ds_read_b128 v[208:211], v170 offset:6144
	ds_read_b128 v[212:215], v170 offset:7168
	global_load_lds_dwordx4 v[216:217], off
	v_lshl_add_u64 v[216:217], s[16:17], 0, v[156:157]
	s_add_i32 m0, s38, 0xe000
	s_nop 0
	global_load_lds_dwordx4 v[216:217], off
	s_waitcnt vmcnt(8)
	s_waitcnt lgkmcnt(0)
	s_barrier
	s_setprio 0
	s_waitcnt lgkmcnt(0)
	v_mfma_f32_16x16x32_bf16 v[142:145], v[122:125], v[184:187], v[142:145]
	v_mfma_f32_16x16x32_bf16 v[138:141], v[130:133], v[184:187], v[138:141]
	v_mfma_f32_16x16x32_bf16 v[106:109], v[130:133], v[192:195], v[106:109]
	v_mfma_f32_16x16x32_bf16 v[118:121], v[122:125], v[192:195], v[118:121]
	v_mfma_f32_16x16x32_bf16 v[102:105], v[122:125], v[200:203], v[102:105]
	v_mfma_f32_16x16x32_bf16 v[90:93], v[130:133], v[200:203], v[90:93]
	v_mfma_f32_16x16x32_bf16 v[74:77], v[130:133], v[208:211], v[74:77]
	v_mfma_f32_16x16x32_bf16 v[86:89], v[122:125], v[208:211], v[86:89]
	v_mfma_f32_16x16x32_bf16 v[142:145], v[126:129], v[188:191], v[142:145]
	v_mfma_f32_16x16x32_bf16 v[138:141], v[134:137], v[188:191], v[138:141]
	v_mfma_f32_16x16x32_bf16 v[106:109], v[134:137], v[196:199], v[106:109]
	v_mfma_f32_16x16x32_bf16 v[118:121], v[126:129], v[196:199], v[118:121]
	v_mfma_f32_16x16x32_bf16 v[102:105], v[126:129], v[204:207], v[102:105]
	v_mfma_f32_16x16x32_bf16 v[90:93], v[134:137], v[204:207], v[90:93]
	v_mfma_f32_16x16x32_bf16 v[74:77], v[134:137], v[212:215], v[74:77]
	v_mfma_f32_16x16x32_bf16 v[86:89], v[126:129], v[212:215], v[86:89]
	s_setprio 2
	s_setprio 0
	v_mfma_f32_16x16x32_bf16 v[114:117], v[162:165], v[184:187], v[114:117]
	v_mfma_f32_16x16x32_bf16 v[110:113], v[176:179], v[184:187], v[110:113]
	v_mfma_f32_16x16x32_bf16 v[94:97], v[176:179], v[192:195], v[94:97]
	v_mfma_f32_16x16x32_bf16 v[98:101], v[162:165], v[192:195], v[98:101]
	v_mfma_f32_16x16x32_bf16 v[82:85], v[162:165], v[200:203], v[82:85]
	v_mfma_f32_16x16x32_bf16 v[78:81], v[176:179], v[200:203], v[78:81]
	v_mfma_f32_16x16x32_bf16 v[66:69], v[176:179], v[208:211], v[66:69]
	v_mfma_f32_16x16x32_bf16 v[70:73], v[162:165], v[208:211], v[70:73]
	v_mfma_f32_16x16x32_bf16 v[114:117], v[172:175], v[188:191], v[114:117]
	v_mfma_f32_16x16x32_bf16 v[110:113], v[180:183], v[188:191], v[110:113]
	v_mfma_f32_16x16x32_bf16 v[94:97], v[180:183], v[196:199], v[94:97]
	v_mfma_f32_16x16x32_bf16 v[98:101], v[172:175], v[196:199], v[98:101]
	v_mfma_f32_16x16x32_bf16 v[82:85], v[172:175], v[204:207], v[82:85]
	v_mfma_f32_16x16x32_bf16 v[78:81], v[180:183], v[204:207], v[78:81]
	v_mfma_f32_16x16x32_bf16 v[66:69], v[180:183], v[212:215], v[66:69]
	v_mfma_f32_16x16x32_bf16 v[70:73], v[172:175], v[212:215], v[70:73]
	s_setprio 2
	s_barrier
	s_add_i32 s16, s54, s36
	v_lshl_add_u64 v[216:217], s[20:21], 0, v[150:151]
	s_mov_b32 m0, s16
	ds_read_b128 v[184:187], v170 offset:16384
	ds_read_b128 v[188:191], v170 offset:17408
	ds_read_b128 v[192:195], v170 offset:18432
	ds_read_b128 v[196:199], v170 offset:19456
	ds_read_b128 v[200:203], v170 offset:20480
	ds_read_b128 v[204:207], v170 offset:21504
	ds_read_b128 v[208:211], v170 offset:22528
	ds_read_b128 v[212:215], v170 offset:23552
	global_load_lds_dwordx4 v[216:217], off
	s_add_i32 m0, s16, 0x2000
	s_add_u32 s16, s20, 0xb0000
	v_lshl_add_u64 v[218:219], s[20:21], 0, v[146:147]
	s_addc_u32 s17, s21, 0
	s_add_i32 s33, s55, s36
	global_load_lds_dwordx4 v[218:219], off
	v_lshl_add_u64 v[220:221], s[16:17], 0, v[150:151]
	s_mov_b32 m0, s33
	v_lshl_add_u64 v[222:223], s[22:23], 0, v[148:149]
	global_load_lds_dwordx4 v[220:221], off
	v_lshl_add_u64 v[220:221], s[16:17], 0, v[146:147]
	s_add_i32 m0, s33, 0x2000
	s_nop 0
	global_load_lds_dwordx4 v[220:221], off
	v_lshl_add_u64 v[220:221], s[22:23], 0, v[152:153]
	s_mov_b32 m0, s38
	s_nop 0
	global_load_lds_dwordx4 v[220:221], off
	s_mov_b32 m0, s39
	s_nop 0
	global_load_lds_dwordx4 v[222:223], off
	s_waitcnt vmcnt(8)
	s_waitcnt lgkmcnt(0)
	s_barrier
; #define PG8_STAGE(bufoff, gbase, voff) do { _Pragma("unroll") for (int _i = 0; _i < 2; ++_i) \
;         __builtin_amdgcn_global_load_lds((const unsigned*)((const char*)(gbase) + (voff)[_i]), (LAS unsigned*)(lds + (bufoff) + ldsw + _i * 8192), 16, 0, 0); } while (0)
; #define PG8_LDA(dst, b, h) do { _Pragma("unroll") for (int m = 0; m < 4; ++m) _Pragma("unroll") for (int k = 0; k < 2; ++k) dst[m][k] = *(const LAS bf16x8*)(lds + PG8_SA(b, h) + aoff + m * 2048 + k * 1024); } while (0)
; #define PG8_LDB(dst, b, h) do { _Pragma("unroll") for (int n = 0; n < 2; ++n) _Pragma("unroll") for (int k = 0; k < 2; ++k) dst[n][k] = *(const LAS bf16x8*)(lds + PG8_SB(b, h) + boff + n * 2048 + k * 1024); } while (0)
; #define PG8_MMA(ai, bj, At, Bt) do { __builtin_amdgcn_s_setprio(1); _Pragma("unroll") for (int m = 0; m < 4; ++m) _Pragma("unroll") for (int n = 0; n < 2; ++n) _Pragma("unroll") for (int k = 0; k < 2; ++k) \
;         acc[ai][bj][m][n] = __builtin_amdgcn_mfma_f32_16x16x32_bf16(Bt[n][k], At[m][k], acc[ai][bj][m][n], 0, 0, 0); __builtin_amdgcn_s_setprio(0); } while (0)
; #define PG8_WAIT_V(n) asm volatile("s_waitcnt vmcnt(" #n ")" ::: "memory")
; #define PG8_WAIT_L(n) asm volatile("s_waitcnt lgkmcnt(" #n ")" ::: "memory")
; #define PG8_BAR __builtin_amdgcn_s_barrier()
; #define PG8_SCHED __builtin_amdgcn_sched_barrier(0)
; template <class Epi>
; __device__ __forceinline__ void gemm_phase(LAS unsigned char* lds, const Gemm g, int G, int c, const Epi& E) {
;     ...
;             PG8_WAIT_V(8); PG8_WAIT_L(0); PG8_BAR; PG8_MMA(1, 0, At, B0); PG8_MMA(1, 1, At, B1); PG8_BAR; PG8_SCHED;
;             PG8_LDB(B0, 1, 0); PG8_LDB(B1, 1, 1); PG8_SCHED; PG8_LDA(At, 1, 0); PG8_STAGE(PG8_SA(0, 1), a2 + hstepA, voffA);
;             PG8_WAIT_V(8); PG8_WAIT_L(0); PG8_BAR; PG8_MMA(0, 0, At, B0); PG8_MMA(0, 1, At, B1); PG8_BAR; PG8_SCHED;
	s_setprio 0
	s_waitcnt lgkmcnt(0)
	v_mfma_f32_16x16x32_bf16 v[62:65], v[122:125], v[184:187], v[62:65]
	v_mfma_f32_16x16x32_bf16 v[58:61], v[130:133], v[184:187], v[58:61]
	v_mfma_f32_16x16x32_bf16 v[42:45], v[130:133], v[192:195], v[42:45]
	v_mfma_f32_16x16x32_bf16 v[54:57], v[122:125], v[192:195], v[54:57]
	v_mfma_f32_16x16x32_bf16 v[38:41], v[122:125], v[200:203], v[38:41]
	v_mfma_f32_16x16x32_bf16 v[26:29], v[130:133], v[200:203], v[26:29]
	v_mfma_f32_16x16x32_bf16 v[10:13], v[130:133], v[208:211], v[10:13]
	v_mfma_f32_16x16x32_bf16 v[22:25], v[122:125], v[208:211], v[22:25]
	v_mfma_f32_16x16x32_bf16 v[62:65], v[126:129], v[188:191], v[62:65]
	v_mfma_f32_16x16x32_bf16 v[58:61], v[134:137], v[188:191], v[58:61]
	v_mfma_f32_16x16x32_bf16 v[42:45], v[134:137], v[196:199], v[42:45]
	v_mfma_f32_16x16x32_bf16 v[54:57], v[126:129], v[196:199], v[54:57]
	v_mfma_f32_16x16x32_bf16 v[38:41], v[126:129], v[204:207], v[38:41]
	v_mfma_f32_16x16x32_bf16 v[26:29], v[134:137], v[204:207], v[26:29]
	v_mfma_f32_16x16x32_bf16 v[10:13], v[134:137], v[212:215], v[10:13]
	v_mfma_f32_16x16x32_bf16 v[22:25], v[126:129], v[212:215], v[22:25]
	s_setprio 2
	s_setprio 0
	v_mfma_f32_16x16x32_bf16 v[50:53], v[162:165], v[184:187], v[50:53]
	v_mfma_f32_16x16x32_bf16 v[46:49], v[176:179], v[184:187], v[46:49]
	v_mfma_f32_16x16x32_bf16 v[30:33], v[176:179], v[192:195], v[30:33]
	v_mfma_f32_16x16x32_bf16 v[34:37], v[162:165], v[192:195], v[34:37]
	v_mfma_f32_16x16x32_bf16 v[18:21], v[162:165], v[200:203], v[18:21]
	v_mfma_f32_16x16x32_bf16 v[14:17], v[176:179], v[200:203], v[14:17]
	v_mfma_f32_16x16x32_bf16 v[2:5], v[176:179], v[208:211], v[2:5]
	v_mfma_f32_16x16x32_bf16 v[6:9], v[162:165], v[208:211], v[6:9]
	v_mfma_f32_16x16x32_bf16 v[50:53], v[172:175], v[188:191], v[50:53]
	v_mfma_f32_16x16x32_bf16 v[46:49], v[180:183], v[188:191], v[46:49]
	v_mfma_f32_16x16x32_bf16 v[30:33], v[180:183], v[196:199], v[30:33]
	v_mfma_f32_16x16x32_bf16 v[34:37], v[172:175], v[196:199], v[34:37]
	v_mfma_f32_16x16x32_bf16 v[18:21], v[172:175], v[204:207], v[18:21]
	v_mfma_f32_16x16x32_bf16 v[14:17], v[180:183], v[204:207], v[14:17]
	v_mfma_f32_16x16x32_bf16 v[2:5], v[180:183], v[212:215], v[2:5]
	v_mfma_f32_16x16x32_bf16 v[6:9], v[172:175], v[212:215], v[6:9]
	s_setprio 2
	s_barrier
	s_add_i32 s33, 0, 0x18000
	s_add_i32 s62, 0, 0x1c000
	v_add_u32_e32 v134, s33, v167
	v_add_u32_e32 v171, s62, v167
	ds_read_b128 v[122:125], v134
	ds_read_b128 v[126:129], v134 offset:1024
	ds_read_b128 v[130:133], v134 offset:2048
	ds_read_b128 v[134:137], v134 offset:3072
	ds_read_b128 v[162:165], v171
	ds_read_b128 v[172:175], v171 offset:1024
	ds_read_b128 v[176:179], v171 offset:2048
	ds_read_b128 v[180:183], v171 offset:3072
	s_add_u32 s16, s22, 0xb0000
	s_addc_u32 s17, s23, 0
	s_mov_b32 m0, s40
	v_lshl_add_u64 v[224:225], s[16:17], 0, v[152:153]
	ds_read_b128 v[184:187], v170 offset:32768
	ds_read_b128 v[188:191], v170 offset:33792
	ds_read_b128 v[192:195], v170 offset:34816
	ds_read_b128 v[196:199], v170 offset:35840
	ds_read_b128 v[200:203], v170 offset:36864
	ds_read_b128 v[204:207], v170 offset:37888
	ds_read_b128 v[208:211], v170 offset:38912
	ds_read_b128 v[212:215], v170 offset:39936
	global_load_lds_dwordx4 v[224:225], off
	v_lshl_add_u64 v[224:225], s[16:17], 0, v[148:149]
	s_mov_b32 m0, s41
	s_nop 0
	global_load_lds_dwordx4 v[224:225], off
	s_waitcnt vmcnt(8)
	s_waitcnt lgkmcnt(0)
	s_barrier
	s_setprio 0
	s_waitcnt lgkmcnt(0)
	v_mfma_f32_16x16x32_bf16 v[142:145], v[122:125], v[184:187], v[142:145]
	v_mfma_f32_16x16x32_bf16 v[138:141], v[130:133], v[184:187], v[138:141]
	v_mfma_f32_16x16x32_bf16 v[106:109], v[130:133], v[192:195], v[106:109]
	v_mfma_f32_16x16x32_bf16 v[118:121], v[122:125], v[192:195], v[118:121]
	v_mfma_f32_16x16x32_bf16 v[102:105], v[122:125], v[200:203], v[102:105]
	v_mfma_f32_16x16x32_bf16 v[90:93], v[130:133], v[200:203], v[90:93]
	v_mfma_f32_16x16x32_bf16 v[74:77], v[130:133], v[208:211], v[74:77]
	v_mfma_f32_16x16x32_bf16 v[86:89], v[122:125], v[208:211], v[86:89]
	v_mfma_f32_16x16x32_bf16 v[142:145], v[126:129], v[188:191], v[142:145]
	v_mfma_f32_16x16x32_bf16 v[138:141], v[134:137], v[188:191], v[138:141]
	v_mfma_f32_16x16x32_bf16 v[106:109], v[134:137], v[196:199], v[106:109]
	v_mfma_f32_16x16x32_bf16 v[118:121], v[126:129], v[196:199], v[118:121]
	v_mfma_f32_16x16x32_bf16 v[102:105], v[126:129], v[204:207], v[102:105]
	v_mfma_f32_16x16x32_bf16 v[90:93], v[134:137], v[204:207], v[90:93]
	v_mfma_f32_16x16x32_bf16 v[74:77], v[134:137], v[212:215], v[74:77]
	v_mfma_f32_16x16x32_bf16 v[86:89], v[126:129], v[212:215], v[86:89]
	s_setprio 2
	s_setprio 0
	v_mfma_f32_16x16x32_bf16 v[114:117], v[162:165], v[184:187], v[114:117]
	v_mfma_f32_16x16x32_bf16 v[110:113], v[176:179], v[184:187], v[110:113]
	v_mfma_f32_16x16x32_bf16 v[94:97], v[176:179], v[192:195], v[94:97]
	v_mfma_f32_16x16x32_bf16 v[98:101], v[162:165], v[192:195], v[98:101]
	v_mfma_f32_16x16x32_bf16 v[82:85], v[162:165], v[200:203], v[82:85]
	v_mfma_f32_16x16x32_bf16 v[78:81], v[176:179], v[200:203], v[78:81]
	v_mfma_f32_16x16x32_bf16 v[66:69], v[176:179], v[208:211], v[66:69]
	v_mfma_f32_16x16x32_bf16 v[70:73], v[162:165], v[208:211], v[70:73]
	v_mfma_f32_16x16x32_bf16 v[114:117], v[172:175], v[188:191], v[114:117]
	v_mfma_f32_16x16x32_bf16 v[110:113], v[180:183], v[188:191], v[110:113]
	v_mfma_f32_16x16x32_bf16 v[94:97], v[180:183], v[196:199], v[94:97]
	v_mfma_f32_16x16x32_bf16 v[98:101], v[172:175], v[196:199], v[98:101]
	v_mfma_f32_16x16x32_bf16 v[82:85], v[172:175], v[204:207], v[82:85]
	v_mfma_f32_16x16x32_bf16 v[78:81], v[180:183], v[204:207], v[78:81]
	v_mfma_f32_16x16x32_bf16 v[66:69], v[180:183], v[212:215], v[66:69]
	v_mfma_f32_16x16x32_bf16 v[70:73], v[172:175], v[212:215], v[70:73]
	s_setprio 2
	s_barrier
; #define PG8_STAGE(bufoff, gbase, voff) do { _Pragma("unroll") for (int _i = 0; _i < 2; ++_i) \
;         __builtin_amdgcn_global_load_lds((const unsigned*)((const char*)(gbase) + (voff)[_i]), (LAS unsigned*)(lds + (bufoff) + ldsw + _i * 8192), 16, 0, 0); } while (0)
; #define PG8_LDA(dst, b, h) do { _Pragma("unroll") for (int m = 0; m < 4; ++m) _Pragma("unroll") for (int k = 0; k < 2; ++k) dst[m][k] = *(const LAS bf16x8*)(lds + PG8_SA(b, h) + aoff + m * 2048 + k * 1024); } while (0)
; #define PG8_MMA(ai, bj, At, Bt) do { __builtin_amdgcn_s_setprio(1); _Pragma("unroll") for (int m = 0; m < 4; ++m) _Pragma("unroll") for (int n = 0; n < 2; ++n) _Pragma("unroll") for (int k = 0; k < 2; ++k) \
;         acc[ai][bj][m][n] = __builtin_amdgcn_mfma_f32_16x16x32_bf16(Bt[n][k], At[m][k], acc[ai][bj][m][n], 0, 0, 0); __builtin_amdgcn_s_setprio(0); } while (0)
; #define PG8_WAIT_V(n) asm volatile("s_waitcnt vmcnt(" #n ")" ::: "memory")
; #define PG8_WAIT_L(n) asm volatile("s_waitcnt lgkmcnt(" #n ")" ::: "memory")
; #define PG8_BAR __builtin_amdgcn_s_barrier()
; #define PG8_SCHED __builtin_amdgcn_sched_barrier(0)
; template <class Epi>
; __device__ __forceinline__ void gemm_phase(LAS unsigned char* lds, const Gemm g, int G, int c, const Epi& E) {
;     ...
;             PG8_LDA(At, 1, 1); PG8_STAGE(PG8_SB(1, 0), b3, voffB); PG8_STAGE(PG8_SB(1, 1), b3 + hstepB, voffB); PG8_STAGE(PG8_SA(1, 0), a3, voffA);
;             PG8_WAIT_V(8); PG8_WAIT_L(0); PG8_BAR; PG8_MMA(1, 0, At, B0); PG8_MMA(1, 1, At, B1); PG8_BAR; PG8_SCHED;
;         }
;         if (wr == 0) PG8_BAR;
	s_add_i32 s16, s33, s36
	v_lshl_add_u64 v[216:217], v[216:217], 0, s[10:11]
	s_mov_b32 m0, s16
	ds_read_b128 v[184:187], v170 offset:49152
	ds_read_b128 v[188:191], v170 offset:50176
	ds_read_b128 v[192:195], v170 offset:51200
	ds_read_b128 v[196:199], v170 offset:52224
	ds_read_b128 v[200:203], v170 offset:53248
	ds_read_b128 v[204:207], v170 offset:54272
	ds_read_b128 v[208:211], v170 offset:55296
	ds_read_b128 v[212:215], v170 offset:56320
	global_load_lds_dwordx4 v[216:217], off
	s_add_i32 m0, s16, 0x2000
	s_add_u32 s16, s20, 0xb0080
	v_lshl_add_u64 v[216:217], v[218:219], 0, s[10:11]
	s_addc_u32 s17, s21, 0
	s_add_i32 s20, s62, s36
	global_load_lds_dwordx4 v[216:217], off
	v_lshl_add_u64 v[216:217], s[16:17], 0, v[150:151]
	s_mov_b32 m0, s20
	s_nop 0
	global_load_lds_dwordx4 v[216:217], off
	v_lshl_add_u64 v[216:217], s[16:17], 0, v[146:147]
	s_add_i32 m0, s20, 0x2000
	s_nop 0
	global_load_lds_dwordx4 v[216:217], off
	v_lshl_add_u64 v[216:217], v[220:221], 0, s[10:11]
	s_mov_b32 m0, s47
	s_nop 0
	global_load_lds_dwordx4 v[216:217], off
	v_lshl_add_u64 v[216:217], v[222:223], 0, s[10:11]
	s_mov_b32 m0, s52
	s_nop 0
	global_load_lds_dwordx4 v[216:217], off
	s_waitcnt vmcnt(8)
	s_waitcnt lgkmcnt(0)
	s_barrier
	s_setprio 0
	s_waitcnt lgkmcnt(0)
	v_mfma_f32_16x16x32_bf16 v[62:65], v[122:125], v[184:187], v[62:65]
	v_mfma_f32_16x16x32_bf16 v[58:61], v[130:133], v[184:187], v[58:61]
	v_mfma_f32_16x16x32_bf16 v[42:45], v[130:133], v[192:195], v[42:45]
	v_mfma_f32_16x16x32_bf16 v[54:57], v[122:125], v[192:195], v[54:57]
	v_mfma_f32_16x16x32_bf16 v[38:41], v[122:125], v[200:203], v[38:41]
	v_mfma_f32_16x16x32_bf16 v[26:29], v[130:133], v[200:203], v[26:29]
	v_mfma_f32_16x16x32_bf16 v[10:13], v[130:133], v[208:211], v[10:13]
	v_mfma_f32_16x16x32_bf16 v[22:25], v[122:125], v[208:211], v[22:25]
	v_mfma_f32_16x16x32_bf16 v[62:65], v[126:129], v[188:191], v[62:65]
	v_mfma_f32_16x16x32_bf16 v[58:61], v[134:137], v[188:191], v[58:61]
	v_mfma_f32_16x16x32_bf16 v[42:45], v[134:137], v[196:199], v[42:45]
	v_mfma_f32_16x16x32_bf16 v[54:57], v[126:129], v[196:199], v[54:57]
	v_mfma_f32_16x16x32_bf16 v[38:41], v[126:129], v[204:207], v[38:41]
	v_mfma_f32_16x16x32_bf16 v[26:29], v[134:137], v[204:207], v[26:29]
	v_mfma_f32_16x16x32_bf16 v[10:13], v[134:137], v[212:215], v[10:13]
	v_mfma_f32_16x16x32_bf16 v[22:25], v[126:129], v[212:215], v[22:25]
	s_setprio 2
	s_setprio 0
	v_mfma_f32_16x16x32_bf16 v[50:53], v[162:165], v[184:187], v[50:53]
	v_mfma_f32_16x16x32_bf16 v[46:49], v[176:179], v[184:187], v[46:49]
	v_mfma_f32_16x16x32_bf16 v[30:33], v[176:179], v[192:195], v[30:33]
	v_mfma_f32_16x16x32_bf16 v[34:37], v[162:165], v[192:195], v[34:37]
	v_mfma_f32_16x16x32_bf16 v[18:21], v[162:165], v[200:203], v[18:21]
	v_mfma_f32_16x16x32_bf16 v[14:17], v[176:179], v[200:203], v[14:17]
	v_mfma_f32_16x16x32_bf16 v[2:5], v[176:179], v[208:211], v[2:5]
	v_mfma_f32_16x16x32_bf16 v[6:9], v[162:165], v[208:211], v[6:9]
	v_mfma_f32_16x16x32_bf16 v[50:53], v[172:175], v[188:191], v[50:53]
	v_mfma_f32_16x16x32_bf16 v[46:49], v[180:183], v[188:191], v[46:49]
	v_mfma_f32_16x16x32_bf16 v[30:33], v[180:183], v[196:199], v[30:33]
	v_mfma_f32_16x16x32_bf16 v[34:37], v[172:175], v[196:199], v[34:37]
	v_mfma_f32_16x16x32_bf16 v[18:21], v[172:175], v[204:207], v[18:21]
	v_mfma_f32_16x16x32_bf16 v[14:17], v[180:183], v[204:207], v[14:17]
	v_mfma_f32_16x16x32_bf16 v[2:5], v[180:183], v[212:215], v[2:5]
	v_mfma_f32_16x16x32_bf16 v[6:9], v[172:175], v[212:215], v[6:9]
	s_setprio 2
	s_barrier
	s_add_i32 s68, s68, 2
	s_add_u32 s66, s66, 0x100
	s_addc_u32 s67, s67, 0
	s_cmp_gt_u32 s68, 41
	s_mov_b64 s[16:17], s[18:19]
	s_cbranch_scc0 .LBB0_1143
	s_and_b64 vcc, exec, s[12:13]
	s_cbranch_vccz .LBB0_1146
	s_barrier

; #define PG8_STAGE(bufoff, gbase, voff) do { _Pragma("unroll") for (int _i = 0; _i < 2; ++_i) \
;         __builtin_amdgcn_global_load_lds((const unsigned*)((const char*)(gbase) + (voff)[_i]), (LAS unsigned*)(lds + (bufoff) + ldsw + _i * 8192), 16, 0, 0); } while (0)
; #define PG8_LDA(dst, b, h) do { _Pragma("unroll") for (int m = 0; m < 4; ++m) _Pragma("unroll") for (int k = 0; k < 2; ++k) dst[m][k] = *(const LAS bf16x8*)(lds + PG8_SA(b, h) + aoff + m * 2048 + k * 1024); } while (0)
; #define PG8_LDB(dst, b, h) do { _Pragma("unroll") for (int n = 0; n < 2; ++n) _Pragma("unroll") for (int k = 0; k < 2; ++k) dst[n][k] = *(const LAS bf16x8*)(lds + PG8_SB(b, h) + boff + n * 2048 + k * 1024); } while (0)
; #define PG8_MMA(ai, bj, At, Bt) do { __builtin_amdgcn_s_setprio(1); _Pragma("unroll") for (int m = 0; m < 4; ++m) _Pragma("unroll") for (int n = 0; n < 2; ++n) _Pragma("unroll") for (int k = 0; k < 2; ++k) \
;         acc[ai][bj][m][n] = __builtin_amdgcn_mfma_f32_16x16x32_bf16(Bt[n][k], At[m][k], acc[ai][bj][m][n], 0, 0, 0); __builtin_amdgcn_s_setprio(0); } while (0)
; #define PG8_WAIT_V(n) asm volatile("s_waitcnt vmcnt(" #n ")" ::: "memory")
; #define PG8_WAIT_L(n) asm volatile("s_waitcnt lgkmcnt(" #n ")" ::: "memory")
; #define PG8_BAR __builtin_amdgcn_s_barrier()
; #define PG8_SCHED __builtin_amdgcn_sched_barrier(0)
; template <class Epi>
; __device__ __forceinline__ void gemm_phase(LAS unsigned char* lds, const Gemm g, int G, int c, const Epi& E) {
;     ...
;         for (int t = 0; t < nt; t += 2) {
;             const bool last = (t == nt - 2);
;             const char* a1 = cA + (size_t)(t + 1) * kstep;
;             const char* a2 = last ? nA : cA + (size_t)(t + 2) * kstep; const char* b2 = last ? nB : cB + (size_t)(t + 2) * kstep;
;             const char* a3 = a2 + kstep; const char* b3 = b2 + kstep;
;             PG8_LDB(B0, 0, 0); PG8_LDB(B1, 0, 1); PG8_SCHED; PG8_LDA(At, 0, 0); PG8_STAGE(PG8_SA(1, 1), a1 + hstepA, voffA);
;             PG8_WAIT_V(8); PG8_WAIT_L(0); PG8_BAR; PG8_MMA(0, 0, At, B0); PG8_MMA(0, 1, At, B1); PG8_BAR; PG8_SCHED;
;             PG8_LDA(At, 0, 1); PG8_STAGE(PG8_SB(0, 0), b2, voffB); PG8_STAGE(PG8_SB(0, 1), b2 + hstepB, voffB); PG8_STAGE(PG8_SA(0, 0), a2, voffA);
.LBB0_1297:
	ds_read_b128 v[146:149], v152
	ds_read_b128 v[158:161], v152 offset:1024
	ds_read_b128 v[162:165], v152 offset:2048
	ds_read_b128 v[166:169], v152 offset:3072
	ds_read_b128 v[170:173], v153
	ds_read_b128 v[174:177], v153 offset:1024
	ds_read_b128 v[178:181], v153 offset:2048
	ds_read_b128 v[182:185], v153 offset:3072
	s_add_u32 s33, s4, 0xfffc0080
	s_addc_u32 s46, s5, -1
	s_cmp_eq_u32 s81, 12
	s_cselect_b32 s49, s43, s46
	s_cselect_b32 s48, s42, s33
	s_cselect_b32 s47, s7, s80
	s_cselect_b32 s46, s39, s41
	v_lshl_add_u64 v[218:219], s[4:5], 0, v[138:139]
	s_add_i32 m0, s11, 0xc000
	ds_read_b128 v[186:189], v154
	ds_read_b128 v[190:193], v154 offset:1024
	ds_read_b128 v[194:197], v154 offset:2048
	ds_read_b128 v[198:201], v154 offset:3072
	ds_read_b128 v[202:205], v154 offset:4096
	ds_read_b128 v[206:209], v154 offset:5120
	ds_read_b128 v[210:213], v154 offset:6144
	ds_read_b128 v[214:217], v154 offset:7168
	global_load_lds_dwordx4 v[218:219], off
	v_lshl_add_u64 v[218:219], s[4:5], 0, v[140:141]
	s_add_i32 m0, s11, 0xe000
	s_nop 0
	global_load_lds_dwordx4 v[218:219], off
	s_waitcnt vmcnt(8)
	s_waitcnt lgkmcnt(0)
	s_barrier
	s_setprio 0
	s_waitcnt lgkmcnt(0)
	v_mfma_f32_16x16x32_bf16 v[126:129], v[146:149], v[186:189], v[126:129]
	v_mfma_f32_16x16x32_bf16 v[122:125], v[162:165], v[186:189], v[122:125]
	v_mfma_f32_16x16x32_bf16 v[106:109], v[162:165], v[194:197], v[106:109]
	v_mfma_f32_16x16x32_bf16 v[110:113], v[146:149], v[194:197], v[110:113]
	v_mfma_f32_16x16x32_bf16 v[94:97], v[146:149], v[202:205], v[94:97]
	v_mfma_f32_16x16x32_bf16 v[90:93], v[162:165], v[202:205], v[90:93]
	v_mfma_f32_16x16x32_bf16 v[74:77], v[162:165], v[210:213], v[74:77]
	v_mfma_f32_16x16x32_bf16 v[78:81], v[146:149], v[210:213], v[78:81]
	v_mfma_f32_16x16x32_bf16 v[126:129], v[158:161], v[190:193], v[126:129]
	v_mfma_f32_16x16x32_bf16 v[122:125], v[166:169], v[190:193], v[122:125]
	v_mfma_f32_16x16x32_bf16 v[106:109], v[166:169], v[198:201], v[106:109]
	v_mfma_f32_16x16x32_bf16 v[110:113], v[158:161], v[198:201], v[110:113]
	v_mfma_f32_16x16x32_bf16 v[94:97], v[158:161], v[206:209], v[94:97]
	v_mfma_f32_16x16x32_bf16 v[90:93], v[166:169], v[206:209], v[90:93]
	v_mfma_f32_16x16x32_bf16 v[74:77], v[166:169], v[214:217], v[74:77]
	v_mfma_f32_16x16x32_bf16 v[78:81], v[158:161], v[214:217], v[78:81]
	s_setprio 2
	s_setprio 0
	v_mfma_f32_16x16x32_bf16 v[118:121], v[170:173], v[186:189], v[118:121]
	v_mfma_f32_16x16x32_bf16 v[114:117], v[178:181], v[186:189], v[114:117]
	v_mfma_f32_16x16x32_bf16 v[98:101], v[178:181], v[194:197], v[98:101]
	v_mfma_f32_16x16x32_bf16 v[102:105], v[170:173], v[194:197], v[102:105]
	v_mfma_f32_16x16x32_bf16 v[86:89], v[170:173], v[202:205], v[86:89]
	v_mfma_f32_16x16x32_bf16 v[82:85], v[178:181], v[202:205], v[82:85]
	v_mfma_f32_16x16x32_bf16 v[66:69], v[178:181], v[210:213], v[66:69]
	v_mfma_f32_16x16x32_bf16 v[70:73], v[170:173], v[210:213], v[70:73]
	v_mfma_f32_16x16x32_bf16 v[118:121], v[174:177], v[190:193], v[118:121]
	v_mfma_f32_16x16x32_bf16 v[114:117], v[182:185], v[190:193], v[114:117]
	v_mfma_f32_16x16x32_bf16 v[98:101], v[182:185], v[198:201], v[98:101]
	v_mfma_f32_16x16x32_bf16 v[102:105], v[174:177], v[198:201], v[102:105]
	v_mfma_f32_16x16x32_bf16 v[86:89], v[174:177], v[206:209], v[86:89]
	v_mfma_f32_16x16x32_bf16 v[82:85], v[182:185], v[206:209], v[82:85]
	v_mfma_f32_16x16x32_bf16 v[66:69], v[182:185], v[214:217], v[66:69]
	v_mfma_f32_16x16x32_bf16 v[70:73], v[174:177], v[214:217], v[70:73]
	s_setprio 2
	s_barrier
	s_add_i32 s33, s71, s56
	v_lshl_add_u64 v[218:219], s[46:47], 0, v[132:133]
	s_mov_b32 m0, s33
	ds_read_b128 v[186:189], v154 offset:16384
	ds_read_b128 v[190:193], v154 offset:17408
	ds_read_b128 v[194:197], v154 offset:18432
	ds_read_b128 v[198:201], v154 offset:19456
	ds_read_b128 v[202:205], v154 offset:20480
	ds_read_b128 v[206:209], v154 offset:21504
	ds_read_b128 v[210:213], v154 offset:22528
	ds_read_b128 v[214:217], v154 offset:23552
	global_load_lds_dwordx4 v[218:219], off
	s_add_i32 m0, s33, 0x2000
	s_add_u32 s62, s46, 0x40000
	v_lshl_add_u64 v[220:221], s[46:47], 0, v[136:137]
	s_addc_u32 s63, s47, 0
	s_add_i32 s33, s72, s56
	global_load_lds_dwordx4 v[220:221], off
	v_lshl_add_u64 v[222:223], s[62:63], 0, v[132:133]
	s_mov_b32 m0, s33
	v_lshl_add_u64 v[224:225], s[48:49], 0, v[134:135]
	global_load_lds_dwordx4 v[222:223], off
	v_lshl_add_u64 v[222:223], s[62:63], 0, v[136:137]
	s_add_i32 m0, s33, 0x2000
	s_nop 0
	global_load_lds_dwordx4 v[222:223], off
	v_lshl_add_u64 v[222:223], s[48:49], 0, v[130:131]
	s_mov_b32 m0, s11
	s_nop 0
	global_load_lds_dwordx4 v[222:223], off
	s_mov_b32 m0, s57
	s_nop 0
	global_load_lds_dwordx4 v[224:225], off
	s_waitcnt vmcnt(8)
	s_waitcnt lgkmcnt(0)
	s_barrier
; #define PG8_STAGE(bufoff, gbase, voff) do { _Pragma("unroll") for (int _i = 0; _i < 2; ++_i) \
;         __builtin_amdgcn_global_load_lds((const unsigned*)((const char*)(gbase) + (voff)[_i]), (LAS unsigned*)(lds + (bufoff) + ldsw + _i * 8192), 16, 0, 0); } while (0)
; #define PG8_LDA(dst, b, h) do { _Pragma("unroll") for (int m = 0; m < 4; ++m) _Pragma("unroll") for (int k = 0; k < 2; ++k) dst[m][k] = *(const LAS bf16x8*)(lds + PG8_SA(b, h) + aoff + m * 2048 + k * 1024); } while (0)
; #define PG8_LDB(dst, b, h) do { _Pragma("unroll") for (int n = 0; n < 2; ++n) _Pragma("unroll") for (int k = 0; k < 2; ++k) dst[n][k] = *(const LAS bf16x8*)(lds + PG8_SB(b, h) + boff + n * 2048 + k * 1024); } while (0)
; #define PG8_MMA(ai, bj, At, Bt) do { __builtin_amdgcn_s_setprio(1); _Pragma("unroll") for (int m = 0; m < 4; ++m) _Pragma("unroll") for (int n = 0; n < 2; ++n) _Pragma("unroll") for (int k = 0; k < 2; ++k) \
;         acc[ai][bj][m][n] = __builtin_amdgcn_mfma_f32_16x16x32_bf16(Bt[n][k], At[m][k], acc[ai][bj][m][n], 0, 0, 0); __builtin_amdgcn_s_setprio(0); } while (0)
; #define PG8_WAIT_V(n) asm volatile("s_waitcnt vmcnt(" #n ")" ::: "memory")
; #define PG8_WAIT_L(n) asm volatile("s_waitcnt lgkmcnt(" #n ")" ::: "memory")
; #define PG8_BAR __builtin_amdgcn_s_barrier()
; #define PG8_SCHED __builtin_amdgcn_sched_barrier(0)
; template <class Epi>
; __device__ __forceinline__ void gemm_phase(LAS unsigned char* lds, const Gemm g, int G, int c, const Epi& E) {
;     ...
;             PG8_WAIT_V(8); PG8_WAIT_L(0); PG8_BAR; PG8_MMA(1, 0, At, B0); PG8_MMA(1, 1, At, B1); PG8_BAR; PG8_SCHED;
;             PG8_LDB(B0, 1, 0); PG8_LDB(B1, 1, 1); PG8_SCHED; PG8_LDA(At, 1, 0); PG8_STAGE(PG8_SA(0, 1), a2 + hstepA, voffA);
;             PG8_WAIT_V(8); PG8_WAIT_L(0); PG8_BAR; PG8_MMA(0, 0, At, B0); PG8_MMA(0, 1, At, B1); PG8_BAR; PG8_SCHED;
	s_setprio 0
	s_waitcnt lgkmcnt(0)
	v_mfma_f32_16x16x32_bf16 v[62:65], v[146:149], v[186:189], v[62:65]
	v_mfma_f32_16x16x32_bf16 v[58:61], v[162:165], v[186:189], v[58:61]
	v_mfma_f32_16x16x32_bf16 v[42:45], v[162:165], v[194:197], v[42:45]
	v_mfma_f32_16x16x32_bf16 v[46:49], v[146:149], v[194:197], v[46:49]
	v_mfma_f32_16x16x32_bf16 v[30:33], v[146:149], v[202:205], v[30:33]
	v_mfma_f32_16x16x32_bf16 v[26:29], v[162:165], v[202:205], v[26:29]
	v_mfma_f32_16x16x32_bf16 v[10:13], v[162:165], v[210:213], v[10:13]
	v_mfma_f32_16x16x32_bf16 v[14:17], v[146:149], v[210:213], v[14:17]
	v_mfma_f32_16x16x32_bf16 v[62:65], v[158:161], v[190:193], v[62:65]
	v_mfma_f32_16x16x32_bf16 v[58:61], v[166:169], v[190:193], v[58:61]
	v_mfma_f32_16x16x32_bf16 v[42:45], v[166:169], v[198:201], v[42:45]
	v_mfma_f32_16x16x32_bf16 v[46:49], v[158:161], v[198:201], v[46:49]
	v_mfma_f32_16x16x32_bf16 v[30:33], v[158:161], v[206:209], v[30:33]
	v_mfma_f32_16x16x32_bf16 v[26:29], v[166:169], v[206:209], v[26:29]
	v_mfma_f32_16x16x32_bf16 v[10:13], v[166:169], v[214:217], v[10:13]
	v_mfma_f32_16x16x32_bf16 v[14:17], v[158:161], v[214:217], v[14:17]
	s_setprio 2
	s_setprio 0
	v_mfma_f32_16x16x32_bf16 v[54:57], v[170:173], v[186:189], v[54:57]
	v_mfma_f32_16x16x32_bf16 v[50:53], v[178:181], v[186:189], v[50:53]
	v_mfma_f32_16x16x32_bf16 v[34:37], v[178:181], v[194:197], v[34:37]
	v_mfma_f32_16x16x32_bf16 v[38:41], v[170:173], v[194:197], v[38:41]
	v_mfma_f32_16x16x32_bf16 v[22:25], v[170:173], v[202:205], v[22:25]
	v_mfma_f32_16x16x32_bf16 v[18:21], v[178:181], v[202:205], v[18:21]
	v_mfma_f32_16x16x32_bf16 v[2:5], v[178:181], v[210:213], v[2:5]
	v_mfma_f32_16x16x32_bf16 v[6:9], v[170:173], v[210:213], v[6:9]
	v_mfma_f32_16x16x32_bf16 v[54:57], v[174:177], v[190:193], v[54:57]
	v_mfma_f32_16x16x32_bf16 v[50:53], v[182:185], v[190:193], v[50:53]
	v_mfma_f32_16x16x32_bf16 v[34:37], v[182:185], v[198:201], v[34:37]
	v_mfma_f32_16x16x32_bf16 v[38:41], v[174:177], v[198:201], v[38:41]
	v_mfma_f32_16x16x32_bf16 v[22:25], v[174:177], v[206:209], v[22:25]
	v_mfma_f32_16x16x32_bf16 v[18:21], v[182:185], v[206:209], v[18:21]
	v_mfma_f32_16x16x32_bf16 v[2:5], v[182:185], v[214:217], v[2:5]
	v_mfma_f32_16x16x32_bf16 v[6:9], v[174:177], v[214:217], v[6:9]
	s_setprio 2
	s_barrier
	s_add_i32 s33, 0, 0x18000
	v_add_u32_e32 v157, s33, v151
	s_add_i32 s62, 0, 0x1c000
	ds_read_b128 v[146:149], v157
	ds_read_b128 v[158:161], v157 offset:1024
	ds_read_b128 v[162:165], v157 offset:2048
	ds_read_b128 v[166:169], v157 offset:3072
	v_add_u32_e32 v157, s62, v151
	ds_read_b128 v[170:173], v157
	ds_read_b128 v[174:177], v157 offset:1024
	ds_read_b128 v[178:181], v157 offset:2048
	ds_read_b128 v[182:185], v157 offset:3072
	s_add_u32 s48, s48, 0x40000
	s_addc_u32 s49, s49, 0
	s_mov_b32 m0, s58
	v_lshl_add_u64 v[226:227], s[48:49], 0, v[130:131]
	ds_read_b128 v[186:189], v154 offset:32768
	ds_read_b128 v[190:193], v154 offset:33792
	ds_read_b128 v[194:197], v154 offset:34816
	ds_read_b128 v[198:201], v154 offset:35840
	ds_read_b128 v[202:205], v154 offset:36864
	ds_read_b128 v[206:209], v154 offset:37888
	ds_read_b128 v[210:213], v154 offset:38912
	ds_read_b128 v[214:217], v154 offset:39936
	global_load_lds_dwordx4 v[226:227], off
	v_lshl_add_u64 v[226:227], s[48:49], 0, v[134:135]
	s_mov_b32 m0, s59
	s_nop 0
	global_load_lds_dwordx4 v[226:227], off
	s_waitcnt vmcnt(8)
	s_waitcnt lgkmcnt(0)
	s_barrier
	s_setprio 0
	s_waitcnt lgkmcnt(0)
	v_mfma_f32_16x16x32_bf16 v[126:129], v[146:149], v[186:189], v[126:129]
	v_mfma_f32_16x16x32_bf16 v[122:125], v[162:165], v[186:189], v[122:125]
	v_mfma_f32_16x16x32_bf16 v[106:109], v[162:165], v[194:197], v[106:109]
	v_mfma_f32_16x16x32_bf16 v[110:113], v[146:149], v[194:197], v[110:113]
	v_mfma_f32_16x16x32_bf16 v[94:97], v[146:149], v[202:205], v[94:97]
	v_mfma_f32_16x16x32_bf16 v[90:93], v[162:165], v[202:205], v[90:93]
	v_mfma_f32_16x16x32_bf16 v[74:77], v[162:165], v[210:213], v[74:77]
	v_mfma_f32_16x16x32_bf16 v[78:81], v[146:149], v[210:213], v[78:81]
	v_mfma_f32_16x16x32_bf16 v[126:129], v[158:161], v[190:193], v[126:129]
	v_mfma_f32_16x16x32_bf16 v[122:125], v[166:169], v[190:193], v[122:125]
	v_mfma_f32_16x16x32_bf16 v[106:109], v[166:169], v[198:201], v[106:109]
	v_mfma_f32_16x16x32_bf16 v[110:113], v[158:161], v[198:201], v[110:113]
	v_mfma_f32_16x16x32_bf16 v[94:97], v[158:161], v[206:209], v[94:97]
	v_mfma_f32_16x16x32_bf16 v[90:93], v[166:169], v[206:209], v[90:93]
	v_mfma_f32_16x16x32_bf16 v[74:77], v[166:169], v[214:217], v[74:77]
	v_mfma_f32_16x16x32_bf16 v[78:81], v[158:161], v[214:217], v[78:81]
	s_setprio 2
	s_setprio 0
	v_mfma_f32_16x16x32_bf16 v[118:121], v[170:173], v[186:189], v[118:121]
	v_mfma_f32_16x16x32_bf16 v[114:117], v[178:181], v[186:189], v[114:117]
	v_mfma_f32_16x16x32_bf16 v[98:101], v[178:181], v[194:197], v[98:101]
	v_mfma_f32_16x16x32_bf16 v[102:105], v[170:173], v[194:197], v[102:105]
	v_mfma_f32_16x16x32_bf16 v[86:89], v[170:173], v[202:205], v[86:89]
	v_mfma_f32_16x16x32_bf16 v[82:85], v[178:181], v[202:205], v[82:85]
	v_mfma_f32_16x16x32_bf16 v[66:69], v[178:181], v[210:213], v[66:69]
	v_mfma_f32_16x16x32_bf16 v[70:73], v[170:173], v[210:213], v[70:73]
	v_mfma_f32_16x16x32_bf16 v[118:121], v[174:177], v[190:193], v[118:121]
	v_mfma_f32_16x16x32_bf16 v[114:117], v[182:185], v[190:193], v[114:117]
	v_mfma_f32_16x16x32_bf16 v[98:101], v[182:185], v[198:201], v[98:101]
	v_mfma_f32_16x16x32_bf16 v[102:105], v[174:177], v[198:201], v[102:105]
	v_mfma_f32_16x16x32_bf16 v[86:89], v[174:177], v[206:209], v[86:89]
	v_mfma_f32_16x16x32_bf16 v[82:85], v[182:185], v[206:209], v[82:85]
	v_mfma_f32_16x16x32_bf16 v[66:69], v[182:185], v[214:217], v[66:69]
	v_mfma_f32_16x16x32_bf16 v[70:73], v[174:177], v[214:217], v[70:73]
	s_setprio 2
	s_barrier
; #define PG8_STAGE(bufoff, gbase, voff) do { _Pragma("unroll") for (int _i = 0; _i < 2; ++_i) \
;         __builtin_amdgcn_global_load_lds((const unsigned*)((const char*)(gbase) + (voff)[_i]), (LAS unsigned*)(lds + (bufoff) + ldsw + _i * 8192), 16, 0, 0); } while (0)
; #define PG8_LDA(dst, b, h) do { _Pragma("unroll") for (int m = 0; m < 4; ++m) _Pragma("unroll") for (int k = 0; k < 2; ++k) dst[m][k] = *(const LAS bf16x8*)(lds + PG8_SA(b, h) + aoff + m * 2048 + k * 1024); } while (0)
; #define PG8_MMA(ai, bj, At, Bt) do { __builtin_amdgcn_s_setprio(1); _Pragma("unroll") for (int m = 0; m < 4; ++m) _Pragma("unroll") for (int n = 0; n < 2; ++n) _Pragma("unroll") for (int k = 0; k < 2; ++k) \
;         acc[ai][bj][m][n] = __builtin_amdgcn_mfma_f32_16x16x32_bf16(Bt[n][k], At[m][k], acc[ai][bj][m][n], 0, 0, 0); __builtin_amdgcn_s_setprio(0); } while (0)
; #define PG8_WAIT_V(n) asm volatile("s_waitcnt vmcnt(" #n ")" ::: "memory")
; #define PG8_WAIT_L(n) asm volatile("s_waitcnt lgkmcnt(" #n ")" ::: "memory")
; #define PG8_BAR __builtin_amdgcn_s_barrier()
; #define PG8_SCHED __builtin_amdgcn_sched_barrier(0)
; template <class Epi>
; __device__ __forceinline__ void gemm_phase(LAS unsigned char* lds, const Gemm g, int G, int c, const Epi& E) {
;     ...
;             PG8_LDA(At, 1, 1); PG8_STAGE(PG8_SB(1, 0), b3, voffB); PG8_STAGE(PG8_SB(1, 1), b3 + hstepB, voffB); PG8_STAGE(PG8_SA(1, 0), a3, voffA);
;             PG8_WAIT_V(8); PG8_WAIT_L(0); PG8_BAR; PG8_MMA(1, 0, At, B0); PG8_MMA(1, 1, At, B1); PG8_BAR; PG8_SCHED;
;         }
;         if (wr == 0) PG8_BAR;
	s_add_i32 s33, s33, s56
	v_lshl_add_u64 v[218:219], v[218:219], 0, s[20:21]
	s_mov_b32 m0, s33
	ds_read_b128 v[186:189], v154 offset:49152
	ds_read_b128 v[190:193], v154 offset:50176
	ds_read_b128 v[194:197], v154 offset:51200
	ds_read_b128 v[198:201], v154 offset:52224
	ds_read_b128 v[202:205], v154 offset:53248
	ds_read_b128 v[206:209], v154 offset:54272
	ds_read_b128 v[210:213], v154 offset:55296
	ds_read_b128 v[214:217], v154 offset:56320
	global_load_lds_dwordx4 v[218:219], off
	s_add_i32 m0, s33, 0x2000
	s_add_u32 s46, s46, 0x40080
	v_lshl_add_u64 v[218:219], v[220:221], 0, s[20:21]
	s_addc_u32 s47, s47, 0
	s_add_i32 s33, s62, s56
	global_load_lds_dwordx4 v[218:219], off
	v_lshl_add_u64 v[218:219], s[46:47], 0, v[132:133]
	s_mov_b32 m0, s33
	s_nop 0
	global_load_lds_dwordx4 v[218:219], off
	v_lshl_add_u64 v[218:219], s[46:47], 0, v[136:137]
	s_add_i32 m0, s33, 0x2000
	s_nop 0
	global_load_lds_dwordx4 v[218:219], off
	v_lshl_add_u64 v[218:219], v[222:223], 0, s[20:21]
	s_mov_b32 m0, s67
	s_nop 0
	global_load_lds_dwordx4 v[218:219], off
	v_lshl_add_u64 v[218:219], v[224:225], 0, s[20:21]
	s_mov_b32 m0, s68
	s_nop 0
	global_load_lds_dwordx4 v[218:219], off
	s_waitcnt vmcnt(8)
	s_waitcnt lgkmcnt(0)
	s_barrier
	s_setprio 0
	s_waitcnt lgkmcnt(0)
	v_mfma_f32_16x16x32_bf16 v[62:65], v[146:149], v[186:189], v[62:65]
	v_mfma_f32_16x16x32_bf16 v[58:61], v[162:165], v[186:189], v[58:61]
	v_mfma_f32_16x16x32_bf16 v[42:45], v[162:165], v[194:197], v[42:45]
	v_mfma_f32_16x16x32_bf16 v[46:49], v[146:149], v[194:197], v[46:49]
	v_mfma_f32_16x16x32_bf16 v[30:33], v[146:149], v[202:205], v[30:33]
	v_mfma_f32_16x16x32_bf16 v[26:29], v[162:165], v[202:205], v[26:29]
	v_mfma_f32_16x16x32_bf16 v[10:13], v[162:165], v[210:213], v[10:13]
	v_mfma_f32_16x16x32_bf16 v[14:17], v[146:149], v[210:213], v[14:17]
	v_mfma_f32_16x16x32_bf16 v[62:65], v[158:161], v[190:193], v[62:65]
	v_mfma_f32_16x16x32_bf16 v[58:61], v[166:169], v[190:193], v[58:61]
	v_mfma_f32_16x16x32_bf16 v[42:45], v[166:169], v[198:201], v[42:45]
	v_mfma_f32_16x16x32_bf16 v[46:49], v[158:161], v[198:201], v[46:49]
	v_mfma_f32_16x16x32_bf16 v[30:33], v[158:161], v[206:209], v[30:33]
	v_mfma_f32_16x16x32_bf16 v[26:29], v[166:169], v[206:209], v[26:29]
	v_mfma_f32_16x16x32_bf16 v[10:13], v[166:169], v[214:217], v[10:13]
	v_mfma_f32_16x16x32_bf16 v[14:17], v[158:161], v[214:217], v[14:17]
	s_setprio 2
	s_setprio 0
	v_mfma_f32_16x16x32_bf16 v[54:57], v[170:173], v[186:189], v[54:57]
	v_mfma_f32_16x16x32_bf16 v[50:53], v[178:181], v[186:189], v[50:53]
	v_mfma_f32_16x16x32_bf16 v[34:37], v[178:181], v[194:197], v[34:37]
	v_mfma_f32_16x16x32_bf16 v[38:41], v[170:173], v[194:197], v[38:41]
	v_mfma_f32_16x16x32_bf16 v[22:25], v[170:173], v[202:205], v[22:25]
	v_mfma_f32_16x16x32_bf16 v[18:21], v[178:181], v[202:205], v[18:21]
	v_mfma_f32_16x16x32_bf16 v[2:5], v[178:181], v[210:213], v[2:5]
	v_mfma_f32_16x16x32_bf16 v[6:9], v[170:173], v[210:213], v[6:9]
	v_mfma_f32_16x16x32_bf16 v[54:57], v[174:177], v[190:193], v[54:57]
	v_mfma_f32_16x16x32_bf16 v[50:53], v[182:185], v[190:193], v[50:53]
	v_mfma_f32_16x16x32_bf16 v[34:37], v[182:185], v[198:201], v[34:37]
	v_mfma_f32_16x16x32_bf16 v[38:41], v[174:177], v[198:201], v[38:41]
	v_mfma_f32_16x16x32_bf16 v[22:25], v[174:177], v[206:209], v[22:25]
	v_mfma_f32_16x16x32_bf16 v[18:21], v[182:185], v[206:209], v[18:21]
	v_mfma_f32_16x16x32_bf16 v[2:5], v[182:185], v[214:217], v[2:5]
	v_mfma_f32_16x16x32_bf16 v[6:9], v[174:177], v[214:217], v[6:9]
	s_setprio 2
	s_barrier
	s_add_i32 s81, s81, 2
	s_add_u32 s4, s4, 0x100
	s_addc_u32 s5, s5, 0
	s_add_u32 s41, s41, 0x100
	s_addc_u32 s80, s80, 0
	s_cmp_gt_u32 s81, 13
	s_cbranch_scc0 .LBB0_1297
	s_and_b64 vcc, exec, s[22:23]
	s_cbranch_vccz .LBB0_1300
	s_barrier

; #define PG8_STAGE(bufoff, gbase, voff) do { _Pragma("unroll") for (int _i = 0; _i < 2; ++_i) \
;         __builtin_amdgcn_global_load_lds((const unsigned*)((const char*)(gbase) + (voff)[_i]), (LAS unsigned*)(lds + (bufoff) + ldsw + _i * 8192), 16, 0, 0); } while (0)
; #define PG8_LDA(dst, b, h) do { _Pragma("unroll") for (int m = 0; m < 4; ++m) _Pragma("unroll") for (int k = 0; k < 2; ++k) dst[m][k] = *(const LAS bf16x8*)(lds + PG8_SA(b, h) + aoff + m * 2048 + k * 1024); } while (0)
; #define PG8_LDB(dst, b, h) do { _Pragma("unroll") for (int n = 0; n < 2; ++n) _Pragma("unroll") for (int k = 0; k < 2; ++k) dst[n][k] = *(const LAS bf16x8*)(lds + PG8_SB(b, h) + boff + n * 2048 + k * 1024); } while (0)
; #define PG8_MMA(ai, bj, At, Bt) do { __builtin_amdgcn_s_setprio(1); _Pragma("unroll") for (int m = 0; m < 4; ++m) _Pragma("unroll") for (int n = 0; n < 2; ++n) _Pragma("unroll") for (int k = 0; k < 2; ++k) \
;         acc[ai][bj][m][n] = __builtin_amdgcn_mfma_f32_16x16x32_bf16(Bt[n][k], At[m][k], acc[ai][bj][m][n], 0, 0, 0); __builtin_amdgcn_s_setprio(0); } while (0)
; #define PG8_WAIT_V(n) asm volatile("s_waitcnt vmcnt(" #n ")" ::: "memory")
; #define PG8_WAIT_L(n) asm volatile("s_waitcnt lgkmcnt(" #n ")" ::: "memory")
; #define PG8_BAR __builtin_amdgcn_s_barrier()
; #define PG8_SCHED __builtin_amdgcn_sched_barrier(0)
; template <class Epi>
; __device__ __forceinline__ void gemm_phase(LAS unsigned char* lds, const Gemm g, int G, int c, const Epi& E) {
;     ...
;         for (int t = 0; t < nt; t += 2) {
;             const bool last = (t == nt - 2);
;             const char* a1 = cA + (size_t)(t + 1) * kstep;
;             const char* a2 = last ? nA : cA + (size_t)(t + 2) * kstep; const char* b2 = last ? nB : cB + (size_t)(t + 2) * kstep;
;             const char* a3 = a2 + kstep; const char* b3 = b2 + kstep;
;             PG8_LDB(B0, 0, 0); PG8_LDB(B1, 0, 1); PG8_SCHED; PG8_LDA(At, 0, 0); PG8_STAGE(PG8_SA(1, 1), a1 + hstepA, voffA);
;             PG8_WAIT_V(8); PG8_WAIT_L(0); PG8_BAR; PG8_MMA(0, 0, At, B0); PG8_MMA(0, 1, At, B1); PG8_BAR; PG8_SCHED;
;             PG8_LDA(At, 0, 1); PG8_STAGE(PG8_SB(0, 0), b2, voffB); PG8_STAGE(PG8_SB(0, 1), b2 + hstepB, voffB); PG8_STAGE(PG8_SA(0, 0), a2, voffA);
.LBB0_1429:
	s_add_u32 s33, s18, s13
	s_addc_u32 s42, s19, 0
	s_add_u32 s38, s33, 0x100
	s_addc_u32 s39, s42, 0
	s_and_b64 s[24:25], s[22:23], exec
	s_cselect_b32 s39, s5, s39
	s_cselect_b32 s38, s4, s38
	s_add_u32 s13, s16, s13
	s_addc_u32 s24, s17, 0
	s_add_u32 s13, s13, 0x100
	s_addc_u32 s24, s24, 0
	s_and_b64 s[22:23], s[22:23], exec
	s_cselect_b32 s41, s15, s24
	s_cselect_b32 s40, s14, s13
	s_add_u32 s44, s33, 0xb0080
	ds_read_b128 v[142:145], v148
	ds_read_b128 v[152:155], v148 offset:1024
	ds_read_b128 v[156:159], v148 offset:2048
	ds_read_b128 v[160:163], v148 offset:3072
	ds_read_b128 v[164:167], v149
	ds_read_b128 v[168:171], v149 offset:1024
	ds_read_b128 v[172:175], v149 offset:2048
	ds_read_b128 v[176:179], v149 offset:3072
	s_addc_u32 s45, s42, 0
	s_add_i32 s65, s72, s48
	s_add_i32 m0, s49, 0xc000
	s_add_i32 s85, s49, 0xe000
	s_add_i32 s62, s65, 0x2000
	s_add_u32 s42, s40, 0xb0000
	s_addc_u32 s43, s41, 0
	s_add_i32 s64, s73, s48
	s_add_i32 s63, s64, 0x2000
	s_add_i32 s84, 0, 0x18000
	s_add_i32 s33, 0, 0x1c000
	s_add_u32 s24, s38, 0xb0000
	s_addc_u32 s25, s39, 0
	s_add_i32 s83, s84, s48
	s_add_i32 s13, s83, 0x2000
	s_add_u32 s22, s40, 0xb0080
	s_addc_u32 s23, s41, 0
	s_add_i32 s75, s33, s48
	s_add_i32 s74, s75, 0x2000
	v_lshl_add_u64 v[212:213], s[44:45], 0, v[136:137]
	ds_read_b128 v[180:183], v150
	ds_read_b128 v[184:187], v150 offset:1024
	ds_read_b128 v[188:191], v150 offset:2048
	ds_read_b128 v[192:195], v150 offset:3072
	ds_read_b128 v[196:199], v150 offset:4096
	ds_read_b128 v[200:203], v150 offset:5120
	ds_read_b128 v[204:207], v150 offset:6144
	ds_read_b128 v[208:211], v150 offset:7168
	global_load_lds_dwordx4 v[212:213], off
	v_lshl_add_u64 v[212:213], s[44:45], 0, v[132:133]
	s_mov_b32 m0, s85
	s_nop 0
	global_load_lds_dwordx4 v[212:213], off
	s_waitcnt vmcnt(8)
	s_waitcnt lgkmcnt(0)
	s_barrier
	s_setprio 0
	s_waitcnt lgkmcnt(0)
	v_mfma_f32_16x16x32_bf16 v[126:129], v[142:145], v[180:183], v[126:129]
	v_mfma_f32_16x16x32_bf16 v[122:125], v[156:159], v[180:183], v[122:125]
	v_mfma_f32_16x16x32_bf16 v[110:113], v[156:159], v[188:191], v[110:113]
	v_mfma_f32_16x16x32_bf16 v[118:121], v[142:145], v[188:191], v[118:121]
	v_mfma_f32_16x16x32_bf16 v[102:105], v[142:145], v[196:199], v[102:105]
	v_mfma_f32_16x16x32_bf16 v[94:97], v[156:159], v[196:199], v[94:97]
	v_mfma_f32_16x16x32_bf16 v[78:81], v[156:159], v[204:207], v[78:81]
	v_mfma_f32_16x16x32_bf16 v[86:89], v[142:145], v[204:207], v[86:89]
	v_mfma_f32_16x16x32_bf16 v[126:129], v[152:155], v[184:187], v[126:129]
	v_mfma_f32_16x16x32_bf16 v[122:125], v[160:163], v[184:187], v[122:125]
	v_mfma_f32_16x16x32_bf16 v[110:113], v[160:163], v[192:195], v[110:113]
	v_mfma_f32_16x16x32_bf16 v[118:121], v[152:155], v[192:195], v[118:121]
	v_mfma_f32_16x16x32_bf16 v[102:105], v[152:155], v[200:203], v[102:105]
	v_mfma_f32_16x16x32_bf16 v[94:97], v[160:163], v[200:203], v[94:97]
	v_mfma_f32_16x16x32_bf16 v[78:81], v[160:163], v[208:211], v[78:81]
	v_mfma_f32_16x16x32_bf16 v[86:89], v[152:155], v[208:211], v[86:89]
	s_setprio 2
	s_setprio 0
	v_mfma_f32_16x16x32_bf16 v[114:117], v[164:167], v[180:183], v[114:117]
	v_mfma_f32_16x16x32_bf16 v[106:109], v[172:175], v[180:183], v[106:109]
	v_mfma_f32_16x16x32_bf16 v[90:93], v[172:175], v[188:191], v[90:93]
	v_mfma_f32_16x16x32_bf16 v[98:101], v[164:167], v[188:191], v[98:101]
	v_mfma_f32_16x16x32_bf16 v[82:85], v[164:167], v[196:199], v[82:85]
	v_mfma_f32_16x16x32_bf16 v[74:77], v[172:175], v[196:199], v[74:77]
	v_mfma_f32_16x16x32_bf16 v[66:69], v[172:175], v[204:207], v[66:69]
	v_mfma_f32_16x16x32_bf16 v[70:73], v[164:167], v[204:207], v[70:73]
	v_mfma_f32_16x16x32_bf16 v[114:117], v[168:171], v[184:187], v[114:117]
	v_mfma_f32_16x16x32_bf16 v[106:109], v[176:179], v[184:187], v[106:109]
	v_mfma_f32_16x16x32_bf16 v[90:93], v[176:179], v[192:195], v[90:93]
	v_mfma_f32_16x16x32_bf16 v[98:101], v[168:171], v[192:195], v[98:101]
	v_mfma_f32_16x16x32_bf16 v[82:85], v[168:171], v[200:203], v[82:85]
	v_mfma_f32_16x16x32_bf16 v[74:77], v[176:179], v[200:203], v[74:77]
	v_mfma_f32_16x16x32_bf16 v[66:69], v[176:179], v[208:211], v[66:69]
	v_mfma_f32_16x16x32_bf16 v[70:73], v[168:171], v[208:211], v[70:73]
	s_setprio 2
	s_barrier
	s_mov_b32 m0, s65
	v_lshl_add_u64 v[212:213], s[40:41], 0, v[134:135]
	ds_read_b128 v[180:183], v150 offset:16384
	ds_read_b128 v[184:187], v150 offset:17408
	ds_read_b128 v[188:191], v150 offset:18432
	ds_read_b128 v[192:195], v150 offset:19456
	ds_read_b128 v[196:199], v150 offset:20480
	ds_read_b128 v[200:203], v150 offset:21504
	ds_read_b128 v[204:207], v150 offset:22528
	ds_read_b128 v[208:211], v150 offset:23552
	global_load_lds_dwordx4 v[212:213], off
	v_lshl_add_u64 v[214:215], s[40:41], 0, v[130:131]
	s_mov_b32 m0, s62
	v_lshl_add_u64 v[216:217], s[42:43], 0, v[134:135]
	global_load_lds_dwordx4 v[214:215], off
	s_mov_b32 m0, s64
	v_lshl_add_u64 v[218:219], s[38:39], 0, v[132:133]
	global_load_lds_dwordx4 v[216:217], off
	v_lshl_add_u64 v[216:217], s[42:43], 0, v[130:131]
	s_mov_b32 m0, s63
	s_nop 0
	global_load_lds_dwordx4 v[216:217], off
	v_lshl_add_u64 v[216:217], s[38:39], 0, v[136:137]
	s_mov_b32 m0, s49
	s_nop 0
	global_load_lds_dwordx4 v[216:217], off
	s_mov_b32 m0, s52
	s_nop 0
	global_load_lds_dwordx4 v[218:219], off
	s_waitcnt vmcnt(8)
	s_waitcnt lgkmcnt(0)
	s_barrier
; #define PG8_STAGE(bufoff, gbase, voff) do { _Pragma("unroll") for (int _i = 0; _i < 2; ++_i) \
;         __builtin_amdgcn_global_load_lds((const unsigned*)((const char*)(gbase) + (voff)[_i]), (LAS unsigned*)(lds + (bufoff) + ldsw + _i * 8192), 16, 0, 0); } while (0)
; #define PG8_LDA(dst, b, h) do { _Pragma("unroll") for (int m = 0; m < 4; ++m) _Pragma("unroll") for (int k = 0; k < 2; ++k) dst[m][k] = *(const LAS bf16x8*)(lds + PG8_SA(b, h) + aoff + m * 2048 + k * 1024); } while (0)
; #define PG8_LDB(dst, b, h) do { _Pragma("unroll") for (int n = 0; n < 2; ++n) _Pragma("unroll") for (int k = 0; k < 2; ++k) dst[n][k] = *(const LAS bf16x8*)(lds + PG8_SB(b, h) + boff + n * 2048 + k * 1024); } while (0)
; #define PG8_MMA(ai, bj, At, Bt) do { __builtin_amdgcn_s_setprio(1); _Pragma("unroll") for (int m = 0; m < 4; ++m) _Pragma("unroll") for (int n = 0; n < 2; ++n) _Pragma("unroll") for (int k = 0; k < 2; ++k) \
;         acc[ai][bj][m][n] = __builtin_amdgcn_mfma_f32_16x16x32_bf16(Bt[n][k], At[m][k], acc[ai][bj][m][n], 0, 0, 0); __builtin_amdgcn_s_setprio(0); } while (0)
; #define PG8_WAIT_V(n) asm volatile("s_waitcnt vmcnt(" #n ")" ::: "memory")
; #define PG8_WAIT_L(n) asm volatile("s_waitcnt lgkmcnt(" #n ")" ::: "memory")
; #define PG8_BAR __builtin_amdgcn_s_barrier()
; #define PG8_SCHED __builtin_amdgcn_sched_barrier(0)
; template <class Epi>
; __device__ __forceinline__ void gemm_phase(LAS unsigned char* lds, const Gemm g, int G, int c, const Epi& E) {
;     ...
;             PG8_WAIT_V(8); PG8_WAIT_L(0); PG8_BAR; PG8_MMA(1, 0, At, B0); PG8_MMA(1, 1, At, B1); PG8_BAR; PG8_SCHED;
;             PG8_LDB(B0, 1, 0); PG8_LDB(B1, 1, 1); PG8_SCHED; PG8_LDA(At, 1, 0); PG8_STAGE(PG8_SA(0, 1), a2 + hstepA, voffA);
;             PG8_WAIT_V(8); PG8_WAIT_L(0); PG8_BAR; PG8_MMA(0, 0, At, B0); PG8_MMA(0, 1, At, B1); PG8_BAR; PG8_SCHED;
	s_setprio 0
	s_waitcnt lgkmcnt(0)
	v_mfma_f32_16x16x32_bf16 v[62:65], v[142:145], v[180:183], v[62:65]
	v_mfma_f32_16x16x32_bf16 v[58:61], v[156:159], v[180:183], v[58:61]
	v_mfma_f32_16x16x32_bf16 v[46:49], v[156:159], v[188:191], v[46:49]
	v_mfma_f32_16x16x32_bf16 v[54:57], v[142:145], v[188:191], v[54:57]
	v_mfma_f32_16x16x32_bf16 v[38:41], v[142:145], v[196:199], v[38:41]
	v_mfma_f32_16x16x32_bf16 v[30:33], v[156:159], v[196:199], v[30:33]
	v_mfma_f32_16x16x32_bf16 v[14:17], v[156:159], v[204:207], v[14:17]
	v_mfma_f32_16x16x32_bf16 v[22:25], v[142:145], v[204:207], v[22:25]
	v_mfma_f32_16x16x32_bf16 v[62:65], v[152:155], v[184:187], v[62:65]
	v_mfma_f32_16x16x32_bf16 v[58:61], v[160:163], v[184:187], v[58:61]
	v_mfma_f32_16x16x32_bf16 v[46:49], v[160:163], v[192:195], v[46:49]
	v_mfma_f32_16x16x32_bf16 v[54:57], v[152:155], v[192:195], v[54:57]
	v_mfma_f32_16x16x32_bf16 v[38:41], v[152:155], v[200:203], v[38:41]
	v_mfma_f32_16x16x32_bf16 v[30:33], v[160:163], v[200:203], v[30:33]
	v_mfma_f32_16x16x32_bf16 v[14:17], v[160:163], v[208:211], v[14:17]
	v_mfma_f32_16x16x32_bf16 v[22:25], v[152:155], v[208:211], v[22:25]
	s_setprio 2
	s_setprio 0
	v_mfma_f32_16x16x32_bf16 v[50:53], v[164:167], v[180:183], v[50:53]
	v_mfma_f32_16x16x32_bf16 v[42:45], v[172:175], v[180:183], v[42:45]
	v_mfma_f32_16x16x32_bf16 v[26:29], v[172:175], v[188:191], v[26:29]
	v_mfma_f32_16x16x32_bf16 v[34:37], v[164:167], v[188:191], v[34:37]
	v_mfma_f32_16x16x32_bf16 v[18:21], v[164:167], v[196:199], v[18:21]
	v_mfma_f32_16x16x32_bf16 v[10:13], v[172:175], v[196:199], v[10:13]
	v_mfma_f32_16x16x32_bf16 v[2:5], v[172:175], v[204:207], v[2:5]
	v_mfma_f32_16x16x32_bf16 v[6:9], v[164:167], v[204:207], v[6:9]
	v_mfma_f32_16x16x32_bf16 v[50:53], v[168:171], v[184:187], v[50:53]
	v_mfma_f32_16x16x32_bf16 v[42:45], v[176:179], v[184:187], v[42:45]
	v_mfma_f32_16x16x32_bf16 v[26:29], v[176:179], v[192:195], v[26:29]
	v_mfma_f32_16x16x32_bf16 v[34:37], v[168:171], v[192:195], v[34:37]
	v_mfma_f32_16x16x32_bf16 v[18:21], v[168:171], v[200:203], v[18:21]
	v_mfma_f32_16x16x32_bf16 v[10:13], v[176:179], v[200:203], v[10:13]
	v_mfma_f32_16x16x32_bf16 v[2:5], v[176:179], v[208:211], v[2:5]
	v_mfma_f32_16x16x32_bf16 v[6:9], v[168:171], v[208:211], v[6:9]
	s_setprio 2
	s_barrier
	v_add_u32_e32 v151, s84, v147
	ds_read_b128 v[142:145], v151
	ds_read_b128 v[152:155], v151 offset:1024
	ds_read_b128 v[156:159], v151 offset:2048
	ds_read_b128 v[160:163], v151 offset:3072
	v_add_u32_e32 v151, s33, v147
	ds_read_b128 v[164:167], v151
	ds_read_b128 v[168:171], v151 offset:1024
	ds_read_b128 v[172:175], v151 offset:2048
	ds_read_b128 v[176:179], v151 offset:3072
	s_mov_b32 m0, s53
	v_lshl_add_u64 v[220:221], s[24:25], 0, v[136:137]
	ds_read_b128 v[180:183], v150 offset:32768
	ds_read_b128 v[184:187], v150 offset:33792
	ds_read_b128 v[188:191], v150 offset:34816
	ds_read_b128 v[192:195], v150 offset:35840
	ds_read_b128 v[196:199], v150 offset:36864
	ds_read_b128 v[200:203], v150 offset:37888
	ds_read_b128 v[204:207], v150 offset:38912
	ds_read_b128 v[208:211], v150 offset:39936
	global_load_lds_dwordx4 v[220:221], off
	v_lshl_add_u64 v[220:221], s[24:25], 0, v[132:133]
	s_mov_b32 m0, s54
	s_nop 0
	global_load_lds_dwordx4 v[220:221], off
	s_waitcnt vmcnt(8)
	s_waitcnt lgkmcnt(0)
	s_barrier
	s_setprio 0
	s_waitcnt lgkmcnt(0)
	v_mfma_f32_16x16x32_bf16 v[126:129], v[142:145], v[180:183], v[126:129]
	v_mfma_f32_16x16x32_bf16 v[122:125], v[156:159], v[180:183], v[122:125]
	v_mfma_f32_16x16x32_bf16 v[110:113], v[156:159], v[188:191], v[110:113]
	v_mfma_f32_16x16x32_bf16 v[118:121], v[142:145], v[188:191], v[118:121]
	v_mfma_f32_16x16x32_bf16 v[102:105], v[142:145], v[196:199], v[102:105]
	v_mfma_f32_16x16x32_bf16 v[94:97], v[156:159], v[196:199], v[94:97]
	v_mfma_f32_16x16x32_bf16 v[78:81], v[156:159], v[204:207], v[78:81]
	v_mfma_f32_16x16x32_bf16 v[86:89], v[142:145], v[204:207], v[86:89]
	v_mfma_f32_16x16x32_bf16 v[126:129], v[152:155], v[184:187], v[126:129]
	v_mfma_f32_16x16x32_bf16 v[122:125], v[160:163], v[184:187], v[122:125]
	v_mfma_f32_16x16x32_bf16 v[110:113], v[160:163], v[192:195], v[110:113]
	v_mfma_f32_16x16x32_bf16 v[118:121], v[152:155], v[192:195], v[118:121]
	v_mfma_f32_16x16x32_bf16 v[102:105], v[152:155], v[200:203], v[102:105]
	v_mfma_f32_16x16x32_bf16 v[94:97], v[160:163], v[200:203], v[94:97]
	v_mfma_f32_16x16x32_bf16 v[78:81], v[160:163], v[208:211], v[78:81]
	v_mfma_f32_16x16x32_bf16 v[86:89], v[152:155], v[208:211], v[86:89]
	s_setprio 2
	s_setprio 0
	v_mfma_f32_16x16x32_bf16 v[114:117], v[164:167], v[180:183], v[114:117]
	v_mfma_f32_16x16x32_bf16 v[106:109], v[172:175], v[180:183], v[106:109]
	v_mfma_f32_16x16x32_bf16 v[90:93], v[172:175], v[188:191], v[90:93]
	v_mfma_f32_16x16x32_bf16 v[98:101], v[164:167], v[188:191], v[98:101]
	v_mfma_f32_16x16x32_bf16 v[82:85], v[164:167], v[196:199], v[82:85]
	v_mfma_f32_16x16x32_bf16 v[74:77], v[172:175], v[196:199], v[74:77]
	v_mfma_f32_16x16x32_bf16 v[66:69], v[172:175], v[204:207], v[66:69]
	v_mfma_f32_16x16x32_bf16 v[70:73], v[164:167], v[204:207], v[70:73]
	v_mfma_f32_16x16x32_bf16 v[114:117], v[168:171], v[184:187], v[114:117]
	v_mfma_f32_16x16x32_bf16 v[106:109], v[176:179], v[184:187], v[106:109]
	v_mfma_f32_16x16x32_bf16 v[90:93], v[176:179], v[192:195], v[90:93]
	v_mfma_f32_16x16x32_bf16 v[98:101], v[168:171], v[192:195], v[98:101]
	v_mfma_f32_16x16x32_bf16 v[82:85], v[168:171], v[200:203], v[82:85]
	v_mfma_f32_16x16x32_bf16 v[74:77], v[176:179], v[200:203], v[74:77]
	v_mfma_f32_16x16x32_bf16 v[66:69], v[176:179], v[208:211], v[66:69]
	v_mfma_f32_16x16x32_bf16 v[70:73], v[168:171], v[208:211], v[70:73]
	s_setprio 2
	s_barrier
; #define PG8_STAGE(bufoff, gbase, voff) do { _Pragma("unroll") for (int _i = 0; _i < 2; ++_i) \
;         __builtin_amdgcn_global_load_lds((const unsigned*)((const char*)(gbase) + (voff)[_i]), (LAS unsigned*)(lds + (bufoff) + ldsw + _i * 8192), 16, 0, 0); } while (0)
; #define PG8_LDA(dst, b, h) do { _Pragma("unroll") for (int m = 0; m < 4; ++m) _Pragma("unroll") for (int k = 0; k < 2; ++k) dst[m][k] = *(const LAS bf16x8*)(lds + PG8_SA(b, h) + aoff + m * 2048 + k * 1024); } while (0)
; #define PG8_MMA(ai, bj, At, Bt) do { __builtin_amdgcn_s_setprio(1); _Pragma("unroll") for (int m = 0; m < 4; ++m) _Pragma("unroll") for (int n = 0; n < 2; ++n) _Pragma("unroll") for (int k = 0; k < 2; ++k) \
;         acc[ai][bj][m][n] = __builtin_amdgcn_mfma_f32_16x16x32_bf16(Bt[n][k], At[m][k], acc[ai][bj][m][n], 0, 0, 0); __builtin_amdgcn_s_setprio(0); } while (0)
; #define PG8_WAIT_V(n) asm volatile("s_waitcnt vmcnt(" #n ")" ::: "memory")
; #define PG8_WAIT_L(n) asm volatile("s_waitcnt lgkmcnt(" #n ")" ::: "memory")
; #define PG8_BAR __builtin_amdgcn_s_barrier()
; #define PG8_SCHED __builtin_amdgcn_sched_barrier(0)
; template <class Epi>
; __device__ __forceinline__ void gemm_phase(LAS unsigned char* lds, const Gemm g, int G, int c, const Epi& E) {
;     ...
;             PG8_LDA(At, 1, 1); PG8_STAGE(PG8_SB(1, 0), b3, voffB); PG8_STAGE(PG8_SB(1, 1), b3 + hstepB, voffB); PG8_STAGE(PG8_SA(1, 0), a3, voffA);
;             PG8_WAIT_V(8); PG8_WAIT_L(0); PG8_BAR; PG8_MMA(1, 0, At, B0); PG8_MMA(1, 1, At, B1); PG8_BAR; PG8_SCHED;
;         }
;         if (wr == 0) PG8_BAR;
	s_mov_b32 m0, s83
	v_lshl_add_u64 v[212:213], v[212:213], 0, s[8:9]
	ds_read_b128 v[180:183], v150 offset:49152
	ds_read_b128 v[184:187], v150 offset:50176
	ds_read_b128 v[188:191], v150 offset:51200
	ds_read_b128 v[192:195], v150 offset:52224
	ds_read_b128 v[196:199], v150 offset:53248
	ds_read_b128 v[200:203], v150 offset:54272
	ds_read_b128 v[204:207], v150 offset:55296
	ds_read_b128 v[208:211], v150 offset:56320
	global_load_lds_dwordx4 v[212:213], off
	v_lshl_add_u64 v[212:213], v[214:215], 0, s[8:9]
	s_mov_b32 m0, s13
	s_nop 0
	global_load_lds_dwordx4 v[212:213], off
	v_lshl_add_u64 v[212:213], s[22:23], 0, v[134:135]
	s_mov_b32 m0, s75
	s_nop 0
	global_load_lds_dwordx4 v[212:213], off
	v_lshl_add_u64 v[212:213], s[22:23], 0, v[130:131]
	s_mov_b32 m0, s74
	s_nop 0
	global_load_lds_dwordx4 v[212:213], off
	v_lshl_add_u64 v[212:213], v[216:217], 0, s[8:9]
	s_mov_b32 m0, s70
	s_nop 0
	global_load_lds_dwordx4 v[212:213], off
	v_lshl_add_u64 v[212:213], v[218:219], 0, s[8:9]
	s_mov_b32 m0, s71
	s_nop 0
	global_load_lds_dwordx4 v[212:213], off
	s_waitcnt vmcnt(8)
	s_waitcnt lgkmcnt(0)
	s_barrier
	s_setprio 0
	s_waitcnt lgkmcnt(0)
	v_mfma_f32_16x16x32_bf16 v[62:65], v[142:145], v[180:183], v[62:65]
	v_mfma_f32_16x16x32_bf16 v[58:61], v[156:159], v[180:183], v[58:61]
	v_mfma_f32_16x16x32_bf16 v[46:49], v[156:159], v[188:191], v[46:49]
	v_mfma_f32_16x16x32_bf16 v[54:57], v[142:145], v[188:191], v[54:57]
	v_mfma_f32_16x16x32_bf16 v[38:41], v[142:145], v[196:199], v[38:41]
	v_mfma_f32_16x16x32_bf16 v[30:33], v[156:159], v[196:199], v[30:33]
	v_mfma_f32_16x16x32_bf16 v[14:17], v[156:159], v[204:207], v[14:17]
	v_mfma_f32_16x16x32_bf16 v[22:25], v[142:145], v[204:207], v[22:25]
	v_mfma_f32_16x16x32_bf16 v[62:65], v[152:155], v[184:187], v[62:65]
	v_mfma_f32_16x16x32_bf16 v[58:61], v[160:163], v[184:187], v[58:61]
	v_mfma_f32_16x16x32_bf16 v[46:49], v[160:163], v[192:195], v[46:49]
	v_mfma_f32_16x16x32_bf16 v[54:57], v[152:155], v[192:195], v[54:57]
	v_mfma_f32_16x16x32_bf16 v[38:41], v[152:155], v[200:203], v[38:41]
	v_mfma_f32_16x16x32_bf16 v[30:33], v[160:163], v[200:203], v[30:33]
	v_mfma_f32_16x16x32_bf16 v[14:17], v[160:163], v[208:211], v[14:17]
	v_mfma_f32_16x16x32_bf16 v[22:25], v[152:155], v[208:211], v[22:25]
	s_setprio 2
	s_setprio 0
	v_mfma_f32_16x16x32_bf16 v[50:53], v[164:167], v[180:183], v[50:53]
	v_mfma_f32_16x16x32_bf16 v[42:45], v[172:175], v[180:183], v[42:45]
	v_mfma_f32_16x16x32_bf16 v[26:29], v[172:175], v[188:191], v[26:29]
	v_mfma_f32_16x16x32_bf16 v[34:37], v[164:167], v[188:191], v[34:37]
	v_mfma_f32_16x16x32_bf16 v[18:21], v[164:167], v[196:199], v[18:21]
	v_mfma_f32_16x16x32_bf16 v[10:13], v[172:175], v[196:199], v[10:13]
	v_mfma_f32_16x16x32_bf16 v[2:5], v[172:175], v[204:207], v[2:5]
	v_mfma_f32_16x16x32_bf16 v[6:9], v[164:167], v[204:207], v[6:9]
	v_mfma_f32_16x16x32_bf16 v[50:53], v[168:171], v[184:187], v[50:53]
	v_mfma_f32_16x16x32_bf16 v[42:45], v[176:179], v[184:187], v[42:45]
	v_mfma_f32_16x16x32_bf16 v[26:29], v[176:179], v[192:195], v[26:29]
	v_mfma_f32_16x16x32_bf16 v[34:37], v[168:171], v[192:195], v[34:37]
	v_mfma_f32_16x16x32_bf16 v[18:21], v[168:171], v[200:203], v[18:21]
	v_mfma_f32_16x16x32_bf16 v[10:13], v[176:179], v[200:203], v[10:13]
	v_mfma_f32_16x16x32_bf16 v[2:5], v[176:179], v[208:211], v[2:5]
	v_mfma_f32_16x16x32_bf16 v[6:9], v[168:171], v[208:211], v[6:9]
	s_setprio 2
	s_barrier
	s_movk_i32 s13, 0x100
	s_andn2_b64 vcc, exec, s[20:21]
	s_mov_b64 s[22:23], -1
	s_mov_b64 s[20:21], 0
	s_cbranch_vccz .LBB0_1429
	s_and_b64 vcc, exec, s[10:11]
	s_cbranch_vccz .LBB0_1432
	s_barrier

; #define PG8_STAGE(bufoff, gbase, voff) do { _Pragma("unroll") for (int _i = 0; _i < 2; ++_i) \
;         __builtin_amdgcn_global_load_lds((const unsigned*)((const char*)(gbase) + (voff)[_i]), (LAS unsigned*)(lds + (bufoff) + ldsw + _i * 8192), 16, 0, 0); } while (0)
; #define PG8_LDA(dst, b, h) do { _Pragma("unroll") for (int m = 0; m < 4; ++m) _Pragma("unroll") for (int k = 0; k < 2; ++k) dst[m][k] = *(const LAS bf16x8*)(lds + PG8_SA(b, h) + aoff + m * 2048 + k * 1024); } while (0)
; #define PG8_LDB(dst, b, h) do { _Pragma("unroll") for (int n = 0; n < 2; ++n) _Pragma("unroll") for (int k = 0; k < 2; ++k) dst[n][k] = *(const LAS bf16x8*)(lds + PG8_SB(b, h) + boff + n * 2048 + k * 1024); } while (0)
; #define PG8_MMA(ai, bj, At, Bt) do { __builtin_amdgcn_s_setprio(1); _Pragma("unroll") for (int m = 0; m < 4; ++m) _Pragma("unroll") for (int n = 0; n < 2; ++n) _Pragma("unroll") for (int k = 0; k < 2; ++k) \
;         acc[ai][bj][m][n] = __builtin_amdgcn_mfma_f32_16x16x32_bf16(Bt[n][k], At[m][k], acc[ai][bj][m][n], 0, 0, 0); __builtin_amdgcn_s_setprio(0); } while (0)
; #define PG8_WAIT_V(n) asm volatile("s_waitcnt vmcnt(" #n ")" ::: "memory")
; #define PG8_WAIT_L(n) asm volatile("s_waitcnt lgkmcnt(" #n ")" ::: "memory")
; #define PG8_BAR __builtin_amdgcn_s_barrier()
; #define PG8_SCHED __builtin_amdgcn_sched_barrier(0)
; template <class Epi>
; __device__ __forceinline__ void gemm_phase(LAS unsigned char* lds, const Gemm g, int G, int c, const Epi& E) {
;     ...
;         for (int t = 0; t < nt; t += 2) {
;             const bool last = (t == nt - 2);
;             const char* a1 = cA + (size_t)(t + 1) * kstep;
;             const char* a2 = last ? nA : cA + (size_t)(t + 2) * kstep; const char* b2 = last ? nB : cB + (size_t)(t + 2) * kstep;
;             const char* a3 = a2 + kstep; const char* b3 = b2 + kstep;
;             PG8_LDB(B0, 0, 0); PG8_LDB(B1, 0, 1); PG8_SCHED; PG8_LDA(At, 0, 0); PG8_STAGE(PG8_SA(1, 1), a1 + hstepA, voffA);
;             PG8_WAIT_V(8); PG8_WAIT_L(0); PG8_BAR; PG8_MMA(0, 0, At, B0); PG8_MMA(0, 1, At, B1); PG8_BAR; PG8_SCHED;
;             PG8_LDA(At, 0, 1); PG8_STAGE(PG8_SB(0, 0), b2, voffB); PG8_STAGE(PG8_SB(0, 1), b2 + hstepB, voffB); PG8_STAGE(PG8_SA(0, 0), a2, voffA);
.LBB0_1451:
	s_add_u32 s33, s8, s44
	s_addc_u32 s45, s9, 0
	s_add_u32 s48, s33, 0x100
	s_addc_u32 s49, s45, 0
	s_and_b64 s[46:47], s[10:11], exec
	s_cselect_b32 s47, s41, s49
	s_cselect_b32 s46, s40, s48
	s_add_u32 s44, s6, s44
	s_addc_u32 s48, s7, 0
	s_add_u32 s44, s44, 0x100
	s_addc_u32 s48, s48, 0
	s_and_b64 s[10:11], s[10:11], exec
	s_cselect_b32 s49, s43, s48
	s_cselect_b32 s48, s42, s44
	s_add_u32 s54, s33, 0xb0080
	ds_read_b128 v[142:145], v160
	ds_read_b128 v[146:149], v160 offset:1024
	ds_read_b128 v[150:153], v160 offset:2048
	ds_read_b128 v[154:157], v160 offset:3072
	ds_read_b128 v[166:169], v161
	ds_read_b128 v[170:173], v161 offset:1024
	ds_read_b128 v[174:177], v161 offset:2048
	ds_read_b128 v[178:181], v161 offset:3072
	s_addc_u32 s55, s45, 0
	s_add_i32 s65, s82, s66
	s_add_i32 m0, s69, 0xc000
	s_add_i32 s74, s69, 0xe000
	s_add_i32 s62, s65, 0x2000
	s_add_u32 s52, s48, 0xb0000
	s_addc_u32 s53, s49, 0
	s_add_i32 s64, s83, s66
	s_add_i32 s63, s64, 0x2000
	s_add_i32 s97, 0, 0x18000
	s_add_i32 s33, 0, 0x1c000
	s_add_u32 s44, s46, 0xb0000
	s_addc_u32 s45, s47, 0
	s_add_i32 s96, s97, s66
	s_add_i32 s94, s96, 0x2000
	s_add_u32 s10, s48, 0xb0080
	s_addc_u32 s11, s49, 0
	s_add_i32 s95, s33, s66
	s_add_i32 s93, s95, 0x2000
	v_lshl_add_u64 v[214:215], s[54:55], 0, v[130:131]
	ds_read_b128 v[182:185], v162
	ds_read_b128 v[186:189], v162 offset:1024
	ds_read_b128 v[190:193], v162 offset:2048
	ds_read_b128 v[194:197], v162 offset:3072
	ds_read_b128 v[198:201], v162 offset:4096
	ds_read_b128 v[202:205], v162 offset:5120
	ds_read_b128 v[206:209], v162 offset:6144
	ds_read_b128 v[210:213], v162 offset:7168
	global_load_lds_dwordx4 v[214:215], off
	v_lshl_add_u64 v[214:215], s[54:55], 0, v[134:135]
	s_mov_b32 m0, s74
	s_nop 0
	global_load_lds_dwordx4 v[214:215], off
	s_waitcnt vmcnt(8)
	s_waitcnt lgkmcnt(0)
	s_barrier
	s_setprio 0
	s_waitcnt lgkmcnt(0)
	v_mfma_f32_16x16x32_bf16 v[126:129], v[142:145], v[182:185], v[126:129]
	v_mfma_f32_16x16x32_bf16 v[122:125], v[150:153], v[182:185], v[122:125]
	v_mfma_f32_16x16x32_bf16 v[106:109], v[150:153], v[190:193], v[106:109]
	v_mfma_f32_16x16x32_bf16 v[110:113], v[142:145], v[190:193], v[110:113]
	v_mfma_f32_16x16x32_bf16 v[94:97], v[142:145], v[198:201], v[94:97]
	v_mfma_f32_16x16x32_bf16 v[90:93], v[150:153], v[198:201], v[90:93]
	v_mfma_f32_16x16x32_bf16 v[74:77], v[150:153], v[206:209], v[74:77]
	v_mfma_f32_16x16x32_bf16 v[78:81], v[142:145], v[206:209], v[78:81]
	v_mfma_f32_16x16x32_bf16 v[126:129], v[146:149], v[186:189], v[126:129]
	v_mfma_f32_16x16x32_bf16 v[122:125], v[154:157], v[186:189], v[122:125]
	v_mfma_f32_16x16x32_bf16 v[106:109], v[154:157], v[194:197], v[106:109]
	v_mfma_f32_16x16x32_bf16 v[110:113], v[146:149], v[194:197], v[110:113]
	v_mfma_f32_16x16x32_bf16 v[94:97], v[146:149], v[202:205], v[94:97]
	v_mfma_f32_16x16x32_bf16 v[90:93], v[154:157], v[202:205], v[90:93]
	v_mfma_f32_16x16x32_bf16 v[74:77], v[154:157], v[210:213], v[74:77]
	v_mfma_f32_16x16x32_bf16 v[78:81], v[146:149], v[210:213], v[78:81]
	s_setprio 2
	s_setprio 0
	v_mfma_f32_16x16x32_bf16 v[118:121], v[166:169], v[182:185], v[118:121]
	v_mfma_f32_16x16x32_bf16 v[114:117], v[174:177], v[182:185], v[114:117]
	v_mfma_f32_16x16x32_bf16 v[98:101], v[174:177], v[190:193], v[98:101]
	v_mfma_f32_16x16x32_bf16 v[102:105], v[166:169], v[190:193], v[102:105]
	v_mfma_f32_16x16x32_bf16 v[86:89], v[166:169], v[198:201], v[86:89]
	v_mfma_f32_16x16x32_bf16 v[82:85], v[174:177], v[198:201], v[82:85]
	v_mfma_f32_16x16x32_bf16 v[66:69], v[174:177], v[206:209], v[66:69]
	v_mfma_f32_16x16x32_bf16 v[70:73], v[166:169], v[206:209], v[70:73]
	v_mfma_f32_16x16x32_bf16 v[118:121], v[170:173], v[186:189], v[118:121]
	v_mfma_f32_16x16x32_bf16 v[114:117], v[178:181], v[186:189], v[114:117]
	v_mfma_f32_16x16x32_bf16 v[98:101], v[178:181], v[194:197], v[98:101]
	v_mfma_f32_16x16x32_bf16 v[102:105], v[170:173], v[194:197], v[102:105]
	v_mfma_f32_16x16x32_bf16 v[86:89], v[170:173], v[202:205], v[86:89]
	v_mfma_f32_16x16x32_bf16 v[82:85], v[178:181], v[202:205], v[82:85]
	v_mfma_f32_16x16x32_bf16 v[66:69], v[178:181], v[210:213], v[66:69]
	v_mfma_f32_16x16x32_bf16 v[70:73], v[170:173], v[210:213], v[70:73]
	s_setprio 2
	s_barrier
	s_mov_b32 m0, s65
	v_lshl_add_u64 v[214:215], s[48:49], 0, v[132:133]
	ds_read_b128 v[182:185], v162 offset:16384
	ds_read_b128 v[186:189], v162 offset:17408
	ds_read_b128 v[190:193], v162 offset:18432
	ds_read_b128 v[194:197], v162 offset:19456
	ds_read_b128 v[198:201], v162 offset:20480
	ds_read_b128 v[202:205], v162 offset:21504
	ds_read_b128 v[206:209], v162 offset:22528
	ds_read_b128 v[210:213], v162 offset:23552
	global_load_lds_dwordx4 v[214:215], off
	v_lshl_add_u64 v[216:217], s[48:49], 0, v[136:137]
	s_mov_b32 m0, s62
	v_lshl_add_u64 v[218:219], s[52:53], 0, v[132:133]
	global_load_lds_dwordx4 v[216:217], off
	s_mov_b32 m0, s64
	v_lshl_add_u64 v[220:221], s[46:47], 0, v[134:135]
	global_load_lds_dwordx4 v[218:219], off
	v_lshl_add_u64 v[218:219], s[52:53], 0, v[136:137]
	s_mov_b32 m0, s63
	s_nop 0
	global_load_lds_dwordx4 v[218:219], off
	v_lshl_add_u64 v[218:219], s[46:47], 0, v[130:131]
	s_mov_b32 m0, s69
	s_nop 0
	global_load_lds_dwordx4 v[218:219], off
	s_mov_b32 m0, s70
	s_nop 0
	global_load_lds_dwordx4 v[220:221], off
	s_waitcnt vmcnt(8)
	s_waitcnt lgkmcnt(0)
	s_barrier
; #define PG8_STAGE(bufoff, gbase, voff) do { _Pragma("unroll") for (int _i = 0; _i < 2; ++_i) \
;         __builtin_amdgcn_global_load_lds((const unsigned*)((const char*)(gbase) + (voff)[_i]), (LAS unsigned*)(lds + (bufoff) + ldsw + _i * 8192), 16, 0, 0); } while (0)
; #define PG8_LDA(dst, b, h) do { _Pragma("unroll") for (int m = 0; m < 4; ++m) _Pragma("unroll") for (int k = 0; k < 2; ++k) dst[m][k] = *(const LAS bf16x8*)(lds + PG8_SA(b, h) + aoff + m * 2048 + k * 1024); } while (0)
; #define PG8_LDB(dst, b, h) do { _Pragma("unroll") for (int n = 0; n < 2; ++n) _Pragma("unroll") for (int k = 0; k < 2; ++k) dst[n][k] = *(const LAS bf16x8*)(lds + PG8_SB(b, h) + boff + n * 2048 + k * 1024); } while (0)
; #define PG8_MMA(ai, bj, At, Bt) do { __builtin_amdgcn_s_setprio(1); _Pragma("unroll") for (int m = 0; m < 4; ++m) _Pragma("unroll") for (int n = 0; n < 2; ++n) _Pragma("unroll") for (int k = 0; k < 2; ++k) \
;         acc[ai][bj][m][n] = __builtin_amdgcn_mfma_f32_16x16x32_bf16(Bt[n][k], At[m][k], acc[ai][bj][m][n], 0, 0, 0); __builtin_amdgcn_s_setprio(0); } while (0)
; #define PG8_WAIT_V(n) asm volatile("s_waitcnt vmcnt(" #n ")" ::: "memory")
; #define PG8_WAIT_L(n) asm volatile("s_waitcnt lgkmcnt(" #n ")" ::: "memory")
; #define PG8_BAR __builtin_amdgcn_s_barrier()
; #define PG8_SCHED __builtin_amdgcn_sched_barrier(0)
; template <class Epi>
; __device__ __forceinline__ void gemm_phase(LAS unsigned char* lds, const Gemm g, int G, int c, const Epi& E) {
;     ...
;             PG8_WAIT_V(8); PG8_WAIT_L(0); PG8_BAR; PG8_MMA(1, 0, At, B0); PG8_MMA(1, 1, At, B1); PG8_BAR; PG8_SCHED;
;             PG8_LDB(B0, 1, 0); PG8_LDB(B1, 1, 1); PG8_SCHED; PG8_LDA(At, 1, 0); PG8_STAGE(PG8_SA(0, 1), a2 + hstepA, voffA);
;             PG8_WAIT_V(8); PG8_WAIT_L(0); PG8_BAR; PG8_MMA(0, 0, At, B0); PG8_MMA(0, 1, At, B1); PG8_BAR; PG8_SCHED;
	s_setprio 0
	s_waitcnt lgkmcnt(0)
	v_mfma_f32_16x16x32_bf16 v[62:65], v[142:145], v[182:185], v[62:65]
	v_mfma_f32_16x16x32_bf16 v[58:61], v[150:153], v[182:185], v[58:61]
	v_mfma_f32_16x16x32_bf16 v[42:45], v[150:153], v[190:193], v[42:45]
	v_mfma_f32_16x16x32_bf16 v[46:49], v[142:145], v[190:193], v[46:49]
	v_mfma_f32_16x16x32_bf16 v[30:33], v[142:145], v[198:201], v[30:33]
	v_mfma_f32_16x16x32_bf16 v[26:29], v[150:153], v[198:201], v[26:29]
	v_mfma_f32_16x16x32_bf16 v[10:13], v[150:153], v[206:209], v[10:13]
	v_mfma_f32_16x16x32_bf16 v[14:17], v[142:145], v[206:209], v[14:17]
	v_mfma_f32_16x16x32_bf16 v[62:65], v[146:149], v[186:189], v[62:65]
	v_mfma_f32_16x16x32_bf16 v[58:61], v[154:157], v[186:189], v[58:61]
	v_mfma_f32_16x16x32_bf16 v[42:45], v[154:157], v[194:197], v[42:45]
	v_mfma_f32_16x16x32_bf16 v[46:49], v[146:149], v[194:197], v[46:49]
	v_mfma_f32_16x16x32_bf16 v[30:33], v[146:149], v[202:205], v[30:33]
	v_mfma_f32_16x16x32_bf16 v[26:29], v[154:157], v[202:205], v[26:29]
	v_mfma_f32_16x16x32_bf16 v[10:13], v[154:157], v[210:213], v[10:13]
	v_mfma_f32_16x16x32_bf16 v[14:17], v[146:149], v[210:213], v[14:17]
	s_setprio 2
	s_setprio 0
	v_mfma_f32_16x16x32_bf16 v[54:57], v[166:169], v[182:185], v[54:57]
	v_mfma_f32_16x16x32_bf16 v[50:53], v[174:177], v[182:185], v[50:53]
	v_mfma_f32_16x16x32_bf16 v[34:37], v[174:177], v[190:193], v[34:37]
	v_mfma_f32_16x16x32_bf16 v[38:41], v[166:169], v[190:193], v[38:41]
	v_mfma_f32_16x16x32_bf16 v[22:25], v[166:169], v[198:201], v[22:25]
	v_mfma_f32_16x16x32_bf16 v[18:21], v[174:177], v[198:201], v[18:21]
	v_mfma_f32_16x16x32_bf16 v[2:5], v[174:177], v[206:209], v[2:5]
	v_mfma_f32_16x16x32_bf16 v[6:9], v[166:169], v[206:209], v[6:9]
	v_mfma_f32_16x16x32_bf16 v[54:57], v[170:173], v[186:189], v[54:57]
	v_mfma_f32_16x16x32_bf16 v[50:53], v[178:181], v[186:189], v[50:53]
	v_mfma_f32_16x16x32_bf16 v[34:37], v[178:181], v[194:197], v[34:37]
	v_mfma_f32_16x16x32_bf16 v[38:41], v[170:173], v[194:197], v[38:41]
	v_mfma_f32_16x16x32_bf16 v[22:25], v[170:173], v[202:205], v[22:25]
	v_mfma_f32_16x16x32_bf16 v[18:21], v[178:181], v[202:205], v[18:21]
	v_mfma_f32_16x16x32_bf16 v[2:5], v[178:181], v[210:213], v[2:5]
	v_mfma_f32_16x16x32_bf16 v[6:9], v[170:173], v[210:213], v[6:9]
	s_setprio 2
	s_barrier
	v_add_u32_e32 v154, s97, v159
	v_add_u32_e32 v178, s33, v159
	ds_read_b128 v[142:145], v154
	ds_read_b128 v[146:149], v154 offset:1024
	ds_read_b128 v[150:153], v154 offset:2048
	ds_read_b128 v[154:157], v154 offset:3072
	ds_read_b128 v[166:169], v178
	ds_read_b128 v[170:173], v178 offset:1024
	ds_read_b128 v[174:177], v178 offset:2048
	ds_read_b128 v[178:181], v178 offset:3072
	s_mov_b32 m0, s71
	v_lshl_add_u64 v[222:223], s[44:45], 0, v[130:131]
	ds_read_b128 v[182:185], v162 offset:32768
	ds_read_b128 v[186:189], v162 offset:33792
	ds_read_b128 v[190:193], v162 offset:34816
	ds_read_b128 v[194:197], v162 offset:35840
	ds_read_b128 v[198:201], v162 offset:36864
	ds_read_b128 v[202:205], v162 offset:37888
	ds_read_b128 v[206:209], v162 offset:38912
	ds_read_b128 v[210:213], v162 offset:39936
	global_load_lds_dwordx4 v[222:223], off
	v_lshl_add_u64 v[222:223], s[44:45], 0, v[134:135]
	s_mov_b32 m0, s72
	s_nop 0
	global_load_lds_dwordx4 v[222:223], off
	s_waitcnt vmcnt(8)
	s_waitcnt lgkmcnt(0)
	s_barrier
	s_setprio 0
	s_waitcnt lgkmcnt(0)
	v_mfma_f32_16x16x32_bf16 v[126:129], v[142:145], v[182:185], v[126:129]
	v_mfma_f32_16x16x32_bf16 v[122:125], v[150:153], v[182:185], v[122:125]
	v_mfma_f32_16x16x32_bf16 v[106:109], v[150:153], v[190:193], v[106:109]
	v_mfma_f32_16x16x32_bf16 v[110:113], v[142:145], v[190:193], v[110:113]
	v_mfma_f32_16x16x32_bf16 v[94:97], v[142:145], v[198:201], v[94:97]
	v_mfma_f32_16x16x32_bf16 v[90:93], v[150:153], v[198:201], v[90:93]
	v_mfma_f32_16x16x32_bf16 v[74:77], v[150:153], v[206:209], v[74:77]
	v_mfma_f32_16x16x32_bf16 v[78:81], v[142:145], v[206:209], v[78:81]
	v_mfma_f32_16x16x32_bf16 v[126:129], v[146:149], v[186:189], v[126:129]
	v_mfma_f32_16x16x32_bf16 v[122:125], v[154:157], v[186:189], v[122:125]
	v_mfma_f32_16x16x32_bf16 v[106:109], v[154:157], v[194:197], v[106:109]
	v_mfma_f32_16x16x32_bf16 v[110:113], v[146:149], v[194:197], v[110:113]
	v_mfma_f32_16x16x32_bf16 v[94:97], v[146:149], v[202:205], v[94:97]
	v_mfma_f32_16x16x32_bf16 v[90:93], v[154:157], v[202:205], v[90:93]
	v_mfma_f32_16x16x32_bf16 v[74:77], v[154:157], v[210:213], v[74:77]
	v_mfma_f32_16x16x32_bf16 v[78:81], v[146:149], v[210:213], v[78:81]
	s_setprio 2
	s_setprio 0
	v_mfma_f32_16x16x32_bf16 v[118:121], v[166:169], v[182:185], v[118:121]
	v_mfma_f32_16x16x32_bf16 v[114:117], v[174:177], v[182:185], v[114:117]
	v_mfma_f32_16x16x32_bf16 v[98:101], v[174:177], v[190:193], v[98:101]
	v_mfma_f32_16x16x32_bf16 v[102:105], v[166:169], v[190:193], v[102:105]
	v_mfma_f32_16x16x32_bf16 v[86:89], v[166:169], v[198:201], v[86:89]
	v_mfma_f32_16x16x32_bf16 v[82:85], v[174:177], v[198:201], v[82:85]
	v_mfma_f32_16x16x32_bf16 v[66:69], v[174:177], v[206:209], v[66:69]
	v_mfma_f32_16x16x32_bf16 v[70:73], v[166:169], v[206:209], v[70:73]
	v_mfma_f32_16x16x32_bf16 v[118:121], v[170:173], v[186:189], v[118:121]
	v_mfma_f32_16x16x32_bf16 v[114:117], v[178:181], v[186:189], v[114:117]
	v_mfma_f32_16x16x32_bf16 v[98:101], v[178:181], v[194:197], v[98:101]
	v_mfma_f32_16x16x32_bf16 v[102:105], v[170:173], v[194:197], v[102:105]
	v_mfma_f32_16x16x32_bf16 v[86:89], v[170:173], v[202:205], v[86:89]
	v_mfma_f32_16x16x32_bf16 v[82:85], v[178:181], v[202:205], v[82:85]
	v_mfma_f32_16x16x32_bf16 v[66:69], v[178:181], v[210:213], v[66:69]
	v_mfma_f32_16x16x32_bf16 v[70:73], v[170:173], v[210:213], v[70:73]
	s_setprio 2
	s_barrier
; #define PG8_STAGE(bufoff, gbase, voff) do { _Pragma("unroll") for (int _i = 0; _i < 2; ++_i) \
;         __builtin_amdgcn_global_load_lds((const unsigned*)((const char*)(gbase) + (voff)[_i]), (LAS unsigned*)(lds + (bufoff) + ldsw + _i * 8192), 16, 0, 0); } while (0)
; #define PG8_LDA(dst, b, h) do { _Pragma("unroll") for (int m = 0; m < 4; ++m) _Pragma("unroll") for (int k = 0; k < 2; ++k) dst[m][k] = *(const LAS bf16x8*)(lds + PG8_SA(b, h) + aoff + m * 2048 + k * 1024); } while (0)
; #define PG8_MMA(ai, bj, At, Bt) do { __builtin_amdgcn_s_setprio(1); _Pragma("unroll") for (int m = 0; m < 4; ++m) _Pragma("unroll") for (int n = 0; n < 2; ++n) _Pragma("unroll") for (int k = 0; k < 2; ++k) \
;         acc[ai][bj][m][n] = __builtin_amdgcn_mfma_f32_16x16x32_bf16(Bt[n][k], At[m][k], acc[ai][bj][m][n], 0, 0, 0); __builtin_amdgcn_s_setprio(0); } while (0)
; #define PG8_WAIT_V(n) asm volatile("s_waitcnt vmcnt(" #n ")" ::: "memory")
; #define PG8_WAIT_L(n) asm volatile("s_waitcnt lgkmcnt(" #n ")" ::: "memory")
; #define PG8_BAR __builtin_amdgcn_s_barrier()
; #define PG8_SCHED __builtin_amdgcn_sched_barrier(0)
; template <class Epi>
; __device__ __forceinline__ void gemm_phase(LAS unsigned char* lds, const Gemm g, int G, int c, const Epi& E) {
;     ...
;             PG8_LDA(At, 1, 1); PG8_STAGE(PG8_SB(1, 0), b3, voffB); PG8_STAGE(PG8_SB(1, 1), b3 + hstepB, voffB); PG8_STAGE(PG8_SA(1, 0), a3, voffA);
;             PG8_WAIT_V(8); PG8_WAIT_L(0); PG8_BAR; PG8_MMA(1, 0, At, B0); PG8_MMA(1, 1, At, B1); PG8_BAR; PG8_SCHED;
;         }
;         if (wr == 0) PG8_BAR;
	s_mov_b32 m0, s96
	v_lshl_add_u64 v[214:215], v[214:215], 0, s[22:23]
	ds_read_b128 v[182:185], v162 offset:49152
	ds_read_b128 v[186:189], v162 offset:50176
	ds_read_b128 v[190:193], v162 offset:51200
	ds_read_b128 v[194:197], v162 offset:52224
	ds_read_b128 v[198:201], v162 offset:53248
	ds_read_b128 v[202:205], v162 offset:54272
	ds_read_b128 v[206:209], v162 offset:55296
	ds_read_b128 v[210:213], v162 offset:56320
	global_load_lds_dwordx4 v[214:215], off
	v_lshl_add_u64 v[214:215], v[216:217], 0, s[22:23]
	s_mov_b32 m0, s94
	s_nop 0
	global_load_lds_dwordx4 v[214:215], off
	v_lshl_add_u64 v[214:215], s[10:11], 0, v[132:133]
	s_mov_b32 m0, s95
	s_nop 0
	global_load_lds_dwordx4 v[214:215], off
	v_lshl_add_u64 v[214:215], s[10:11], 0, v[136:137]
	s_mov_b32 m0, s93
	s_nop 0
	global_load_lds_dwordx4 v[214:215], off
	v_lshl_add_u64 v[214:215], v[218:219], 0, s[22:23]
	s_mov_b32 m0, s80
	s_nop 0
	global_load_lds_dwordx4 v[214:215], off
	v_lshl_add_u64 v[214:215], v[220:221], 0, s[22:23]
	s_mov_b32 m0, s81
	s_nop 0
	global_load_lds_dwordx4 v[214:215], off
	s_waitcnt vmcnt(8)
	s_waitcnt lgkmcnt(0)
	s_barrier
	s_setprio 0
	s_waitcnt lgkmcnt(0)
	v_mfma_f32_16x16x32_bf16 v[62:65], v[142:145], v[182:185], v[62:65]
	v_mfma_f32_16x16x32_bf16 v[58:61], v[150:153], v[182:185], v[58:61]
	v_mfma_f32_16x16x32_bf16 v[42:45], v[150:153], v[190:193], v[42:45]
	v_mfma_f32_16x16x32_bf16 v[46:49], v[142:145], v[190:193], v[46:49]
	v_mfma_f32_16x16x32_bf16 v[30:33], v[142:145], v[198:201], v[30:33]
	v_mfma_f32_16x16x32_bf16 v[26:29], v[150:153], v[198:201], v[26:29]
	v_mfma_f32_16x16x32_bf16 v[10:13], v[150:153], v[206:209], v[10:13]
	v_mfma_f32_16x16x32_bf16 v[14:17], v[142:145], v[206:209], v[14:17]
	v_mfma_f32_16x16x32_bf16 v[62:65], v[146:149], v[186:189], v[62:65]
	v_mfma_f32_16x16x32_bf16 v[58:61], v[154:157], v[186:189], v[58:61]
	v_mfma_f32_16x16x32_bf16 v[42:45], v[154:157], v[194:197], v[42:45]
	v_mfma_f32_16x16x32_bf16 v[46:49], v[146:149], v[194:197], v[46:49]
	v_mfma_f32_16x16x32_bf16 v[30:33], v[146:149], v[202:205], v[30:33]
	v_mfma_f32_16x16x32_bf16 v[26:29], v[154:157], v[202:205], v[26:29]
	v_mfma_f32_16x16x32_bf16 v[10:13], v[154:157], v[210:213], v[10:13]
	v_mfma_f32_16x16x32_bf16 v[14:17], v[146:149], v[210:213], v[14:17]
	s_setprio 2
	s_setprio 0
	v_mfma_f32_16x16x32_bf16 v[54:57], v[166:169], v[182:185], v[54:57]
	v_mfma_f32_16x16x32_bf16 v[50:53], v[174:177], v[182:185], v[50:53]
	v_mfma_f32_16x16x32_bf16 v[34:37], v[174:177], v[190:193], v[34:37]
	v_mfma_f32_16x16x32_bf16 v[38:41], v[166:169], v[190:193], v[38:41]
	v_mfma_f32_16x16x32_bf16 v[22:25], v[166:169], v[198:201], v[22:25]
	v_mfma_f32_16x16x32_bf16 v[18:21], v[174:177], v[198:201], v[18:21]
	v_mfma_f32_16x16x32_bf16 v[2:5], v[174:177], v[206:209], v[2:5]
	v_mfma_f32_16x16x32_bf16 v[6:9], v[166:169], v[206:209], v[6:9]
	v_mfma_f32_16x16x32_bf16 v[54:57], v[170:173], v[186:189], v[54:57]
	v_mfma_f32_16x16x32_bf16 v[50:53], v[178:181], v[186:189], v[50:53]
	v_mfma_f32_16x16x32_bf16 v[34:37], v[178:181], v[194:197], v[34:37]
	v_mfma_f32_16x16x32_bf16 v[38:41], v[170:173], v[194:197], v[38:41]
	v_mfma_f32_16x16x32_bf16 v[22:25], v[170:173], v[202:205], v[22:25]
	v_mfma_f32_16x16x32_bf16 v[18:21], v[178:181], v[202:205], v[18:21]
	v_mfma_f32_16x16x32_bf16 v[2:5], v[178:181], v[210:213], v[2:5]
	v_mfma_f32_16x16x32_bf16 v[6:9], v[170:173], v[210:213], v[6:9]
	s_setprio 2
	s_barrier
	s_movk_i32 s44, 0x100
	s_andn2_b64 vcc, exec, s[4:5]
	s_mov_b64 s[10:11], -1
	s_mov_b64 s[4:5], 0
	s_cbranch_vccz .LBB0_1451
	s_and_b64 vcc, exec, s[24:25]
	s_cbranch_vccz .LBB0_1454
	s_barrier

; #define PG8_STAGE(bufoff, gbase, voff) do { _Pragma("unroll") for (int _i = 0; _i < 2; ++_i) \
;         __builtin_amdgcn_global_load_lds((const unsigned*)((const char*)(gbase) + (voff)[_i]), (LAS unsigned*)(lds + (bufoff) + ldsw + _i * 8192), 16, 0, 0); } while (0)
; #define PG8_LDA(dst, b, h) do { _Pragma("unroll") for (int m = 0; m < 4; ++m) _Pragma("unroll") for (int k = 0; k < 2; ++k) dst[m][k] = *(const LAS bf16x8*)(lds + PG8_SA(b, h) + aoff + m * 2048 + k * 1024); } while (0)
; #define PG8_LDB(dst, b, h) do { _Pragma("unroll") for (int n = 0; n < 2; ++n) _Pragma("unroll") for (int k = 0; k < 2; ++k) dst[n][k] = *(const LAS bf16x8*)(lds + PG8_SB(b, h) + boff + n * 2048 + k * 1024); } while (0)
; #define PG8_MMA(ai, bj, At, Bt) do { __builtin_amdgcn_s_setprio(1); _Pragma("unroll") for (int m = 0; m < 4; ++m) _Pragma("unroll") for (int n = 0; n < 2; ++n) _Pragma("unroll") for (int k = 0; k < 2; ++k) \
;         acc[ai][bj][m][n] = __builtin_amdgcn_mfma_f32_16x16x32_bf16(Bt[n][k], At[m][k], acc[ai][bj][m][n], 0, 0, 0); __builtin_amdgcn_s_setprio(0); } while (0)
; #define PG8_WAIT_V(n) asm volatile("s_waitcnt vmcnt(" #n ")" ::: "memory")
; #define PG8_WAIT_L(n) asm volatile("s_waitcnt lgkmcnt(" #n ")" ::: "memory")
; #define PG8_BAR __builtin_amdgcn_s_barrier()
; #define PG8_SCHED __builtin_amdgcn_sched_barrier(0)
; template <class Epi>
; __device__ __forceinline__ void gemm_phase(LAS unsigned char* lds, const Gemm g, int G, int c, const Epi& E) {
;     ...
;         for (int t = 0; t < nt; t += 2) {
;             const bool last = (t == nt - 2);
;             const char* a1 = cA + (size_t)(t + 1) * kstep;
;             const char* a2 = last ? nA : cA + (size_t)(t + 2) * kstep; const char* b2 = last ? nB : cB + (size_t)(t + 2) * kstep;
;             const char* a3 = a2 + kstep; const char* b3 = b2 + kstep;
;             PG8_LDB(B0, 0, 0); PG8_LDB(B1, 0, 1); PG8_SCHED; PG8_LDA(At, 0, 0); PG8_STAGE(PG8_SA(1, 1), a1 + hstepA, voffA);
;             PG8_WAIT_V(8); PG8_WAIT_L(0); PG8_BAR; PG8_MMA(0, 0, At, B0); PG8_MMA(0, 1, At, B1); PG8_BAR; PG8_SCHED;
;             PG8_LDA(At, 0, 1); PG8_STAGE(PG8_SB(0, 0), b2, voffB); PG8_STAGE(PG8_SB(0, 1), b2 + hstepB, voffB); PG8_STAGE(PG8_SA(0, 0), a2, voffA);
.LBB0_1537:
	s_add_u32 s33, s8, s44
	s_addc_u32 s45, s9, 0
	s_add_u32 s48, s33, 0x100
	s_addc_u32 s49, s45, 0
	s_and_b64 s[46:47], s[10:11], exec
	s_cselect_b32 s47, s41, s49
	s_cselect_b32 s46, s40, s48
	s_add_u32 s44, s6, s44
	s_addc_u32 s48, s7, 0
	s_add_u32 s44, s44, 0x100
	s_addc_u32 s48, s48, 0
	s_and_b64 s[10:11], s[10:11], exec
	s_cselect_b32 s49, s43, s48
	s_cselect_b32 s48, s42, s44
	s_add_u32 s54, s33, 0xb0080
	ds_read_b128 v[130:133], v166
	ds_read_b128 v[134:137], v166 offset:1024
	ds_read_b128 v[150:153], v166 offset:2048
	ds_read_b128 v[154:157], v166 offset:3072
	ds_read_b128 v[158:161], v167
	ds_read_b128 v[172:175], v167 offset:1024
	ds_read_b128 v[176:179], v167 offset:2048
	ds_read_b128 v[180:183], v167 offset:3072
	s_addc_u32 s55, s45, 0
	s_add_i32 s63, s87, s70
	s_add_i32 m0, s73, 0xc000
	s_add_i32 s64, s73, 0xe000
	s_add_i32 s74, s63, 0x2000
	s_add_u32 s52, s48, 0xb0000
	s_addc_u32 s53, s49, 0
	s_add_i32 s62, s88, s70
	s_add_i32 s75, s62, 0x2000
	s_add_i32 s97, 0, 0x18000
	s_add_i32 s33, 0, 0x1c000
	s_add_u32 s44, s46, 0xb0000
	s_addc_u32 s45, s47, 0
	s_add_i32 s96, s97, s70
	s_add_i32 s94, s96, 0x2000
	s_add_u32 s10, s48, 0xb0080
	s_addc_u32 s11, s49, 0
	s_add_i32 s95, s33, s70
	s_add_i32 s93, s95, 0x2000
	v_lshl_add_u64 v[162:163], s[54:55], 0, v[138:139]
	ds_read_b128 v[184:187], v168
	ds_read_b128 v[188:191], v168 offset:1024
	ds_read_b128 v[192:195], v168 offset:2048
	ds_read_b128 v[196:199], v168 offset:3072
	ds_read_b128 v[200:203], v168 offset:4096
	ds_read_b128 v[204:207], v168 offset:5120
	ds_read_b128 v[208:211], v168 offset:6144
	ds_read_b128 v[212:215], v168 offset:7168
	global_load_lds_dwordx4 v[162:163], off
	v_lshl_add_u64 v[162:163], s[54:55], 0, v[142:143]
	s_mov_b32 m0, s64
	s_nop 0
	global_load_lds_dwordx4 v[162:163], off
	s_waitcnt vmcnt(8)
	s_waitcnt lgkmcnt(0)
	s_barrier
	s_setprio 0
	s_waitcnt lgkmcnt(0)
	v_mfma_f32_16x16x32_bf16 v[126:129], v[130:133], v[184:187], v[126:129]
	v_mfma_f32_16x16x32_bf16 v[122:125], v[150:153], v[184:187], v[122:125]
	v_mfma_f32_16x16x32_bf16 v[106:109], v[150:153], v[192:195], v[106:109]
	v_mfma_f32_16x16x32_bf16 v[110:113], v[130:133], v[192:195], v[110:113]
	v_mfma_f32_16x16x32_bf16 v[94:97], v[130:133], v[200:203], v[94:97]
	v_mfma_f32_16x16x32_bf16 v[90:93], v[150:153], v[200:203], v[90:93]
	v_mfma_f32_16x16x32_bf16 v[74:77], v[150:153], v[208:211], v[74:77]
	v_mfma_f32_16x16x32_bf16 v[78:81], v[130:133], v[208:211], v[78:81]
	v_mfma_f32_16x16x32_bf16 v[126:129], v[134:137], v[188:191], v[126:129]
	v_mfma_f32_16x16x32_bf16 v[122:125], v[154:157], v[188:191], v[122:125]
	v_mfma_f32_16x16x32_bf16 v[106:109], v[154:157], v[196:199], v[106:109]
	v_mfma_f32_16x16x32_bf16 v[110:113], v[134:137], v[196:199], v[110:113]
	v_mfma_f32_16x16x32_bf16 v[94:97], v[134:137], v[204:207], v[94:97]
	v_mfma_f32_16x16x32_bf16 v[90:93], v[154:157], v[204:207], v[90:93]
	v_mfma_f32_16x16x32_bf16 v[74:77], v[154:157], v[212:215], v[74:77]
	v_mfma_f32_16x16x32_bf16 v[78:81], v[134:137], v[212:215], v[78:81]
	s_setprio 2
	s_setprio 0
	v_mfma_f32_16x16x32_bf16 v[118:121], v[158:161], v[184:187], v[118:121]
	v_mfma_f32_16x16x32_bf16 v[114:117], v[176:179], v[184:187], v[114:117]
	v_mfma_f32_16x16x32_bf16 v[98:101], v[176:179], v[192:195], v[98:101]
	v_mfma_f32_16x16x32_bf16 v[102:105], v[158:161], v[192:195], v[102:105]
	v_mfma_f32_16x16x32_bf16 v[86:89], v[158:161], v[200:203], v[86:89]
	v_mfma_f32_16x16x32_bf16 v[82:85], v[176:179], v[200:203], v[82:85]
	v_mfma_f32_16x16x32_bf16 v[66:69], v[176:179], v[208:211], v[66:69]
	v_mfma_f32_16x16x32_bf16 v[70:73], v[158:161], v[208:211], v[70:73]
	v_mfma_f32_16x16x32_bf16 v[118:121], v[172:175], v[188:191], v[118:121]
	v_mfma_f32_16x16x32_bf16 v[114:117], v[180:183], v[188:191], v[114:117]
	v_mfma_f32_16x16x32_bf16 v[98:101], v[180:183], v[196:199], v[98:101]
	v_mfma_f32_16x16x32_bf16 v[102:105], v[172:175], v[196:199], v[102:105]
	v_mfma_f32_16x16x32_bf16 v[86:89], v[172:175], v[204:207], v[86:89]
	v_mfma_f32_16x16x32_bf16 v[82:85], v[180:183], v[204:207], v[82:85]
	v_mfma_f32_16x16x32_bf16 v[66:69], v[180:183], v[212:215], v[66:69]
	v_mfma_f32_16x16x32_bf16 v[70:73], v[172:175], v[212:215], v[70:73]
	s_setprio 2
	s_barrier
	s_mov_b32 m0, s63
	v_lshl_add_u64 v[162:163], s[48:49], 0, v[140:141]
	ds_read_b128 v[184:187], v168 offset:16384
	ds_read_b128 v[188:191], v168 offset:17408
	ds_read_b128 v[192:195], v168 offset:18432
	ds_read_b128 v[196:199], v168 offset:19456
	ds_read_b128 v[200:203], v168 offset:20480
	ds_read_b128 v[204:207], v168 offset:21504
	ds_read_b128 v[208:211], v168 offset:22528
	ds_read_b128 v[212:215], v168 offset:23552
	global_load_lds_dwordx4 v[162:163], off
	v_lshl_add_u64 v[216:217], s[48:49], 0, v[144:145]
	s_mov_b32 m0, s74
	v_lshl_add_u64 v[218:219], s[52:53], 0, v[140:141]
	global_load_lds_dwordx4 v[216:217], off
	s_mov_b32 m0, s62
	v_lshl_add_u64 v[220:221], s[46:47], 0, v[142:143]
	global_load_lds_dwordx4 v[218:219], off
	v_lshl_add_u64 v[218:219], s[52:53], 0, v[144:145]
	s_mov_b32 m0, s75
	s_nop 0
	global_load_lds_dwordx4 v[218:219], off
	v_lshl_add_u64 v[218:219], s[46:47], 0, v[138:139]
	s_mov_b32 m0, s73
	s_nop 0
	global_load_lds_dwordx4 v[218:219], off
	s_mov_b32 m0, s79
	s_nop 0
	global_load_lds_dwordx4 v[220:221], off
	s_waitcnt vmcnt(8)
	s_waitcnt lgkmcnt(0)
	s_barrier
; #define PG8_STAGE(bufoff, gbase, voff) do { _Pragma("unroll") for (int _i = 0; _i < 2; ++_i) \
;         __builtin_amdgcn_global_load_lds((const unsigned*)((const char*)(gbase) + (voff)[_i]), (LAS unsigned*)(lds + (bufoff) + ldsw + _i * 8192), 16, 0, 0); } while (0)
; #define PG8_LDA(dst, b, h) do { _Pragma("unroll") for (int m = 0; m < 4; ++m) _Pragma("unroll") for (int k = 0; k < 2; ++k) dst[m][k] = *(const LAS bf16x8*)(lds + PG8_SA(b, h) + aoff + m * 2048 + k * 1024); } while (0)
; #define PG8_LDB(dst, b, h) do { _Pragma("unroll") for (int n = 0; n < 2; ++n) _Pragma("unroll") for (int k = 0; k < 2; ++k) dst[n][k] = *(const LAS bf16x8*)(lds + PG8_SB(b, h) + boff + n * 2048 + k * 1024); } while (0)
; #define PG8_MMA(ai, bj, At, Bt) do { __builtin_amdgcn_s_setprio(1); _Pragma("unroll") for (int m = 0; m < 4; ++m) _Pragma("unroll") for (int n = 0; n < 2; ++n) _Pragma("unroll") for (int k = 0; k < 2; ++k) \
;         acc[ai][bj][m][n] = __builtin_amdgcn_mfma_f32_16x16x32_bf16(Bt[n][k], At[m][k], acc[ai][bj][m][n], 0, 0, 0); __builtin_amdgcn_s_setprio(0); } while (0)
; #define PG8_WAIT_V(n) asm volatile("s_waitcnt vmcnt(" #n ")" ::: "memory")
; #define PG8_WAIT_L(n) asm volatile("s_waitcnt lgkmcnt(" #n ")" ::: "memory")
; #define PG8_BAR __builtin_amdgcn_s_barrier()
; #define PG8_SCHED __builtin_amdgcn_sched_barrier(0)
; template <class Epi>
; __device__ __forceinline__ void gemm_phase(LAS unsigned char* lds, const Gemm g, int G, int c, const Epi& E) {
;     ...
;             PG8_WAIT_V(8); PG8_WAIT_L(0); PG8_BAR; PG8_MMA(1, 0, At, B0); PG8_MMA(1, 1, At, B1); PG8_BAR; PG8_SCHED;
;             PG8_LDB(B0, 1, 0); PG8_LDB(B1, 1, 1); PG8_SCHED; PG8_LDA(At, 1, 0); PG8_STAGE(PG8_SA(0, 1), a2 + hstepA, voffA);
;             PG8_WAIT_V(8); PG8_WAIT_L(0); PG8_BAR; PG8_MMA(0, 0, At, B0); PG8_MMA(0, 1, At, B1); PG8_BAR; PG8_SCHED;
	s_setprio 0
	s_waitcnt lgkmcnt(0)
	v_mfma_f32_16x16x32_bf16 v[62:65], v[130:133], v[184:187], v[62:65]
	v_mfma_f32_16x16x32_bf16 v[58:61], v[150:153], v[184:187], v[58:61]
	v_mfma_f32_16x16x32_bf16 v[42:45], v[150:153], v[192:195], v[42:45]
	v_mfma_f32_16x16x32_bf16 v[46:49], v[130:133], v[192:195], v[46:49]
	v_mfma_f32_16x16x32_bf16 v[30:33], v[130:133], v[200:203], v[30:33]
	v_mfma_f32_16x16x32_bf16 v[26:29], v[150:153], v[200:203], v[26:29]
	v_mfma_f32_16x16x32_bf16 v[10:13], v[150:153], v[208:211], v[10:13]
	v_mfma_f32_16x16x32_bf16 v[14:17], v[130:133], v[208:211], v[14:17]
	v_mfma_f32_16x16x32_bf16 v[62:65], v[134:137], v[188:191], v[62:65]
	v_mfma_f32_16x16x32_bf16 v[58:61], v[154:157], v[188:191], v[58:61]
	v_mfma_f32_16x16x32_bf16 v[42:45], v[154:157], v[196:199], v[42:45]
	v_mfma_f32_16x16x32_bf16 v[46:49], v[134:137], v[196:199], v[46:49]
	v_mfma_f32_16x16x32_bf16 v[30:33], v[134:137], v[204:207], v[30:33]
	v_mfma_f32_16x16x32_bf16 v[26:29], v[154:157], v[204:207], v[26:29]
	v_mfma_f32_16x16x32_bf16 v[10:13], v[154:157], v[212:215], v[10:13]
	v_mfma_f32_16x16x32_bf16 v[14:17], v[134:137], v[212:215], v[14:17]
	s_setprio 2
	s_setprio 0
	v_mfma_f32_16x16x32_bf16 v[54:57], v[158:161], v[184:187], v[54:57]
	v_mfma_f32_16x16x32_bf16 v[50:53], v[176:179], v[184:187], v[50:53]
	v_mfma_f32_16x16x32_bf16 v[34:37], v[176:179], v[192:195], v[34:37]
	v_mfma_f32_16x16x32_bf16 v[38:41], v[158:161], v[192:195], v[38:41]
	v_mfma_f32_16x16x32_bf16 v[22:25], v[158:161], v[200:203], v[22:25]
	v_mfma_f32_16x16x32_bf16 v[18:21], v[176:179], v[200:203], v[18:21]
	v_mfma_f32_16x16x32_bf16 v[2:5], v[176:179], v[208:211], v[2:5]
	v_mfma_f32_16x16x32_bf16 v[6:9], v[158:161], v[208:211], v[6:9]
	v_mfma_f32_16x16x32_bf16 v[54:57], v[172:175], v[188:191], v[54:57]
	v_mfma_f32_16x16x32_bf16 v[50:53], v[180:183], v[188:191], v[50:53]
	v_mfma_f32_16x16x32_bf16 v[34:37], v[180:183], v[196:199], v[34:37]
	v_mfma_f32_16x16x32_bf16 v[38:41], v[172:175], v[196:199], v[38:41]
	v_mfma_f32_16x16x32_bf16 v[22:25], v[172:175], v[204:207], v[22:25]
	v_mfma_f32_16x16x32_bf16 v[18:21], v[180:183], v[204:207], v[18:21]
	v_mfma_f32_16x16x32_bf16 v[2:5], v[180:183], v[212:215], v[2:5]
	v_mfma_f32_16x16x32_bf16 v[6:9], v[172:175], v[212:215], v[6:9]
	s_setprio 2
	s_barrier
	v_add_u32_e32 v154, s97, v165
	v_add_u32_e32 v180, s33, v165
	ds_read_b128 v[130:133], v154
	ds_read_b128 v[134:137], v154 offset:1024
	ds_read_b128 v[150:153], v154 offset:2048
	ds_read_b128 v[154:157], v154 offset:3072
	ds_read_b128 v[158:161], v180
	ds_read_b128 v[172:175], v180 offset:1024
	ds_read_b128 v[176:179], v180 offset:2048
	ds_read_b128 v[180:183], v180 offset:3072
	s_mov_b32 m0, s80
	v_lshl_add_u64 v[222:223], s[44:45], 0, v[138:139]
	ds_read_b128 v[184:187], v168 offset:32768
	ds_read_b128 v[188:191], v168 offset:33792
	ds_read_b128 v[192:195], v168 offset:34816
	ds_read_b128 v[196:199], v168 offset:35840
	ds_read_b128 v[200:203], v168 offset:36864
	ds_read_b128 v[204:207], v168 offset:37888
	ds_read_b128 v[208:211], v168 offset:38912
	ds_read_b128 v[212:215], v168 offset:39936
	global_load_lds_dwordx4 v[222:223], off
	v_lshl_add_u64 v[222:223], s[44:45], 0, v[142:143]
	s_mov_b32 m0, s81
	s_nop 0
	global_load_lds_dwordx4 v[222:223], off
	s_waitcnt vmcnt(8)
	s_waitcnt lgkmcnt(0)
	s_barrier
	s_setprio 0
	s_waitcnt lgkmcnt(0)
	v_mfma_f32_16x16x32_bf16 v[126:129], v[130:133], v[184:187], v[126:129]
	v_mfma_f32_16x16x32_bf16 v[122:125], v[150:153], v[184:187], v[122:125]
	v_mfma_f32_16x16x32_bf16 v[106:109], v[150:153], v[192:195], v[106:109]
	v_mfma_f32_16x16x32_bf16 v[110:113], v[130:133], v[192:195], v[110:113]
	v_mfma_f32_16x16x32_bf16 v[94:97], v[130:133], v[200:203], v[94:97]
	v_mfma_f32_16x16x32_bf16 v[90:93], v[150:153], v[200:203], v[90:93]
	v_mfma_f32_16x16x32_bf16 v[74:77], v[150:153], v[208:211], v[74:77]
	v_mfma_f32_16x16x32_bf16 v[78:81], v[130:133], v[208:211], v[78:81]
	v_mfma_f32_16x16x32_bf16 v[126:129], v[134:137], v[188:191], v[126:129]
	v_mfma_f32_16x16x32_bf16 v[122:125], v[154:157], v[188:191], v[122:125]
	v_mfma_f32_16x16x32_bf16 v[106:109], v[154:157], v[196:199], v[106:109]
	v_mfma_f32_16x16x32_bf16 v[110:113], v[134:137], v[196:199], v[110:113]
	v_mfma_f32_16x16x32_bf16 v[94:97], v[134:137], v[204:207], v[94:97]
	v_mfma_f32_16x16x32_bf16 v[90:93], v[154:157], v[204:207], v[90:93]
	v_mfma_f32_16x16x32_bf16 v[74:77], v[154:157], v[212:215], v[74:77]
	v_mfma_f32_16x16x32_bf16 v[78:81], v[134:137], v[212:215], v[78:81]
	s_setprio 2
	s_setprio 0
	v_mfma_f32_16x16x32_bf16 v[118:121], v[158:161], v[184:187], v[118:121]
	v_mfma_f32_16x16x32_bf16 v[114:117], v[176:179], v[184:187], v[114:117]
	v_mfma_f32_16x16x32_bf16 v[98:101], v[176:179], v[192:195], v[98:101]
	v_mfma_f32_16x16x32_bf16 v[102:105], v[158:161], v[192:195], v[102:105]
	v_mfma_f32_16x16x32_bf16 v[86:89], v[158:161], v[200:203], v[86:89]
	v_mfma_f32_16x16x32_bf16 v[82:85], v[176:179], v[200:203], v[82:85]
	v_mfma_f32_16x16x32_bf16 v[66:69], v[176:179], v[208:211], v[66:69]
	v_mfma_f32_16x16x32_bf16 v[70:73], v[158:161], v[208:211], v[70:73]
	v_mfma_f32_16x16x32_bf16 v[118:121], v[172:175], v[188:191], v[118:121]
	v_mfma_f32_16x16x32_bf16 v[114:117], v[180:183], v[188:191], v[114:117]
	v_mfma_f32_16x16x32_bf16 v[98:101], v[180:183], v[196:199], v[98:101]
	v_mfma_f32_16x16x32_bf16 v[102:105], v[172:175], v[196:199], v[102:105]
	v_mfma_f32_16x16x32_bf16 v[86:89], v[172:175], v[204:207], v[86:89]
	v_mfma_f32_16x16x32_bf16 v[82:85], v[180:183], v[204:207], v[82:85]
	v_mfma_f32_16x16x32_bf16 v[66:69], v[180:183], v[212:215], v[66:69]
	v_mfma_f32_16x16x32_bf16 v[70:73], v[172:175], v[212:215], v[70:73]
	s_setprio 2
	s_barrier
; #define PG8_STAGE(bufoff, gbase, voff) do { _Pragma("unroll") for (int _i = 0; _i < 2; ++_i) \
;         __builtin_amdgcn_global_load_lds((const unsigned*)((const char*)(gbase) + (voff)[_i]), (LAS unsigned*)(lds + (bufoff) + ldsw + _i * 8192), 16, 0, 0); } while (0)
; #define PG8_LDA(dst, b, h) do { _Pragma("unroll") for (int m = 0; m < 4; ++m) _Pragma("unroll") for (int k = 0; k < 2; ++k) dst[m][k] = *(const LAS bf16x8*)(lds + PG8_SA(b, h) + aoff + m * 2048 + k * 1024); } while (0)
; #define PG8_MMA(ai, bj, At, Bt) do { __builtin_amdgcn_s_setprio(1); _Pragma("unroll") for (int m = 0; m < 4; ++m) _Pragma("unroll") for (int n = 0; n < 2; ++n) _Pragma("unroll") for (int k = 0; k < 2; ++k) \
;         acc[ai][bj][m][n] = __builtin_amdgcn_mfma_f32_16x16x32_bf16(Bt[n][k], At[m][k], acc[ai][bj][m][n], 0, 0, 0); __builtin_amdgcn_s_setprio(0); } while (0)
; #define PG8_WAIT_V(n) asm volatile("s_waitcnt vmcnt(" #n ")" ::: "memory")
; #define PG8_WAIT_L(n) asm volatile("s_waitcnt lgkmcnt(" #n ")" ::: "memory")
; #define PG8_BAR __builtin_amdgcn_s_barrier()
; #define PG8_SCHED __builtin_amdgcn_sched_barrier(0)
; template <class Epi>
; __device__ __forceinline__ void gemm_phase(LAS unsigned char* lds, const Gemm g, int G, int c, const Epi& E) {
;     ...
;             PG8_LDA(At, 1, 1); PG8_STAGE(PG8_SB(1, 0), b3, voffB); PG8_STAGE(PG8_SB(1, 1), b3 + hstepB, voffB); PG8_STAGE(PG8_SA(1, 0), a3, voffA);
;             PG8_WAIT_V(8); PG8_WAIT_L(0); PG8_BAR; PG8_MMA(1, 0, At, B0); PG8_MMA(1, 1, At, B1); PG8_BAR; PG8_SCHED;
;         }
;         if (wr == 0) PG8_BAR;
	s_mov_b32 m0, s96
	v_lshl_add_u64 v[162:163], v[162:163], 0, s[22:23]
	ds_read_b128 v[184:187], v168 offset:49152
	ds_read_b128 v[188:191], v168 offset:50176
	ds_read_b128 v[192:195], v168 offset:51200
	ds_read_b128 v[196:199], v168 offset:52224
	ds_read_b128 v[200:203], v168 offset:53248
	ds_read_b128 v[204:207], v168 offset:54272
	ds_read_b128 v[208:211], v168 offset:55296
	ds_read_b128 v[212:215], v168 offset:56320
	global_load_lds_dwordx4 v[162:163], off
	v_lshl_add_u64 v[162:163], v[216:217], 0, s[22:23]
	s_mov_b32 m0, s94
	s_nop 0
	global_load_lds_dwordx4 v[162:163], off
	v_lshl_add_u64 v[162:163], s[10:11], 0, v[140:141]
	s_mov_b32 m0, s95
	s_nop 0
	global_load_lds_dwordx4 v[162:163], off
	v_lshl_add_u64 v[162:163], s[10:11], 0, v[144:145]
	s_mov_b32 m0, s93
	s_nop 0
	global_load_lds_dwordx4 v[162:163], off
	v_lshl_add_u64 v[162:163], v[218:219], 0, s[22:23]
	s_mov_b32 m0, s85
	s_nop 0
	global_load_lds_dwordx4 v[162:163], off
	v_lshl_add_u64 v[162:163], v[220:221], 0, s[22:23]
	s_mov_b32 m0, s86
	s_nop 0
	global_load_lds_dwordx4 v[162:163], off
	s_waitcnt vmcnt(8)
	s_waitcnt lgkmcnt(0)
	s_barrier
	s_setprio 0
	s_waitcnt lgkmcnt(0)
	v_mfma_f32_16x16x32_bf16 v[62:65], v[130:133], v[184:187], v[62:65]
	v_mfma_f32_16x16x32_bf16 v[58:61], v[150:153], v[184:187], v[58:61]
	v_mfma_f32_16x16x32_bf16 v[42:45], v[150:153], v[192:195], v[42:45]
	v_mfma_f32_16x16x32_bf16 v[46:49], v[130:133], v[192:195], v[46:49]
	v_mfma_f32_16x16x32_bf16 v[30:33], v[130:133], v[200:203], v[30:33]
	v_mfma_f32_16x16x32_bf16 v[26:29], v[150:153], v[200:203], v[26:29]
	v_mfma_f32_16x16x32_bf16 v[10:13], v[150:153], v[208:211], v[10:13]
	v_mfma_f32_16x16x32_bf16 v[14:17], v[130:133], v[208:211], v[14:17]
	v_mfma_f32_16x16x32_bf16 v[62:65], v[134:137], v[188:191], v[62:65]
	v_mfma_f32_16x16x32_bf16 v[58:61], v[154:157], v[188:191], v[58:61]
	v_mfma_f32_16x16x32_bf16 v[42:45], v[154:157], v[196:199], v[42:45]
	v_mfma_f32_16x16x32_bf16 v[46:49], v[134:137], v[196:199], v[46:49]
	v_mfma_f32_16x16x32_bf16 v[30:33], v[134:137], v[204:207], v[30:33]
	v_mfma_f32_16x16x32_bf16 v[26:29], v[154:157], v[204:207], v[26:29]
	v_mfma_f32_16x16x32_bf16 v[10:13], v[154:157], v[212:215], v[10:13]
	v_mfma_f32_16x16x32_bf16 v[14:17], v[134:137], v[212:215], v[14:17]
	s_setprio 2
	s_setprio 0
	v_mfma_f32_16x16x32_bf16 v[54:57], v[158:161], v[184:187], v[54:57]
	v_mfma_f32_16x16x32_bf16 v[50:53], v[176:179], v[184:187], v[50:53]
	v_mfma_f32_16x16x32_bf16 v[34:37], v[176:179], v[192:195], v[34:37]
	v_mfma_f32_16x16x32_bf16 v[38:41], v[158:161], v[192:195], v[38:41]
	v_mfma_f32_16x16x32_bf16 v[22:25], v[158:161], v[200:203], v[22:25]
	v_mfma_f32_16x16x32_bf16 v[18:21], v[176:179], v[200:203], v[18:21]
	v_mfma_f32_16x16x32_bf16 v[2:5], v[176:179], v[208:211], v[2:5]
	v_mfma_f32_16x16x32_bf16 v[6:9], v[158:161], v[208:211], v[6:9]
	v_mfma_f32_16x16x32_bf16 v[54:57], v[172:175], v[188:191], v[54:57]
	v_mfma_f32_16x16x32_bf16 v[50:53], v[180:183], v[188:191], v[50:53]
	v_mfma_f32_16x16x32_bf16 v[34:37], v[180:183], v[196:199], v[34:37]
	v_mfma_f32_16x16x32_bf16 v[38:41], v[172:175], v[196:199], v[38:41]
	v_mfma_f32_16x16x32_bf16 v[22:25], v[172:175], v[204:207], v[22:25]
	v_mfma_f32_16x16x32_bf16 v[18:21], v[180:183], v[204:207], v[18:21]
	v_mfma_f32_16x16x32_bf16 v[2:5], v[180:183], v[212:215], v[2:5]
	v_mfma_f32_16x16x32_bf16 v[6:9], v[172:175], v[212:215], v[6:9]
	s_setprio 2
	s_barrier
	s_movk_i32 s44, 0x100
	s_andn2_b64 vcc, exec, s[4:5]
	s_mov_b64 s[10:11], -1
	s_mov_b64 s[4:5], 0
	s_cbranch_vccz .LBB0_1537
	s_and_b64 vcc, exec, s[24:25]
	s_cbranch_vccz .LBB0_1540
	s_barrier

; #define PG8_STAGE(bufoff, gbase, voff) do { _Pragma("unroll") for (int _i = 0; _i < 2; ++_i) \
;         __builtin_amdgcn_global_load_lds((const unsigned*)((const char*)(gbase) + (voff)[_i]), (LAS unsigned*)(lds + (bufoff) + ldsw + _i * 8192), 16, 0, 0); } while (0)
; #define PG8_LDA(dst, b, h) do { _Pragma("unroll") for (int m = 0; m < 4; ++m) _Pragma("unroll") for (int k = 0; k < 2; ++k) dst[m][k] = *(const LAS bf16x8*)(lds + PG8_SA(b, h) + aoff + m * 2048 + k * 1024); } while (0)
; #define PG8_LDB(dst, b, h) do { _Pragma("unroll") for (int n = 0; n < 2; ++n) _Pragma("unroll") for (int k = 0; k < 2; ++k) dst[n][k] = *(const LAS bf16x8*)(lds + PG8_SB(b, h) + boff + n * 2048 + k * 1024); } while (0)
; #define PG8_MMA(ai, bj, At, Bt) do { __builtin_amdgcn_s_setprio(1); _Pragma("unroll") for (int m = 0; m < 4; ++m) _Pragma("unroll") for (int n = 0; n < 2; ++n) _Pragma("unroll") for (int k = 0; k < 2; ++k) \
;         acc[ai][bj][m][n] = __builtin_amdgcn_mfma_f32_16x16x32_bf16(Bt[n][k], At[m][k], acc[ai][bj][m][n], 0, 0, 0); __builtin_amdgcn_s_setprio(0); } while (0)
; #define PG8_WAIT_V(n) asm volatile("s_waitcnt vmcnt(" #n ")" ::: "memory")
; #define PG8_WAIT_L(n) asm volatile("s_waitcnt lgkmcnt(" #n ")" ::: "memory")
; #define PG8_BAR __builtin_amdgcn_s_barrier()
; #define PG8_SCHED __builtin_amdgcn_sched_barrier(0)
; template <class Epi>
; __device__ __forceinline__ void gemm_phase(LAS unsigned char* lds, const Gemm g, int G, int c, const Epi& E) {
;     ...
;             const bool last = (t == nt - 2);
;             const char* a1 = cA + (size_t)(t + 1) * kstep;
;             const char* a2 = last ? nA : cA + (size_t)(t + 2) * kstep; const char* b2 = last ? nB : cB + (size_t)(t + 2) * kstep;
;             const char* a3 = a2 + kstep; const char* b3 = b2 + kstep;
;             PG8_LDB(B0, 0, 0); PG8_LDB(B1, 0, 1); PG8_SCHED; PG8_LDA(At, 0, 0); PG8_STAGE(PG8_SA(1, 1), a1 + hstepA, voffA);
;             PG8_WAIT_V(8); PG8_WAIT_L(0); PG8_BAR; PG8_MMA(0, 0, At, B0); PG8_MMA(0, 1, At, B1); PG8_BAR; PG8_SCHED;
;             PG8_LDA(At, 0, 1); PG8_STAGE(PG8_SB(0, 0), b2, voffB); PG8_STAGE(PG8_SB(0, 1), b2 + hstepB, voffB); PG8_STAGE(PG8_SA(0, 0), a2, voffA);
.LBB0_1653:
	s_add_u32 s33, s8, s48
	s_addc_u32 s49, s9, 0
	s_add_u32 s54, s33, 0x100
	s_addc_u32 s55, s49, 0
	s_and_b64 s[52:53], s[46:47], exec
	s_cselect_b32 s53, s41, s55
	s_cselect_b32 s52, s40, s54
	s_add_u32 s48, s6, s48
	s_addc_u32 s54, s7, 0
	s_add_u32 s48, s48, 0x100
	s_addc_u32 s54, s54, 0
	s_and_b64 s[46:47], s[46:47], exec
	s_cselect_b32 s55, s43, s54
	s_cselect_b32 s54, s42, s48
	s_add_u32 s58, s33, 0xb0080
	ds_read_b128 v[142:145], v166
	ds_read_b128 v[146:149], v166 offset:1024
	ds_read_b128 v[150:153], v166 offset:2048
	ds_read_b128 v[154:157], v166 offset:3072
	ds_read_b128 v[158:161], v167
	ds_read_b128 v[170:173], v167 offset:1024
	ds_read_b128 v[174:177], v167 offset:2048
	ds_read_b128 v[178:181], v167 offset:3072
	s_addc_u32 s59, s49, 0
	s_add_i32 s63, s80, s23
	s_add_i32 m0, s68, 0xc000
	s_add_i32 s64, s68, 0xe000
	s_add_i32 s74, s63, 0x2000
	s_add_u32 s56, s54, 0xb0000
	s_addc_u32 s57, s55, 0
	s_add_i32 s62, s81, s23
	s_add_i32 s75, s62, 0x2000
	s_add_i32 s93, 0, 0x18000
	s_add_i32 s33, 0, 0x1c000
	s_add_u32 s48, s52, 0xb0000
	s_addc_u32 s49, s53, 0
	s_add_i32 s92, s93, s23
	s_add_i32 s90, s92, 0x2000
	s_add_u32 s46, s54, 0xb0080
	s_addc_u32 s47, s55, 0
	s_add_i32 s91, s33, s23
	s_add_i32 s89, s91, 0x2000
	v_lshl_add_u64 v[162:163], s[58:59], 0, v[136:137]
	ds_read_b128 v[182:185], v168
	ds_read_b128 v[186:189], v168 offset:1024
	ds_read_b128 v[190:193], v168 offset:2048
	ds_read_b128 v[194:197], v168 offset:3072
	ds_read_b128 v[198:201], v168 offset:4096
	ds_read_b128 v[202:205], v168 offset:5120
	ds_read_b128 v[206:209], v168 offset:6144
	ds_read_b128 v[210:213], v168 offset:7168
	global_load_lds_dwordx4 v[162:163], off
	v_lshl_add_u64 v[162:163], s[58:59], 0, v[132:133]
	s_mov_b32 m0, s64
	s_nop 0
	global_load_lds_dwordx4 v[162:163], off
	s_waitcnt vmcnt(8)
	s_waitcnt lgkmcnt(0)
	s_barrier
	s_setprio 0
	s_waitcnt lgkmcnt(0)
	v_mfma_f32_16x16x32_bf16 v[126:129], v[142:145], v[182:185], v[126:129]
	v_mfma_f32_16x16x32_bf16 v[122:125], v[150:153], v[182:185], v[122:125]
	v_mfma_f32_16x16x32_bf16 v[106:109], v[150:153], v[190:193], v[106:109]
	v_mfma_f32_16x16x32_bf16 v[110:113], v[142:145], v[190:193], v[110:113]
	v_mfma_f32_16x16x32_bf16 v[94:97], v[142:145], v[198:201], v[94:97]
	v_mfma_f32_16x16x32_bf16 v[90:93], v[150:153], v[198:201], v[90:93]
	v_mfma_f32_16x16x32_bf16 v[74:77], v[150:153], v[206:209], v[74:77]
	v_mfma_f32_16x16x32_bf16 v[78:81], v[142:145], v[206:209], v[78:81]
	v_mfma_f32_16x16x32_bf16 v[126:129], v[146:149], v[186:189], v[126:129]
	v_mfma_f32_16x16x32_bf16 v[122:125], v[154:157], v[186:189], v[122:125]
	v_mfma_f32_16x16x32_bf16 v[106:109], v[154:157], v[194:197], v[106:109]
	v_mfma_f32_16x16x32_bf16 v[110:113], v[146:149], v[194:197], v[110:113]
	v_mfma_f32_16x16x32_bf16 v[94:97], v[146:149], v[202:205], v[94:97]
	v_mfma_f32_16x16x32_bf16 v[90:93], v[154:157], v[202:205], v[90:93]
	v_mfma_f32_16x16x32_bf16 v[74:77], v[154:157], v[210:213], v[74:77]
	v_mfma_f32_16x16x32_bf16 v[78:81], v[146:149], v[210:213], v[78:81]
	s_setprio 2
	s_setprio 0
	v_mfma_f32_16x16x32_bf16 v[118:121], v[158:161], v[182:185], v[118:121]
	v_mfma_f32_16x16x32_bf16 v[114:117], v[174:177], v[182:185], v[114:117]
	v_mfma_f32_16x16x32_bf16 v[98:101], v[174:177], v[190:193], v[98:101]
	v_mfma_f32_16x16x32_bf16 v[102:105], v[158:161], v[190:193], v[102:105]
	v_mfma_f32_16x16x32_bf16 v[86:89], v[158:161], v[198:201], v[86:89]
	v_mfma_f32_16x16x32_bf16 v[82:85], v[174:177], v[198:201], v[82:85]
	v_mfma_f32_16x16x32_bf16 v[66:69], v[174:177], v[206:209], v[66:69]
	v_mfma_f32_16x16x32_bf16 v[70:73], v[158:161], v[206:209], v[70:73]
	v_mfma_f32_16x16x32_bf16 v[118:121], v[170:173], v[186:189], v[118:121]
	v_mfma_f32_16x16x32_bf16 v[114:117], v[178:181], v[186:189], v[114:117]
	v_mfma_f32_16x16x32_bf16 v[98:101], v[178:181], v[194:197], v[98:101]
	v_mfma_f32_16x16x32_bf16 v[102:105], v[170:173], v[194:197], v[102:105]
	v_mfma_f32_16x16x32_bf16 v[86:89], v[170:173], v[202:205], v[86:89]
	v_mfma_f32_16x16x32_bf16 v[82:85], v[178:181], v[202:205], v[82:85]
	v_mfma_f32_16x16x32_bf16 v[66:69], v[178:181], v[210:213], v[66:69]
	v_mfma_f32_16x16x32_bf16 v[70:73], v[170:173], v[210:213], v[70:73]
	s_setprio 2
	s_barrier
	s_mov_b32 m0, s63
	v_lshl_add_u64 v[162:163], s[54:55], 0, v[134:135]
	ds_read_b128 v[182:185], v168 offset:16384
	ds_read_b128 v[186:189], v168 offset:17408
	ds_read_b128 v[190:193], v168 offset:18432
	ds_read_b128 v[194:197], v168 offset:19456
	ds_read_b128 v[198:201], v168 offset:20480
	ds_read_b128 v[202:205], v168 offset:21504
	ds_read_b128 v[206:209], v168 offset:22528
	ds_read_b128 v[210:213], v168 offset:23552
	global_load_lds_dwordx4 v[162:163], off
	v_lshl_add_u64 v[214:215], s[54:55], 0, v[130:131]
	s_mov_b32 m0, s74
	v_lshl_add_u64 v[216:217], s[56:57], 0, v[134:135]
	global_load_lds_dwordx4 v[214:215], off
	s_mov_b32 m0, s62
	v_lshl_add_u64 v[218:219], s[52:53], 0, v[132:133]
	global_load_lds_dwordx4 v[216:217], off
	v_lshl_add_u64 v[216:217], s[56:57], 0, v[130:131]
	s_mov_b32 m0, s75
	s_nop 0
	global_load_lds_dwordx4 v[216:217], off
	v_lshl_add_u64 v[216:217], s[52:53], 0, v[136:137]
	s_mov_b32 m0, s68
	s_nop 0
	global_load_lds_dwordx4 v[216:217], off
	s_mov_b32 m0, s69
	s_nop 0
	global_load_lds_dwordx4 v[218:219], off
	s_waitcnt vmcnt(8)
	s_waitcnt lgkmcnt(0)
	s_barrier
; #define PG8_STAGE(bufoff, gbase, voff) do { _Pragma("unroll") for (int _i = 0; _i < 2; ++_i) \
;         __builtin_amdgcn_global_load_lds((const unsigned*)((const char*)(gbase) + (voff)[_i]), (LAS unsigned*)(lds + (bufoff) + ldsw + _i * 8192), 16, 0, 0); } while (0)
; #define PG8_LDA(dst, b, h) do { _Pragma("unroll") for (int m = 0; m < 4; ++m) _Pragma("unroll") for (int k = 0; k < 2; ++k) dst[m][k] = *(const LAS bf16x8*)(lds + PG8_SA(b, h) + aoff + m * 2048 + k * 1024); } while (0)
; #define PG8_LDB(dst, b, h) do { _Pragma("unroll") for (int n = 0; n < 2; ++n) _Pragma("unroll") for (int k = 0; k < 2; ++k) dst[n][k] = *(const LAS bf16x8*)(lds + PG8_SB(b, h) + boff + n * 2048 + k * 1024); } while (0)
; #define PG8_MMA(ai, bj, At, Bt) do { __builtin_amdgcn_s_setprio(1); _Pragma("unroll") for (int m = 0; m < 4; ++m) _Pragma("unroll") for (int n = 0; n < 2; ++n) _Pragma("unroll") for (int k = 0; k < 2; ++k) \
;         acc[ai][bj][m][n] = __builtin_amdgcn_mfma_f32_16x16x32_bf16(Bt[n][k], At[m][k], acc[ai][bj][m][n], 0, 0, 0); __builtin_amdgcn_s_setprio(0); } while (0)
; #define PG8_WAIT_V(n) asm volatile("s_waitcnt vmcnt(" #n ")" ::: "memory")
; #define PG8_WAIT_L(n) asm volatile("s_waitcnt lgkmcnt(" #n ")" ::: "memory")
; #define PG8_BAR __builtin_amdgcn_s_barrier()
; #define PG8_SCHED __builtin_amdgcn_sched_barrier(0)
; template <class Epi>
; __device__ __forceinline__ void gemm_phase(LAS unsigned char* lds, const Gemm g, int G, int c, const Epi& E) {
;     ...
;             PG8_WAIT_V(8); PG8_WAIT_L(0); PG8_BAR; PG8_MMA(1, 0, At, B0); PG8_MMA(1, 1, At, B1); PG8_BAR; PG8_SCHED;
;             PG8_LDB(B0, 1, 0); PG8_LDB(B1, 1, 1); PG8_SCHED; PG8_LDA(At, 1, 0); PG8_STAGE(PG8_SA(0, 1), a2 + hstepA, voffA);
;             PG8_WAIT_V(8); PG8_WAIT_L(0); PG8_BAR; PG8_MMA(0, 0, At, B0); PG8_MMA(0, 1, At, B1); PG8_BAR; PG8_SCHED;
	s_setprio 0
	s_waitcnt lgkmcnt(0)
	v_mfma_f32_16x16x32_bf16 v[62:65], v[142:145], v[182:185], v[62:65]
	v_mfma_f32_16x16x32_bf16 v[58:61], v[150:153], v[182:185], v[58:61]
	v_mfma_f32_16x16x32_bf16 v[42:45], v[150:153], v[190:193], v[42:45]
	v_mfma_f32_16x16x32_bf16 v[46:49], v[142:145], v[190:193], v[46:49]
	v_mfma_f32_16x16x32_bf16 v[30:33], v[142:145], v[198:201], v[30:33]
	v_mfma_f32_16x16x32_bf16 v[26:29], v[150:153], v[198:201], v[26:29]
	v_mfma_f32_16x16x32_bf16 v[10:13], v[150:153], v[206:209], v[10:13]
	v_mfma_f32_16x16x32_bf16 v[14:17], v[142:145], v[206:209], v[14:17]
	v_mfma_f32_16x16x32_bf16 v[62:65], v[146:149], v[186:189], v[62:65]
	v_mfma_f32_16x16x32_bf16 v[58:61], v[154:157], v[186:189], v[58:61]
	v_mfma_f32_16x16x32_bf16 v[42:45], v[154:157], v[194:197], v[42:45]
	v_mfma_f32_16x16x32_bf16 v[46:49], v[146:149], v[194:197], v[46:49]
	v_mfma_f32_16x16x32_bf16 v[30:33], v[146:149], v[202:205], v[30:33]
	v_mfma_f32_16x16x32_bf16 v[26:29], v[154:157], v[202:205], v[26:29]
	v_mfma_f32_16x16x32_bf16 v[10:13], v[154:157], v[210:213], v[10:13]
	v_mfma_f32_16x16x32_bf16 v[14:17], v[146:149], v[210:213], v[14:17]
	s_setprio 2
	s_setprio 0
	v_mfma_f32_16x16x32_bf16 v[54:57], v[158:161], v[182:185], v[54:57]
	v_mfma_f32_16x16x32_bf16 v[50:53], v[174:177], v[182:185], v[50:53]
	v_mfma_f32_16x16x32_bf16 v[34:37], v[174:177], v[190:193], v[34:37]
	v_mfma_f32_16x16x32_bf16 v[38:41], v[158:161], v[190:193], v[38:41]
	v_mfma_f32_16x16x32_bf16 v[22:25], v[158:161], v[198:201], v[22:25]
	v_mfma_f32_16x16x32_bf16 v[18:21], v[174:177], v[198:201], v[18:21]
	v_mfma_f32_16x16x32_bf16 v[2:5], v[174:177], v[206:209], v[2:5]
	v_mfma_f32_16x16x32_bf16 v[6:9], v[158:161], v[206:209], v[6:9]
	v_mfma_f32_16x16x32_bf16 v[54:57], v[170:173], v[186:189], v[54:57]
	v_mfma_f32_16x16x32_bf16 v[50:53], v[178:181], v[186:189], v[50:53]
	v_mfma_f32_16x16x32_bf16 v[34:37], v[178:181], v[194:197], v[34:37]
	v_mfma_f32_16x16x32_bf16 v[38:41], v[170:173], v[194:197], v[38:41]
	v_mfma_f32_16x16x32_bf16 v[22:25], v[170:173], v[202:205], v[22:25]
	v_mfma_f32_16x16x32_bf16 v[18:21], v[178:181], v[202:205], v[18:21]
	v_mfma_f32_16x16x32_bf16 v[2:5], v[178:181], v[210:213], v[2:5]
	v_mfma_f32_16x16x32_bf16 v[6:9], v[170:173], v[210:213], v[6:9]
	s_setprio 2
	s_barrier
	v_add_u32_e32 v154, s93, v165
	v_add_u32_e32 v178, s33, v165
	ds_read_b128 v[142:145], v154
	ds_read_b128 v[146:149], v154 offset:1024
	ds_read_b128 v[150:153], v154 offset:2048
	ds_read_b128 v[154:157], v154 offset:3072
	ds_read_b128 v[158:161], v178
	ds_read_b128 v[170:173], v178 offset:1024
	ds_read_b128 v[174:177], v178 offset:2048
	ds_read_b128 v[178:181], v178 offset:3072
	s_mov_b32 m0, s70
	v_lshl_add_u64 v[220:221], s[48:49], 0, v[136:137]
	ds_read_b128 v[182:185], v168 offset:32768
	ds_read_b128 v[186:189], v168 offset:33792
	ds_read_b128 v[190:193], v168 offset:34816
	ds_read_b128 v[194:197], v168 offset:35840
	ds_read_b128 v[198:201], v168 offset:36864
	ds_read_b128 v[202:205], v168 offset:37888
	ds_read_b128 v[206:209], v168 offset:38912
	ds_read_b128 v[210:213], v168 offset:39936
	global_load_lds_dwordx4 v[220:221], off
	v_lshl_add_u64 v[220:221], s[48:49], 0, v[132:133]
	s_mov_b32 m0, s71
	s_nop 0
	global_load_lds_dwordx4 v[220:221], off
	s_waitcnt vmcnt(8)
	s_waitcnt lgkmcnt(0)
	s_barrier
	s_setprio 0
	s_waitcnt lgkmcnt(0)
	v_mfma_f32_16x16x32_bf16 v[126:129], v[142:145], v[182:185], v[126:129]
	v_mfma_f32_16x16x32_bf16 v[122:125], v[150:153], v[182:185], v[122:125]
	v_mfma_f32_16x16x32_bf16 v[106:109], v[150:153], v[190:193], v[106:109]
	v_mfma_f32_16x16x32_bf16 v[110:113], v[142:145], v[190:193], v[110:113]
	v_mfma_f32_16x16x32_bf16 v[94:97], v[142:145], v[198:201], v[94:97]
	v_mfma_f32_16x16x32_bf16 v[90:93], v[150:153], v[198:201], v[90:93]
	v_mfma_f32_16x16x32_bf16 v[74:77], v[150:153], v[206:209], v[74:77]
	v_mfma_f32_16x16x32_bf16 v[78:81], v[142:145], v[206:209], v[78:81]
	v_mfma_f32_16x16x32_bf16 v[126:129], v[146:149], v[186:189], v[126:129]
	v_mfma_f32_16x16x32_bf16 v[122:125], v[154:157], v[186:189], v[122:125]
	v_mfma_f32_16x16x32_bf16 v[106:109], v[154:157], v[194:197], v[106:109]
	v_mfma_f32_16x16x32_bf16 v[110:113], v[146:149], v[194:197], v[110:113]
	v_mfma_f32_16x16x32_bf16 v[94:97], v[146:149], v[202:205], v[94:97]
	v_mfma_f32_16x16x32_bf16 v[90:93], v[154:157], v[202:205], v[90:93]
	v_mfma_f32_16x16x32_bf16 v[74:77], v[154:157], v[210:213], v[74:77]
	v_mfma_f32_16x16x32_bf16 v[78:81], v[146:149], v[210:213], v[78:81]
	s_setprio 2
	s_setprio 0
	v_mfma_f32_16x16x32_bf16 v[118:121], v[158:161], v[182:185], v[118:121]
	v_mfma_f32_16x16x32_bf16 v[114:117], v[174:177], v[182:185], v[114:117]
	v_mfma_f32_16x16x32_bf16 v[98:101], v[174:177], v[190:193], v[98:101]
	v_mfma_f32_16x16x32_bf16 v[102:105], v[158:161], v[190:193], v[102:105]
	v_mfma_f32_16x16x32_bf16 v[86:89], v[158:161], v[198:201], v[86:89]
	v_mfma_f32_16x16x32_bf16 v[82:85], v[174:177], v[198:201], v[82:85]
	v_mfma_f32_16x16x32_bf16 v[66:69], v[174:177], v[206:209], v[66:69]
	v_mfma_f32_16x16x32_bf16 v[70:73], v[158:161], v[206:209], v[70:73]
	v_mfma_f32_16x16x32_bf16 v[118:121], v[170:173], v[186:189], v[118:121]
	v_mfma_f32_16x16x32_bf16 v[114:117], v[178:181], v[186:189], v[114:117]
	v_mfma_f32_16x16x32_bf16 v[98:101], v[178:181], v[194:197], v[98:101]
	v_mfma_f32_16x16x32_bf16 v[102:105], v[170:173], v[194:197], v[102:105]
	v_mfma_f32_16x16x32_bf16 v[86:89], v[170:173], v[202:205], v[86:89]
	v_mfma_f32_16x16x32_bf16 v[82:85], v[178:181], v[202:205], v[82:85]
	v_mfma_f32_16x16x32_bf16 v[66:69], v[178:181], v[210:213], v[66:69]
	v_mfma_f32_16x16x32_bf16 v[70:73], v[170:173], v[210:213], v[70:73]
	s_setprio 2
	s_barrier
; #define PG8_STAGE(bufoff, gbase, voff) do { _Pragma("unroll") for (int _i = 0; _i < 2; ++_i) \
;         __builtin_amdgcn_global_load_lds((const unsigned*)((const char*)(gbase) + (voff)[_i]), (LAS unsigned*)(lds + (bufoff) + ldsw + _i * 8192), 16, 0, 0); } while (0)
; #define PG8_LDA(dst, b, h) do { _Pragma("unroll") for (int m = 0; m < 4; ++m) _Pragma("unroll") for (int k = 0; k < 2; ++k) dst[m][k] = *(const LAS bf16x8*)(lds + PG8_SA(b, h) + aoff + m * 2048 + k * 1024); } while (0)
; #define PG8_MMA(ai, bj, At, Bt) do { __builtin_amdgcn_s_setprio(1); _Pragma("unroll") for (int m = 0; m < 4; ++m) _Pragma("unroll") for (int n = 0; n < 2; ++n) _Pragma("unroll") for (int k = 0; k < 2; ++k) \
;         acc[ai][bj][m][n] = __builtin_amdgcn_mfma_f32_16x16x32_bf16(Bt[n][k], At[m][k], acc[ai][bj][m][n], 0, 0, 0); __builtin_amdgcn_s_setprio(0); } while (0)
; #define PG8_WAIT_V(n) asm volatile("s_waitcnt vmcnt(" #n ")" ::: "memory")
; #define PG8_WAIT_L(n) asm volatile("s_waitcnt lgkmcnt(" #n ")" ::: "memory")
; #define PG8_BAR __builtin_amdgcn_s_barrier()
; #define PG8_SCHED __builtin_amdgcn_sched_barrier(0)
; template <class Epi>
; __device__ __forceinline__ void gemm_phase(LAS unsigned char* lds, const Gemm g, int G, int c, const Epi& E) {
;     ...
;             PG8_LDA(At, 1, 1); PG8_STAGE(PG8_SB(1, 0), b3, voffB); PG8_STAGE(PG8_SB(1, 1), b3 + hstepB, voffB); PG8_STAGE(PG8_SA(1, 0), a3, voffA);
;             PG8_WAIT_V(8); PG8_WAIT_L(0); PG8_BAR; PG8_MMA(1, 0, At, B0); PG8_MMA(1, 1, At, B1); PG8_BAR; PG8_SCHED;
;         }
;         if (wr == 0) PG8_BAR;
	s_mov_b32 m0, s92
	v_lshl_add_u64 v[162:163], v[162:163], 0, s[18:19]
	ds_read_b128 v[182:185], v168 offset:49152
	ds_read_b128 v[186:189], v168 offset:50176
	ds_read_b128 v[190:193], v168 offset:51200
	ds_read_b128 v[194:197], v168 offset:52224
	ds_read_b128 v[198:201], v168 offset:53248
	ds_read_b128 v[202:205], v168 offset:54272
	ds_read_b128 v[206:209], v168 offset:55296
	ds_read_b128 v[210:213], v168 offset:56320
	global_load_lds_dwordx4 v[162:163], off
	v_lshl_add_u64 v[162:163], v[214:215], 0, s[18:19]
	s_mov_b32 m0, s90
	s_nop 0
	global_load_lds_dwordx4 v[162:163], off
	v_lshl_add_u64 v[162:163], s[46:47], 0, v[134:135]
	s_mov_b32 m0, s91
	s_nop 0
	global_load_lds_dwordx4 v[162:163], off
	v_lshl_add_u64 v[162:163], s[46:47], 0, v[130:131]
	s_mov_b32 m0, s89
	s_nop 0
	global_load_lds_dwordx4 v[162:163], off
	v_lshl_add_u64 v[162:163], v[216:217], 0, s[18:19]
	s_mov_b32 m0, s78
	s_nop 0
	global_load_lds_dwordx4 v[162:163], off
	v_lshl_add_u64 v[162:163], v[218:219], 0, s[18:19]
	s_mov_b32 m0, s79
	s_nop 0
	global_load_lds_dwordx4 v[162:163], off
	s_waitcnt vmcnt(8)
	s_waitcnt lgkmcnt(0)
	s_barrier
	s_setprio 0
	s_waitcnt lgkmcnt(0)
	v_mfma_f32_16x16x32_bf16 v[62:65], v[142:145], v[182:185], v[62:65]
	v_mfma_f32_16x16x32_bf16 v[58:61], v[150:153], v[182:185], v[58:61]
	v_mfma_f32_16x16x32_bf16 v[42:45], v[150:153], v[190:193], v[42:45]
	v_mfma_f32_16x16x32_bf16 v[46:49], v[142:145], v[190:193], v[46:49]
	v_mfma_f32_16x16x32_bf16 v[30:33], v[142:145], v[198:201], v[30:33]
	v_mfma_f32_16x16x32_bf16 v[26:29], v[150:153], v[198:201], v[26:29]
	v_mfma_f32_16x16x32_bf16 v[10:13], v[150:153], v[206:209], v[10:13]
	v_mfma_f32_16x16x32_bf16 v[14:17], v[142:145], v[206:209], v[14:17]
	v_mfma_f32_16x16x32_bf16 v[62:65], v[146:149], v[186:189], v[62:65]
	v_mfma_f32_16x16x32_bf16 v[58:61], v[154:157], v[186:189], v[58:61]
	v_mfma_f32_16x16x32_bf16 v[42:45], v[154:157], v[194:197], v[42:45]
	v_mfma_f32_16x16x32_bf16 v[46:49], v[146:149], v[194:197], v[46:49]
	v_mfma_f32_16x16x32_bf16 v[30:33], v[146:149], v[202:205], v[30:33]
	v_mfma_f32_16x16x32_bf16 v[26:29], v[154:157], v[202:205], v[26:29]
	v_mfma_f32_16x16x32_bf16 v[10:13], v[154:157], v[210:213], v[10:13]
	v_mfma_f32_16x16x32_bf16 v[14:17], v[146:149], v[210:213], v[14:17]
	s_setprio 2
	s_setprio 0
	v_mfma_f32_16x16x32_bf16 v[54:57], v[158:161], v[182:185], v[54:57]
	v_mfma_f32_16x16x32_bf16 v[50:53], v[174:177], v[182:185], v[50:53]
	v_mfma_f32_16x16x32_bf16 v[34:37], v[174:177], v[190:193], v[34:37]
	v_mfma_f32_16x16x32_bf16 v[38:41], v[158:161], v[190:193], v[38:41]
	v_mfma_f32_16x16x32_bf16 v[22:25], v[158:161], v[198:201], v[22:25]
	v_mfma_f32_16x16x32_bf16 v[18:21], v[174:177], v[198:201], v[18:21]
	v_mfma_f32_16x16x32_bf16 v[2:5], v[174:177], v[206:209], v[2:5]
	v_mfma_f32_16x16x32_bf16 v[6:9], v[158:161], v[206:209], v[6:9]
	v_mfma_f32_16x16x32_bf16 v[54:57], v[170:173], v[186:189], v[54:57]
	v_mfma_f32_16x16x32_bf16 v[50:53], v[178:181], v[186:189], v[50:53]
	v_mfma_f32_16x16x32_bf16 v[34:37], v[178:181], v[194:197], v[34:37]
	v_mfma_f32_16x16x32_bf16 v[38:41], v[170:173], v[194:197], v[38:41]
	v_mfma_f32_16x16x32_bf16 v[22:25], v[170:173], v[202:205], v[22:25]
	v_mfma_f32_16x16x32_bf16 v[18:21], v[178:181], v[202:205], v[18:21]
	v_mfma_f32_16x16x32_bf16 v[2:5], v[178:181], v[210:213], v[2:5]
	v_mfma_f32_16x16x32_bf16 v[6:9], v[170:173], v[210:213], v[6:9]
	s_setprio 2
	s_barrier
	s_movk_i32 s48, 0x100
	s_andn2_b64 vcc, exec, s[4:5]
	s_mov_b64 s[46:47], -1
	s_mov_b64 s[4:5], 0
	s_cbranch_vccz .LBB0_1653
	s_and_b64 vcc, exec, s[20:21]
	s_cbranch_vccz .LBB0_1656
	s_barrier

; #define PG8_STAGE(bufoff, gbase, voff) do { _Pragma("unroll") for (int _i = 0; _i < 2; ++_i) \
;         __builtin_amdgcn_global_load_lds((const unsigned*)((const char*)(gbase) + (voff)[_i]), (LAS unsigned*)(lds + (bufoff) + ldsw + _i * 8192), 16, 0, 0); } while (0)
; #define PG8_LDA(dst, b, h) do { _Pragma("unroll") for (int m = 0; m < 4; ++m) _Pragma("unroll") for (int k = 0; k < 2; ++k) dst[m][k] = *(const LAS bf16x8*)(lds + PG8_SA(b, h) + aoff + m * 2048 + k * 1024); } while (0)
; #define PG8_LDB(dst, b, h) do { _Pragma("unroll") for (int n = 0; n < 2; ++n) _Pragma("unroll") for (int k = 0; k < 2; ++k) dst[n][k] = *(const LAS bf16x8*)(lds + PG8_SB(b, h) + boff + n * 2048 + k * 1024); } while (0)
; #define PG8_MMA(ai, bj, At, Bt) do { __builtin_amdgcn_s_setprio(1); _Pragma("unroll") for (int m = 0; m < 4; ++m) _Pragma("unroll") for (int n = 0; n < 2; ++n) _Pragma("unroll") for (int k = 0; k < 2; ++k) \
;         acc[ai][bj][m][n] = __builtin_amdgcn_mfma_f32_16x16x32_bf16(Bt[n][k], At[m][k], acc[ai][bj][m][n], 0, 0, 0); __builtin_amdgcn_s_setprio(0); } while (0)
; #define PG8_WAIT_V(n) asm volatile("s_waitcnt vmcnt(" #n ")" ::: "memory")
; #define PG8_WAIT_L(n) asm volatile("s_waitcnt lgkmcnt(" #n ")" ::: "memory")
; #define PG8_BAR __builtin_amdgcn_s_barrier()
; #define PG8_SCHED __builtin_amdgcn_sched_barrier(0)
; template <class Epi>
; __device__ __forceinline__ void gemm_phase(LAS unsigned char* lds, const Gemm g, int G, int c, const Epi& E) {
;     ...
;         for (int t = 0; t < nt; t += 2) {
;             const bool last = (t == nt - 2);
;             const char* a1 = cA + (size_t)(t + 1) * kstep;
;             const char* a2 = last ? nA : cA + (size_t)(t + 2) * kstep; const char* b2 = last ? nB : cB + (size_t)(t + 2) * kstep;
;             const char* a3 = a2 + kstep; const char* b3 = b2 + kstep;
;             PG8_LDB(B0, 0, 0); PG8_LDB(B1, 0, 1); PG8_SCHED; PG8_LDA(At, 0, 0); PG8_STAGE(PG8_SA(1, 1), a1 + hstepA, voffA);
;             PG8_WAIT_V(8); PG8_WAIT_L(0); PG8_BAR; PG8_MMA(0, 0, At, B0); PG8_MMA(0, 1, At, B1); PG8_BAR; PG8_SCHED;
;             PG8_LDA(At, 0, 1); PG8_STAGE(PG8_SB(0, 0), b2, voffB); PG8_STAGE(PG8_SB(0, 1), b2 + hstepB, voffB); PG8_STAGE(PG8_SA(0, 0), a2, voffA);
.LBB0_1825:
	ds_read_b128 v[146:149], v152
	ds_read_b128 v[156:159], v152 offset:1024
	ds_read_b128 v[160:163], v152 offset:2048
	ds_read_b128 v[164:167], v152 offset:3072
	ds_read_b128 v[168:171], v153
	ds_read_b128 v[172:175], v153 offset:1024
	ds_read_b128 v[176:179], v153 offset:2048
	ds_read_b128 v[180:183], v153 offset:3072
	s_add_u32 s33, s40, 0xfff00080
	s_addc_u32 s42, s41, -1
	s_cmp_eq_u32 s68, 60
	s_cselect_b32 s45, s15, s42
	s_cselect_b32 s44, s63, s33
	s_cselect_b32 s43, s11, s67
	s_cselect_b32 s42, s13, s66
	v_lshl_add_u64 v[216:217], s[40:41], 0, v[138:139]
	s_add_i32 m0, s17, 0xc000
	ds_read_b128 v[184:187], v154
	ds_read_b128 v[188:191], v154 offset:1024
	ds_read_b128 v[192:195], v154 offset:2048
	ds_read_b128 v[196:199], v154 offset:3072
	ds_read_b128 v[200:203], v154 offset:4096
	ds_read_b128 v[204:207], v154 offset:5120
	ds_read_b128 v[208:211], v154 offset:6144
	ds_read_b128 v[212:215], v154 offset:7168
	global_load_lds_dwordx4 v[216:217], off
	v_lshl_add_u64 v[216:217], s[40:41], 0, v[140:141]
	s_add_i32 m0, s17, 0xe000
	s_nop 0
	global_load_lds_dwordx4 v[216:217], off
	s_waitcnt vmcnt(8)
	s_waitcnt lgkmcnt(0)
	s_barrier
	s_setprio 0
	s_waitcnt lgkmcnt(0)
	v_mfma_f32_16x16x32_bf16 v[126:129], v[146:149], v[184:187], v[126:129]
	v_mfma_f32_16x16x32_bf16 v[122:125], v[160:163], v[184:187], v[122:125]
	v_mfma_f32_16x16x32_bf16 v[110:113], v[160:163], v[192:195], v[110:113]
	v_mfma_f32_16x16x32_bf16 v[118:121], v[146:149], v[192:195], v[118:121]
	v_mfma_f32_16x16x32_bf16 v[102:105], v[146:149], v[200:203], v[102:105]
	v_mfma_f32_16x16x32_bf16 v[94:97], v[160:163], v[200:203], v[94:97]
	v_mfma_f32_16x16x32_bf16 v[78:81], v[160:163], v[208:211], v[78:81]
	v_mfma_f32_16x16x32_bf16 v[86:89], v[146:149], v[208:211], v[86:89]
	v_mfma_f32_16x16x32_bf16 v[126:129], v[156:159], v[188:191], v[126:129]
	v_mfma_f32_16x16x32_bf16 v[122:125], v[164:167], v[188:191], v[122:125]
	v_mfma_f32_16x16x32_bf16 v[110:113], v[164:167], v[196:199], v[110:113]
	v_mfma_f32_16x16x32_bf16 v[118:121], v[156:159], v[196:199], v[118:121]
	v_mfma_f32_16x16x32_bf16 v[102:105], v[156:159], v[204:207], v[102:105]
	v_mfma_f32_16x16x32_bf16 v[94:97], v[164:167], v[204:207], v[94:97]
	v_mfma_f32_16x16x32_bf16 v[78:81], v[164:167], v[212:215], v[78:81]
	v_mfma_f32_16x16x32_bf16 v[86:89], v[156:159], v[212:215], v[86:89]
	s_setprio 2
	s_setprio 0
	v_mfma_f32_16x16x32_bf16 v[114:117], v[168:171], v[184:187], v[114:117]
	v_mfma_f32_16x16x32_bf16 v[106:109], v[176:179], v[184:187], v[106:109]
	v_mfma_f32_16x16x32_bf16 v[90:93], v[176:179], v[192:195], v[90:93]
	v_mfma_f32_16x16x32_bf16 v[98:101], v[168:171], v[192:195], v[98:101]
	v_mfma_f32_16x16x32_bf16 v[82:85], v[168:171], v[200:203], v[82:85]
	v_mfma_f32_16x16x32_bf16 v[74:77], v[176:179], v[200:203], v[74:77]
	v_mfma_f32_16x16x32_bf16 v[66:69], v[176:179], v[208:211], v[66:69]
	v_mfma_f32_16x16x32_bf16 v[70:73], v[168:171], v[208:211], v[70:73]
	v_mfma_f32_16x16x32_bf16 v[114:117], v[172:175], v[188:191], v[114:117]
	v_mfma_f32_16x16x32_bf16 v[106:109], v[180:183], v[188:191], v[106:109]
	v_mfma_f32_16x16x32_bf16 v[90:93], v[180:183], v[196:199], v[90:93]
	v_mfma_f32_16x16x32_bf16 v[98:101], v[172:175], v[196:199], v[98:101]
	v_mfma_f32_16x16x32_bf16 v[82:85], v[172:175], v[204:207], v[82:85]
	v_mfma_f32_16x16x32_bf16 v[74:77], v[180:183], v[204:207], v[74:77]
	v_mfma_f32_16x16x32_bf16 v[66:69], v[180:183], v[212:215], v[66:69]
	v_mfma_f32_16x16x32_bf16 v[70:73], v[172:175], v[212:215], v[70:73]
	s_setprio 2
	s_barrier
	s_add_i32 s33, s61, s52
	v_lshl_add_u64 v[216:217], s[42:43], 0, v[134:135]
	s_mov_b32 m0, s33
	ds_read_b128 v[184:187], v154 offset:16384
	ds_read_b128 v[188:191], v154 offset:17408
	ds_read_b128 v[192:195], v154 offset:18432
	ds_read_b128 v[196:199], v154 offset:19456
	ds_read_b128 v[200:203], v154 offset:20480
	ds_read_b128 v[204:207], v154 offset:21504
	ds_read_b128 v[208:211], v154 offset:22528
	ds_read_b128 v[212:215], v154 offset:23552
	global_load_lds_dwordx4 v[216:217], off
	s_add_i32 m0, s33, 0x2000
	s_add_u32 s64, s42, 0x100000
	v_lshl_add_u64 v[218:219], s[42:43], 0, v[130:131]
	s_addc_u32 s65, s43, 0
	s_add_i32 s33, s62, s52
	global_load_lds_dwordx4 v[218:219], off
	v_lshl_add_u64 v[220:221], s[64:65], 0, v[134:135]
	s_mov_b32 m0, s33
	v_lshl_add_u64 v[222:223], s[44:45], 0, v[132:133]
	global_load_lds_dwordx4 v[220:221], off
	v_lshl_add_u64 v[220:221], s[64:65], 0, v[130:131]
	s_add_i32 m0, s33, 0x2000
	s_nop 0
	global_load_lds_dwordx4 v[220:221], off
	v_lshl_add_u64 v[220:221], s[44:45], 0, v[136:137]
	s_mov_b32 m0, s17
	s_nop 0
	global_load_lds_dwordx4 v[220:221], off
	s_mov_b32 m0, s37
	s_nop 0
	global_load_lds_dwordx4 v[222:223], off
	s_waitcnt vmcnt(8)
	s_waitcnt lgkmcnt(0)
	s_barrier
; #define PG8_STAGE(bufoff, gbase, voff) do { _Pragma("unroll") for (int _i = 0; _i < 2; ++_i) \
;         __builtin_amdgcn_global_load_lds((const unsigned*)((const char*)(gbase) + (voff)[_i]), (LAS unsigned*)(lds + (bufoff) + ldsw + _i * 8192), 16, 0, 0); } while (0)
; #define PG8_LDA(dst, b, h) do { _Pragma("unroll") for (int m = 0; m < 4; ++m) _Pragma("unroll") for (int k = 0; k < 2; ++k) dst[m][k] = *(const LAS bf16x8*)(lds + PG8_SA(b, h) + aoff + m * 2048 + k * 1024); } while (0)
; #define PG8_LDB(dst, b, h) do { _Pragma("unroll") for (int n = 0; n < 2; ++n) _Pragma("unroll") for (int k = 0; k < 2; ++k) dst[n][k] = *(const LAS bf16x8*)(lds + PG8_SB(b, h) + boff + n * 2048 + k * 1024); } while (0)
; #define PG8_MMA(ai, bj, At, Bt) do { __builtin_amdgcn_s_setprio(1); _Pragma("unroll") for (int m = 0; m < 4; ++m) _Pragma("unroll") for (int n = 0; n < 2; ++n) _Pragma("unroll") for (int k = 0; k < 2; ++k) \
;         acc[ai][bj][m][n] = __builtin_amdgcn_mfma_f32_16x16x32_bf16(Bt[n][k], At[m][k], acc[ai][bj][m][n], 0, 0, 0); __builtin_amdgcn_s_setprio(0); } while (0)
; #define PG8_WAIT_V(n) asm volatile("s_waitcnt vmcnt(" #n ")" ::: "memory")
; #define PG8_WAIT_L(n) asm volatile("s_waitcnt lgkmcnt(" #n ")" ::: "memory")
; #define PG8_BAR __builtin_amdgcn_s_barrier()
; #define PG8_SCHED __builtin_amdgcn_sched_barrier(0)
; template <class Epi>
; __device__ __forceinline__ void gemm_phase(LAS unsigned char* lds, const Gemm g, int G, int c, const Epi& E) {
;     ...
;             PG8_WAIT_V(8); PG8_WAIT_L(0); PG8_BAR; PG8_MMA(1, 0, At, B0); PG8_MMA(1, 1, At, B1); PG8_BAR; PG8_SCHED;
;             PG8_LDB(B0, 1, 0); PG8_LDB(B1, 1, 1); PG8_SCHED; PG8_LDA(At, 1, 0); PG8_STAGE(PG8_SA(0, 1), a2 + hstepA, voffA);
;             PG8_WAIT_V(8); PG8_WAIT_L(0); PG8_BAR; PG8_MMA(0, 0, At, B0); PG8_MMA(0, 1, At, B1); PG8_BAR; PG8_SCHED;
	s_setprio 0
	s_waitcnt lgkmcnt(0)
	v_mfma_f32_16x16x32_bf16 v[62:65], v[146:149], v[184:187], v[62:65]
	v_mfma_f32_16x16x32_bf16 v[58:61], v[160:163], v[184:187], v[58:61]
	v_mfma_f32_16x16x32_bf16 v[46:49], v[160:163], v[192:195], v[46:49]
	v_mfma_f32_16x16x32_bf16 v[54:57], v[146:149], v[192:195], v[54:57]
	v_mfma_f32_16x16x32_bf16 v[38:41], v[146:149], v[200:203], v[38:41]
	v_mfma_f32_16x16x32_bf16 v[30:33], v[160:163], v[200:203], v[30:33]
	v_mfma_f32_16x16x32_bf16 v[14:17], v[160:163], v[208:211], v[14:17]
	v_mfma_f32_16x16x32_bf16 v[22:25], v[146:149], v[208:211], v[22:25]
	v_mfma_f32_16x16x32_bf16 v[62:65], v[156:159], v[188:191], v[62:65]
	v_mfma_f32_16x16x32_bf16 v[58:61], v[164:167], v[188:191], v[58:61]
	v_mfma_f32_16x16x32_bf16 v[46:49], v[164:167], v[196:199], v[46:49]
	v_mfma_f32_16x16x32_bf16 v[54:57], v[156:159], v[196:199], v[54:57]
	v_mfma_f32_16x16x32_bf16 v[38:41], v[156:159], v[204:207], v[38:41]
	v_mfma_f32_16x16x32_bf16 v[30:33], v[164:167], v[204:207], v[30:33]
	v_mfma_f32_16x16x32_bf16 v[14:17], v[164:167], v[212:215], v[14:17]
	v_mfma_f32_16x16x32_bf16 v[22:25], v[156:159], v[212:215], v[22:25]
	s_setprio 2
	s_setprio 0
	v_mfma_f32_16x16x32_bf16 v[50:53], v[168:171], v[184:187], v[50:53]
	v_mfma_f32_16x16x32_bf16 v[42:45], v[176:179], v[184:187], v[42:45]
	v_mfma_f32_16x16x32_bf16 v[26:29], v[176:179], v[192:195], v[26:29]
	v_mfma_f32_16x16x32_bf16 v[34:37], v[168:171], v[192:195], v[34:37]
	v_mfma_f32_16x16x32_bf16 v[18:21], v[168:171], v[200:203], v[18:21]
	v_mfma_f32_16x16x32_bf16 v[10:13], v[176:179], v[200:203], v[10:13]
	v_mfma_f32_16x16x32_bf16 v[2:5], v[176:179], v[208:211], v[2:5]
	v_mfma_f32_16x16x32_bf16 v[6:9], v[168:171], v[208:211], v[6:9]
	v_mfma_f32_16x16x32_bf16 v[50:53], v[172:175], v[188:191], v[50:53]
	v_mfma_f32_16x16x32_bf16 v[42:45], v[180:183], v[188:191], v[42:45]
	v_mfma_f32_16x16x32_bf16 v[26:29], v[180:183], v[196:199], v[26:29]
	v_mfma_f32_16x16x32_bf16 v[34:37], v[172:175], v[196:199], v[34:37]
	v_mfma_f32_16x16x32_bf16 v[18:21], v[172:175], v[204:207], v[18:21]
	v_mfma_f32_16x16x32_bf16 v[10:13], v[180:183], v[204:207], v[10:13]
	v_mfma_f32_16x16x32_bf16 v[2:5], v[180:183], v[212:215], v[2:5]
	v_mfma_f32_16x16x32_bf16 v[6:9], v[172:175], v[212:215], v[6:9]
	s_setprio 2
	s_barrier
	s_add_i32 s33, 0, 0x18000
	v_add_u32_e32 v155, s33, v151
	s_add_i32 s64, 0, 0x1c000
	ds_read_b128 v[146:149], v155
	ds_read_b128 v[156:159], v155 offset:1024
	ds_read_b128 v[160:163], v155 offset:2048
	ds_read_b128 v[164:167], v155 offset:3072
	v_add_u32_e32 v155, s64, v151
	ds_read_b128 v[168:171], v155
	ds_read_b128 v[172:175], v155 offset:1024
	ds_read_b128 v[176:179], v155 offset:2048
	ds_read_b128 v[180:183], v155 offset:3072
	s_add_u32 s44, s44, 0x100000
	s_addc_u32 s45, s45, 0
	s_mov_b32 m0, s39
	v_lshl_add_u64 v[226:227], s[44:45], 0, v[136:137]
	ds_read_b128 v[184:187], v154 offset:32768
	ds_read_b128 v[188:191], v154 offset:33792
	ds_read_b128 v[192:195], v154 offset:34816
	ds_read_b128 v[196:199], v154 offset:35840
	ds_read_b128 v[200:203], v154 offset:36864
	ds_read_b128 v[204:207], v154 offset:37888
	ds_read_b128 v[208:211], v154 offset:38912
	ds_read_b128 v[212:215], v154 offset:39936
	global_load_lds_dwordx4 v[226:227], off
	v_lshl_add_u64 v[226:227], s[44:45], 0, v[132:133]
	s_mov_b32 m0, s53
	s_nop 0
	global_load_lds_dwordx4 v[226:227], off
	s_waitcnt vmcnt(8)
	s_waitcnt lgkmcnt(0)
	s_barrier
	s_setprio 0
	s_waitcnt lgkmcnt(0)
	v_mfma_f32_16x16x32_bf16 v[126:129], v[146:149], v[184:187], v[126:129]
	v_mfma_f32_16x16x32_bf16 v[122:125], v[160:163], v[184:187], v[122:125]
	v_mfma_f32_16x16x32_bf16 v[110:113], v[160:163], v[192:195], v[110:113]
	v_mfma_f32_16x16x32_bf16 v[118:121], v[146:149], v[192:195], v[118:121]
	v_mfma_f32_16x16x32_bf16 v[102:105], v[146:149], v[200:203], v[102:105]
	v_mfma_f32_16x16x32_bf16 v[94:97], v[160:163], v[200:203], v[94:97]
	v_mfma_f32_16x16x32_bf16 v[78:81], v[160:163], v[208:211], v[78:81]
	v_mfma_f32_16x16x32_bf16 v[86:89], v[146:149], v[208:211], v[86:89]
	v_mfma_f32_16x16x32_bf16 v[126:129], v[156:159], v[188:191], v[126:129]
	v_mfma_f32_16x16x32_bf16 v[122:125], v[164:167], v[188:191], v[122:125]
	v_mfma_f32_16x16x32_bf16 v[110:113], v[164:167], v[196:199], v[110:113]
	v_mfma_f32_16x16x32_bf16 v[118:121], v[156:159], v[196:199], v[118:121]
	v_mfma_f32_16x16x32_bf16 v[102:105], v[156:159], v[204:207], v[102:105]
	v_mfma_f32_16x16x32_bf16 v[94:97], v[164:167], v[204:207], v[94:97]
	v_mfma_f32_16x16x32_bf16 v[78:81], v[164:167], v[212:215], v[78:81]
	v_mfma_f32_16x16x32_bf16 v[86:89], v[156:159], v[212:215], v[86:89]
	s_setprio 2
	s_setprio 0
	v_mfma_f32_16x16x32_bf16 v[114:117], v[168:171], v[184:187], v[114:117]
	v_mfma_f32_16x16x32_bf16 v[106:109], v[176:179], v[184:187], v[106:109]
	v_mfma_f32_16x16x32_bf16 v[90:93], v[176:179], v[192:195], v[90:93]
	v_mfma_f32_16x16x32_bf16 v[98:101], v[168:171], v[192:195], v[98:101]
	v_mfma_f32_16x16x32_bf16 v[82:85], v[168:171], v[200:203], v[82:85]
	v_mfma_f32_16x16x32_bf16 v[74:77], v[176:179], v[200:203], v[74:77]
	v_mfma_f32_16x16x32_bf16 v[66:69], v[176:179], v[208:211], v[66:69]
	v_mfma_f32_16x16x32_bf16 v[70:73], v[168:171], v[208:211], v[70:73]
	v_mfma_f32_16x16x32_bf16 v[114:117], v[172:175], v[188:191], v[114:117]
	v_mfma_f32_16x16x32_bf16 v[106:109], v[180:183], v[188:191], v[106:109]
	v_mfma_f32_16x16x32_bf16 v[90:93], v[180:183], v[196:199], v[90:93]
	v_mfma_f32_16x16x32_bf16 v[98:101], v[172:175], v[196:199], v[98:101]
	v_mfma_f32_16x16x32_bf16 v[82:85], v[172:175], v[204:207], v[82:85]
	v_mfma_f32_16x16x32_bf16 v[74:77], v[180:183], v[204:207], v[74:77]
	v_mfma_f32_16x16x32_bf16 v[66:69], v[180:183], v[212:215], v[66:69]
	v_mfma_f32_16x16x32_bf16 v[70:73], v[172:175], v[212:215], v[70:73]
	s_setprio 2
	s_barrier
; #define PG8_STAGE(bufoff, gbase, voff) do { _Pragma("unroll") for (int _i = 0; _i < 2; ++_i) \
;         __builtin_amdgcn_global_load_lds((const unsigned*)((const char*)(gbase) + (voff)[_i]), (LAS unsigned*)(lds + (bufoff) + ldsw + _i * 8192), 16, 0, 0); } while (0)
; #define PG8_LDA(dst, b, h) do { _Pragma("unroll") for (int m = 0; m < 4; ++m) _Pragma("unroll") for (int k = 0; k < 2; ++k) dst[m][k] = *(const LAS bf16x8*)(lds + PG8_SA(b, h) + aoff + m * 2048 + k * 1024); } while (0)
; #define PG8_MMA(ai, bj, At, Bt) do { __builtin_amdgcn_s_setprio(1); _Pragma("unroll") for (int m = 0; m < 4; ++m) _Pragma("unroll") for (int n = 0; n < 2; ++n) _Pragma("unroll") for (int k = 0; k < 2; ++k) \
;         acc[ai][bj][m][n] = __builtin_amdgcn_mfma_f32_16x16x32_bf16(Bt[n][k], At[m][k], acc[ai][bj][m][n], 0, 0, 0); __builtin_amdgcn_s_setprio(0); } while (0)
; #define PG8_WAIT_V(n) asm volatile("s_waitcnt vmcnt(" #n ")" ::: "memory")
; #define PG8_WAIT_L(n) asm volatile("s_waitcnt lgkmcnt(" #n ")" ::: "memory")
; #define PG8_BAR __builtin_amdgcn_s_barrier()
; #define PG8_SCHED __builtin_amdgcn_sched_barrier(0)
; template <class Epi>
; __device__ __forceinline__ void gemm_phase(LAS unsigned char* lds, const Gemm g, int G, int c, const Epi& E) {
;     ...
;             PG8_LDA(At, 1, 1); PG8_STAGE(PG8_SB(1, 0), b3, voffB); PG8_STAGE(PG8_SB(1, 1), b3 + hstepB, voffB); PG8_STAGE(PG8_SA(1, 0), a3, voffA);
;             PG8_WAIT_V(8); PG8_WAIT_L(0); PG8_BAR; PG8_MMA(1, 0, At, B0); PG8_MMA(1, 1, At, B1); PG8_BAR; PG8_SCHED;
;         }
;         if (wr == 0) PG8_BAR;
	s_add_i32 s33, s33, s52
	v_lshl_add_u64 v[216:217], v[216:217], 0, s[6:7]
	s_mov_b32 m0, s33
	ds_read_b128 v[184:187], v154 offset:49152
	ds_read_b128 v[188:191], v154 offset:50176
	ds_read_b128 v[192:195], v154 offset:51200
	ds_read_b128 v[196:199], v154 offset:52224
	ds_read_b128 v[200:203], v154 offset:53248
	ds_read_b128 v[204:207], v154 offset:54272
	ds_read_b128 v[208:211], v154 offset:55296
	ds_read_b128 v[212:215], v154 offset:56320
	global_load_lds_dwordx4 v[216:217], off
	s_add_i32 m0, s33, 0x2000
	s_add_u32 s42, s42, 0x100080
	v_lshl_add_u64 v[216:217], v[218:219], 0, s[6:7]
	s_addc_u32 s43, s43, 0
	s_add_i32 s33, s64, s52
	global_load_lds_dwordx4 v[216:217], off
	v_lshl_add_u64 v[216:217], s[42:43], 0, v[134:135]
	s_mov_b32 m0, s33
	s_nop 0
	global_load_lds_dwordx4 v[216:217], off
	v_lshl_add_u64 v[216:217], s[42:43], 0, v[130:131]
	s_add_i32 m0, s33, 0x2000
	s_nop 0
	global_load_lds_dwordx4 v[216:217], off
	v_lshl_add_u64 v[216:217], v[220:221], 0, s[6:7]
	s_mov_b32 m0, s59
	s_nop 0
	global_load_lds_dwordx4 v[216:217], off
	v_lshl_add_u64 v[216:217], v[222:223], 0, s[6:7]
	s_mov_b32 m0, s60
	s_nop 0
	global_load_lds_dwordx4 v[216:217], off
	s_waitcnt vmcnt(8)
	s_waitcnt lgkmcnt(0)
	s_barrier
	s_setprio 0
	s_waitcnt lgkmcnt(0)
	v_mfma_f32_16x16x32_bf16 v[62:65], v[146:149], v[184:187], v[62:65]
	v_mfma_f32_16x16x32_bf16 v[58:61], v[160:163], v[184:187], v[58:61]
	v_mfma_f32_16x16x32_bf16 v[46:49], v[160:163], v[192:195], v[46:49]
	v_mfma_f32_16x16x32_bf16 v[54:57], v[146:149], v[192:195], v[54:57]
	v_mfma_f32_16x16x32_bf16 v[38:41], v[146:149], v[200:203], v[38:41]
	v_mfma_f32_16x16x32_bf16 v[30:33], v[160:163], v[200:203], v[30:33]
	v_mfma_f32_16x16x32_bf16 v[14:17], v[160:163], v[208:211], v[14:17]
	v_mfma_f32_16x16x32_bf16 v[22:25], v[146:149], v[208:211], v[22:25]
	v_mfma_f32_16x16x32_bf16 v[62:65], v[156:159], v[188:191], v[62:65]
	v_mfma_f32_16x16x32_bf16 v[58:61], v[164:167], v[188:191], v[58:61]
	v_mfma_f32_16x16x32_bf16 v[46:49], v[164:167], v[196:199], v[46:49]
	v_mfma_f32_16x16x32_bf16 v[54:57], v[156:159], v[196:199], v[54:57]
	v_mfma_f32_16x16x32_bf16 v[38:41], v[156:159], v[204:207], v[38:41]
	v_mfma_f32_16x16x32_bf16 v[30:33], v[164:167], v[204:207], v[30:33]
	v_mfma_f32_16x16x32_bf16 v[14:17], v[164:167], v[212:215], v[14:17]
	v_mfma_f32_16x16x32_bf16 v[22:25], v[156:159], v[212:215], v[22:25]
	s_setprio 2
	s_setprio 0
	v_mfma_f32_16x16x32_bf16 v[50:53], v[168:171], v[184:187], v[50:53]
	v_mfma_f32_16x16x32_bf16 v[42:45], v[176:179], v[184:187], v[42:45]
	v_mfma_f32_16x16x32_bf16 v[26:29], v[176:179], v[192:195], v[26:29]
	v_mfma_f32_16x16x32_bf16 v[34:37], v[168:171], v[192:195], v[34:37]
	v_mfma_f32_16x16x32_bf16 v[18:21], v[168:171], v[200:203], v[18:21]
	v_mfma_f32_16x16x32_bf16 v[10:13], v[176:179], v[200:203], v[10:13]
	v_mfma_f32_16x16x32_bf16 v[2:5], v[176:179], v[208:211], v[2:5]
	v_mfma_f32_16x16x32_bf16 v[6:9], v[168:171], v[208:211], v[6:9]
	v_mfma_f32_16x16x32_bf16 v[50:53], v[172:175], v[188:191], v[50:53]
	v_mfma_f32_16x16x32_bf16 v[42:45], v[180:183], v[188:191], v[42:45]
	v_mfma_f32_16x16x32_bf16 v[26:29], v[180:183], v[196:199], v[26:29]
	v_mfma_f32_16x16x32_bf16 v[34:37], v[172:175], v[196:199], v[34:37]
	v_mfma_f32_16x16x32_bf16 v[18:21], v[172:175], v[204:207], v[18:21]
	v_mfma_f32_16x16x32_bf16 v[10:13], v[180:183], v[204:207], v[10:13]
	v_mfma_f32_16x16x32_bf16 v[2:5], v[180:183], v[212:215], v[2:5]
	v_mfma_f32_16x16x32_bf16 v[6:9], v[172:175], v[212:215], v[6:9]
	s_setprio 2
	s_barrier
	s_add_i32 s68, s68, 2
	s_add_u32 s40, s40, 0x100
	s_addc_u32 s41, s41, 0
	s_add_u32 s66, s66, 0x100
	s_addc_u32 s67, s67, 0
	s_cmp_gt_u32 s68, 61
	s_cbranch_scc0 .LBB0_1825
	s_and_b64 vcc, exec, s[8:9]
	s_cbranch_vccz .LBB0_1828
	s_barrier

; #define PG8_STAGE(bufoff, gbase, voff) do { _Pragma("unroll") for (int _i = 0; _i < 2; ++_i) \
;         __builtin_amdgcn_global_load_lds((const unsigned*)((const char*)(gbase) + (voff)[_i]), (LAS unsigned*)(lds + (bufoff) + ldsw + _i * 8192), 16, 0, 0); } while (0)
; #define PG8_LDA(dst, b, h) do { _Pragma("unroll") for (int m = 0; m < 4; ++m) _Pragma("unroll") for (int k = 0; k < 2; ++k) dst[m][k] = *(const LAS bf16x8*)(lds + PG8_SA(b, h) + aoff + m * 2048 + k * 1024); } while (0)
; #define PG8_LDB(dst, b, h) do { _Pragma("unroll") for (int n = 0; n < 2; ++n) _Pragma("unroll") for (int k = 0; k < 2; ++k) dst[n][k] = *(const LAS bf16x8*)(lds + PG8_SB(b, h) + boff + n * 2048 + k * 1024); } while (0)
; #define PG8_MMA(ai, bj, At, Bt) do { __builtin_amdgcn_s_setprio(1); _Pragma("unroll") for (int m = 0; m < 4; ++m) _Pragma("unroll") for (int n = 0; n < 2; ++n) _Pragma("unroll") for (int k = 0; k < 2; ++k) \
;         acc[ai][bj][m][n] = __builtin_amdgcn_mfma_f32_16x16x32_bf16(Bt[n][k], At[m][k], acc[ai][bj][m][n], 0, 0, 0); __builtin_amdgcn_s_setprio(0); } while (0)
; #define PG8_WAIT_V(n) asm volatile("s_waitcnt vmcnt(" #n ")" ::: "memory")
; #define PG8_WAIT_L(n) asm volatile("s_waitcnt lgkmcnt(" #n ")" ::: "memory")
; #define PG8_BAR __builtin_amdgcn_s_barrier()
; #define PG8_SCHED __builtin_amdgcn_sched_barrier(0)
; template <class Epi>
; __device__ __forceinline__ void gemm_phase(LAS unsigned char* lds, const Gemm g, int G, int c, const Epi& E) {
;     ...
;         for (int t = 0; t < nt; t += 2) {
;             const bool last = (t == nt - 2);
;             const char* a1 = cA + (size_t)(t + 1) * kstep;
;             const char* a2 = last ? nA : cA + (size_t)(t + 2) * kstep; const char* b2 = last ? nB : cB + (size_t)(t + 2) * kstep;
;             const char* a3 = a2 + kstep; const char* b3 = b2 + kstep;
;             PG8_LDB(B0, 0, 0); PG8_LDB(B1, 0, 1); PG8_SCHED; PG8_LDA(At, 0, 0); PG8_STAGE(PG8_SA(1, 1), a1 + hstepA, voffA);
;             PG8_WAIT_V(8); PG8_WAIT_L(0); PG8_BAR; PG8_MMA(0, 0, At, B0); PG8_MMA(0, 1, At, B1); PG8_BAR; PG8_SCHED;
;             PG8_LDA(At, 0, 1); PG8_STAGE(PG8_SB(0, 0), b2, voffB); PG8_STAGE(PG8_SB(0, 1), b2 + hstepB, voffB); PG8_STAGE(PG8_SA(0, 0), a2, voffA);
.LBB0_1931:
	ds_read_b128 v[122:125], v168
	ds_read_b128 v[126:129], v168 offset:1024
	ds_read_b128 v[130:133], v168 offset:2048
	ds_read_b128 v[134:137], v168 offset:3072
	ds_read_b128 v[162:165], v169
	ds_read_b128 v[172:175], v169 offset:1024
	ds_read_b128 v[176:179], v169 offset:2048
	ds_read_b128 v[180:183], v169 offset:3072
	s_add_u32 s33, s4, 0xfffc0080
	s_addc_u32 s36, s5, -1
	s_cmp_eq_u32 s62, 12
	s_cselect_b32 s39, s19, s36
	s_cselect_b32 s38, s18, s33
	s_cselect_b32 s37, s15, s61
	s_cselect_b32 s36, s17, s60
	v_lshl_add_u64 v[216:217], s[4:5], 0, v[154:155]
	s_add_i32 m0, s23, 0xc000
	ds_read_b128 v[184:187], v170
	ds_read_b128 v[188:191], v170 offset:1024
	ds_read_b128 v[192:195], v170 offset:2048
	ds_read_b128 v[196:199], v170 offset:3072
	ds_read_b128 v[200:203], v170 offset:4096
	ds_read_b128 v[204:207], v170 offset:5120
	ds_read_b128 v[208:211], v170 offset:6144
	ds_read_b128 v[212:215], v170 offset:7168
	global_load_lds_dwordx4 v[216:217], off
	v_lshl_add_u64 v[216:217], s[4:5], 0, v[156:157]
	s_add_i32 m0, s23, 0xe000
	s_nop 0
	global_load_lds_dwordx4 v[216:217], off
	s_waitcnt vmcnt(8)
	s_waitcnt lgkmcnt(0)
	s_barrier
	s_setprio 0
	s_waitcnt lgkmcnt(0)
	v_mfma_f32_16x16x32_bf16 v[142:145], v[122:125], v[184:187], v[142:145]
	v_mfma_f32_16x16x32_bf16 v[138:141], v[130:133], v[184:187], v[138:141]
	v_mfma_f32_16x16x32_bf16 v[106:109], v[130:133], v[192:195], v[106:109]
	v_mfma_f32_16x16x32_bf16 v[118:121], v[122:125], v[192:195], v[118:121]
	v_mfma_f32_16x16x32_bf16 v[102:105], v[122:125], v[200:203], v[102:105]
	v_mfma_f32_16x16x32_bf16 v[90:93], v[130:133], v[200:203], v[90:93]
	v_mfma_f32_16x16x32_bf16 v[74:77], v[130:133], v[208:211], v[74:77]
	v_mfma_f32_16x16x32_bf16 v[86:89], v[122:125], v[208:211], v[86:89]
	v_mfma_f32_16x16x32_bf16 v[142:145], v[126:129], v[188:191], v[142:145]
	v_mfma_f32_16x16x32_bf16 v[138:141], v[134:137], v[188:191], v[138:141]
	v_mfma_f32_16x16x32_bf16 v[106:109], v[134:137], v[196:199], v[106:109]
	v_mfma_f32_16x16x32_bf16 v[118:121], v[126:129], v[196:199], v[118:121]
	v_mfma_f32_16x16x32_bf16 v[102:105], v[126:129], v[204:207], v[102:105]
	v_mfma_f32_16x16x32_bf16 v[90:93], v[134:137], v[204:207], v[90:93]
	v_mfma_f32_16x16x32_bf16 v[74:77], v[134:137], v[212:215], v[74:77]
	v_mfma_f32_16x16x32_bf16 v[86:89], v[126:129], v[212:215], v[86:89]
	s_setprio 2
	s_setprio 0
	v_mfma_f32_16x16x32_bf16 v[114:117], v[162:165], v[184:187], v[114:117]
	v_mfma_f32_16x16x32_bf16 v[110:113], v[176:179], v[184:187], v[110:113]
	v_mfma_f32_16x16x32_bf16 v[94:97], v[176:179], v[192:195], v[94:97]
	v_mfma_f32_16x16x32_bf16 v[98:101], v[162:165], v[192:195], v[98:101]
	v_mfma_f32_16x16x32_bf16 v[82:85], v[162:165], v[200:203], v[82:85]
	v_mfma_f32_16x16x32_bf16 v[78:81], v[176:179], v[200:203], v[78:81]
	v_mfma_f32_16x16x32_bf16 v[66:69], v[176:179], v[208:211], v[66:69]
	v_mfma_f32_16x16x32_bf16 v[70:73], v[162:165], v[208:211], v[70:73]
	v_mfma_f32_16x16x32_bf16 v[114:117], v[172:175], v[188:191], v[114:117]
	v_mfma_f32_16x16x32_bf16 v[110:113], v[180:183], v[188:191], v[110:113]
	v_mfma_f32_16x16x32_bf16 v[94:97], v[180:183], v[196:199], v[94:97]
	v_mfma_f32_16x16x32_bf16 v[98:101], v[172:175], v[196:199], v[98:101]
	v_mfma_f32_16x16x32_bf16 v[82:85], v[172:175], v[204:207], v[82:85]
	v_mfma_f32_16x16x32_bf16 v[78:81], v[180:183], v[204:207], v[78:81]
	v_mfma_f32_16x16x32_bf16 v[66:69], v[180:183], v[212:215], v[66:69]
	v_mfma_f32_16x16x32_bf16 v[70:73], v[172:175], v[212:215], v[70:73]
	s_setprio 2
	s_barrier
	s_add_i32 s33, s56, s42
	v_lshl_add_u64 v[216:217], s[36:37], 0, v[150:151]
	s_mov_b32 m0, s33
	ds_read_b128 v[184:187], v170 offset:16384
	ds_read_b128 v[188:191], v170 offset:17408
	ds_read_b128 v[192:195], v170 offset:18432
	ds_read_b128 v[196:199], v170 offset:19456
	ds_read_b128 v[200:203], v170 offset:20480
	ds_read_b128 v[204:207], v170 offset:21504
	ds_read_b128 v[208:211], v170 offset:22528
	ds_read_b128 v[212:215], v170 offset:23552
	global_load_lds_dwordx4 v[216:217], off
	s_add_i32 m0, s33, 0x2000
	s_add_u32 s64, s36, 0x40000
	v_lshl_add_u64 v[218:219], s[36:37], 0, v[146:147]
	s_addc_u32 s65, s37, 0
	s_add_i32 s33, s57, s42
	global_load_lds_dwordx4 v[218:219], off
	v_lshl_add_u64 v[220:221], s[64:65], 0, v[150:151]
	s_mov_b32 m0, s33
	v_lshl_add_u64 v[222:223], s[38:39], 0, v[148:149]
	global_load_lds_dwordx4 v[220:221], off
	v_lshl_add_u64 v[220:221], s[64:65], 0, v[146:147]
	s_add_i32 m0, s33, 0x2000
	s_nop 0
	global_load_lds_dwordx4 v[220:221], off
	v_lshl_add_u64 v[220:221], s[38:39], 0, v[152:153]
	s_mov_b32 m0, s23
	s_nop 0
	global_load_lds_dwordx4 v[220:221], off
	s_mov_b32 m0, s25
	s_nop 0
	global_load_lds_dwordx4 v[222:223], off
	s_waitcnt vmcnt(8)
	s_waitcnt lgkmcnt(0)
	s_barrier
; #define PG8_STAGE(bufoff, gbase, voff) do { _Pragma("unroll") for (int _i = 0; _i < 2; ++_i) \
;         __builtin_amdgcn_global_load_lds((const unsigned*)((const char*)(gbase) + (voff)[_i]), (LAS unsigned*)(lds + (bufoff) + ldsw + _i * 8192), 16, 0, 0); } while (0)
; #define PG8_LDA(dst, b, h) do { _Pragma("unroll") for (int m = 0; m < 4; ++m) _Pragma("unroll") for (int k = 0; k < 2; ++k) dst[m][k] = *(const LAS bf16x8*)(lds + PG8_SA(b, h) + aoff + m * 2048 + k * 1024); } while (0)
; #define PG8_LDB(dst, b, h) do { _Pragma("unroll") for (int n = 0; n < 2; ++n) _Pragma("unroll") for (int k = 0; k < 2; ++k) dst[n][k] = *(const LAS bf16x8*)(lds + PG8_SB(b, h) + boff + n * 2048 + k * 1024); } while (0)
; #define PG8_MMA(ai, bj, At, Bt) do { __builtin_amdgcn_s_setprio(1); _Pragma("unroll") for (int m = 0; m < 4; ++m) _Pragma("unroll") for (int n = 0; n < 2; ++n) _Pragma("unroll") for (int k = 0; k < 2; ++k) \
;         acc[ai][bj][m][n] = __builtin_amdgcn_mfma_f32_16x16x32_bf16(Bt[n][k], At[m][k], acc[ai][bj][m][n], 0, 0, 0); __builtin_amdgcn_s_setprio(0); } while (0)
; #define PG8_WAIT_V(n) asm volatile("s_waitcnt vmcnt(" #n ")" ::: "memory")
; #define PG8_WAIT_L(n) asm volatile("s_waitcnt lgkmcnt(" #n ")" ::: "memory")
; #define PG8_BAR __builtin_amdgcn_s_barrier()
; #define PG8_SCHED __builtin_amdgcn_sched_barrier(0)
; template <class Epi>
; __device__ __forceinline__ void gemm_phase(LAS unsigned char* lds, const Gemm g, int G, int c, const Epi& E) {
;     ...
;             PG8_WAIT_V(8); PG8_WAIT_L(0); PG8_BAR; PG8_MMA(1, 0, At, B0); PG8_MMA(1, 1, At, B1); PG8_BAR; PG8_SCHED;
;             PG8_LDB(B0, 1, 0); PG8_LDB(B1, 1, 1); PG8_SCHED; PG8_LDA(At, 1, 0); PG8_STAGE(PG8_SA(0, 1), a2 + hstepA, voffA);
;             PG8_WAIT_V(8); PG8_WAIT_L(0); PG8_BAR; PG8_MMA(0, 0, At, B0); PG8_MMA(0, 1, At, B1); PG8_BAR; PG8_SCHED;
	s_setprio 0
	s_waitcnt lgkmcnt(0)
	v_mfma_f32_16x16x32_bf16 v[62:65], v[122:125], v[184:187], v[62:65]
	v_mfma_f32_16x16x32_bf16 v[58:61], v[130:133], v[184:187], v[58:61]
	v_mfma_f32_16x16x32_bf16 v[42:45], v[130:133], v[192:195], v[42:45]
	v_mfma_f32_16x16x32_bf16 v[54:57], v[122:125], v[192:195], v[54:57]
	v_mfma_f32_16x16x32_bf16 v[38:41], v[122:125], v[200:203], v[38:41]
	v_mfma_f32_16x16x32_bf16 v[26:29], v[130:133], v[200:203], v[26:29]
	v_mfma_f32_16x16x32_bf16 v[10:13], v[130:133], v[208:211], v[10:13]
	v_mfma_f32_16x16x32_bf16 v[22:25], v[122:125], v[208:211], v[22:25]
	v_mfma_f32_16x16x32_bf16 v[62:65], v[126:129], v[188:191], v[62:65]
	v_mfma_f32_16x16x32_bf16 v[58:61], v[134:137], v[188:191], v[58:61]
	v_mfma_f32_16x16x32_bf16 v[42:45], v[134:137], v[196:199], v[42:45]
	v_mfma_f32_16x16x32_bf16 v[54:57], v[126:129], v[196:199], v[54:57]
	v_mfma_f32_16x16x32_bf16 v[38:41], v[126:129], v[204:207], v[38:41]
	v_mfma_f32_16x16x32_bf16 v[26:29], v[134:137], v[204:207], v[26:29]
	v_mfma_f32_16x16x32_bf16 v[10:13], v[134:137], v[212:215], v[10:13]
	v_mfma_f32_16x16x32_bf16 v[22:25], v[126:129], v[212:215], v[22:25]
	s_setprio 2
	s_setprio 0
	v_mfma_f32_16x16x32_bf16 v[50:53], v[162:165], v[184:187], v[50:53]
	v_mfma_f32_16x16x32_bf16 v[46:49], v[176:179], v[184:187], v[46:49]
	v_mfma_f32_16x16x32_bf16 v[30:33], v[176:179], v[192:195], v[30:33]
	v_mfma_f32_16x16x32_bf16 v[34:37], v[162:165], v[192:195], v[34:37]
	v_mfma_f32_16x16x32_bf16 v[18:21], v[162:165], v[200:203], v[18:21]
	v_mfma_f32_16x16x32_bf16 v[14:17], v[176:179], v[200:203], v[14:17]
	v_mfma_f32_16x16x32_bf16 v[2:5], v[176:179], v[208:211], v[2:5]
	v_mfma_f32_16x16x32_bf16 v[6:9], v[162:165], v[208:211], v[6:9]
	v_mfma_f32_16x16x32_bf16 v[50:53], v[172:175], v[188:191], v[50:53]
	v_mfma_f32_16x16x32_bf16 v[46:49], v[180:183], v[188:191], v[46:49]
	v_mfma_f32_16x16x32_bf16 v[30:33], v[180:183], v[196:199], v[30:33]
	v_mfma_f32_16x16x32_bf16 v[34:37], v[172:175], v[196:199], v[34:37]
	v_mfma_f32_16x16x32_bf16 v[18:21], v[172:175], v[204:207], v[18:21]
	v_mfma_f32_16x16x32_bf16 v[14:17], v[180:183], v[204:207], v[14:17]
	v_mfma_f32_16x16x32_bf16 v[2:5], v[180:183], v[212:215], v[2:5]
	v_mfma_f32_16x16x32_bf16 v[6:9], v[172:175], v[212:215], v[6:9]
	s_setprio 2
	s_barrier
	s_add_i32 s33, 0, 0x18000
	s_add_i32 s63, 0, 0x1c000
	v_add_u32_e32 v134, s33, v167
	v_add_u32_e32 v171, s63, v167
	ds_read_b128 v[122:125], v134
	ds_read_b128 v[126:129], v134 offset:1024
	ds_read_b128 v[130:133], v134 offset:2048
	ds_read_b128 v[134:137], v134 offset:3072
	ds_read_b128 v[162:165], v171
	ds_read_b128 v[172:175], v171 offset:1024
	ds_read_b128 v[176:179], v171 offset:2048
	ds_read_b128 v[180:183], v171 offset:3072
	s_add_u32 s38, s38, 0x40000
	s_addc_u32 s39, s39, 0
	s_mov_b32 m0, s44
	v_lshl_add_u64 v[224:225], s[38:39], 0, v[152:153]
	ds_read_b128 v[184:187], v170 offset:32768
	ds_read_b128 v[188:191], v170 offset:33792
	ds_read_b128 v[192:195], v170 offset:34816
	ds_read_b128 v[196:199], v170 offset:35840
	ds_read_b128 v[200:203], v170 offset:36864
	ds_read_b128 v[204:207], v170 offset:37888
	ds_read_b128 v[208:211], v170 offset:38912
	ds_read_b128 v[212:215], v170 offset:39936
	global_load_lds_dwordx4 v[224:225], off
	v_lshl_add_u64 v[224:225], s[38:39], 0, v[148:149]
	s_mov_b32 m0, s45
	s_nop 0
	global_load_lds_dwordx4 v[224:225], off
	s_waitcnt vmcnt(8)
	s_waitcnt lgkmcnt(0)
	s_barrier
	s_setprio 0
	s_waitcnt lgkmcnt(0)
	v_mfma_f32_16x16x32_bf16 v[142:145], v[122:125], v[184:187], v[142:145]
	v_mfma_f32_16x16x32_bf16 v[138:141], v[130:133], v[184:187], v[138:141]
	v_mfma_f32_16x16x32_bf16 v[106:109], v[130:133], v[192:195], v[106:109]
	v_mfma_f32_16x16x32_bf16 v[118:121], v[122:125], v[192:195], v[118:121]
	v_mfma_f32_16x16x32_bf16 v[102:105], v[122:125], v[200:203], v[102:105]
	v_mfma_f32_16x16x32_bf16 v[90:93], v[130:133], v[200:203], v[90:93]
	v_mfma_f32_16x16x32_bf16 v[74:77], v[130:133], v[208:211], v[74:77]
	v_mfma_f32_16x16x32_bf16 v[86:89], v[122:125], v[208:211], v[86:89]
	v_mfma_f32_16x16x32_bf16 v[142:145], v[126:129], v[188:191], v[142:145]
	v_mfma_f32_16x16x32_bf16 v[138:141], v[134:137], v[188:191], v[138:141]
	v_mfma_f32_16x16x32_bf16 v[106:109], v[134:137], v[196:199], v[106:109]
	v_mfma_f32_16x16x32_bf16 v[118:121], v[126:129], v[196:199], v[118:121]
	v_mfma_f32_16x16x32_bf16 v[102:105], v[126:129], v[204:207], v[102:105]
	v_mfma_f32_16x16x32_bf16 v[90:93], v[134:137], v[204:207], v[90:93]
	v_mfma_f32_16x16x32_bf16 v[74:77], v[134:137], v[212:215], v[74:77]
	v_mfma_f32_16x16x32_bf16 v[86:89], v[126:129], v[212:215], v[86:89]
	s_setprio 2
	s_setprio 0
	v_mfma_f32_16x16x32_bf16 v[114:117], v[162:165], v[184:187], v[114:117]
	v_mfma_f32_16x16x32_bf16 v[110:113], v[176:179], v[184:187], v[110:113]
	v_mfma_f32_16x16x32_bf16 v[94:97], v[176:179], v[192:195], v[94:97]
	v_mfma_f32_16x16x32_bf16 v[98:101], v[162:165], v[192:195], v[98:101]
	v_mfma_f32_16x16x32_bf16 v[82:85], v[162:165], v[200:203], v[82:85]
	v_mfma_f32_16x16x32_bf16 v[78:81], v[176:179], v[200:203], v[78:81]
	v_mfma_f32_16x16x32_bf16 v[66:69], v[176:179], v[208:211], v[66:69]
	v_mfma_f32_16x16x32_bf16 v[70:73], v[162:165], v[208:211], v[70:73]
	v_mfma_f32_16x16x32_bf16 v[114:117], v[172:175], v[188:191], v[114:117]
	v_mfma_f32_16x16x32_bf16 v[110:113], v[180:183], v[188:191], v[110:113]
	v_mfma_f32_16x16x32_bf16 v[94:97], v[180:183], v[196:199], v[94:97]
	v_mfma_f32_16x16x32_bf16 v[98:101], v[172:175], v[196:199], v[98:101]
	v_mfma_f32_16x16x32_bf16 v[82:85], v[172:175], v[204:207], v[82:85]
	v_mfma_f32_16x16x32_bf16 v[78:81], v[180:183], v[204:207], v[78:81]
	v_mfma_f32_16x16x32_bf16 v[66:69], v[180:183], v[212:215], v[66:69]
	v_mfma_f32_16x16x32_bf16 v[70:73], v[172:175], v[212:215], v[70:73]
	s_setprio 2
	s_barrier
; #define PG8_STAGE(bufoff, gbase, voff) do { _Pragma("unroll") for (int _i = 0; _i < 2; ++_i) \
;         __builtin_amdgcn_global_load_lds((const unsigned*)((const char*)(gbase) + (voff)[_i]), (LAS unsigned*)(lds + (bufoff) + ldsw + _i * 8192), 16, 0, 0); } while (0)
; #define PG8_LDA(dst, b, h) do { _Pragma("unroll") for (int m = 0; m < 4; ++m) _Pragma("unroll") for (int k = 0; k < 2; ++k) dst[m][k] = *(const LAS bf16x8*)(lds + PG8_SA(b, h) + aoff + m * 2048 + k * 1024); } while (0)
; #define PG8_MMA(ai, bj, At, Bt) do { __builtin_amdgcn_s_setprio(1); _Pragma("unroll") for (int m = 0; m < 4; ++m) _Pragma("unroll") for (int n = 0; n < 2; ++n) _Pragma("unroll") for (int k = 0; k < 2; ++k) \
;         acc[ai][bj][m][n] = __builtin_amdgcn_mfma_f32_16x16x32_bf16(Bt[n][k], At[m][k], acc[ai][bj][m][n], 0, 0, 0); __builtin_amdgcn_s_setprio(0); } while (0)
; #define PG8_WAIT_V(n) asm volatile("s_waitcnt vmcnt(" #n ")" ::: "memory")
; #define PG8_WAIT_L(n) asm volatile("s_waitcnt lgkmcnt(" #n ")" ::: "memory")
; #define PG8_BAR __builtin_amdgcn_s_barrier()
; #define PG8_SCHED __builtin_amdgcn_sched_barrier(0)
; template <class Epi>
; __device__ __forceinline__ void gemm_phase(LAS unsigned char* lds, const Gemm g, int G, int c, const Epi& E) {
;     ...
;             PG8_LDA(At, 1, 1); PG8_STAGE(PG8_SB(1, 0), b3, voffB); PG8_STAGE(PG8_SB(1, 1), b3 + hstepB, voffB); PG8_STAGE(PG8_SA(1, 0), a3, voffA);
;             PG8_WAIT_V(8); PG8_WAIT_L(0); PG8_BAR; PG8_MMA(1, 0, At, B0); PG8_MMA(1, 1, At, B1); PG8_BAR; PG8_SCHED;
;         }
;         if (wr == 0) PG8_BAR;
	s_add_i32 s33, s33, s42
	v_lshl_add_u64 v[216:217], v[216:217], 0, s[10:11]
	s_mov_b32 m0, s33
	ds_read_b128 v[184:187], v170 offset:49152
	ds_read_b128 v[188:191], v170 offset:50176
	ds_read_b128 v[192:195], v170 offset:51200
	ds_read_b128 v[196:199], v170 offset:52224
	ds_read_b128 v[200:203], v170 offset:53248
	ds_read_b128 v[204:207], v170 offset:54272
	ds_read_b128 v[208:211], v170 offset:55296
	ds_read_b128 v[212:215], v170 offset:56320
	global_load_lds_dwordx4 v[216:217], off
	s_add_i32 m0, s33, 0x2000
	s_add_u32 s36, s36, 0x40080
	v_lshl_add_u64 v[216:217], v[218:219], 0, s[10:11]
	s_addc_u32 s37, s37, 0
	s_add_i32 s33, s63, s42
	global_load_lds_dwordx4 v[216:217], off
	v_lshl_add_u64 v[216:217], s[36:37], 0, v[150:151]
	s_mov_b32 m0, s33
	s_nop 0
	global_load_lds_dwordx4 v[216:217], off
	v_lshl_add_u64 v[216:217], s[36:37], 0, v[146:147]
	s_add_i32 m0, s33, 0x2000
	s_nop 0
	global_load_lds_dwordx4 v[216:217], off
	v_lshl_add_u64 v[216:217], v[220:221], 0, s[10:11]
	s_mov_b32 m0, s53
	s_nop 0
	global_load_lds_dwordx4 v[216:217], off
	v_lshl_add_u64 v[216:217], v[222:223], 0, s[10:11]
	s_mov_b32 m0, s54
	s_nop 0
	global_load_lds_dwordx4 v[216:217], off
	s_waitcnt vmcnt(8)
	s_waitcnt lgkmcnt(0)
	s_barrier
	s_setprio 0
	s_waitcnt lgkmcnt(0)
	v_mfma_f32_16x16x32_bf16 v[62:65], v[122:125], v[184:187], v[62:65]
	v_mfma_f32_16x16x32_bf16 v[58:61], v[130:133], v[184:187], v[58:61]
	v_mfma_f32_16x16x32_bf16 v[42:45], v[130:133], v[192:195], v[42:45]
	v_mfma_f32_16x16x32_bf16 v[54:57], v[122:125], v[192:195], v[54:57]
	v_mfma_f32_16x16x32_bf16 v[38:41], v[122:125], v[200:203], v[38:41]
	v_mfma_f32_16x16x32_bf16 v[26:29], v[130:133], v[200:203], v[26:29]
	v_mfma_f32_16x16x32_bf16 v[10:13], v[130:133], v[208:211], v[10:13]
	v_mfma_f32_16x16x32_bf16 v[22:25], v[122:125], v[208:211], v[22:25]
	v_mfma_f32_16x16x32_bf16 v[62:65], v[126:129], v[188:191], v[62:65]
	v_mfma_f32_16x16x32_bf16 v[58:61], v[134:137], v[188:191], v[58:61]
	v_mfma_f32_16x16x32_bf16 v[42:45], v[134:137], v[196:199], v[42:45]
	v_mfma_f32_16x16x32_bf16 v[54:57], v[126:129], v[196:199], v[54:57]
	v_mfma_f32_16x16x32_bf16 v[38:41], v[126:129], v[204:207], v[38:41]
	v_mfma_f32_16x16x32_bf16 v[26:29], v[134:137], v[204:207], v[26:29]
	v_mfma_f32_16x16x32_bf16 v[10:13], v[134:137], v[212:215], v[10:13]
	v_mfma_f32_16x16x32_bf16 v[22:25], v[126:129], v[212:215], v[22:25]
	s_setprio 2
	s_setprio 0
	v_mfma_f32_16x16x32_bf16 v[50:53], v[162:165], v[184:187], v[50:53]
	v_mfma_f32_16x16x32_bf16 v[46:49], v[176:179], v[184:187], v[46:49]
	v_mfma_f32_16x16x32_bf16 v[30:33], v[176:179], v[192:195], v[30:33]
	v_mfma_f32_16x16x32_bf16 v[34:37], v[162:165], v[192:195], v[34:37]
	v_mfma_f32_16x16x32_bf16 v[18:21], v[162:165], v[200:203], v[18:21]
	v_mfma_f32_16x16x32_bf16 v[14:17], v[176:179], v[200:203], v[14:17]
	v_mfma_f32_16x16x32_bf16 v[2:5], v[176:179], v[208:211], v[2:5]
	v_mfma_f32_16x16x32_bf16 v[6:9], v[162:165], v[208:211], v[6:9]
	v_mfma_f32_16x16x32_bf16 v[50:53], v[172:175], v[188:191], v[50:53]
	v_mfma_f32_16x16x32_bf16 v[46:49], v[180:183], v[188:191], v[46:49]
	v_mfma_f32_16x16x32_bf16 v[30:33], v[180:183], v[196:199], v[30:33]
	v_mfma_f32_16x16x32_bf16 v[34:37], v[172:175], v[196:199], v[34:37]
	v_mfma_f32_16x16x32_bf16 v[18:21], v[172:175], v[204:207], v[18:21]
	v_mfma_f32_16x16x32_bf16 v[14:17], v[180:183], v[204:207], v[14:17]
	v_mfma_f32_16x16x32_bf16 v[2:5], v[180:183], v[212:215], v[2:5]
	v_mfma_f32_16x16x32_bf16 v[6:9], v[172:175], v[212:215], v[6:9]
	s_setprio 2
	s_barrier
	s_add_i32 s62, s62, 2
	s_add_u32 s4, s4, 0x100
	s_addc_u32 s5, s5, 0
	s_add_u32 s60, s60, 0x100
	s_addc_u32 s61, s61, 0
	s_cmp_gt_u32 s62, 13
	s_cbranch_scc0 .LBB0_1931
	s_and_b64 vcc, exec, s[12:13]
	s_cbranch_vccz .LBB0_1934
	s_barrier

; #define PG8_STAGE(bufoff, gbase, voff) do { _Pragma("unroll") for (int _i = 0; _i < 2; ++_i) \
;         __builtin_amdgcn_global_load_lds((const unsigned*)((const char*)(gbase) + (voff)[_i]), (LAS unsigned*)(lds + (bufoff) + ldsw + _i * 8192), 16, 0, 0); } while (0)
; #define PG8_LDA(dst, b, h) do { _Pragma("unroll") for (int m = 0; m < 4; ++m) _Pragma("unroll") for (int k = 0; k < 2; ++k) dst[m][k] = *(const LAS bf16x8*)(lds + PG8_SA(b, h) + aoff + m * 2048 + k * 1024); } while (0)
; #define PG8_LDB(dst, b, h) do { _Pragma("unroll") for (int n = 0; n < 2; ++n) _Pragma("unroll") for (int k = 0; k < 2; ++k) dst[n][k] = *(const LAS bf16x8*)(lds + PG8_SB(b, h) + boff + n * 2048 + k * 1024); } while (0)
; #define PG8_MMA(ai, bj, At, Bt) do { __builtin_amdgcn_s_setprio(1); _Pragma("unroll") for (int m = 0; m < 4; ++m) _Pragma("unroll") for (int n = 0; n < 2; ++n) _Pragma("unroll") for (int k = 0; k < 2; ++k) \
;         acc[ai][bj][m][n] = __builtin_amdgcn_mfma_f32_16x16x32_bf16(Bt[n][k], At[m][k], acc[ai][bj][m][n], 0, 0, 0); __builtin_amdgcn_s_setprio(0); } while (0)
; #define PG8_WAIT_V(n) asm volatile("s_waitcnt vmcnt(" #n ")" ::: "memory")
; #define PG8_WAIT_L(n) asm volatile("s_waitcnt lgkmcnt(" #n ")" ::: "memory")
; #define PG8_BAR __builtin_amdgcn_s_barrier()
; #define PG8_SCHED __builtin_amdgcn_sched_barrier(0)
; template <class Epi>
; __device__ __forceinline__ void gemm_phase(LAS unsigned char* lds, const Gemm g, int G, int c, const Epi& E) {
;     ...
;         for (int t = 0; t < nt; t += 2) {
;             const bool last = (t == nt - 2);
;             const char* a1 = cA + (size_t)(t + 1) * kstep;
;             const char* a2 = last ? nA : cA + (size_t)(t + 2) * kstep; const char* b2 = last ? nB : cB + (size_t)(t + 2) * kstep;
;             const char* a3 = a2 + kstep; const char* b3 = b2 + kstep;
;             PG8_LDB(B0, 0, 0); PG8_LDB(B1, 0, 1); PG8_SCHED; PG8_LDA(At, 0, 0); PG8_STAGE(PG8_SA(1, 1), a1 + hstepA, voffA);
;             PG8_WAIT_V(8); PG8_WAIT_L(0); PG8_BAR; PG8_MMA(0, 0, At, B0); PG8_MMA(0, 1, At, B1); PG8_BAR; PG8_SCHED;
;             PG8_LDA(At, 0, 1); PG8_STAGE(PG8_SB(0, 0), b2, voffB); PG8_STAGE(PG8_SB(0, 1), b2 + hstepB, voffB); PG8_STAGE(PG8_SA(0, 0), a2, voffA);
.LBB0_2084:
	ds_read_b128 v[152:155], v148
	ds_read_b128 v[156:159], v148 offset:1024
	ds_read_b128 v[160:163], v148 offset:2048
	ds_read_b128 v[164:167], v148 offset:3072
	ds_read_b128 v[168:171], v149
	ds_read_b128 v[172:175], v149 offset:1024
	ds_read_b128 v[176:179], v149 offset:2048
	ds_read_b128 v[180:183], v149 offset:3072
	s_add_u32 s33, s4, 0xfffc0080
	s_addc_u32 s38, s5, -1
	s_cmp_eq_u32 s68, 12
	s_cselect_b32 s41, s21, s38
	s_cselect_b32 s40, s20, s33
	s_cselect_b32 s39, s17, s67
	s_cselect_b32 s38, s19, s66
	v_lshl_add_u64 v[216:217], s[4:5], 0, v[138:139]
	s_add_i32 m0, s25, 0xc000
	ds_read_b128 v[184:187], v150
	ds_read_b128 v[188:191], v150 offset:1024
	ds_read_b128 v[192:195], v150 offset:2048
	ds_read_b128 v[196:199], v150 offset:3072
	ds_read_b128 v[200:203], v150 offset:4096
	ds_read_b128 v[204:207], v150 offset:5120
	ds_read_b128 v[208:211], v150 offset:6144
	ds_read_b128 v[212:215], v150 offset:7168
	global_load_lds_dwordx4 v[216:217], off
	v_lshl_add_u64 v[216:217], s[4:5], 0, v[140:141]
	s_add_i32 m0, s25, 0xe000
	s_nop 0
	global_load_lds_dwordx4 v[216:217], off
	s_waitcnt vmcnt(8)
	s_waitcnt lgkmcnt(0)
	s_barrier
	s_setprio 0
	s_waitcnt lgkmcnt(0)
	v_mfma_f32_16x16x32_bf16 v[126:129], v[152:155], v[184:187], v[126:129]
	v_mfma_f32_16x16x32_bf16 v[122:125], v[160:163], v[184:187], v[122:125]
	v_mfma_f32_16x16x32_bf16 v[106:109], v[160:163], v[192:195], v[106:109]
	v_mfma_f32_16x16x32_bf16 v[110:113], v[152:155], v[192:195], v[110:113]
	v_mfma_f32_16x16x32_bf16 v[94:97], v[152:155], v[200:203], v[94:97]
	v_mfma_f32_16x16x32_bf16 v[90:93], v[160:163], v[200:203], v[90:93]
	v_mfma_f32_16x16x32_bf16 v[74:77], v[160:163], v[208:211], v[74:77]
	v_mfma_f32_16x16x32_bf16 v[78:81], v[152:155], v[208:211], v[78:81]
	v_mfma_f32_16x16x32_bf16 v[126:129], v[156:159], v[188:191], v[126:129]
	v_mfma_f32_16x16x32_bf16 v[122:125], v[164:167], v[188:191], v[122:125]
	v_mfma_f32_16x16x32_bf16 v[106:109], v[164:167], v[196:199], v[106:109]
	v_mfma_f32_16x16x32_bf16 v[110:113], v[156:159], v[196:199], v[110:113]
	v_mfma_f32_16x16x32_bf16 v[94:97], v[156:159], v[204:207], v[94:97]
	v_mfma_f32_16x16x32_bf16 v[90:93], v[164:167], v[204:207], v[90:93]
	v_mfma_f32_16x16x32_bf16 v[74:77], v[164:167], v[212:215], v[74:77]
	v_mfma_f32_16x16x32_bf16 v[78:81], v[156:159], v[212:215], v[78:81]
	s_setprio 2
	s_setprio 0
	v_mfma_f32_16x16x32_bf16 v[118:121], v[168:171], v[184:187], v[118:121]
	v_mfma_f32_16x16x32_bf16 v[114:117], v[176:179], v[184:187], v[114:117]
	v_mfma_f32_16x16x32_bf16 v[98:101], v[176:179], v[192:195], v[98:101]
	v_mfma_f32_16x16x32_bf16 v[102:105], v[168:171], v[192:195], v[102:105]
	v_mfma_f32_16x16x32_bf16 v[86:89], v[168:171], v[200:203], v[86:89]
	v_mfma_f32_16x16x32_bf16 v[82:85], v[176:179], v[200:203], v[82:85]
	v_mfma_f32_16x16x32_bf16 v[66:69], v[176:179], v[208:211], v[66:69]
	v_mfma_f32_16x16x32_bf16 v[70:73], v[168:171], v[208:211], v[70:73]
	v_mfma_f32_16x16x32_bf16 v[118:121], v[172:175], v[188:191], v[118:121]
	v_mfma_f32_16x16x32_bf16 v[114:117], v[180:183], v[188:191], v[114:117]
	v_mfma_f32_16x16x32_bf16 v[98:101], v[180:183], v[196:199], v[98:101]
	v_mfma_f32_16x16x32_bf16 v[102:105], v[172:175], v[196:199], v[102:105]
	v_mfma_f32_16x16x32_bf16 v[86:89], v[172:175], v[204:207], v[86:89]
	v_mfma_f32_16x16x32_bf16 v[82:85], v[180:183], v[204:207], v[82:85]
	v_mfma_f32_16x16x32_bf16 v[66:69], v[180:183], v[212:215], v[66:69]
	v_mfma_f32_16x16x32_bf16 v[70:73], v[172:175], v[212:215], v[70:73]
	s_setprio 2
	s_barrier
	s_add_i32 s33, s56, s46
	v_lshl_add_u64 v[216:217], s[38:39], 0, v[134:135]
	s_mov_b32 m0, s33
	ds_read_b128 v[184:187], v150 offset:16384
	ds_read_b128 v[188:191], v150 offset:17408
	ds_read_b128 v[192:195], v150 offset:18432
	ds_read_b128 v[196:199], v150 offset:19456
	ds_read_b128 v[200:203], v150 offset:20480
	ds_read_b128 v[204:207], v150 offset:21504
	ds_read_b128 v[208:211], v150 offset:22528
	ds_read_b128 v[212:215], v150 offset:23552
	global_load_lds_dwordx4 v[216:217], off
	s_add_i32 m0, s33, 0x2000
	s_add_u32 s70, s38, 0x40000
	v_lshl_add_u64 v[218:219], s[38:39], 0, v[130:131]
	s_addc_u32 s71, s39, 0
	s_add_i32 s33, s57, s46
	global_load_lds_dwordx4 v[218:219], off
	v_lshl_add_u64 v[220:221], s[70:71], 0, v[134:135]
	s_mov_b32 m0, s33
	v_lshl_add_u64 v[222:223], s[40:41], 0, v[132:133]
	global_load_lds_dwordx4 v[220:221], off
	v_lshl_add_u64 v[220:221], s[70:71], 0, v[130:131]
	s_add_i32 m0, s33, 0x2000
	s_nop 0
	global_load_lds_dwordx4 v[220:221], off
	v_lshl_add_u64 v[220:221], s[40:41], 0, v[136:137]
	s_mov_b32 m0, s25
	s_nop 0
	global_load_lds_dwordx4 v[220:221], off
	s_mov_b32 m0, s37
	s_nop 0
	global_load_lds_dwordx4 v[222:223], off
	s_waitcnt vmcnt(8)
	s_waitcnt lgkmcnt(0)
	s_barrier
; #define PG8_STAGE(bufoff, gbase, voff) do { _Pragma("unroll") for (int _i = 0; _i < 2; ++_i) \
;         __builtin_amdgcn_global_load_lds((const unsigned*)((const char*)(gbase) + (voff)[_i]), (LAS unsigned*)(lds + (bufoff) + ldsw + _i * 8192), 16, 0, 0); } while (0)
; #define PG8_LDA(dst, b, h) do { _Pragma("unroll") for (int m = 0; m < 4; ++m) _Pragma("unroll") for (int k = 0; k < 2; ++k) dst[m][k] = *(const LAS bf16x8*)(lds + PG8_SA(b, h) + aoff + m * 2048 + k * 1024); } while (0)
; #define PG8_LDB(dst, b, h) do { _Pragma("unroll") for (int n = 0; n < 2; ++n) _Pragma("unroll") for (int k = 0; k < 2; ++k) dst[n][k] = *(const LAS bf16x8*)(lds + PG8_SB(b, h) + boff + n * 2048 + k * 1024); } while (0)
; #define PG8_MMA(ai, bj, At, Bt) do { __builtin_amdgcn_s_setprio(1); _Pragma("unroll") for (int m = 0; m < 4; ++m) _Pragma("unroll") for (int n = 0; n < 2; ++n) _Pragma("unroll") for (int k = 0; k < 2; ++k) \
;         acc[ai][bj][m][n] = __builtin_amdgcn_mfma_f32_16x16x32_bf16(Bt[n][k], At[m][k], acc[ai][bj][m][n], 0, 0, 0); __builtin_amdgcn_s_setprio(0); } while (0)
; #define PG8_WAIT_V(n) asm volatile("s_waitcnt vmcnt(" #n ")" ::: "memory")
; #define PG8_WAIT_L(n) asm volatile("s_waitcnt lgkmcnt(" #n ")" ::: "memory")
; #define PG8_BAR __builtin_amdgcn_s_barrier()
; #define PG8_SCHED __builtin_amdgcn_sched_barrier(0)
; template <class Epi>
; __device__ __forceinline__ void gemm_phase(LAS unsigned char* lds, const Gemm g, int G, int c, const Epi& E) {
;     ...
;             PG8_WAIT_V(8); PG8_WAIT_L(0); PG8_BAR; PG8_MMA(1, 0, At, B0); PG8_MMA(1, 1, At, B1); PG8_BAR; PG8_SCHED;
;             PG8_LDB(B0, 1, 0); PG8_LDB(B1, 1, 1); PG8_SCHED; PG8_LDA(At, 1, 0); PG8_STAGE(PG8_SA(0, 1), a2 + hstepA, voffA);
;             PG8_WAIT_V(8); PG8_WAIT_L(0); PG8_BAR; PG8_MMA(0, 0, At, B0); PG8_MMA(0, 1, At, B1); PG8_BAR; PG8_SCHED;
	s_setprio 0
	s_waitcnt lgkmcnt(0)
	v_mfma_f32_16x16x32_bf16 v[62:65], v[152:155], v[184:187], v[62:65]
	v_mfma_f32_16x16x32_bf16 v[58:61], v[160:163], v[184:187], v[58:61]
	v_mfma_f32_16x16x32_bf16 v[42:45], v[160:163], v[192:195], v[42:45]
	v_mfma_f32_16x16x32_bf16 v[46:49], v[152:155], v[192:195], v[46:49]
	v_mfma_f32_16x16x32_bf16 v[30:33], v[152:155], v[200:203], v[30:33]
	v_mfma_f32_16x16x32_bf16 v[26:29], v[160:163], v[200:203], v[26:29]
	v_mfma_f32_16x16x32_bf16 v[10:13], v[160:163], v[208:211], v[10:13]
	v_mfma_f32_16x16x32_bf16 v[14:17], v[152:155], v[208:211], v[14:17]
	v_mfma_f32_16x16x32_bf16 v[62:65], v[156:159], v[188:191], v[62:65]
	v_mfma_f32_16x16x32_bf16 v[58:61], v[164:167], v[188:191], v[58:61]
	v_mfma_f32_16x16x32_bf16 v[42:45], v[164:167], v[196:199], v[42:45]
	v_mfma_f32_16x16x32_bf16 v[46:49], v[156:159], v[196:199], v[46:49]
	v_mfma_f32_16x16x32_bf16 v[30:33], v[156:159], v[204:207], v[30:33]
	v_mfma_f32_16x16x32_bf16 v[26:29], v[164:167], v[204:207], v[26:29]
	v_mfma_f32_16x16x32_bf16 v[10:13], v[164:167], v[212:215], v[10:13]
	v_mfma_f32_16x16x32_bf16 v[14:17], v[156:159], v[212:215], v[14:17]
	s_setprio 2
	s_setprio 0
	v_mfma_f32_16x16x32_bf16 v[54:57], v[168:171], v[184:187], v[54:57]
	v_mfma_f32_16x16x32_bf16 v[50:53], v[176:179], v[184:187], v[50:53]
	v_mfma_f32_16x16x32_bf16 v[34:37], v[176:179], v[192:195], v[34:37]
	v_mfma_f32_16x16x32_bf16 v[38:41], v[168:171], v[192:195], v[38:41]
	v_mfma_f32_16x16x32_bf16 v[22:25], v[168:171], v[200:203], v[22:25]
	v_mfma_f32_16x16x32_bf16 v[18:21], v[176:179], v[200:203], v[18:21]
	v_mfma_f32_16x16x32_bf16 v[2:5], v[176:179], v[208:211], v[2:5]
	v_mfma_f32_16x16x32_bf16 v[6:9], v[168:171], v[208:211], v[6:9]
	v_mfma_f32_16x16x32_bf16 v[54:57], v[172:175], v[188:191], v[54:57]
	v_mfma_f32_16x16x32_bf16 v[50:53], v[180:183], v[188:191], v[50:53]
	v_mfma_f32_16x16x32_bf16 v[34:37], v[180:183], v[196:199], v[34:37]
	v_mfma_f32_16x16x32_bf16 v[38:41], v[172:175], v[196:199], v[38:41]
	v_mfma_f32_16x16x32_bf16 v[22:25], v[172:175], v[204:207], v[22:25]
	v_mfma_f32_16x16x32_bf16 v[18:21], v[180:183], v[204:207], v[18:21]
	v_mfma_f32_16x16x32_bf16 v[2:5], v[180:183], v[212:215], v[2:5]
	v_mfma_f32_16x16x32_bf16 v[6:9], v[172:175], v[212:215], v[6:9]
	s_setprio 2
	s_barrier
	s_add_i32 s33, 0, 0x18000
	s_add_i32 s69, 0, 0x1c000
	v_add_u32_e32 v164, s33, v147
	v_add_u32_e32 v180, s69, v147
	ds_read_b128 v[152:155], v164
	ds_read_b128 v[156:159], v164 offset:1024
	ds_read_b128 v[160:163], v164 offset:2048
	ds_read_b128 v[164:167], v164 offset:3072
	ds_read_b128 v[168:171], v180
	ds_read_b128 v[172:175], v180 offset:1024
	ds_read_b128 v[176:179], v180 offset:2048
	ds_read_b128 v[180:183], v180 offset:3072
	s_add_u32 s40, s40, 0x40000
	s_addc_u32 s41, s41, 0
	s_mov_b32 m0, s47
	v_lshl_add_u64 v[224:225], s[40:41], 0, v[136:137]
	ds_read_b128 v[184:187], v150 offset:32768
	ds_read_b128 v[188:191], v150 offset:33792
	ds_read_b128 v[192:195], v150 offset:34816
	ds_read_b128 v[196:199], v150 offset:35840
	ds_read_b128 v[200:203], v150 offset:36864
	ds_read_b128 v[204:207], v150 offset:37888
	ds_read_b128 v[208:211], v150 offset:38912
	ds_read_b128 v[212:215], v150 offset:39936
	global_load_lds_dwordx4 v[224:225], off
	v_lshl_add_u64 v[224:225], s[40:41], 0, v[132:133]
	s_mov_b32 m0, s48
	s_nop 0
	global_load_lds_dwordx4 v[224:225], off
	s_waitcnt vmcnt(8)
	s_waitcnt lgkmcnt(0)
	s_barrier
	s_setprio 0
	s_waitcnt lgkmcnt(0)
	v_mfma_f32_16x16x32_bf16 v[126:129], v[152:155], v[184:187], v[126:129]
	v_mfma_f32_16x16x32_bf16 v[122:125], v[160:163], v[184:187], v[122:125]
	v_mfma_f32_16x16x32_bf16 v[106:109], v[160:163], v[192:195], v[106:109]
	v_mfma_f32_16x16x32_bf16 v[110:113], v[152:155], v[192:195], v[110:113]
	v_mfma_f32_16x16x32_bf16 v[94:97], v[152:155], v[200:203], v[94:97]
	v_mfma_f32_16x16x32_bf16 v[90:93], v[160:163], v[200:203], v[90:93]
	v_mfma_f32_16x16x32_bf16 v[74:77], v[160:163], v[208:211], v[74:77]
	v_mfma_f32_16x16x32_bf16 v[78:81], v[152:155], v[208:211], v[78:81]
	v_mfma_f32_16x16x32_bf16 v[126:129], v[156:159], v[188:191], v[126:129]
	v_mfma_f32_16x16x32_bf16 v[122:125], v[164:167], v[188:191], v[122:125]
	v_mfma_f32_16x16x32_bf16 v[106:109], v[164:167], v[196:199], v[106:109]
	v_mfma_f32_16x16x32_bf16 v[110:113], v[156:159], v[196:199], v[110:113]
	v_mfma_f32_16x16x32_bf16 v[94:97], v[156:159], v[204:207], v[94:97]
	v_mfma_f32_16x16x32_bf16 v[90:93], v[164:167], v[204:207], v[90:93]
	v_mfma_f32_16x16x32_bf16 v[74:77], v[164:167], v[212:215], v[74:77]
	v_mfma_f32_16x16x32_bf16 v[78:81], v[156:159], v[212:215], v[78:81]
	s_setprio 2
	s_setprio 0
	v_mfma_f32_16x16x32_bf16 v[118:121], v[168:171], v[184:187], v[118:121]
	v_mfma_f32_16x16x32_bf16 v[114:117], v[176:179], v[184:187], v[114:117]
	v_mfma_f32_16x16x32_bf16 v[98:101], v[176:179], v[192:195], v[98:101]
	v_mfma_f32_16x16x32_bf16 v[102:105], v[168:171], v[192:195], v[102:105]
	v_mfma_f32_16x16x32_bf16 v[86:89], v[168:171], v[200:203], v[86:89]
	v_mfma_f32_16x16x32_bf16 v[82:85], v[176:179], v[200:203], v[82:85]
	v_mfma_f32_16x16x32_bf16 v[66:69], v[176:179], v[208:211], v[66:69]
	v_mfma_f32_16x16x32_bf16 v[70:73], v[168:171], v[208:211], v[70:73]
	v_mfma_f32_16x16x32_bf16 v[118:121], v[172:175], v[188:191], v[118:121]
	v_mfma_f32_16x16x32_bf16 v[114:117], v[180:183], v[188:191], v[114:117]
	v_mfma_f32_16x16x32_bf16 v[98:101], v[180:183], v[196:199], v[98:101]
	v_mfma_f32_16x16x32_bf16 v[102:105], v[172:175], v[196:199], v[102:105]
	v_mfma_f32_16x16x32_bf16 v[86:89], v[172:175], v[204:207], v[86:89]
	v_mfma_f32_16x16x32_bf16 v[82:85], v[180:183], v[204:207], v[82:85]
	v_mfma_f32_16x16x32_bf16 v[66:69], v[180:183], v[212:215], v[66:69]
	v_mfma_f32_16x16x32_bf16 v[70:73], v[172:175], v[212:215], v[70:73]
	s_setprio 2
	s_barrier
; #define PG8_STAGE(bufoff, gbase, voff) do { _Pragma("unroll") for (int _i = 0; _i < 2; ++_i) \
;         __builtin_amdgcn_global_load_lds((const unsigned*)((const char*)(gbase) + (voff)[_i]), (LAS unsigned*)(lds + (bufoff) + ldsw + _i * 8192), 16, 0, 0); } while (0)
; #define PG8_LDA(dst, b, h) do { _Pragma("unroll") for (int m = 0; m < 4; ++m) _Pragma("unroll") for (int k = 0; k < 2; ++k) dst[m][k] = *(const LAS bf16x8*)(lds + PG8_SA(b, h) + aoff + m * 2048 + k * 1024); } while (0)
; #define PG8_MMA(ai, bj, At, Bt) do { __builtin_amdgcn_s_setprio(1); _Pragma("unroll") for (int m = 0; m < 4; ++m) _Pragma("unroll") for (int n = 0; n < 2; ++n) _Pragma("unroll") for (int k = 0; k < 2; ++k) \
;         acc[ai][bj][m][n] = __builtin_amdgcn_mfma_f32_16x16x32_bf16(Bt[n][k], At[m][k], acc[ai][bj][m][n], 0, 0, 0); __builtin_amdgcn_s_setprio(0); } while (0)
; #define PG8_WAIT_V(n) asm volatile("s_waitcnt vmcnt(" #n ")" ::: "memory")
; #define PG8_WAIT_L(n) asm volatile("s_waitcnt lgkmcnt(" #n ")" ::: "memory")
; #define PG8_BAR __builtin_amdgcn_s_barrier()
; #define PG8_SCHED __builtin_amdgcn_sched_barrier(0)
; template <class Epi>
; __device__ __forceinline__ void gemm_phase(LAS unsigned char* lds, const Gemm g, int G, int c, const Epi& E) {
;     ...
;             PG8_LDA(At, 1, 1); PG8_STAGE(PG8_SB(1, 0), b3, voffB); PG8_STAGE(PG8_SB(1, 1), b3 + hstepB, voffB); PG8_STAGE(PG8_SA(1, 0), a3, voffA);
;             PG8_WAIT_V(8); PG8_WAIT_L(0); PG8_BAR; PG8_MMA(1, 0, At, B0); PG8_MMA(1, 1, At, B1); PG8_BAR; PG8_SCHED;
;         }
;         if (wr == 0) PG8_BAR;
	s_add_i32 s33, s33, s46
	v_lshl_add_u64 v[216:217], v[216:217], 0, s[12:13]
	s_mov_b32 m0, s33
	ds_read_b128 v[184:187], v150 offset:49152
	ds_read_b128 v[188:191], v150 offset:50176
	ds_read_b128 v[192:195], v150 offset:51200
	ds_read_b128 v[196:199], v150 offset:52224
	ds_read_b128 v[200:203], v150 offset:53248
	ds_read_b128 v[204:207], v150 offset:54272
	ds_read_b128 v[208:211], v150 offset:55296
	ds_read_b128 v[212:215], v150 offset:56320
	global_load_lds_dwordx4 v[216:217], off
	s_add_i32 m0, s33, 0x2000
	s_add_u32 s38, s38, 0x40080
	v_lshl_add_u64 v[216:217], v[218:219], 0, s[12:13]
	s_addc_u32 s39, s39, 0
	s_add_i32 s33, s69, s46
	global_load_lds_dwordx4 v[216:217], off
	v_lshl_add_u64 v[216:217], s[38:39], 0, v[134:135]
	s_mov_b32 m0, s33
	s_nop 0
	global_load_lds_dwordx4 v[216:217], off
	v_lshl_add_u64 v[216:217], s[38:39], 0, v[130:131]
	s_add_i32 m0, s33, 0x2000
	s_nop 0
	global_load_lds_dwordx4 v[216:217], off
	v_lshl_add_u64 v[216:217], v[220:221], 0, s[12:13]
	s_mov_b32 m0, s53
	s_nop 0
	global_load_lds_dwordx4 v[216:217], off
	v_lshl_add_u64 v[216:217], v[222:223], 0, s[12:13]
	s_mov_b32 m0, s54
	s_nop 0
	global_load_lds_dwordx4 v[216:217], off
	s_waitcnt vmcnt(8)
	s_waitcnt lgkmcnt(0)
	s_barrier
	s_setprio 0
	s_waitcnt lgkmcnt(0)
	v_mfma_f32_16x16x32_bf16 v[62:65], v[152:155], v[184:187], v[62:65]
	v_mfma_f32_16x16x32_bf16 v[58:61], v[160:163], v[184:187], v[58:61]
	v_mfma_f32_16x16x32_bf16 v[42:45], v[160:163], v[192:195], v[42:45]
	v_mfma_f32_16x16x32_bf16 v[46:49], v[152:155], v[192:195], v[46:49]
	v_mfma_f32_16x16x32_bf16 v[30:33], v[152:155], v[200:203], v[30:33]
	v_mfma_f32_16x16x32_bf16 v[26:29], v[160:163], v[200:203], v[26:29]
	v_mfma_f32_16x16x32_bf16 v[10:13], v[160:163], v[208:211], v[10:13]
	v_mfma_f32_16x16x32_bf16 v[14:17], v[152:155], v[208:211], v[14:17]
	v_mfma_f32_16x16x32_bf16 v[62:65], v[156:159], v[188:191], v[62:65]
	v_mfma_f32_16x16x32_bf16 v[58:61], v[164:167], v[188:191], v[58:61]
	v_mfma_f32_16x16x32_bf16 v[42:45], v[164:167], v[196:199], v[42:45]
	v_mfma_f32_16x16x32_bf16 v[46:49], v[156:159], v[196:199], v[46:49]
	v_mfma_f32_16x16x32_bf16 v[30:33], v[156:159], v[204:207], v[30:33]
	v_mfma_f32_16x16x32_bf16 v[26:29], v[164:167], v[204:207], v[26:29]
	v_mfma_f32_16x16x32_bf16 v[10:13], v[164:167], v[212:215], v[10:13]
	v_mfma_f32_16x16x32_bf16 v[14:17], v[156:159], v[212:215], v[14:17]
	s_setprio 2
	s_setprio 0
	v_mfma_f32_16x16x32_bf16 v[54:57], v[168:171], v[184:187], v[54:57]
	v_mfma_f32_16x16x32_bf16 v[50:53], v[176:179], v[184:187], v[50:53]
	v_mfma_f32_16x16x32_bf16 v[34:37], v[176:179], v[192:195], v[34:37]
	v_mfma_f32_16x16x32_bf16 v[38:41], v[168:171], v[192:195], v[38:41]
	v_mfma_f32_16x16x32_bf16 v[22:25], v[168:171], v[200:203], v[22:25]
	v_mfma_f32_16x16x32_bf16 v[18:21], v[176:179], v[200:203], v[18:21]
	v_mfma_f32_16x16x32_bf16 v[2:5], v[176:179], v[208:211], v[2:5]
	v_mfma_f32_16x16x32_bf16 v[6:9], v[168:171], v[208:211], v[6:9]
	v_mfma_f32_16x16x32_bf16 v[54:57], v[172:175], v[188:191], v[54:57]
	v_mfma_f32_16x16x32_bf16 v[50:53], v[180:183], v[188:191], v[50:53]
	v_mfma_f32_16x16x32_bf16 v[34:37], v[180:183], v[196:199], v[34:37]
	v_mfma_f32_16x16x32_bf16 v[38:41], v[172:175], v[196:199], v[38:41]
	v_mfma_f32_16x16x32_bf16 v[22:25], v[172:175], v[204:207], v[22:25]
	v_mfma_f32_16x16x32_bf16 v[18:21], v[180:183], v[204:207], v[18:21]
	v_mfma_f32_16x16x32_bf16 v[2:5], v[180:183], v[212:215], v[2:5]
	v_mfma_f32_16x16x32_bf16 v[6:9], v[172:175], v[212:215], v[6:9]
	s_setprio 2
	s_barrier
	s_add_i32 s68, s68, 2
	s_add_u32 s4, s4, 0x100
	s_addc_u32 s5, s5, 0
	s_add_u32 s66, s66, 0x100
	s_addc_u32 s67, s67, 0
	s_cmp_gt_u32 s68, 13
	s_cbranch_scc0 .LBB0_2084
	s_and_b64 vcc, exec, s[14:15]
	s_cbranch_vccz .LBB0_2087
	s_barrier

; #define PG8_STAGE(bufoff, gbase, voff) do { _Pragma("unroll") for (int _i = 0; _i < 2; ++_i) \
;         __builtin_amdgcn_global_load_lds((const unsigned*)((const char*)(gbase) + (voff)[_i]), (LAS unsigned*)(lds + (bufoff) + ldsw + _i * 8192), 16, 0, 0); } while (0)
; #define PG8_LDA(dst, b, h) do { _Pragma("unroll") for (int m = 0; m < 4; ++m) _Pragma("unroll") for (int k = 0; k < 2; ++k) dst[m][k] = *(const LAS bf16x8*)(lds + PG8_SA(b, h) + aoff + m * 2048 + k * 1024); } while (0)
; #define PG8_LDB(dst, b, h) do { _Pragma("unroll") for (int n = 0; n < 2; ++n) _Pragma("unroll") for (int k = 0; k < 2; ++k) dst[n][k] = *(const LAS bf16x8*)(lds + PG8_SB(b, h) + boff + n * 2048 + k * 1024); } while (0)
; #define PG8_MMA(ai, bj, At, Bt) do { __builtin_amdgcn_s_setprio(1); _Pragma("unroll") for (int m = 0; m < 4; ++m) _Pragma("unroll") for (int n = 0; n < 2; ++n) _Pragma("unroll") for (int k = 0; k < 2; ++k) \
;         acc[ai][bj][m][n] = __builtin_amdgcn_mfma_f32_16x16x32_bf16(Bt[n][k], At[m][k], acc[ai][bj][m][n], 0, 0, 0); __builtin_amdgcn_s_setprio(0); } while (0)
; #define PG8_WAIT_V(n) asm volatile("s_waitcnt vmcnt(" #n ")" ::: "memory")
; #define PG8_WAIT_L(n) asm volatile("s_waitcnt lgkmcnt(" #n ")" ::: "memory")
; #define PG8_BAR __builtin_amdgcn_s_barrier()
; #define PG8_SCHED __builtin_amdgcn_sched_barrier(0)
; template <class Epi>
; __device__ __forceinline__ void gemm_phase(LAS unsigned char* lds, const Gemm g, int G, int c, const Epi& E) {
;     ...
;         for (int t = 0; t < nt; t += 2) {
;             const bool last = (t == nt - 2);
;             const char* a1 = cA + (size_t)(t + 1) * kstep;
;             const char* a2 = last ? nA : cA + (size_t)(t + 2) * kstep; const char* b2 = last ? nB : cB + (size_t)(t + 2) * kstep;
;             const char* a3 = a2 + kstep; const char* b3 = b2 + kstep;
;             PG8_LDB(B0, 0, 0); PG8_LDB(B1, 0, 1); PG8_SCHED; PG8_LDA(At, 0, 0); PG8_STAGE(PG8_SA(1, 1), a1 + hstepA, voffA);
;             PG8_WAIT_V(8); PG8_WAIT_L(0); PG8_BAR; PG8_MMA(0, 0, At, B0); PG8_MMA(0, 1, At, B1); PG8_BAR; PG8_SCHED;
;             PG8_LDA(At, 0, 1); PG8_STAGE(PG8_SB(0, 0), b2, voffB); PG8_STAGE(PG8_SB(0, 1), b2 + hstepB, voffB); PG8_STAGE(PG8_SA(0, 0), a2, voffA);
.LBB0_2169:
	ds_read_b128 v[106:109], v168
	ds_read_b128 v[110:113], v168 offset:1024
	ds_read_b128 v[114:117], v168 offset:2048
	ds_read_b128 v[118:121], v168 offset:3072
	ds_read_b128 v[162:165], v169
	ds_read_b128 v[172:175], v169 offset:1024
	ds_read_b128 v[176:179], v169 offset:2048
	ds_read_b128 v[180:183], v169 offset:3072
	s_add_u32 s20, s18, 0x100
	s_addc_u32 s21, s19, 0
	s_cmp_eq_u32 s62, 40
	s_cselect_b32 s25, s5, s21
	s_cselect_b32 s24, s4, s20
	s_cselect_b32 s23, s17, s61
	s_cselect_b32 s22, s16, s60
	v_lshl_add_u64 v[216:217], s[18:19], 0, v[154:155]
	s_add_i32 m0, s40, 0xc000
	ds_read_b128 v[184:187], v170
	ds_read_b128 v[188:191], v170 offset:1024
	ds_read_b128 v[192:195], v170 offset:2048
	ds_read_b128 v[196:199], v170 offset:3072
	ds_read_b128 v[200:203], v170 offset:4096
	ds_read_b128 v[204:207], v170 offset:5120
	ds_read_b128 v[208:211], v170 offset:6144
	ds_read_b128 v[212:215], v170 offset:7168
	global_load_lds_dwordx4 v[216:217], off
	v_lshl_add_u64 v[216:217], s[18:19], 0, v[156:157]
	s_add_i32 m0, s40, 0xe000
	s_nop 0
	global_load_lds_dwordx4 v[216:217], off
	s_waitcnt vmcnt(8)
	s_waitcnt lgkmcnt(0)
	s_barrier
	s_setprio 0
	s_waitcnt lgkmcnt(0)
	v_mfma_f32_16x16x32_bf16 v[142:145], v[106:109], v[184:187], v[142:145]
	v_mfma_f32_16x16x32_bf16 v[138:141], v[114:117], v[184:187], v[138:141]
	v_mfma_f32_16x16x32_bf16 v[122:125], v[114:117], v[192:195], v[122:125]
	v_mfma_f32_16x16x32_bf16 v[126:129], v[106:109], v[192:195], v[126:129]
	v_mfma_f32_16x16x32_bf16 v[94:97], v[106:109], v[200:203], v[94:97]
	v_mfma_f32_16x16x32_bf16 v[90:93], v[114:117], v[200:203], v[90:93]
	v_mfma_f32_16x16x32_bf16 v[74:77], v[114:117], v[208:211], v[74:77]
	v_mfma_f32_16x16x32_bf16 v[78:81], v[106:109], v[208:211], v[78:81]
	v_mfma_f32_16x16x32_bf16 v[142:145], v[110:113], v[188:191], v[142:145]
	v_mfma_f32_16x16x32_bf16 v[138:141], v[118:121], v[188:191], v[138:141]
	v_mfma_f32_16x16x32_bf16 v[122:125], v[118:121], v[196:199], v[122:125]
	v_mfma_f32_16x16x32_bf16 v[126:129], v[110:113], v[196:199], v[126:129]
	v_mfma_f32_16x16x32_bf16 v[94:97], v[110:113], v[204:207], v[94:97]
	v_mfma_f32_16x16x32_bf16 v[90:93], v[118:121], v[204:207], v[90:93]
	v_mfma_f32_16x16x32_bf16 v[74:77], v[118:121], v[212:215], v[74:77]
	v_mfma_f32_16x16x32_bf16 v[78:81], v[110:113], v[212:215], v[78:81]
	s_setprio 2
	s_setprio 0
	v_mfma_f32_16x16x32_bf16 v[134:137], v[162:165], v[184:187], v[134:137]
	v_mfma_f32_16x16x32_bf16 v[130:133], v[176:179], v[184:187], v[130:133]
	v_mfma_f32_16x16x32_bf16 v[98:101], v[176:179], v[192:195], v[98:101]
	v_mfma_f32_16x16x32_bf16 v[102:105], v[162:165], v[192:195], v[102:105]
	v_mfma_f32_16x16x32_bf16 v[86:89], v[162:165], v[200:203], v[86:89]
	v_mfma_f32_16x16x32_bf16 v[82:85], v[176:179], v[200:203], v[82:85]
	v_mfma_f32_16x16x32_bf16 v[66:69], v[176:179], v[208:211], v[66:69]
	v_mfma_f32_16x16x32_bf16 v[70:73], v[162:165], v[208:211], v[70:73]
	v_mfma_f32_16x16x32_bf16 v[134:137], v[172:175], v[188:191], v[134:137]
	v_mfma_f32_16x16x32_bf16 v[130:133], v[180:183], v[188:191], v[130:133]
	v_mfma_f32_16x16x32_bf16 v[98:101], v[180:183], v[196:199], v[98:101]
	v_mfma_f32_16x16x32_bf16 v[102:105], v[172:175], v[196:199], v[102:105]
	v_mfma_f32_16x16x32_bf16 v[86:89], v[172:175], v[204:207], v[86:89]
	v_mfma_f32_16x16x32_bf16 v[82:85], v[180:183], v[204:207], v[82:85]
	v_mfma_f32_16x16x32_bf16 v[66:69], v[180:183], v[212:215], v[66:69]
	v_mfma_f32_16x16x32_bf16 v[70:73], v[172:175], v[212:215], v[70:73]
	s_setprio 2
	s_barrier
	s_add_i32 s18, s52, s38
	v_lshl_add_u64 v[216:217], s[22:23], 0, v[150:151]
	s_mov_b32 m0, s18
	ds_read_b128 v[184:187], v170 offset:16384
	ds_read_b128 v[188:191], v170 offset:17408
	ds_read_b128 v[192:195], v170 offset:18432
	ds_read_b128 v[196:199], v170 offset:19456
	ds_read_b128 v[200:203], v170 offset:20480
	ds_read_b128 v[204:207], v170 offset:21504
	ds_read_b128 v[208:211], v170 offset:22528
	ds_read_b128 v[212:215], v170 offset:23552
	global_load_lds_dwordx4 v[216:217], off
	s_add_i32 m0, s18, 0x2000
	s_add_u32 s18, s22, 0xb0000
	v_lshl_add_u64 v[218:219], s[22:23], 0, v[146:147]
	s_addc_u32 s19, s23, 0
	s_add_i32 s33, s53, s38
	global_load_lds_dwordx4 v[218:219], off
	v_lshl_add_u64 v[220:221], s[18:19], 0, v[150:151]
	s_mov_b32 m0, s33
	v_lshl_add_u64 v[222:223], s[24:25], 0, v[148:149]
	global_load_lds_dwordx4 v[220:221], off
	v_lshl_add_u64 v[220:221], s[18:19], 0, v[146:147]
	s_add_i32 m0, s33, 0x2000
	s_nop 0
	global_load_lds_dwordx4 v[220:221], off
	v_lshl_add_u64 v[220:221], s[24:25], 0, v[152:153]
	s_mov_b32 m0, s40
	s_nop 0
	global_load_lds_dwordx4 v[220:221], off
	s_mov_b32 m0, s41
	s_nop 0
	global_load_lds_dwordx4 v[222:223], off
	s_waitcnt vmcnt(8)
	s_waitcnt lgkmcnt(0)
	s_barrier
; #define PG8_STAGE(bufoff, gbase, voff) do { _Pragma("unroll") for (int _i = 0; _i < 2; ++_i) \
;         __builtin_amdgcn_global_load_lds((const unsigned*)((const char*)(gbase) + (voff)[_i]), (LAS unsigned*)(lds + (bufoff) + ldsw + _i * 8192), 16, 0, 0); } while (0)
; #define PG8_LDA(dst, b, h) do { _Pragma("unroll") for (int m = 0; m < 4; ++m) _Pragma("unroll") for (int k = 0; k < 2; ++k) dst[m][k] = *(const LAS bf16x8*)(lds + PG8_SA(b, h) + aoff + m * 2048 + k * 1024); } while (0)
; #define PG8_LDB(dst, b, h) do { _Pragma("unroll") for (int n = 0; n < 2; ++n) _Pragma("unroll") for (int k = 0; k < 2; ++k) dst[n][k] = *(const LAS bf16x8*)(lds + PG8_SB(b, h) + boff + n * 2048 + k * 1024); } while (0)
; #define PG8_MMA(ai, bj, At, Bt) do { __builtin_amdgcn_s_setprio(1); _Pragma("unroll") for (int m = 0; m < 4; ++m) _Pragma("unroll") for (int n = 0; n < 2; ++n) _Pragma("unroll") for (int k = 0; k < 2; ++k) \
;         acc[ai][bj][m][n] = __builtin_amdgcn_mfma_f32_16x16x32_bf16(Bt[n][k], At[m][k], acc[ai][bj][m][n], 0, 0, 0); __builtin_amdgcn_s_setprio(0); } while (0)
; #define PG8_WAIT_V(n) asm volatile("s_waitcnt vmcnt(" #n ")" ::: "memory")
; #define PG8_WAIT_L(n) asm volatile("s_waitcnt lgkmcnt(" #n ")" ::: "memory")
; #define PG8_BAR __builtin_amdgcn_s_barrier()
; #define PG8_SCHED __builtin_amdgcn_sched_barrier(0)
; template <class Epi>
; __device__ __forceinline__ void gemm_phase(LAS unsigned char* lds, const Gemm g, int G, int c, const Epi& E) {
;     ...
;             PG8_WAIT_V(8); PG8_WAIT_L(0); PG8_BAR; PG8_MMA(1, 0, At, B0); PG8_MMA(1, 1, At, B1); PG8_BAR; PG8_SCHED;
;             PG8_LDB(B0, 1, 0); PG8_LDB(B1, 1, 1); PG8_SCHED; PG8_LDA(At, 1, 0); PG8_STAGE(PG8_SA(0, 1), a2 + hstepA, voffA);
;             PG8_WAIT_V(8); PG8_WAIT_L(0); PG8_BAR; PG8_MMA(0, 0, At, B0); PG8_MMA(0, 1, At, B1); PG8_BAR; PG8_SCHED;
	s_setprio 0
	s_waitcnt lgkmcnt(0)
	v_mfma_f32_16x16x32_bf16 v[62:65], v[106:109], v[184:187], v[62:65]
	v_mfma_f32_16x16x32_bf16 v[58:61], v[114:117], v[184:187], v[58:61]
	v_mfma_f32_16x16x32_bf16 v[42:45], v[114:117], v[192:195], v[42:45]
	v_mfma_f32_16x16x32_bf16 v[46:49], v[106:109], v[192:195], v[46:49]
	v_mfma_f32_16x16x32_bf16 v[30:33], v[106:109], v[200:203], v[30:33]
	v_mfma_f32_16x16x32_bf16 v[26:29], v[114:117], v[200:203], v[26:29]
	v_mfma_f32_16x16x32_bf16 v[10:13], v[114:117], v[208:211], v[10:13]
	v_mfma_f32_16x16x32_bf16 v[14:17], v[106:109], v[208:211], v[14:17]
	v_mfma_f32_16x16x32_bf16 v[62:65], v[110:113], v[188:191], v[62:65]
	v_mfma_f32_16x16x32_bf16 v[58:61], v[118:121], v[188:191], v[58:61]
	v_mfma_f32_16x16x32_bf16 v[42:45], v[118:121], v[196:199], v[42:45]
	v_mfma_f32_16x16x32_bf16 v[46:49], v[110:113], v[196:199], v[46:49]
	v_mfma_f32_16x16x32_bf16 v[30:33], v[110:113], v[204:207], v[30:33]
	v_mfma_f32_16x16x32_bf16 v[26:29], v[118:121], v[204:207], v[26:29]
	v_mfma_f32_16x16x32_bf16 v[10:13], v[118:121], v[212:215], v[10:13]
	v_mfma_f32_16x16x32_bf16 v[14:17], v[110:113], v[212:215], v[14:17]
	s_setprio 2
	s_setprio 0
	v_mfma_f32_16x16x32_bf16 v[54:57], v[162:165], v[184:187], v[54:57]
	v_mfma_f32_16x16x32_bf16 v[50:53], v[176:179], v[184:187], v[50:53]
	v_mfma_f32_16x16x32_bf16 v[34:37], v[176:179], v[192:195], v[34:37]
	v_mfma_f32_16x16x32_bf16 v[38:41], v[162:165], v[192:195], v[38:41]
	v_mfma_f32_16x16x32_bf16 v[22:25], v[162:165], v[200:203], v[22:25]
	v_mfma_f32_16x16x32_bf16 v[18:21], v[176:179], v[200:203], v[18:21]
	v_mfma_f32_16x16x32_bf16 v[2:5], v[176:179], v[208:211], v[2:5]
	v_mfma_f32_16x16x32_bf16 v[6:9], v[162:165], v[208:211], v[6:9]
	v_mfma_f32_16x16x32_bf16 v[54:57], v[172:175], v[188:191], v[54:57]
	v_mfma_f32_16x16x32_bf16 v[50:53], v[180:183], v[188:191], v[50:53]
	v_mfma_f32_16x16x32_bf16 v[34:37], v[180:183], v[196:199], v[34:37]
	v_mfma_f32_16x16x32_bf16 v[38:41], v[172:175], v[196:199], v[38:41]
	v_mfma_f32_16x16x32_bf16 v[22:25], v[172:175], v[204:207], v[22:25]
	v_mfma_f32_16x16x32_bf16 v[18:21], v[180:183], v[204:207], v[18:21]
	v_mfma_f32_16x16x32_bf16 v[2:5], v[180:183], v[212:215], v[2:5]
	v_mfma_f32_16x16x32_bf16 v[6:9], v[172:175], v[212:215], v[6:9]
	s_setprio 2
	s_barrier
	s_add_i32 s33, 0, 0x18000
	s_add_i32 s63, 0, 0x1c000
	v_add_u32_e32 v118, s33, v167
	v_add_u32_e32 v171, s63, v167
	ds_read_b128 v[106:109], v118
	ds_read_b128 v[110:113], v118 offset:1024
	ds_read_b128 v[114:117], v118 offset:2048
	ds_read_b128 v[118:121], v118 offset:3072
	ds_read_b128 v[162:165], v171
	ds_read_b128 v[172:175], v171 offset:1024
	ds_read_b128 v[176:179], v171 offset:2048
	ds_read_b128 v[180:183], v171 offset:3072
	s_add_u32 s18, s24, 0xb0000
	s_addc_u32 s19, s25, 0
	s_mov_b32 m0, s42
	v_lshl_add_u64 v[224:225], s[18:19], 0, v[152:153]
	ds_read_b128 v[184:187], v170 offset:32768
	ds_read_b128 v[188:191], v170 offset:33792
	ds_read_b128 v[192:195], v170 offset:34816
	ds_read_b128 v[196:199], v170 offset:35840
	ds_read_b128 v[200:203], v170 offset:36864
	ds_read_b128 v[204:207], v170 offset:37888
	ds_read_b128 v[208:211], v170 offset:38912
	ds_read_b128 v[212:215], v170 offset:39936
	global_load_lds_dwordx4 v[224:225], off
	v_lshl_add_u64 v[224:225], s[18:19], 0, v[148:149]
	s_mov_b32 m0, s43
	s_nop 0
	global_load_lds_dwordx4 v[224:225], off
	s_waitcnt vmcnt(8)
	s_waitcnt lgkmcnt(0)
	s_barrier
	s_setprio 0
	s_waitcnt lgkmcnt(0)
	v_mfma_f32_16x16x32_bf16 v[142:145], v[106:109], v[184:187], v[142:145]
	v_mfma_f32_16x16x32_bf16 v[138:141], v[114:117], v[184:187], v[138:141]
	v_mfma_f32_16x16x32_bf16 v[122:125], v[114:117], v[192:195], v[122:125]
	v_mfma_f32_16x16x32_bf16 v[126:129], v[106:109], v[192:195], v[126:129]
	v_mfma_f32_16x16x32_bf16 v[94:97], v[106:109], v[200:203], v[94:97]
	v_mfma_f32_16x16x32_bf16 v[90:93], v[114:117], v[200:203], v[90:93]
	v_mfma_f32_16x16x32_bf16 v[74:77], v[114:117], v[208:211], v[74:77]
	v_mfma_f32_16x16x32_bf16 v[78:81], v[106:109], v[208:211], v[78:81]
	v_mfma_f32_16x16x32_bf16 v[142:145], v[110:113], v[188:191], v[142:145]
	v_mfma_f32_16x16x32_bf16 v[138:141], v[118:121], v[188:191], v[138:141]
	v_mfma_f32_16x16x32_bf16 v[122:125], v[118:121], v[196:199], v[122:125]
	v_mfma_f32_16x16x32_bf16 v[126:129], v[110:113], v[196:199], v[126:129]
	v_mfma_f32_16x16x32_bf16 v[94:97], v[110:113], v[204:207], v[94:97]
	v_mfma_f32_16x16x32_bf16 v[90:93], v[118:121], v[204:207], v[90:93]
	v_mfma_f32_16x16x32_bf16 v[74:77], v[118:121], v[212:215], v[74:77]
	v_mfma_f32_16x16x32_bf16 v[78:81], v[110:113], v[212:215], v[78:81]
	s_setprio 2
	s_setprio 0
	v_mfma_f32_16x16x32_bf16 v[134:137], v[162:165], v[184:187], v[134:137]
	v_mfma_f32_16x16x32_bf16 v[130:133], v[176:179], v[184:187], v[130:133]
	v_mfma_f32_16x16x32_bf16 v[98:101], v[176:179], v[192:195], v[98:101]
	v_mfma_f32_16x16x32_bf16 v[102:105], v[162:165], v[192:195], v[102:105]
	v_mfma_f32_16x16x32_bf16 v[86:89], v[162:165], v[200:203], v[86:89]
	v_mfma_f32_16x16x32_bf16 v[82:85], v[176:179], v[200:203], v[82:85]
	v_mfma_f32_16x16x32_bf16 v[66:69], v[176:179], v[208:211], v[66:69]
	v_mfma_f32_16x16x32_bf16 v[70:73], v[162:165], v[208:211], v[70:73]
	v_mfma_f32_16x16x32_bf16 v[134:137], v[172:175], v[188:191], v[134:137]
	v_mfma_f32_16x16x32_bf16 v[130:133], v[180:183], v[188:191], v[130:133]
	v_mfma_f32_16x16x32_bf16 v[98:101], v[180:183], v[196:199], v[98:101]
	v_mfma_f32_16x16x32_bf16 v[102:105], v[172:175], v[196:199], v[102:105]
	v_mfma_f32_16x16x32_bf16 v[86:89], v[172:175], v[204:207], v[86:89]
	v_mfma_f32_16x16x32_bf16 v[82:85], v[180:183], v[204:207], v[82:85]
	v_mfma_f32_16x16x32_bf16 v[66:69], v[180:183], v[212:215], v[66:69]
	v_mfma_f32_16x16x32_bf16 v[70:73], v[172:175], v[212:215], v[70:73]
	s_setprio 2
	s_barrier
; #define PG8_STAGE(bufoff, gbase, voff) do { _Pragma("unroll") for (int _i = 0; _i < 2; ++_i) \
;         __builtin_amdgcn_global_load_lds((const unsigned*)((const char*)(gbase) + (voff)[_i]), (LAS unsigned*)(lds + (bufoff) + ldsw + _i * 8192), 16, 0, 0); } while (0)
; #define PG8_LDA(dst, b, h) do { _Pragma("unroll") for (int m = 0; m < 4; ++m) _Pragma("unroll") for (int k = 0; k < 2; ++k) dst[m][k] = *(const LAS bf16x8*)(lds + PG8_SA(b, h) + aoff + m * 2048 + k * 1024); } while (0)
; #define PG8_MMA(ai, bj, At, Bt) do { __builtin_amdgcn_s_setprio(1); _Pragma("unroll") for (int m = 0; m < 4; ++m) _Pragma("unroll") for (int n = 0; n < 2; ++n) _Pragma("unroll") for (int k = 0; k < 2; ++k) \
;         acc[ai][bj][m][n] = __builtin_amdgcn_mfma_f32_16x16x32_bf16(Bt[n][k], At[m][k], acc[ai][bj][m][n], 0, 0, 0); __builtin_amdgcn_s_setprio(0); } while (0)
; #define PG8_WAIT_V(n) asm volatile("s_waitcnt vmcnt(" #n ")" ::: "memory")
; #define PG8_WAIT_L(n) asm volatile("s_waitcnt lgkmcnt(" #n ")" ::: "memory")
; #define PG8_BAR __builtin_amdgcn_s_barrier()
; #define PG8_SCHED __builtin_amdgcn_sched_barrier(0)
; template <class Epi>
; __device__ __forceinline__ void gemm_phase(LAS unsigned char* lds, const Gemm g, int G, int c, const Epi& E) {
;     ...
;             PG8_LDA(At, 1, 1); PG8_STAGE(PG8_SB(1, 0), b3, voffB); PG8_STAGE(PG8_SB(1, 1), b3 + hstepB, voffB); PG8_STAGE(PG8_SA(1, 0), a3, voffA);
;             PG8_WAIT_V(8); PG8_WAIT_L(0); PG8_BAR; PG8_MMA(1, 0, At, B0); PG8_MMA(1, 1, At, B1); PG8_BAR; PG8_SCHED;
;         }
;         if (wr == 0) PG8_BAR;
	s_add_i32 s18, s33, s38
	v_lshl_add_u64 v[216:217], v[216:217], 0, s[12:13]
	s_mov_b32 m0, s18
	ds_read_b128 v[184:187], v170 offset:49152
	ds_read_b128 v[188:191], v170 offset:50176
	ds_read_b128 v[192:195], v170 offset:51200
	ds_read_b128 v[196:199], v170 offset:52224
	ds_read_b128 v[200:203], v170 offset:53248
	ds_read_b128 v[204:207], v170 offset:54272
	ds_read_b128 v[208:211], v170 offset:55296
	ds_read_b128 v[212:215], v170 offset:56320
	global_load_lds_dwordx4 v[216:217], off
	s_add_i32 m0, s18, 0x2000
	s_add_u32 s18, s22, 0xb0080
	v_lshl_add_u64 v[216:217], v[218:219], 0, s[12:13]
	s_addc_u32 s19, s23, 0
	s_add_i32 s22, s63, s38
	global_load_lds_dwordx4 v[216:217], off
	v_lshl_add_u64 v[216:217], s[18:19], 0, v[150:151]
	s_mov_b32 m0, s22
	s_nop 0
	global_load_lds_dwordx4 v[216:217], off
	v_lshl_add_u64 v[216:217], s[18:19], 0, v[146:147]
	s_add_i32 m0, s22, 0x2000
	s_nop 0
	global_load_lds_dwordx4 v[216:217], off
	v_lshl_add_u64 v[216:217], v[220:221], 0, s[12:13]
	s_mov_b32 m0, s49
	s_nop 0
	global_load_lds_dwordx4 v[216:217], off
	v_lshl_add_u64 v[216:217], v[222:223], 0, s[12:13]
	s_mov_b32 m0, s50
	s_nop 0
	global_load_lds_dwordx4 v[216:217], off
	s_waitcnt vmcnt(8)
	s_waitcnt lgkmcnt(0)
	s_barrier
	s_setprio 0
	s_waitcnt lgkmcnt(0)
	v_mfma_f32_16x16x32_bf16 v[62:65], v[106:109], v[184:187], v[62:65]
	v_mfma_f32_16x16x32_bf16 v[58:61], v[114:117], v[184:187], v[58:61]
	v_mfma_f32_16x16x32_bf16 v[42:45], v[114:117], v[192:195], v[42:45]
	v_mfma_f32_16x16x32_bf16 v[46:49], v[106:109], v[192:195], v[46:49]
	v_mfma_f32_16x16x32_bf16 v[30:33], v[106:109], v[200:203], v[30:33]
	v_mfma_f32_16x16x32_bf16 v[26:29], v[114:117], v[200:203], v[26:29]
	v_mfma_f32_16x16x32_bf16 v[10:13], v[114:117], v[208:211], v[10:13]
	v_mfma_f32_16x16x32_bf16 v[14:17], v[106:109], v[208:211], v[14:17]
	v_mfma_f32_16x16x32_bf16 v[62:65], v[110:113], v[188:191], v[62:65]
	v_mfma_f32_16x16x32_bf16 v[58:61], v[118:121], v[188:191], v[58:61]
	v_mfma_f32_16x16x32_bf16 v[42:45], v[118:121], v[196:199], v[42:45]
	v_mfma_f32_16x16x32_bf16 v[46:49], v[110:113], v[196:199], v[46:49]
	v_mfma_f32_16x16x32_bf16 v[30:33], v[110:113], v[204:207], v[30:33]
	v_mfma_f32_16x16x32_bf16 v[26:29], v[118:121], v[204:207], v[26:29]
	v_mfma_f32_16x16x32_bf16 v[10:13], v[118:121], v[212:215], v[10:13]
	v_mfma_f32_16x16x32_bf16 v[14:17], v[110:113], v[212:215], v[14:17]
	s_setprio 2
	s_setprio 0
	v_mfma_f32_16x16x32_bf16 v[54:57], v[162:165], v[184:187], v[54:57]
	v_mfma_f32_16x16x32_bf16 v[50:53], v[176:179], v[184:187], v[50:53]
	v_mfma_f32_16x16x32_bf16 v[34:37], v[176:179], v[192:195], v[34:37]
	v_mfma_f32_16x16x32_bf16 v[38:41], v[162:165], v[192:195], v[38:41]
	v_mfma_f32_16x16x32_bf16 v[22:25], v[162:165], v[200:203], v[22:25]
	v_mfma_f32_16x16x32_bf16 v[18:21], v[176:179], v[200:203], v[18:21]
	v_mfma_f32_16x16x32_bf16 v[2:5], v[176:179], v[208:211], v[2:5]
	v_mfma_f32_16x16x32_bf16 v[6:9], v[162:165], v[208:211], v[6:9]
	v_mfma_f32_16x16x32_bf16 v[54:57], v[172:175], v[188:191], v[54:57]
	v_mfma_f32_16x16x32_bf16 v[50:53], v[180:183], v[188:191], v[50:53]
	v_mfma_f32_16x16x32_bf16 v[34:37], v[180:183], v[196:199], v[34:37]
	v_mfma_f32_16x16x32_bf16 v[38:41], v[172:175], v[196:199], v[38:41]
	v_mfma_f32_16x16x32_bf16 v[22:25], v[172:175], v[204:207], v[22:25]
	v_mfma_f32_16x16x32_bf16 v[18:21], v[180:183], v[204:207], v[18:21]
	v_mfma_f32_16x16x32_bf16 v[2:5], v[180:183], v[212:215], v[2:5]
	v_mfma_f32_16x16x32_bf16 v[6:9], v[172:175], v[212:215], v[6:9]
	s_setprio 2
	s_barrier
	s_add_i32 s62, s62, 2
	s_add_u32 s60, s60, 0x100
	s_addc_u32 s61, s61, 0
	s_cmp_gt_u32 s62, 41
	s_mov_b64 s[18:19], s[20:21]
	s_cbranch_scc0 .LBB0_2169
	s_and_b64 vcc, exec, s[14:15]
	s_cbranch_vccz .LBB0_2172
	s_barrier
